# j2 + PEER gather rows: conservative s_nop 0 pads around inline-asm fp4 converts/dots removed where no register dependence
# baseline (speedup 1.0000x reference)
; #define P4_FOR16(M) M(0) M(1) M(2) M(3) M(4) M(5) M(6) M(7) M(8) M(9) M(10) M(11) M(12) M(13) M(14) M(15)
; #define P4_U(i) { P4_DOT(b##i, part[i]); const int nk_ = __builtin_amdgcn_readlane(ksel, nb + i); P4_LOAD(b##i, Ug, nk_); }
; #define P4_U(i) { P4_DOT(b##i, part[i]); const int nk_ = __builtin_amdgcn_readlane(kn, i); P4_LOAD(b##i, nbase, nk_); }
; __device__ __forceinline__ void peer_gather_f4p(const float* X, const int* __restrict__ IDX, const float* __restrict__ G, ...
;     ...
; #pragma unroll 1
;         for (int bt = 0; bt < 7; ++bt) {
;             const int ksel = (bt + 1 < 4) ? k0 : k1;
;             const int nb = (16 * (bt + 1)) & 63;
;     ...
;             P4_FOR16(P4_U)
;     ...
;             P4_RED(bt);
;         }
.LBB0_533:
	s_mov_b32 s87, s86
	s_waitcnt vmcnt(15)
	v_cvt_scalef32_pk_bf16_fp4 v48, v64, 1.0
	v_cvt_scalef32_pk_bf16_fp4 v50, v64, 1.0 op_sel:[1,0,0]
	v_cvt_scalef32_pk_bf16_fp4 v52, v64, 1.0 op_sel:[0,1,0]
	v_cvt_scalef32_pk_bf16_fp4 v54, v64, 1.0 op_sel:[1,1,0]
	v_dot2_f32_bf16 v56, v48, v6, 0
	v_dot2_f32_bf16 v48, v50, v4, 0
	v_dot2_f32_bf16 v56, v52, v10, v56
	s_cmp_lt_u32 s29, 3
	v_dot2_f32_bf16 v48, v54, v8, v48
	v_cvt_scalef32_pk_bf16_fp4 v50, v65, 1.0
	v_cvt_scalef32_pk_bf16_fp4 v52, v65, 1.0 op_sel:[1,0,0]
	v_cvt_scalef32_pk_bf16_fp4 v54, v65, 1.0 op_sel:[0,1,0]
	v_cvt_scalef32_pk_bf16_fp4 v58, v65, 1.0 op_sel:[1,1,0]
	s_cselect_b64 s[50:51], -1, 0
	v_dot2_f32_bf16 v56, v50, v14, v56
	v_dot2_f32_bf16 v48, v52, v12, v48
	s_waitcnt lgkmcnt(1)
	v_cndmask_b32_e64 v46, v39, v38, s[50:51]
	v_dot2_f32_bf16 v56, v54, v18, v56
	v_dot2_f32_bf16 v48, v58, v16, v48
	v_cvt_scalef32_pk_bf16_fp4 v50, v66, 1.0
	v_cvt_scalef32_pk_bf16_fp4 v52, v66, 1.0 op_sel:[1,0,0]
	v_cvt_scalef32_pk_bf16_fp4 v54, v66, 1.0 op_sel:[0,1,0]
	v_cvt_scalef32_pk_bf16_fp4 v58, v66, 1.0 op_sel:[1,1,0]
	s_add_i32 s12, s28, -15
	v_dot2_f32_bf16 v56, v50, v22, v56
	v_dot2_f32_bf16 v48, v52, v20, v48
	v_readlane_b32 s12, v46, s12
	v_dot2_f32_bf16 v56, v54, v26, v56
	v_dot2_f32_bf16 v48, v58, v24, v48
	v_cvt_scalef32_pk_bf16_fp4 v50, v67, 1.0
	v_cvt_scalef32_pk_bf16_fp4 v52, v67, 1.0 op_sel:[1,0,0]
	v_cvt_scalef32_pk_bf16_fp4 v54, v67, 1.0 op_sel:[0,1,0]
	v_cvt_scalef32_pk_bf16_fp4 v58, v67, 1.0 op_sel:[1,1,0]
	s_lshr_b32 s12, s12, 7
	v_dot2_f32_bf16 v56, v50, v30, v56
	v_dot2_f32_bf16 v48, v52, v28, v48
	s_mov_b32 s13, s86
	v_dot2_f32_bf16 v56, v54, v36, v56
	v_dot2_f32_bf16 v48, v58, v34, v48
	s_lshl_b64 s[12:13], s[12:13], 10
	s_nop 2
	v_readfirstlane_b32 s100, v40
	v_readfirstlane_b32 s101, v41
	v_subrev_u32_e32 v207, s100, v40
	v_add_f32_e32 v47, v56, v48
	s_add_u32 s12, s12, s100
	s_addc_u32 s13, s13, s101
	global_load_dwordx4 v[64:67], v207, s[12:13]
	s_waitcnt vmcnt(15)
	v_cvt_scalef32_pk_bf16_fp4 v48, v68, 1.0
	v_cvt_scalef32_pk_bf16_fp4 v50, v68, 1.0 op_sel:[1,0,0]
	v_cvt_scalef32_pk_bf16_fp4 v52, v68, 1.0 op_sel:[0,1,0]
	v_cvt_scalef32_pk_bf16_fp4 v54, v68, 1.0 op_sel:[1,1,0]
	v_dot2_f32_bf16 v56, v48, v6, 0
	v_dot2_f32_bf16 v48, v50, v4, 0
	v_dot2_f32_bf16 v56, v52, v10, v56
	s_add_i32 s12, s28, -14
	v_dot2_f32_bf16 v48, v54, v8, v48
	v_cvt_scalef32_pk_bf16_fp4 v50, v69, 1.0
	v_cvt_scalef32_pk_bf16_fp4 v52, v69, 1.0 op_sel:[1,0,0]
	v_cvt_scalef32_pk_bf16_fp4 v54, v69, 1.0 op_sel:[0,1,0]
	v_cvt_scalef32_pk_bf16_fp4 v58, v69, 1.0 op_sel:[1,1,0]
	v_readlane_b32 s12, v46, s12
	v_dot2_f32_bf16 v56, v50, v14, v56
	v_dot2_f32_bf16 v48, v52, v12, v48
	s_lshr_b32 s12, s12, 7
	v_dot2_f32_bf16 v56, v54, v18, v56
	v_dot2_f32_bf16 v48, v58, v16, v48
	v_cvt_scalef32_pk_bf16_fp4 v50, v70, 1.0
	v_cvt_scalef32_pk_bf16_fp4 v52, v70, 1.0 op_sel:[1,0,0]
	v_cvt_scalef32_pk_bf16_fp4 v54, v70, 1.0 op_sel:[0,1,0]
	v_cvt_scalef32_pk_bf16_fp4 v58, v70, 1.0 op_sel:[1,1,0]
	s_mov_b32 s13, s86
	v_dot2_f32_bf16 v56, v50, v22, v56
	v_dot2_f32_bf16 v48, v52, v20, v48
	s_lshl_b64 s[12:13], s[12:13], 10
	v_dot2_f32_bf16 v56, v54, v26, v56
	v_dot2_f32_bf16 v48, v58, v24, v48
	v_cvt_scalef32_pk_bf16_fp4 v50, v71, 1.0
	v_cvt_scalef32_pk_bf16_fp4 v52, v71, 1.0 op_sel:[1,0,0]
	v_cvt_scalef32_pk_bf16_fp4 v54, v71, 1.0 op_sel:[0,1,0]
	v_cvt_scalef32_pk_bf16_fp4 v58, v71, 1.0 op_sel:[1,1,0]
	v_mov_b32_e32 v100, 0
	v_dot2_f32_bf16 v56, v50, v30, v56
	v_dot2_f32_bf16 v48, v52, v28, v48
	v_mov_b32_e32 v42, 0
	v_dot2_f32_bf16 v56, v54, v36, v56
	v_dot2_f32_bf16 v48, v58, v34, v48
	s_nop 2
	v_add_f32_e32 v48, v56, v48
	s_add_u32 s12, s12, s100
	s_addc_u32 s13, s13, s101
	global_load_dwordx4 v[68:71], v207, s[12:13]
	s_waitcnt vmcnt(15)
	v_cvt_scalef32_pk_bf16_fp4 v50, v72, 1.0
	v_cvt_scalef32_pk_bf16_fp4 v52, v72, 1.0 op_sel:[1,0,0]
	v_cvt_scalef32_pk_bf16_fp4 v54, v72, 1.0 op_sel:[0,1,0]
	v_cvt_scalef32_pk_bf16_fp4 v56, v72, 1.0 op_sel:[1,1,0]
	s_add_i32 s12, s28, -13
	v_dot2_f32_bf16 v58, v50, v6, 0
	v_dot2_f32_bf16 v50, v52, v4, 0
	v_dot2_f32_bf16 v58, v54, v10, v58
	v_readlane_b32 s12, v46, s12
	v_dot2_f32_bf16 v50, v56, v8, v50
	v_cvt_scalef32_pk_bf16_fp4 v52, v73, 1.0
	v_cvt_scalef32_pk_bf16_fp4 v54, v73, 1.0 op_sel:[1,0,0]
	v_cvt_scalef32_pk_bf16_fp4 v56, v73, 1.0 op_sel:[0,1,0]
	v_cvt_scalef32_pk_bf16_fp4 v60, v73, 1.0 op_sel:[1,1,0]
	s_lshr_b32 s12, s12, 7
	v_dot2_f32_bf16 v58, v52, v14, v58
	v_dot2_f32_bf16 v50, v54, v12, v50
	s_mov_b32 s13, s86
	v_dot2_f32_bf16 v58, v56, v18, v58
	v_dot2_f32_bf16 v50, v60, v16, v50
	v_cvt_scalef32_pk_bf16_fp4 v52, v74, 1.0
	v_cvt_scalef32_pk_bf16_fp4 v54, v74, 1.0 op_sel:[1,0,0]
	v_cvt_scalef32_pk_bf16_fp4 v56, v74, 1.0 op_sel:[0,1,0]
	v_cvt_scalef32_pk_bf16_fp4 v60, v74, 1.0 op_sel:[1,1,0]
	s_lshl_b64 s[12:13], s[12:13], 10
	v_dot2_f32_bf16 v58, v52, v22, v58
	v_dot2_f32_bf16 v50, v54, v20, v50
	v_dot2_f32_bf16 v58, v56, v26, v58
	v_dot2_f32_bf16 v50, v60, v24, v50
	v_cvt_scalef32_pk_bf16_fp4 v52, v75, 1.0
	v_cvt_scalef32_pk_bf16_fp4 v54, v75, 1.0 op_sel:[1,0,0]
	v_cvt_scalef32_pk_bf16_fp4 v56, v75, 1.0 op_sel:[0,1,0]
	v_cvt_scalef32_pk_bf16_fp4 v60, v75, 1.0 op_sel:[1,1,0]
	v_dot2_f32_bf16 v58, v52, v30, v58
	v_dot2_f32_bf16 v50, v54, v28, v50
	v_dot2_f32_bf16 v58, v56, v36, v58
	v_dot2_f32_bf16 v50, v60, v34, v50
	s_nop 2
	v_add_f32_e32 v49, v58, v50
	s_add_u32 s12, s12, s100
	s_addc_u32 s13, s13, s101
	global_load_dwordx4 v[72:75], v207, s[12:13]
	s_waitcnt vmcnt(15)
; #define P4_FOR16(M) M(0) M(1) M(2) M(3) M(4) M(5) M(6) M(7) M(8) M(9) M(10) M(11) M(12) M(13) M(14) M(15)
; #define P4_U(i) { P4_DOT(b##i, part[i]); const int nk_ = __builtin_amdgcn_readlane(ksel, nb + i); P4_LOAD(b##i, Ug, nk_); }
; #define P4_U(i) { P4_DOT(b##i, part[i]); const int nk_ = __builtin_amdgcn_readlane(kn, i); P4_LOAD(b##i, nbase, nk_); }
; __device__ __forceinline__ void peer_gather_f4p(const float* X, const int* __restrict__ IDX, const float* __restrict__ G, ...
;     ...
; #pragma unroll 1
;         for (int bt = 0; bt < 7; ++bt) {
;             const int ksel = (bt + 1 < 4) ? k0 : k1;
;             const int nb = (16 * (bt + 1)) & 63;
;     ...
;             P4_FOR16(P4_U)
;     ...
;             P4_RED(bt);
;         }
	v_cvt_scalef32_pk_bf16_fp4 v50, v76, 1.0
	v_cvt_scalef32_pk_bf16_fp4 v52, v76, 1.0 op_sel:[1,0,0]
	v_cvt_scalef32_pk_bf16_fp4 v54, v76, 1.0 op_sel:[0,1,0]
	v_cvt_scalef32_pk_bf16_fp4 v56, v76, 1.0 op_sel:[1,1,0]
	v_dot2_f32_bf16 v58, v50, v6, 0
	v_dot2_f32_bf16 v50, v52, v4, 0
	v_dot2_f32_bf16 v58, v54, v10, v58
	s_add_i32 s12, s28, -12
	v_dot2_f32_bf16 v50, v56, v8, v50
	v_cvt_scalef32_pk_bf16_fp4 v52, v77, 1.0
	v_cvt_scalef32_pk_bf16_fp4 v54, v77, 1.0 op_sel:[1,0,0]
	v_cvt_scalef32_pk_bf16_fp4 v56, v77, 1.0 op_sel:[0,1,0]
	v_cvt_scalef32_pk_bf16_fp4 v60, v77, 1.0 op_sel:[1,1,0]
	v_readlane_b32 s12, v46, s12
	v_dot2_f32_bf16 v58, v52, v14, v58
	v_dot2_f32_bf16 v50, v54, v12, v50
	s_lshr_b32 s12, s12, 7
	v_dot2_f32_bf16 v58, v56, v18, v58
	v_dot2_f32_bf16 v50, v60, v16, v50
	v_cvt_scalef32_pk_bf16_fp4 v52, v78, 1.0
	v_cvt_scalef32_pk_bf16_fp4 v54, v78, 1.0 op_sel:[1,0,0]
	v_cvt_scalef32_pk_bf16_fp4 v56, v78, 1.0 op_sel:[0,1,0]
	v_cvt_scalef32_pk_bf16_fp4 v60, v78, 1.0 op_sel:[1,1,0]
	s_mov_b32 s13, s86
	v_dot2_f32_bf16 v58, v52, v22, v58
	v_dot2_f32_bf16 v50, v54, v20, v50
	s_lshl_b64 s[12:13], s[12:13], 10
	v_dot2_f32_bf16 v58, v56, v26, v58
	v_dot2_f32_bf16 v50, v60, v24, v50
	v_cvt_scalef32_pk_bf16_fp4 v52, v79, 1.0
	v_cvt_scalef32_pk_bf16_fp4 v54, v79, 1.0 op_sel:[1,0,0]
	v_cvt_scalef32_pk_bf16_fp4 v56, v79, 1.0 op_sel:[0,1,0]
	v_cvt_scalef32_pk_bf16_fp4 v60, v79, 1.0 op_sel:[1,1,0]
	v_dot2_f32_bf16 v58, v52, v30, v58
	v_dot2_f32_bf16 v50, v54, v28, v50
	v_dot2_f32_bf16 v58, v56, v36, v58
	v_dot2_f32_bf16 v50, v60, v34, v50
	s_nop 2
	v_add_f32_e32 v50, v58, v50
	s_add_u32 s12, s12, s100
	s_addc_u32 s13, s13, s101
	global_load_dwordx4 v[76:79], v207, s[12:13]
	s_waitcnt vmcnt(15)
	v_cvt_scalef32_pk_bf16_fp4 v52, v80, 1.0
	v_cvt_scalef32_pk_bf16_fp4 v54, v80, 1.0 op_sel:[1,0,0]
	v_cvt_scalef32_pk_bf16_fp4 v56, v80, 1.0 op_sel:[0,1,0]
	v_cvt_scalef32_pk_bf16_fp4 v58, v80, 1.0 op_sel:[1,1,0]
	s_add_i32 s12, s28, -11
	v_dot2_f32_bf16 v60, v52, v6, 0
	v_dot2_f32_bf16 v52, v54, v4, 0
	v_dot2_f32_bf16 v60, v56, v10, v60
	v_readlane_b32 s12, v46, s12
	v_dot2_f32_bf16 v52, v58, v8, v52
	v_cvt_scalef32_pk_bf16_fp4 v54, v81, 1.0
	v_cvt_scalef32_pk_bf16_fp4 v56, v81, 1.0 op_sel:[1,0,0]
	v_cvt_scalef32_pk_bf16_fp4 v58, v81, 1.0 op_sel:[0,1,0]
	v_cvt_scalef32_pk_bf16_fp4 v62, v81, 1.0 op_sel:[1,1,0]
	s_lshr_b32 s12, s12, 7
	v_dot2_f32_bf16 v60, v54, v14, v60
	v_dot2_f32_bf16 v52, v56, v12, v52
	s_mov_b32 s13, s86
	v_dot2_f32_bf16 v60, v58, v18, v60
	v_dot2_f32_bf16 v52, v62, v16, v52
	v_cvt_scalef32_pk_bf16_fp4 v54, v82, 1.0
	v_cvt_scalef32_pk_bf16_fp4 v56, v82, 1.0 op_sel:[1,0,0]
	v_cvt_scalef32_pk_bf16_fp4 v58, v82, 1.0 op_sel:[0,1,0]
	v_cvt_scalef32_pk_bf16_fp4 v62, v82, 1.0 op_sel:[1,1,0]
	s_lshl_b64 s[12:13], s[12:13], 10
	v_dot2_f32_bf16 v60, v54, v22, v60
	v_dot2_f32_bf16 v52, v56, v20, v52
	v_dot2_f32_bf16 v60, v58, v26, v60
	v_dot2_f32_bf16 v52, v62, v24, v52
	v_cvt_scalef32_pk_bf16_fp4 v54, v83, 1.0
	v_cvt_scalef32_pk_bf16_fp4 v56, v83, 1.0 op_sel:[1,0,0]
	v_cvt_scalef32_pk_bf16_fp4 v58, v83, 1.0 op_sel:[0,1,0]
	v_cvt_scalef32_pk_bf16_fp4 v62, v83, 1.0 op_sel:[1,1,0]
	v_dot2_f32_bf16 v60, v54, v30, v60
	v_dot2_f32_bf16 v52, v56, v28, v52
	v_dot2_f32_bf16 v60, v58, v36, v60
	v_dot2_f32_bf16 v52, v62, v34, v52
	s_nop 2
	v_add_f32_e32 v51, v60, v52
	s_add_u32 s12, s12, s100
	s_addc_u32 s13, s13, s101
	global_load_dwordx4 v[80:83], v207, s[12:13]
	s_waitcnt vmcnt(15)
	v_cvt_scalef32_pk_bf16_fp4 v52, v84, 1.0
	v_cvt_scalef32_pk_bf16_fp4 v54, v84, 1.0 op_sel:[1,0,0]
	v_cvt_scalef32_pk_bf16_fp4 v56, v84, 1.0 op_sel:[0,1,0]
	v_cvt_scalef32_pk_bf16_fp4 v58, v84, 1.0 op_sel:[1,1,0]
	v_dot2_f32_bf16 v60, v52, v6, 0
	v_dot2_f32_bf16 v52, v54, v4, 0
	v_dot2_f32_bf16 v60, v56, v10, v60
	s_add_i32 s12, s28, -10
	v_dot2_f32_bf16 v52, v58, v8, v52
	v_cvt_scalef32_pk_bf16_fp4 v54, v85, 1.0
	v_cvt_scalef32_pk_bf16_fp4 v56, v85, 1.0 op_sel:[1,0,0]
	v_cvt_scalef32_pk_bf16_fp4 v58, v85, 1.0 op_sel:[0,1,0]
	v_cvt_scalef32_pk_bf16_fp4 v62, v85, 1.0 op_sel:[1,1,0]
	v_readlane_b32 s12, v46, s12
	v_dot2_f32_bf16 v60, v54, v14, v60
	v_dot2_f32_bf16 v52, v56, v12, v52
	s_lshr_b32 s12, s12, 7
	v_dot2_f32_bf16 v60, v58, v18, v60
	v_dot2_f32_bf16 v52, v62, v16, v52
	v_cvt_scalef32_pk_bf16_fp4 v54, v86, 1.0
	v_cvt_scalef32_pk_bf16_fp4 v56, v86, 1.0 op_sel:[1,0,0]
	v_cvt_scalef32_pk_bf16_fp4 v58, v86, 1.0 op_sel:[0,1,0]
	v_cvt_scalef32_pk_bf16_fp4 v62, v86, 1.0 op_sel:[1,1,0]
	s_mov_b32 s13, s86
	v_dot2_f32_bf16 v60, v54, v22, v60
	v_dot2_f32_bf16 v52, v56, v20, v52
	s_lshl_b64 s[12:13], s[12:13], 10
	v_dot2_f32_bf16 v60, v58, v26, v60
	v_dot2_f32_bf16 v52, v62, v24, v52
	v_cvt_scalef32_pk_bf16_fp4 v54, v87, 1.0
	v_cvt_scalef32_pk_bf16_fp4 v56, v87, 1.0 op_sel:[1,0,0]
	v_cvt_scalef32_pk_bf16_fp4 v58, v87, 1.0 op_sel:[0,1,0]
	v_cvt_scalef32_pk_bf16_fp4 v62, v87, 1.0 op_sel:[1,1,0]
	v_dot2_f32_bf16 v60, v54, v30, v60
	v_dot2_f32_bf16 v52, v56, v28, v52
	v_dot2_f32_bf16 v60, v58, v36, v60
	v_dot2_f32_bf16 v52, v62, v34, v52
	s_nop 2
	v_add_f32_e32 v52, v60, v52
	s_add_u32 s12, s12, s100
	s_addc_u32 s13, s13, s101
	global_load_dwordx4 v[84:87], v207, s[12:13]
	s_waitcnt vmcnt(15)
; #define P4_FOR16(M) M(0) M(1) M(2) M(3) M(4) M(5) M(6) M(7) M(8) M(9) M(10) M(11) M(12) M(13) M(14) M(15)
; #define P4_U(i) { P4_DOT(b##i, part[i]); const int nk_ = __builtin_amdgcn_readlane(ksel, nb + i); P4_LOAD(b##i, Ug, nk_); }
; #define P4_U(i) { P4_DOT(b##i, part[i]); const int nk_ = __builtin_amdgcn_readlane(kn, i); P4_LOAD(b##i, nbase, nk_); }
; __device__ __forceinline__ void peer_gather_f4p(const float* X, const int* __restrict__ IDX, const float* __restrict__ G, ...
;     ...
; #pragma unroll 1
;         for (int bt = 0; bt < 7; ++bt) {
;             const int ksel = (bt + 1 < 4) ? k0 : k1;
;             const int nb = (16 * (bt + 1)) & 63;
;     ...
;             P4_FOR16(P4_U)
;     ...
;             P4_RED(bt);
;         }
	v_cvt_scalef32_pk_bf16_fp4 v54, v88, 1.0
	v_cvt_scalef32_pk_bf16_fp4 v56, v88, 1.0 op_sel:[1,0,0]
	v_cvt_scalef32_pk_bf16_fp4 v58, v88, 1.0 op_sel:[0,1,0]
	v_cvt_scalef32_pk_bf16_fp4 v60, v88, 1.0 op_sel:[1,1,0]
	s_add_i32 s12, s28, -9
	v_dot2_f32_bf16 v62, v54, v6, 0
	v_dot2_f32_bf16 v54, v56, v4, 0
	v_dot2_f32_bf16 v62, v58, v10, v62
	v_readlane_b32 s12, v46, s12
	v_dot2_f32_bf16 v54, v60, v8, v54
	v_cvt_scalef32_pk_bf16_fp4 v56, v89, 1.0
	v_cvt_scalef32_pk_bf16_fp4 v58, v89, 1.0 op_sel:[1,0,0]
	v_cvt_scalef32_pk_bf16_fp4 v60, v89, 1.0 op_sel:[0,1,0]
	v_cvt_scalef32_pk_bf16_fp4 v88, v89, 1.0 op_sel:[1,1,0]
	s_lshr_b32 s12, s12, 7
	v_dot2_f32_bf16 v62, v56, v14, v62
	v_dot2_f32_bf16 v54, v58, v12, v54
	s_mov_b32 s13, s86
	v_dot2_f32_bf16 v62, v60, v18, v62
	v_dot2_f32_bf16 v54, v88, v16, v54
	v_cvt_scalef32_pk_bf16_fp4 v56, v90, 1.0
	v_cvt_scalef32_pk_bf16_fp4 v58, v90, 1.0 op_sel:[1,0,0]
	v_cvt_scalef32_pk_bf16_fp4 v60, v90, 1.0 op_sel:[0,1,0]
	v_cvt_scalef32_pk_bf16_fp4 v88, v90, 1.0 op_sel:[1,1,0]
	s_lshl_b64 s[12:13], s[12:13], 10
	v_dot2_f32_bf16 v62, v56, v22, v62
	v_dot2_f32_bf16 v54, v58, v20, v54
	v_dot2_f32_bf16 v62, v60, v26, v62
	v_dot2_f32_bf16 v54, v88, v24, v54
	v_cvt_scalef32_pk_bf16_fp4 v56, v91, 1.0
	v_cvt_scalef32_pk_bf16_fp4 v58, v91, 1.0 op_sel:[1,0,0]
	v_cvt_scalef32_pk_bf16_fp4 v60, v91, 1.0 op_sel:[0,1,0]
	v_cvt_scalef32_pk_bf16_fp4 v88, v91, 1.0 op_sel:[1,1,0]
	v_dot2_f32_bf16 v62, v56, v30, v62
	v_dot2_f32_bf16 v54, v58, v28, v54
	v_dot2_f32_bf16 v62, v60, v36, v62
	v_dot2_f32_bf16 v54, v88, v34, v54
	s_nop 2
	v_add_f32_e32 v53, v62, v54
	s_add_u32 s12, s12, s100
	s_addc_u32 s13, s13, s101
	global_load_dwordx4 v[88:91], v207, s[12:13]
	s_waitcnt vmcnt(15)
	v_cvt_scalef32_pk_bf16_fp4 v54, v92, 1.0
	v_cvt_scalef32_pk_bf16_fp4 v56, v92, 1.0 op_sel:[1,0,0]
	v_cvt_scalef32_pk_bf16_fp4 v58, v92, 1.0 op_sel:[0,1,0]
	v_cvt_scalef32_pk_bf16_fp4 v60, v92, 1.0 op_sel:[1,1,0]
	v_dot2_f32_bf16 v62, v54, v6, 0
	v_dot2_f32_bf16 v54, v56, v4, 0
	v_dot2_f32_bf16 v62, v58, v10, v62
	s_add_i32 s12, s28, -8
	v_dot2_f32_bf16 v54, v60, v8, v54
	v_cvt_scalef32_pk_bf16_fp4 v56, v93, 1.0
	v_cvt_scalef32_pk_bf16_fp4 v58, v93, 1.0 op_sel:[1,0,0]
	v_cvt_scalef32_pk_bf16_fp4 v60, v93, 1.0 op_sel:[0,1,0]
	v_cvt_scalef32_pk_bf16_fp4 v92, v93, 1.0 op_sel:[1,1,0]
	v_readlane_b32 s12, v46, s12
	v_dot2_f32_bf16 v62, v56, v14, v62
	v_dot2_f32_bf16 v54, v58, v12, v54
	s_lshr_b32 s12, s12, 7
	v_dot2_f32_bf16 v62, v60, v18, v62
	v_dot2_f32_bf16 v54, v92, v16, v54
	v_cvt_scalef32_pk_bf16_fp4 v56, v94, 1.0
	v_cvt_scalef32_pk_bf16_fp4 v58, v94, 1.0 op_sel:[1,0,0]
	v_cvt_scalef32_pk_bf16_fp4 v60, v94, 1.0 op_sel:[0,1,0]
	v_cvt_scalef32_pk_bf16_fp4 v92, v94, 1.0 op_sel:[1,1,0]
	s_mov_b32 s13, s86
	v_dot2_f32_bf16 v62, v56, v22, v62
	v_dot2_f32_bf16 v54, v58, v20, v54
	s_lshl_b64 s[12:13], s[12:13], 10
	v_dot2_f32_bf16 v62, v60, v26, v62
	v_dot2_f32_bf16 v54, v92, v24, v54
	v_cvt_scalef32_pk_bf16_fp4 v56, v95, 1.0
	v_cvt_scalef32_pk_bf16_fp4 v58, v95, 1.0 op_sel:[1,0,0]
	v_cvt_scalef32_pk_bf16_fp4 v60, v95, 1.0 op_sel:[0,1,0]
	v_cvt_scalef32_pk_bf16_fp4 v92, v95, 1.0 op_sel:[1,1,0]
	v_dot2_f32_bf16 v62, v56, v30, v62
	v_dot2_f32_bf16 v54, v58, v28, v54
	v_dot2_f32_bf16 v62, v60, v36, v62
	v_dot2_f32_bf16 v54, v92, v34, v54
	s_nop 2
	v_add_f32_e32 v54, v62, v54
	s_add_u32 s12, s12, s100
	s_addc_u32 s13, s13, s101
	global_load_dwordx4 v[92:95], v207, s[12:13]
	s_waitcnt vmcnt(15)
	v_cvt_scalef32_pk_bf16_fp4 v56, v96, 1.0
	v_cvt_scalef32_pk_bf16_fp4 v58, v96, 1.0 op_sel:[1,0,0]
	v_cvt_scalef32_pk_bf16_fp4 v60, v96, 1.0 op_sel:[0,1,0]
	v_cvt_scalef32_pk_bf16_fp4 v62, v96, 1.0 op_sel:[1,1,0]
	s_add_i32 s12, s28, -7
	v_dot2c_f32_bf16_e32 v100, v56, v6
	v_dot2_f32_bf16 v56, v58, v4, 0
	v_dot2c_f32_bf16_e32 v100, v60, v10
	v_readlane_b32 s12, v46, s12
	v_dot2_f32_bf16 v56, v62, v8, v56
	v_cvt_scalef32_pk_bf16_fp4 v58, v97, 1.0
	v_cvt_scalef32_pk_bf16_fp4 v60, v97, 1.0 op_sel:[1,0,0]
	v_cvt_scalef32_pk_bf16_fp4 v62, v97, 1.0 op_sel:[0,1,0]
	v_cvt_scalef32_pk_bf16_fp4 v96, v97, 1.0 op_sel:[1,1,0]
	s_lshr_b32 s12, s12, 7
	v_dot2c_f32_bf16_e32 v100, v58, v14
	v_dot2_f32_bf16 v56, v60, v12, v56
	s_mov_b32 s13, s86
	v_dot2c_f32_bf16_e32 v100, v62, v18
	v_dot2_f32_bf16 v56, v96, v16, v56
	v_cvt_scalef32_pk_bf16_fp4 v58, v98, 1.0
	v_cvt_scalef32_pk_bf16_fp4 v60, v98, 1.0 op_sel:[1,0,0]
	v_cvt_scalef32_pk_bf16_fp4 v62, v98, 1.0 op_sel:[0,1,0]
	v_cvt_scalef32_pk_bf16_fp4 v96, v98, 1.0 op_sel:[1,1,0]
	s_lshl_b64 s[12:13], s[12:13], 10
	v_dot2c_f32_bf16_e32 v100, v58, v22
	v_dot2_f32_bf16 v56, v60, v20, v56
	v_dot2c_f32_bf16_e32 v100, v62, v26
	v_dot2_f32_bf16 v56, v96, v24, v56
	v_cvt_scalef32_pk_bf16_fp4 v58, v99, 1.0
	v_cvt_scalef32_pk_bf16_fp4 v60, v99, 1.0 op_sel:[1,0,0]
	v_cvt_scalef32_pk_bf16_fp4 v62, v99, 1.0 op_sel:[0,1,0]
	v_cvt_scalef32_pk_bf16_fp4 v96, v99, 1.0 op_sel:[1,1,0]
	v_dot2c_f32_bf16_e32 v100, v58, v30
	v_dot2_f32_bf16 v56, v60, v28, v56
	v_dot2c_f32_bf16_e32 v100, v62, v36
	v_dot2_f32_bf16 v56, v96, v34, v56
	s_nop 2
	v_add_f32_e32 v55, v100, v56
	s_add_u32 s12, s12, s100
	s_addc_u32 s13, s13, s101
	global_load_dwordx4 v[96:99], v207, s[12:13]
	s_waitcnt vmcnt(15)
; #define P4_FOR16(M) M(0) M(1) M(2) M(3) M(4) M(5) M(6) M(7) M(8) M(9) M(10) M(11) M(12) M(13) M(14) M(15)
; #define P4_U(i) { P4_DOT(b##i, part[i]); const int nk_ = __builtin_amdgcn_readlane(ksel, nb + i); P4_LOAD(b##i, Ug, nk_); }
; #define P4_U(i) { P4_DOT(b##i, part[i]); const int nk_ = __builtin_amdgcn_readlane(kn, i); P4_LOAD(b##i, nbase, nk_); }
; __device__ __forceinline__ void peer_gather_f4p(const float* X, const int* __restrict__ IDX, const float* __restrict__ G, ...
;     ...
; #pragma unroll 1
;         for (int bt = 0; bt < 7; ++bt) {
;             const int ksel = (bt + 1 < 4) ? k0 : k1;
;             const int nb = (16 * (bt + 1)) & 63;
;     ...
;             P4_FOR16(P4_U)
;     ...
;             P4_RED(bt);
;         }
	v_cvt_scalef32_pk_bf16_fp4 v56, v104, 1.0
	v_cvt_scalef32_pk_bf16_fp4 v58, v104, 1.0 op_sel:[1,0,0]
	v_cvt_scalef32_pk_bf16_fp4 v60, v104, 1.0 op_sel:[0,1,0]
	v_cvt_scalef32_pk_bf16_fp4 v62, v104, 1.0 op_sel:[1,1,0]
	v_dot2_f32_bf16 v100, v56, v6, 0
	v_dot2_f32_bf16 v56, v58, v4, 0
	v_dot2_f32_bf16 v100, v60, v10, v100
	s_add_i32 s12, s28, -6
	v_dot2_f32_bf16 v56, v62, v8, v56
	v_cvt_scalef32_pk_bf16_fp4 v58, v105, 1.0
	v_cvt_scalef32_pk_bf16_fp4 v60, v105, 1.0 op_sel:[1,0,0]
	v_cvt_scalef32_pk_bf16_fp4 v62, v105, 1.0 op_sel:[0,1,0]
	v_cvt_scalef32_pk_bf16_fp4 v102, v105, 1.0 op_sel:[1,1,0]
	v_readlane_b32 s12, v46, s12
	v_dot2_f32_bf16 v100, v58, v14, v100
	v_dot2_f32_bf16 v56, v60, v12, v56
	s_lshr_b32 s12, s12, 7
	v_dot2_f32_bf16 v100, v62, v18, v100
	v_dot2_f32_bf16 v56, v102, v16, v56
	v_cvt_scalef32_pk_bf16_fp4 v58, v106, 1.0
	v_cvt_scalef32_pk_bf16_fp4 v60, v106, 1.0 op_sel:[1,0,0]
	v_cvt_scalef32_pk_bf16_fp4 v62, v106, 1.0 op_sel:[0,1,0]
	v_cvt_scalef32_pk_bf16_fp4 v102, v106, 1.0 op_sel:[1,1,0]
	s_mov_b32 s13, s86
	v_dot2_f32_bf16 v100, v58, v22, v100
	v_dot2_f32_bf16 v56, v60, v20, v56
	s_lshl_b64 s[12:13], s[12:13], 10
	v_dot2_f32_bf16 v100, v62, v26, v100
	v_dot2_f32_bf16 v56, v102, v24, v56
	v_cvt_scalef32_pk_bf16_fp4 v58, v107, 1.0
	v_cvt_scalef32_pk_bf16_fp4 v60, v107, 1.0 op_sel:[1,0,0]
	v_cvt_scalef32_pk_bf16_fp4 v62, v107, 1.0 op_sel:[0,1,0]
	v_cvt_scalef32_pk_bf16_fp4 v102, v107, 1.0 op_sel:[1,1,0]
	v_dot2_f32_bf16 v100, v58, v30, v100
	v_dot2_f32_bf16 v56, v60, v28, v56
	v_dot2_f32_bf16 v100, v62, v36, v100
	v_dot2_f32_bf16 v56, v102, v34, v56
	s_nop 2
	v_add_f32_e32 v56, v100, v56
	s_add_u32 s12, s12, s100
	s_addc_u32 s13, s13, s101
	global_load_dwordx4 v[104:107], v207, s[12:13]
	s_waitcnt vmcnt(15)
	v_cvt_scalef32_pk_bf16_fp4 v58, v108, 1.0
	v_cvt_scalef32_pk_bf16_fp4 v60, v108, 1.0 op_sel:[1,0,0]
	v_cvt_scalef32_pk_bf16_fp4 v62, v108, 1.0 op_sel:[0,1,0]
	v_cvt_scalef32_pk_bf16_fp4 v100, v108, 1.0 op_sel:[1,1,0]
	s_add_i32 s12, s28, -5
	v_dot2_f32_bf16 v102, v58, v6, 0
	v_dot2_f32_bf16 v58, v60, v4, 0
	v_dot2_f32_bf16 v102, v62, v10, v102
	v_readlane_b32 s12, v46, s12
	v_dot2_f32_bf16 v58, v100, v8, v58
	v_cvt_scalef32_pk_bf16_fp4 v60, v109, 1.0
	v_cvt_scalef32_pk_bf16_fp4 v62, v109, 1.0 op_sel:[1,0,0]
	v_cvt_scalef32_pk_bf16_fp4 v100, v109, 1.0 op_sel:[0,1,0]
	v_cvt_scalef32_pk_bf16_fp4 v108, v109, 1.0 op_sel:[1,1,0]
	s_lshr_b32 s12, s12, 7
	v_dot2_f32_bf16 v102, v60, v14, v102
	v_dot2_f32_bf16 v58, v62, v12, v58
	s_mov_b32 s13, s86
	v_dot2_f32_bf16 v102, v100, v18, v102
	v_dot2_f32_bf16 v58, v108, v16, v58
	v_cvt_scalef32_pk_bf16_fp4 v60, v110, 1.0
	v_cvt_scalef32_pk_bf16_fp4 v62, v110, 1.0 op_sel:[1,0,0]
	v_cvt_scalef32_pk_bf16_fp4 v100, v110, 1.0 op_sel:[0,1,0]
	v_cvt_scalef32_pk_bf16_fp4 v108, v110, 1.0 op_sel:[1,1,0]
	s_lshl_b64 s[12:13], s[12:13], 10
	v_dot2_f32_bf16 v102, v60, v22, v102
	v_dot2_f32_bf16 v58, v62, v20, v58
	v_dot2_f32_bf16 v102, v100, v26, v102
	v_dot2_f32_bf16 v58, v108, v24, v58
	v_cvt_scalef32_pk_bf16_fp4 v60, v111, 1.0
	v_cvt_scalef32_pk_bf16_fp4 v62, v111, 1.0 op_sel:[1,0,0]
	v_cvt_scalef32_pk_bf16_fp4 v100, v111, 1.0 op_sel:[0,1,0]
	v_cvt_scalef32_pk_bf16_fp4 v108, v111, 1.0 op_sel:[1,1,0]
	v_dot2_f32_bf16 v102, v60, v30, v102
	v_dot2_f32_bf16 v58, v62, v28, v58
	v_dot2_f32_bf16 v102, v100, v36, v102
	v_dot2_f32_bf16 v58, v108, v34, v58
	s_nop 2
	v_add_f32_e32 v57, v102, v58
	s_add_u32 s12, s12, s100
	s_addc_u32 s13, s13, s101
	global_load_dwordx4 v[108:111], v207, s[12:13]
	s_waitcnt vmcnt(15)
	v_cvt_scalef32_pk_bf16_fp4 v58, v112, 1.0
	v_cvt_scalef32_pk_bf16_fp4 v60, v112, 1.0 op_sel:[1,0,0]
	v_cvt_scalef32_pk_bf16_fp4 v62, v112, 1.0 op_sel:[0,1,0]
	v_cvt_scalef32_pk_bf16_fp4 v100, v112, 1.0 op_sel:[1,1,0]
	v_dot2_f32_bf16 v102, v58, v6, 0
	v_dot2_f32_bf16 v58, v60, v4, 0
	v_dot2_f32_bf16 v102, v62, v10, v102
	s_add_i32 s12, s28, -4
	v_dot2_f32_bf16 v58, v100, v8, v58
	v_cvt_scalef32_pk_bf16_fp4 v60, v113, 1.0
	v_cvt_scalef32_pk_bf16_fp4 v62, v113, 1.0 op_sel:[1,0,0]
	v_cvt_scalef32_pk_bf16_fp4 v100, v113, 1.0 op_sel:[0,1,0]
	v_cvt_scalef32_pk_bf16_fp4 v112, v113, 1.0 op_sel:[1,1,0]
	v_readlane_b32 s12, v46, s12
	v_dot2_f32_bf16 v102, v60, v14, v102
	v_dot2_f32_bf16 v58, v62, v12, v58
	s_lshr_b32 s12, s12, 7
	v_dot2_f32_bf16 v102, v100, v18, v102
	v_dot2_f32_bf16 v58, v112, v16, v58
	v_cvt_scalef32_pk_bf16_fp4 v60, v114, 1.0
	v_cvt_scalef32_pk_bf16_fp4 v62, v114, 1.0 op_sel:[1,0,0]
	v_cvt_scalef32_pk_bf16_fp4 v100, v114, 1.0 op_sel:[0,1,0]
	v_cvt_scalef32_pk_bf16_fp4 v112, v114, 1.0 op_sel:[1,1,0]
	s_mov_b32 s13, s86
	v_dot2_f32_bf16 v102, v60, v22, v102
	v_dot2_f32_bf16 v58, v62, v20, v58
	s_lshl_b64 s[12:13], s[12:13], 10
	v_dot2_f32_bf16 v102, v100, v26, v102
	v_dot2_f32_bf16 v58, v112, v24, v58
	v_cvt_scalef32_pk_bf16_fp4 v60, v115, 1.0
	v_cvt_scalef32_pk_bf16_fp4 v62, v115, 1.0 op_sel:[1,0,0]
	v_cvt_scalef32_pk_bf16_fp4 v100, v115, 1.0 op_sel:[0,1,0]
	v_cvt_scalef32_pk_bf16_fp4 v112, v115, 1.0 op_sel:[1,1,0]
	v_dot2_f32_bf16 v102, v60, v30, v102
	v_dot2_f32_bf16 v58, v62, v28, v58
	v_dot2_f32_bf16 v102, v100, v36, v102
	v_dot2_f32_bf16 v58, v112, v34, v58
	s_nop 2
	v_add_f32_e32 v132, v102, v58
	s_add_u32 s12, s12, s100
	s_addc_u32 s13, s13, s101
	global_load_dwordx4 v[112:115], v207, s[12:13]
	s_waitcnt vmcnt(15)
; #define P4_FOR16(M) M(0) M(1) M(2) M(3) M(4) M(5) M(6) M(7) M(8) M(9) M(10) M(11) M(12) M(13) M(14) M(15)
; #define P4_U(i) { P4_DOT(b##i, part[i]); const int nk_ = __builtin_amdgcn_readlane(ksel, nb + i); P4_LOAD(b##i, Ug, nk_); }
; #define P4_U(i) { P4_DOT(b##i, part[i]); const int nk_ = __builtin_amdgcn_readlane(kn, i); P4_LOAD(b##i, nbase, nk_); }
; __device__ __forceinline__ void peer_gather_f4p(const float* X, const int* __restrict__ IDX, const float* __restrict__ G, ...
;     ...
; #pragma unroll 1
;         for (int bt = 0; bt < 7; ++bt) {
;             const int ksel = (bt + 1 < 4) ? k0 : k1;
;             const int nb = (16 * (bt + 1)) & 63;
;     ...
;             P4_FOR16(P4_U)
;     ...
;             P4_RED(bt);
;         }
	v_cvt_scalef32_pk_bf16_fp4 v58, v116, 1.0
	v_cvt_scalef32_pk_bf16_fp4 v60, v116, 1.0 op_sel:[1,0,0]
	v_cvt_scalef32_pk_bf16_fp4 v62, v116, 1.0 op_sel:[0,1,0]
	v_cvt_scalef32_pk_bf16_fp4 v100, v116, 1.0 op_sel:[1,1,0]
	v_dot2_f32_bf16 v102, v58, v6, 0
	v_dot2_f32_bf16 v58, v60, v4, 0
	v_dot2_f32_bf16 v102, v62, v10, v102
	s_add_i32 s12, s28, -3
	v_dot2_f32_bf16 v58, v100, v8, v58
	v_cvt_scalef32_pk_bf16_fp4 v60, v117, 1.0
	v_cvt_scalef32_pk_bf16_fp4 v62, v117, 1.0 op_sel:[1,0,0]
	v_cvt_scalef32_pk_bf16_fp4 v100, v117, 1.0 op_sel:[0,1,0]
	v_cvt_scalef32_pk_bf16_fp4 v116, v117, 1.0 op_sel:[1,1,0]
	v_readlane_b32 s12, v46, s12
	v_dot2_f32_bf16 v102, v60, v14, v102
	v_dot2_f32_bf16 v58, v62, v12, v58
	s_lshr_b32 s12, s12, 7
	v_dot2_f32_bf16 v102, v100, v18, v102
	v_dot2_f32_bf16 v58, v116, v16, v58
	v_cvt_scalef32_pk_bf16_fp4 v60, v118, 1.0
	v_cvt_scalef32_pk_bf16_fp4 v62, v118, 1.0 op_sel:[1,0,0]
	v_cvt_scalef32_pk_bf16_fp4 v100, v118, 1.0 op_sel:[0,1,0]
	v_cvt_scalef32_pk_bf16_fp4 v116, v118, 1.0 op_sel:[1,1,0]
	s_mov_b32 s13, s86
	v_dot2_f32_bf16 v102, v60, v22, v102
	v_dot2_f32_bf16 v58, v62, v20, v58
	s_lshl_b64 s[12:13], s[12:13], 10
	v_dot2_f32_bf16 v102, v100, v26, v102
	v_dot2_f32_bf16 v58, v116, v24, v58
	v_cvt_scalef32_pk_bf16_fp4 v60, v119, 1.0
	v_cvt_scalef32_pk_bf16_fp4 v62, v119, 1.0 op_sel:[1,0,0]
	v_cvt_scalef32_pk_bf16_fp4 v100, v119, 1.0 op_sel:[0,1,0]
	v_cvt_scalef32_pk_bf16_fp4 v116, v119, 1.0 op_sel:[1,1,0]
	v_dot2_f32_bf16 v102, v60, v30, v102
	v_dot2_f32_bf16 v58, v62, v28, v58
	v_dot2_f32_bf16 v102, v100, v36, v102
	v_dot2_f32_bf16 v58, v116, v34, v58
	s_nop 2
	v_add_f32_e32 v133, v102, v58
	s_add_u32 s12, s12, s100
	s_addc_u32 s13, s13, s101
	global_load_dwordx4 v[116:119], v207, s[12:13]
	s_waitcnt vmcnt(15)
	v_cvt_scalef32_pk_bf16_fp4 v58, v120, 1.0
	v_cvt_scalef32_pk_bf16_fp4 v60, v120, 1.0 op_sel:[1,0,0]
	v_cvt_scalef32_pk_bf16_fp4 v62, v120, 1.0 op_sel:[0,1,0]
	v_cvt_scalef32_pk_bf16_fp4 v100, v120, 1.0 op_sel:[1,1,0]
	v_dot2_f32_bf16 v102, v58, v6, 0
	v_dot2_f32_bf16 v58, v60, v4, 0
	v_dot2_f32_bf16 v102, v62, v10, v102
	s_add_i32 s12, s28, -2
	v_dot2_f32_bf16 v58, v100, v8, v58
	v_cvt_scalef32_pk_bf16_fp4 v60, v121, 1.0
	v_cvt_scalef32_pk_bf16_fp4 v62, v121, 1.0 op_sel:[1,0,0]
	v_cvt_scalef32_pk_bf16_fp4 v100, v121, 1.0 op_sel:[0,1,0]
	v_cvt_scalef32_pk_bf16_fp4 v120, v121, 1.0 op_sel:[1,1,0]
	v_readlane_b32 s12, v46, s12
	v_dot2_f32_bf16 v102, v60, v14, v102
	v_dot2_f32_bf16 v58, v62, v12, v58
	s_lshr_b32 s12, s12, 7
	v_dot2_f32_bf16 v102, v100, v18, v102
	v_dot2_f32_bf16 v58, v120, v16, v58
	v_cvt_scalef32_pk_bf16_fp4 v60, v122, 1.0
	v_cvt_scalef32_pk_bf16_fp4 v62, v122, 1.0 op_sel:[1,0,0]
	v_cvt_scalef32_pk_bf16_fp4 v100, v122, 1.0 op_sel:[0,1,0]
	v_cvt_scalef32_pk_bf16_fp4 v120, v122, 1.0 op_sel:[1,1,0]
	s_mov_b32 s13, s86
	v_dot2_f32_bf16 v102, v60, v22, v102
	v_dot2_f32_bf16 v58, v62, v20, v58
	s_lshl_b64 s[12:13], s[12:13], 10
	v_dot2_f32_bf16 v102, v100, v26, v102
	v_dot2_f32_bf16 v58, v120, v24, v58
	v_cvt_scalef32_pk_bf16_fp4 v60, v123, 1.0
	v_cvt_scalef32_pk_bf16_fp4 v62, v123, 1.0 op_sel:[1,0,0]
	v_cvt_scalef32_pk_bf16_fp4 v100, v123, 1.0 op_sel:[0,1,0]
	v_cvt_scalef32_pk_bf16_fp4 v120, v123, 1.0 op_sel:[1,1,0]
	v_dot2_f32_bf16 v102, v60, v30, v102
	v_dot2_f32_bf16 v58, v62, v28, v58
	v_dot2_f32_bf16 v102, v100, v36, v102
	v_dot2_f32_bf16 v58, v120, v34, v58
	s_nop 2
	v_add_f32_e32 v134, v102, v58
	s_add_u32 s12, s12, s100
	s_addc_u32 s13, s13, s101
	global_load_dwordx4 v[120:123], v207, s[12:13]
	s_waitcnt vmcnt(15)
	v_cvt_scalef32_pk_bf16_fp4 v58, v124, 1.0
	v_cvt_scalef32_pk_bf16_fp4 v60, v124, 1.0 op_sel:[1,0,0]
	v_cvt_scalef32_pk_bf16_fp4 v62, v124, 1.0 op_sel:[0,1,0]
	v_cvt_scalef32_pk_bf16_fp4 v100, v124, 1.0 op_sel:[1,1,0]
	v_dot2_f32_bf16 v102, v58, v6, 0
	v_dot2_f32_bf16 v58, v60, v4, 0
	v_dot2_f32_bf16 v102, v62, v10, v102
	s_add_i32 s12, s28, -1
	v_dot2_f32_bf16 v58, v100, v8, v58
	v_cvt_scalef32_pk_bf16_fp4 v60, v125, 1.0
	v_cvt_scalef32_pk_bf16_fp4 v62, v125, 1.0 op_sel:[1,0,0]
	v_cvt_scalef32_pk_bf16_fp4 v100, v125, 1.0 op_sel:[0,1,0]
	v_cvt_scalef32_pk_bf16_fp4 v124, v125, 1.0 op_sel:[1,1,0]
	v_readlane_b32 s12, v46, s12
	v_dot2_f32_bf16 v102, v60, v14, v102
	v_dot2_f32_bf16 v58, v62, v12, v58
	s_lshr_b32 s12, s12, 7
	v_dot2_f32_bf16 v102, v100, v18, v102
	v_dot2_f32_bf16 v58, v124, v16, v58
	v_cvt_scalef32_pk_bf16_fp4 v60, v126, 1.0
	v_cvt_scalef32_pk_bf16_fp4 v62, v126, 1.0 op_sel:[1,0,0]
	v_cvt_scalef32_pk_bf16_fp4 v100, v126, 1.0 op_sel:[0,1,0]
	v_cvt_scalef32_pk_bf16_fp4 v124, v126, 1.0 op_sel:[1,1,0]
	s_mov_b32 s13, s86
	v_dot2_f32_bf16 v102, v60, v22, v102
	v_dot2_f32_bf16 v58, v62, v20, v58
	s_lshl_b64 s[12:13], s[12:13], 10
	v_dot2_f32_bf16 v102, v100, v26, v102
	v_dot2_f32_bf16 v58, v124, v24, v58
	v_cvt_scalef32_pk_bf16_fp4 v60, v127, 1.0
	v_cvt_scalef32_pk_bf16_fp4 v62, v127, 1.0 op_sel:[1,0,0]
	v_cvt_scalef32_pk_bf16_fp4 v100, v127, 1.0 op_sel:[0,1,0]
	v_cvt_scalef32_pk_bf16_fp4 v124, v127, 1.0 op_sel:[1,1,0]
	v_dot2_f32_bf16 v102, v60, v30, v102
	v_dot2_f32_bf16 v58, v62, v28, v58
	v_dot2_f32_bf16 v102, v100, v36, v102
	v_dot2_f32_bf16 v58, v124, v34, v58
	s_nop 2
	v_add_f32_e32 v135, v102, v58
	s_add_u32 s12, s12, s100
	s_addc_u32 s13, s13, s101
	global_load_dwordx4 v[124:127], v207, s[12:13]
	s_waitcnt vmcnt(15)
; #define P4_FOR16(M) M(0) M(1) M(2) M(3) M(4) M(5) M(6) M(7) M(8) M(9) M(10) M(11) M(12) M(13) M(14) M(15)
; #define P4_U(i) { P4_DOT(b##i, part[i]); const int nk_ = __builtin_amdgcn_readlane(ksel, nb + i); P4_LOAD(b##i, Ug, nk_); }
; #define P4_U(i) { P4_DOT(b##i, part[i]); const int nk_ = __builtin_amdgcn_readlane(kn, i); P4_LOAD(b##i, nbase, nk_); }
; __device__ __forceinline__ float gelu_tanh(float h) {
;     return 0.5f * h * (1.f + tanhf(0.7978845608028654f * (h + 0.044715f * h * h * h)));
; }
; __device__ __forceinline__ void peer_gather_f4p(const float* X, const int* __restrict__ IDX, const float* __restrict__ G, ...
;     ...
; #pragma unroll 1
;         for (int bt = 0; bt < 7; ++bt) {
;             const int ksel = (bt + 1 < 4) ? k0 : k1;
;             const int nb = (16 * (bt + 1)) & 63;
;     ...
;             P4_FOR16(P4_U)
;     ...
;             P4_RED(bt);
;         }
	v_cvt_scalef32_pk_bf16_fp4 v58, v128, 1.0
	v_cvt_scalef32_pk_bf16_fp4 v60, v128, 1.0 op_sel:[1,0,0]
	v_cvt_scalef32_pk_bf16_fp4 v62, v128, 1.0 op_sel:[0,1,0]
	v_cvt_scalef32_pk_bf16_fp4 v100, v128, 1.0 op_sel:[1,1,0]
	v_readlane_b32 s12, v46, s28
	v_dot2_f32_bf16 v102, v58, v6, 0
	v_dot2c_f32_bf16_e32 v42, v60, v4
	s_lshr_b32 s12, s12, 7
	v_dot2_f32_bf16 v102, v62, v10, v102
	v_dot2c_f32_bf16_e32 v42, v100, v8
	v_cvt_scalef32_pk_bf16_fp4 v58, v129, 1.0
	v_cvt_scalef32_pk_bf16_fp4 v60, v129, 1.0 op_sel:[1,0,0]
	v_cvt_scalef32_pk_bf16_fp4 v62, v129, 1.0 op_sel:[0,1,0]
	v_cvt_scalef32_pk_bf16_fp4 v100, v129, 1.0 op_sel:[1,1,0]
	s_mov_b32 s13, s86
	v_dot2_f32_bf16 v102, v58, v14, v102
	v_dot2c_f32_bf16_e32 v42, v60, v12
	s_lshl_b64 s[12:13], s[12:13], 10
	v_dot2_f32_bf16 v102, v62, v18, v102
	v_dot2c_f32_bf16_e32 v42, v100, v16
	v_cvt_scalef32_pk_bf16_fp4 v58, v130, 1.0
	v_cvt_scalef32_pk_bf16_fp4 v60, v130, 1.0 op_sel:[1,0,0]
	v_cvt_scalef32_pk_bf16_fp4 v62, v130, 1.0 op_sel:[0,1,0]
	v_cvt_scalef32_pk_bf16_fp4 v100, v130, 1.0 op_sel:[1,1,0]
	v_cndmask_b32_e64 v46, v48, v56, s[48:49]
	v_dot2_f32_bf16 v102, v58, v22, v102
	v_dot2c_f32_bf16_e32 v42, v60, v20
	ds_swizzle_b32 v46, v46 offset:swizzle(SWAP,8)
	v_dot2_f32_bf16 v102, v62, v26, v102
	v_dot2c_f32_bf16_e32 v42, v100, v24
	v_cvt_scalef32_pk_bf16_fp4 v58, v131, 1.0
	v_cvt_scalef32_pk_bf16_fp4 v60, v131, 1.0 op_sel:[1,0,0]
	v_cvt_scalef32_pk_bf16_fp4 v62, v131, 1.0 op_sel:[0,1,0]
	v_cvt_scalef32_pk_bf16_fp4 v100, v131, 1.0 op_sel:[1,1,0]
	v_dot2_f32_bf16 v102, v58, v30, v102
	v_dot2c_f32_bf16_e32 v42, v60, v28
	v_dot2_f32_bf16 v102, v62, v36, v102
	v_dot2c_f32_bf16_e32 v42, v100, v34
	s_nop 2
	v_add_f32_e32 v58, v102, v42
	v_lshl_add_u64 v[42:43], v[40:41], 0, s[12:13]
	global_load_dwordx4 v[128:131], v[42:43], off
	v_cndmask_b32_e64 v43, v47, v55, s[48:49]
	ds_swizzle_b32 v43, v43 offset:swizzle(SWAP,8)
	v_cndmask_b32_e64 v42, v55, v47, s[48:49]
	v_cndmask_b32_e64 v47, v49, v57, s[48:49]
	ds_swizzle_b32 v47, v47 offset:swizzle(SWAP,8)
	s_waitcnt lgkmcnt(1)
	v_add_f32_e32 v42, v42, v43
	v_cndmask_b32_e64 v43, v56, v48, s[48:49]
	v_cndmask_b32_e64 v48, v50, v132, s[48:49]
	v_add_f32_e32 v43, v43, v46
	v_cndmask_b32_e64 v46, v57, v49, s[48:49]
	ds_swizzle_b32 v48, v48 offset:swizzle(SWAP,8)
	v_cndmask_b32_e64 v49, v51, v133, s[48:49]
	ds_swizzle_b32 v49, v49 offset:swizzle(SWAP,8)
	s_waitcnt lgkmcnt(2)
	v_add_f32_e32 v46, v46, v47
	v_cndmask_b32_e64 v47, v132, v50, s[48:49]
	v_cndmask_b32_e64 v50, v52, v134, s[48:49]
	ds_swizzle_b32 v50, v50 offset:swizzle(SWAP,8)
	s_waitcnt lgkmcnt(2)
	v_add_f32_e32 v47, v47, v48
	v_cndmask_b32_e64 v48, v133, v51, s[48:49]
	v_cndmask_b32_e64 v51, v53, v135, s[48:49]
	s_waitcnt lgkmcnt(1)
	v_add_f32_e32 v48, v48, v49
	v_cndmask_b32_e64 v49, v134, v52, s[48:49]
	ds_swizzle_b32 v51, v51 offset:swizzle(SWAP,8)
	v_cndmask_b32_e64 v52, v54, v58, s[48:49]
	ds_swizzle_b32 v52, v52 offset:swizzle(SWAP,8)
	s_waitcnt lgkmcnt(2)
	v_add_f32_e32 v49, v49, v50
	v_cndmask_b32_e64 v50, v135, v53, s[48:49]
	s_waitcnt lgkmcnt(1)
	v_add_f32_e32 v50, v50, v51
	v_cndmask_b32_e64 v51, v58, v54, s[48:49]
	s_waitcnt lgkmcnt(0)
	v_add_f32_e32 v51, v51, v52
	v_cndmask_b32_e64 v53, v42, v48, s[46:47]
	v_cndmask_b32_e64 v42, v48, v42, s[46:47]
	v_cndmask_b32_e64 v48, v49, v43, s[46:47]
	v_cndmask_b32_e64 v43, v43, v49, s[46:47]
	v_cndmask_b32_e64 v49, v46, v50, s[46:47]
	v_cndmask_b32_e64 v52, v47, v51, s[46:47]
	ds_swizzle_b32 v53, v53 offset:swizzle(SWAP,4)
	ds_swizzle_b32 v43, v43 offset:swizzle(SWAP,4)
	ds_swizzle_b32 v49, v49 offset:swizzle(SWAP,4)
	ds_swizzle_b32 v52, v52 offset:swizzle(SWAP,4)
	v_cndmask_b32_e64 v46, v50, v46, s[46:47]
	v_cndmask_b32_e64 v47, v51, v47, s[46:47]
	s_waitcnt lgkmcnt(3)
	v_add_f32_e32 v42, v42, v53
	s_waitcnt lgkmcnt(2)
	v_add_f32_e32 v43, v48, v43
	s_waitcnt lgkmcnt(1)
	v_add_f32_e32 v46, v46, v49
	s_waitcnt lgkmcnt(0)
	v_add_f32_e32 v47, v47, v52
	v_cndmask_b32_e64 v48, v42, v46, s[44:45]
	v_cndmask_b32_e64 v49, v43, v47, s[44:45]
	ds_swizzle_b32 v48, v48 offset:swizzle(SWAP,2)
	ds_swizzle_b32 v49, v49 offset:swizzle(SWAP,2)
	v_cndmask_b32_e64 v42, v46, v42, s[44:45]
	v_cndmask_b32_e64 v43, v47, v43, s[44:45]
	s_waitcnt lgkmcnt(1)
	v_add_f32_e32 v42, v42, v48
	s_waitcnt lgkmcnt(0)
	v_add_f32_e32 v43, v43, v49
	v_cndmask_b32_e64 v46, v42, v43, s[42:43]
	ds_swizzle_b32 v46, v46 offset:swizzle(SWAP,1)
	v_cndmask_b32_e64 v42, v43, v42, s[42:43]
	s_waitcnt lgkmcnt(0)
	v_add_f32_e32 v42, v42, v46
	ds_swizzle_b32 v43, v42 offset:swizzle(SWAP,16)
	s_waitcnt lgkmcnt(0)
	v_add_f32_e32 v46, v42, v43
	ds_read2st64_b32 v[42:43], v45 offset1:8
	v_mov_b32_e32 v47, v46
	s_nop 1
	v_permlane32_swap_b32_e32 v46, v47
	v_add_f32_e32 v46, v46, v47
	s_waitcnt lgkmcnt(0)
	v_mul_f32_e32 v42, v42, v46
	v_mul_f32_e32 v46, 0x3d372713, v42
	v_mul_f32_e32 v46, v42, v46
	v_fma_f32 v46, v42, v46, v42
	v_mul_f32_e32 v46, 0x3f4c422a, v46
	v_cmp_nlt_f32_e64 s[12:13], |v46|, s25
	s_and_saveexec_b64 s[40:41], s[12:13]
	s_xor_b64 s[12:13], exec, s[40:41]
	s_cbranch_execz .LBB0_536
	v_add_f32_e64 v47, |v46|, |v46|
	v_mul_f32_e32 v48, 0x3fb8aa3b, v47
	v_rndne_f32_e32 v49, v48
	v_sub_f32_e32 v50, v48, v49
	v_fma_f32 v48, v47, s70, -v48
	v_fmac_f32_e32 v48, 0x32a5705f, v47
	v_add_f32_e32 v48, v50, v48
	v_cvt_i32_f32_e32 v49, v49
	v_exp_f32_e32 v48, v48
	v_cmp_ngt_f32_e64 s[50:51], s67, v47
	v_ldexp_f32 v48, v48, v49
	s_nop 0
	v_cndmask_b32_e64 v48, 0, v48, s[50:51]
	v_cmp_nlt_f32_e64 s[50:51], s68, v47
	s_nop 1
	v_cndmask_b32_e64 v47, v205, v48, s[50:51]
	v_add_f32_e32 v47, 1.0, v47
	v_rcp_f32_e32 v47, v47
	s_nop 0
	v_fma_f32 v47, v47, -2.0, 1.0
	s_andn2_saveexec_b64 s[12:13], s[12:13]
	s_cbranch_execnz .LBB0_537

; #define P4_FOR16(M) M(0) M(1) M(2) M(3) M(4) M(5) M(6) M(7) M(8) M(9) M(10) M(11) M(12) M(13) M(14) M(15)
; #define P4_U(i) { P4_DOT(b##i, part[i]); const int nk_ = __builtin_amdgcn_readlane(ksel, nb + i); P4_LOAD(b##i, Ug, nk_); }
; #define P4_U(i) { P4_DOT(b##i, part[i]); const int nk_ = __builtin_amdgcn_readlane(kn, i); P4_LOAD(b##i, nbase, nk_); }
; __device__ __forceinline__ void peer_gather_f4p(const float* X, const int* __restrict__ IDX, const float* __restrict__ G, ...
;     ...
;         {
;     ...
;             P4_FOR16(P4_U)
;     ...
;             P4_RED(7);
;         }
.LBB0_539:
	s_mov_b32 s87, s86
	s_waitcnt vmcnt(15)
	v_cvt_scalef32_pk_bf16_fp4 v42, v64, 1.0
	v_or_b32_e32 v40, s27, v44
	v_cvt_scalef32_pk_bf16_fp4 v44, v64, 1.0 op_sel:[1,0,0]
	v_cvt_scalef32_pk_bf16_fp4 v46, v64, 1.0 op_sel:[0,1,0]
	v_cvt_scalef32_pk_bf16_fp4 v48, v64, 1.0 op_sel:[1,1,0]
	v_dot2_f32_bf16 v50, v42, v6, 0
	v_dot2_f32_bf16 v42, v44, v4, 0
	v_dot2_f32_bf16 v50, v46, v10, v50
	s_cmp_eq_u32 s26, 3
	v_dot2_f32_bf16 v42, v48, v8, v42
	v_cvt_scalef32_pk_bf16_fp4 v44, v65, 1.0
	v_cvt_scalef32_pk_bf16_fp4 v46, v65, 1.0 op_sel:[1,0,0]
	v_cvt_scalef32_pk_bf16_fp4 v48, v65, 1.0 op_sel:[0,1,0]
	v_cvt_scalef32_pk_bf16_fp4 v52, v65, 1.0 op_sel:[1,1,0]
	v_readlane_b32 s26, v2, 0
	v_dot2_f32_bf16 v50, v44, v14, v50
	v_dot2_f32_bf16 v42, v46, v12, v42
	s_cselect_b32 s12, s53, s55
	v_dot2_f32_bf16 v50, v48, v18, v50
	v_dot2_f32_bf16 v42, v52, v16, v42
	v_cvt_scalef32_pk_bf16_fp4 v44, v66, 1.0
	v_cvt_scalef32_pk_bf16_fp4 v46, v66, 1.0 op_sel:[1,0,0]
	v_cvt_scalef32_pk_bf16_fp4 v48, v66, 1.0 op_sel:[0,1,0]
	v_cvt_scalef32_pk_bf16_fp4 v52, v66, 1.0 op_sel:[1,1,0]
	s_cselect_b32 s13, s52, s54
	v_dot2_f32_bf16 v50, v44, v22, v50
	v_dot2_f32_bf16 v42, v46, v20, v42
	s_lshr_b32 s26, s26, 7
	v_dot2_f32_bf16 v50, v48, v26, v50
	v_dot2_f32_bf16 v42, v52, v24, v42
	s_mov_b32 s27, s86
	v_cvt_scalef32_pk_bf16_fp4 v44, v67, 1.0
	v_cvt_scalef32_pk_bf16_fp4 v46, v67, 1.0 op_sel:[1,0,0]
	v_cvt_scalef32_pk_bf16_fp4 v48, v67, 1.0 op_sel:[0,1,0]
	v_cvt_scalef32_pk_bf16_fp4 v52, v67, 1.0 op_sel:[1,1,0]
	s_lshl_b64 s[26:27], s[26:27], 10
	v_dot2_f32_bf16 v50, v44, v30, v50
	v_dot2_f32_bf16 v42, v46, v28, v42
	s_add_u32 s26, s13, s26
	v_dot2_f32_bf16 v50, v48, v36, v50
	v_dot2_f32_bf16 v42, v52, v34, v42
	s_addc_u32 s27, s12, s27
	s_nop 2
	v_add_f32_e32 v41, v50, v42
	v_lshl_add_u64 v[42:43], s[26:27], 0, v[32:33]
	global_load_dwordx4 v[64:67], v[42:43], off
	s_waitcnt vmcnt(15)
	v_cvt_scalef32_pk_bf16_fp4 v42, v68, 1.0
	v_cvt_scalef32_pk_bf16_fp4 v44, v68, 1.0 op_sel:[1,0,0]
	v_cvt_scalef32_pk_bf16_fp4 v46, v68, 1.0 op_sel:[0,1,0]
	v_cvt_scalef32_pk_bf16_fp4 v48, v68, 1.0 op_sel:[1,1,0]
	v_dot2_f32_bf16 v50, v42, v6, 0
	v_dot2_f32_bf16 v42, v44, v4, 0
	v_dot2_f32_bf16 v50, v46, v10, v50
	v_readlane_b32 s26, v2, 1
	v_dot2_f32_bf16 v42, v48, v8, v42
	v_cvt_scalef32_pk_bf16_fp4 v44, v69, 1.0
	v_cvt_scalef32_pk_bf16_fp4 v46, v69, 1.0 op_sel:[1,0,0]
	v_cvt_scalef32_pk_bf16_fp4 v48, v69, 1.0 op_sel:[0,1,0]
	v_cvt_scalef32_pk_bf16_fp4 v52, v69, 1.0 op_sel:[1,1,0]
	s_lshr_b32 s26, s26, 7
	v_dot2_f32_bf16 v50, v44, v14, v50
	v_dot2_f32_bf16 v42, v46, v12, v42
	s_mov_b32 s27, s86
	v_dot2_f32_bf16 v50, v48, v18, v50
	v_dot2_f32_bf16 v42, v52, v16, v42
	v_cvt_scalef32_pk_bf16_fp4 v44, v70, 1.0
	v_cvt_scalef32_pk_bf16_fp4 v46, v70, 1.0 op_sel:[1,0,0]
	v_cvt_scalef32_pk_bf16_fp4 v48, v70, 1.0 op_sel:[0,1,0]
	v_cvt_scalef32_pk_bf16_fp4 v52, v70, 1.0 op_sel:[1,1,0]
	s_lshl_b64 s[26:27], s[26:27], 10
	v_dot2_f32_bf16 v50, v44, v22, v50
	v_dot2_f32_bf16 v42, v46, v20, v42
	s_add_u32 s26, s13, s26
	v_dot2_f32_bf16 v50, v48, v26, v50
	v_dot2_f32_bf16 v42, v52, v24, v42
	v_cvt_scalef32_pk_bf16_fp4 v44, v71, 1.0
	v_cvt_scalef32_pk_bf16_fp4 v46, v71, 1.0 op_sel:[1,0,0]
	v_cvt_scalef32_pk_bf16_fp4 v48, v71, 1.0 op_sel:[0,1,0]
	v_cvt_scalef32_pk_bf16_fp4 v52, v71, 1.0 op_sel:[1,1,0]
	s_addc_u32 s27, s12, s27
	v_dot2_f32_bf16 v50, v44, v30, v50
	v_dot2_f32_bf16 v42, v46, v28, v42
	v_mov_b32_e32 v38, 0
	v_dot2_f32_bf16 v50, v48, v36, v50
	v_dot2_f32_bf16 v42, v52, v34, v42
	s_nop 2
	v_add_f32_e32 v42, v50, v42
	v_lshl_add_u64 v[44:45], s[26:27], 0, v[32:33]
	global_load_dwordx4 v[68:71], v[44:45], off
	s_waitcnt vmcnt(15)
	v_cvt_scalef32_pk_bf16_fp4 v44, v72, 1.0
	v_cvt_scalef32_pk_bf16_fp4 v46, v72, 1.0 op_sel:[1,0,0]
	v_cvt_scalef32_pk_bf16_fp4 v48, v72, 1.0 op_sel:[0,1,0]
	v_cvt_scalef32_pk_bf16_fp4 v50, v72, 1.0 op_sel:[1,1,0]
	v_readlane_b32 s26, v2, 2
	v_dot2_f32_bf16 v52, v44, v6, 0
	v_dot2_f32_bf16 v44, v46, v4, 0
	v_dot2_f32_bf16 v52, v48, v10, v52
	s_lshr_b32 s26, s26, 7
	v_dot2_f32_bf16 v44, v50, v8, v44
	v_cvt_scalef32_pk_bf16_fp4 v46, v73, 1.0
	v_cvt_scalef32_pk_bf16_fp4 v48, v73, 1.0 op_sel:[1,0,0]
	v_cvt_scalef32_pk_bf16_fp4 v50, v73, 1.0 op_sel:[0,1,0]
	v_cvt_scalef32_pk_bf16_fp4 v54, v73, 1.0 op_sel:[1,1,0]
	s_mov_b32 s27, s86
	v_dot2_f32_bf16 v52, v46, v14, v52
	v_dot2_f32_bf16 v44, v48, v12, v44
	s_lshl_b64 s[26:27], s[26:27], 10
	v_dot2_f32_bf16 v52, v50, v18, v52
	v_dot2_f32_bf16 v44, v54, v16, v44
	v_cvt_scalef32_pk_bf16_fp4 v46, v74, 1.0
	v_cvt_scalef32_pk_bf16_fp4 v48, v74, 1.0 op_sel:[1,0,0]
	v_cvt_scalef32_pk_bf16_fp4 v50, v74, 1.0 op_sel:[0,1,0]
	v_cvt_scalef32_pk_bf16_fp4 v54, v74, 1.0 op_sel:[1,1,0]
	s_add_u32 s26, s13, s26
	v_dot2_f32_bf16 v52, v46, v22, v52
	v_dot2_f32_bf16 v44, v48, v20, v44
	s_addc_u32 s27, s12, s27
	v_dot2_f32_bf16 v52, v50, v26, v52
	v_dot2_f32_bf16 v44, v54, v24, v44
	v_cvt_scalef32_pk_bf16_fp4 v46, v75, 1.0
	v_cvt_scalef32_pk_bf16_fp4 v48, v75, 1.0 op_sel:[1,0,0]
	v_cvt_scalef32_pk_bf16_fp4 v50, v75, 1.0 op_sel:[0,1,0]
	v_cvt_scalef32_pk_bf16_fp4 v54, v75, 1.0 op_sel:[1,1,0]
	v_dot2_f32_bf16 v52, v46, v30, v52
	v_dot2_f32_bf16 v44, v48, v28, v44
	v_dot2_f32_bf16 v52, v50, v36, v52
	v_dot2_f32_bf16 v44, v54, v34, v44
	s_nop 2
	v_add_f32_e32 v43, v52, v44
	v_lshl_add_u64 v[44:45], s[26:27], 0, v[32:33]
	global_load_dwordx4 v[72:75], v[44:45], off
	s_waitcnt vmcnt(15)
; #define P4_FOR16(M) M(0) M(1) M(2) M(3) M(4) M(5) M(6) M(7) M(8) M(9) M(10) M(11) M(12) M(13) M(14) M(15)
; #define P4_U(i) { P4_DOT(b##i, part[i]); const int nk_ = __builtin_amdgcn_readlane(ksel, nb + i); P4_LOAD(b##i, Ug, nk_); }
; #define P4_U(i) { P4_DOT(b##i, part[i]); const int nk_ = __builtin_amdgcn_readlane(kn, i); P4_LOAD(b##i, nbase, nk_); }
; __device__ __forceinline__ void peer_gather_f4p(const float* X, const int* __restrict__ IDX, const float* __restrict__ G, ...
;     ...
;         {
;     ...
;             P4_FOR16(P4_U)
;     ...
;             P4_RED(7);
;         }
	v_cvt_scalef32_pk_bf16_fp4 v44, v76, 1.0
	v_cvt_scalef32_pk_bf16_fp4 v46, v76, 1.0 op_sel:[1,0,0]
	v_cvt_scalef32_pk_bf16_fp4 v48, v76, 1.0 op_sel:[0,1,0]
	v_cvt_scalef32_pk_bf16_fp4 v50, v76, 1.0 op_sel:[1,1,0]
	v_dot2_f32_bf16 v52, v44, v6, 0
	v_dot2_f32_bf16 v44, v46, v4, 0
	v_dot2_f32_bf16 v52, v48, v10, v52
	v_readlane_b32 s26, v2, 3
	v_dot2_f32_bf16 v44, v50, v8, v44
	v_cvt_scalef32_pk_bf16_fp4 v46, v77, 1.0
	v_cvt_scalef32_pk_bf16_fp4 v48, v77, 1.0 op_sel:[1,0,0]
	v_cvt_scalef32_pk_bf16_fp4 v50, v77, 1.0 op_sel:[0,1,0]
	v_cvt_scalef32_pk_bf16_fp4 v54, v77, 1.0 op_sel:[1,1,0]
	s_lshr_b32 s26, s26, 7
	v_dot2_f32_bf16 v52, v46, v14, v52
	v_dot2_f32_bf16 v44, v48, v12, v44
	s_mov_b32 s27, s86
	v_dot2_f32_bf16 v52, v50, v18, v52
	v_dot2_f32_bf16 v44, v54, v16, v44
	v_cvt_scalef32_pk_bf16_fp4 v46, v78, 1.0
	v_cvt_scalef32_pk_bf16_fp4 v48, v78, 1.0 op_sel:[1,0,0]
	v_cvt_scalef32_pk_bf16_fp4 v50, v78, 1.0 op_sel:[0,1,0]
	v_cvt_scalef32_pk_bf16_fp4 v54, v78, 1.0 op_sel:[1,1,0]
	s_lshl_b64 s[26:27], s[26:27], 10
	v_dot2_f32_bf16 v52, v46, v22, v52
	v_dot2_f32_bf16 v44, v48, v20, v44
	s_add_u32 s26, s13, s26
	v_dot2_f32_bf16 v52, v50, v26, v52
	v_dot2_f32_bf16 v44, v54, v24, v44
	v_cvt_scalef32_pk_bf16_fp4 v46, v79, 1.0
	v_cvt_scalef32_pk_bf16_fp4 v48, v79, 1.0 op_sel:[1,0,0]
	v_cvt_scalef32_pk_bf16_fp4 v50, v79, 1.0 op_sel:[0,1,0]
	v_cvt_scalef32_pk_bf16_fp4 v54, v79, 1.0 op_sel:[1,1,0]
	s_addc_u32 s27, s12, s27
	v_dot2_f32_bf16 v52, v46, v30, v52
	v_dot2_f32_bf16 v44, v48, v28, v44
	v_dot2_f32_bf16 v52, v50, v36, v52
	v_dot2_f32_bf16 v44, v54, v34, v44
	s_nop 2
	v_add_f32_e32 v44, v52, v44
	v_lshl_add_u64 v[46:47], s[26:27], 0, v[32:33]
	global_load_dwordx4 v[76:79], v[46:47], off
	s_waitcnt vmcnt(15)
	v_cvt_scalef32_pk_bf16_fp4 v46, v80, 1.0
	v_cvt_scalef32_pk_bf16_fp4 v48, v80, 1.0 op_sel:[1,0,0]
	v_cvt_scalef32_pk_bf16_fp4 v50, v80, 1.0 op_sel:[0,1,0]
	v_cvt_scalef32_pk_bf16_fp4 v52, v80, 1.0 op_sel:[1,1,0]
	v_readlane_b32 s26, v2, 4
	v_dot2_f32_bf16 v54, v46, v6, 0
	v_dot2_f32_bf16 v46, v48, v4, 0
	v_dot2_f32_bf16 v54, v50, v10, v54
	s_lshr_b32 s26, s26, 7
	v_dot2_f32_bf16 v46, v52, v8, v46
	v_cvt_scalef32_pk_bf16_fp4 v48, v81, 1.0
	v_cvt_scalef32_pk_bf16_fp4 v50, v81, 1.0 op_sel:[1,0,0]
	v_cvt_scalef32_pk_bf16_fp4 v52, v81, 1.0 op_sel:[0,1,0]
	v_cvt_scalef32_pk_bf16_fp4 v56, v81, 1.0 op_sel:[1,1,0]
	s_mov_b32 s27, s86
	v_dot2_f32_bf16 v54, v48, v14, v54
	v_dot2_f32_bf16 v46, v50, v12, v46
	s_lshl_b64 s[26:27], s[26:27], 10
	v_dot2_f32_bf16 v54, v52, v18, v54
	v_dot2_f32_bf16 v46, v56, v16, v46
	v_cvt_scalef32_pk_bf16_fp4 v48, v82, 1.0
	v_cvt_scalef32_pk_bf16_fp4 v50, v82, 1.0 op_sel:[1,0,0]
	v_cvt_scalef32_pk_bf16_fp4 v52, v82, 1.0 op_sel:[0,1,0]
	v_cvt_scalef32_pk_bf16_fp4 v56, v82, 1.0 op_sel:[1,1,0]
	s_add_u32 s26, s13, s26
	v_dot2_f32_bf16 v54, v48, v22, v54
	v_dot2_f32_bf16 v46, v50, v20, v46
	s_addc_u32 s27, s12, s27
	v_dot2_f32_bf16 v54, v52, v26, v54
	v_dot2_f32_bf16 v46, v56, v24, v46
	v_cvt_scalef32_pk_bf16_fp4 v48, v83, 1.0
	v_cvt_scalef32_pk_bf16_fp4 v50, v83, 1.0 op_sel:[1,0,0]
	v_cvt_scalef32_pk_bf16_fp4 v52, v83, 1.0 op_sel:[0,1,0]
	v_cvt_scalef32_pk_bf16_fp4 v56, v83, 1.0 op_sel:[1,1,0]
	v_dot2_f32_bf16 v54, v48, v30, v54
	v_dot2_f32_bf16 v46, v50, v28, v46
	v_dot2_f32_bf16 v54, v52, v36, v54
	v_dot2_f32_bf16 v46, v56, v34, v46
	s_nop 2
	v_add_f32_e32 v45, v54, v46
	v_lshl_add_u64 v[46:47], s[26:27], 0, v[32:33]
	global_load_dwordx4 v[80:83], v[46:47], off
	s_waitcnt vmcnt(15)
	v_cvt_scalef32_pk_bf16_fp4 v46, v84, 1.0
	v_cvt_scalef32_pk_bf16_fp4 v48, v84, 1.0 op_sel:[1,0,0]
	v_cvt_scalef32_pk_bf16_fp4 v50, v84, 1.0 op_sel:[0,1,0]
	v_cvt_scalef32_pk_bf16_fp4 v52, v84, 1.0 op_sel:[1,1,0]
	v_dot2_f32_bf16 v54, v46, v6, 0
	v_dot2_f32_bf16 v46, v48, v4, 0
	v_dot2_f32_bf16 v54, v50, v10, v54
	v_readlane_b32 s26, v2, 5
	v_dot2_f32_bf16 v46, v52, v8, v46
	v_cvt_scalef32_pk_bf16_fp4 v48, v85, 1.0
	v_cvt_scalef32_pk_bf16_fp4 v50, v85, 1.0 op_sel:[1,0,0]
	v_cvt_scalef32_pk_bf16_fp4 v52, v85, 1.0 op_sel:[0,1,0]
	v_cvt_scalef32_pk_bf16_fp4 v56, v85, 1.0 op_sel:[1,1,0]
	s_lshr_b32 s26, s26, 7
	v_dot2_f32_bf16 v54, v48, v14, v54
	v_dot2_f32_bf16 v46, v50, v12, v46
	s_mov_b32 s27, s86
	v_dot2_f32_bf16 v54, v52, v18, v54
	v_dot2_f32_bf16 v46, v56, v16, v46
	v_cvt_scalef32_pk_bf16_fp4 v48, v86, 1.0
	v_cvt_scalef32_pk_bf16_fp4 v50, v86, 1.0 op_sel:[1,0,0]
	v_cvt_scalef32_pk_bf16_fp4 v52, v86, 1.0 op_sel:[0,1,0]
	v_cvt_scalef32_pk_bf16_fp4 v56, v86, 1.0 op_sel:[1,1,0]
	s_lshl_b64 s[26:27], s[26:27], 10
	v_dot2_f32_bf16 v54, v48, v22, v54
	v_dot2_f32_bf16 v46, v50, v20, v46
	s_add_u32 s26, s13, s26
	v_dot2_f32_bf16 v54, v52, v26, v54
	v_dot2_f32_bf16 v46, v56, v24, v46
	v_cvt_scalef32_pk_bf16_fp4 v48, v87, 1.0
	v_cvt_scalef32_pk_bf16_fp4 v50, v87, 1.0 op_sel:[1,0,0]
	v_cvt_scalef32_pk_bf16_fp4 v52, v87, 1.0 op_sel:[0,1,0]
	v_cvt_scalef32_pk_bf16_fp4 v56, v87, 1.0 op_sel:[1,1,0]
	s_addc_u32 s27, s12, s27
	v_dot2_f32_bf16 v54, v48, v30, v54
	v_dot2_f32_bf16 v46, v50, v28, v46
	v_dot2_f32_bf16 v54, v52, v36, v54
	v_dot2_f32_bf16 v46, v56, v34, v46
	s_nop 2
	v_add_f32_e32 v46, v54, v46
	v_lshl_add_u64 v[48:49], s[26:27], 0, v[32:33]
	global_load_dwordx4 v[84:87], v[48:49], off
	s_waitcnt vmcnt(15)
; #define P4_FOR16(M) M(0) M(1) M(2) M(3) M(4) M(5) M(6) M(7) M(8) M(9) M(10) M(11) M(12) M(13) M(14) M(15)
; #define P4_U(i) { P4_DOT(b##i, part[i]); const int nk_ = __builtin_amdgcn_readlane(ksel, nb + i); P4_LOAD(b##i, Ug, nk_); }
; #define P4_U(i) { P4_DOT(b##i, part[i]); const int nk_ = __builtin_amdgcn_readlane(kn, i); P4_LOAD(b##i, nbase, nk_); }
; __device__ __forceinline__ void peer_gather_f4p(const float* X, const int* __restrict__ IDX, const float* __restrict__ G, ...
;     ...
;         {
;     ...
;             P4_FOR16(P4_U)
;     ...
;             P4_RED(7);
;         }
	v_cvt_scalef32_pk_bf16_fp4 v48, v88, 1.0
	v_cvt_scalef32_pk_bf16_fp4 v50, v88, 1.0 op_sel:[1,0,0]
	v_cvt_scalef32_pk_bf16_fp4 v52, v88, 1.0 op_sel:[0,1,0]
	v_cvt_scalef32_pk_bf16_fp4 v54, v88, 1.0 op_sel:[1,1,0]
	v_readlane_b32 s26, v2, 6
	v_dot2_f32_bf16 v56, v48, v6, 0
	v_dot2_f32_bf16 v48, v50, v4, 0
	v_dot2_f32_bf16 v56, v52, v10, v56
	s_lshr_b32 s26, s26, 7
	v_dot2_f32_bf16 v48, v54, v8, v48
	v_cvt_scalef32_pk_bf16_fp4 v50, v89, 1.0
	v_cvt_scalef32_pk_bf16_fp4 v52, v89, 1.0 op_sel:[1,0,0]
	v_cvt_scalef32_pk_bf16_fp4 v54, v89, 1.0 op_sel:[0,1,0]
	v_cvt_scalef32_pk_bf16_fp4 v58, v89, 1.0 op_sel:[1,1,0]
	s_mov_b32 s27, s86
	v_dot2_f32_bf16 v56, v50, v14, v56
	v_dot2_f32_bf16 v48, v52, v12, v48
	s_lshl_b64 s[26:27], s[26:27], 10
	v_dot2_f32_bf16 v56, v54, v18, v56
	v_dot2_f32_bf16 v48, v58, v16, v48
	v_cvt_scalef32_pk_bf16_fp4 v50, v90, 1.0
	v_cvt_scalef32_pk_bf16_fp4 v52, v90, 1.0 op_sel:[1,0,0]
	v_cvt_scalef32_pk_bf16_fp4 v54, v90, 1.0 op_sel:[0,1,0]
	v_cvt_scalef32_pk_bf16_fp4 v58, v90, 1.0 op_sel:[1,1,0]
	s_add_u32 s26, s13, s26
	v_dot2_f32_bf16 v56, v50, v22, v56
	v_dot2_f32_bf16 v48, v52, v20, v48
	s_addc_u32 s27, s12, s27
	v_dot2_f32_bf16 v56, v54, v26, v56
	v_dot2_f32_bf16 v48, v58, v24, v48
	v_cvt_scalef32_pk_bf16_fp4 v50, v91, 1.0
	v_cvt_scalef32_pk_bf16_fp4 v52, v91, 1.0 op_sel:[1,0,0]
	v_cvt_scalef32_pk_bf16_fp4 v54, v91, 1.0 op_sel:[0,1,0]
	v_cvt_scalef32_pk_bf16_fp4 v58, v91, 1.0 op_sel:[1,1,0]
	v_dot2_f32_bf16 v56, v50, v30, v56
	v_dot2_f32_bf16 v48, v52, v28, v48
	v_dot2_f32_bf16 v56, v54, v36, v56
	v_dot2_f32_bf16 v48, v58, v34, v48
	s_nop 2
	v_add_f32_e32 v47, v56, v48
	v_lshl_add_u64 v[48:49], s[26:27], 0, v[32:33]
	global_load_dwordx4 v[88:91], v[48:49], off
	s_waitcnt vmcnt(15)
	v_cvt_scalef32_pk_bf16_fp4 v48, v92, 1.0
	v_cvt_scalef32_pk_bf16_fp4 v50, v92, 1.0 op_sel:[1,0,0]
	v_cvt_scalef32_pk_bf16_fp4 v52, v92, 1.0 op_sel:[0,1,0]
	v_cvt_scalef32_pk_bf16_fp4 v54, v92, 1.0 op_sel:[1,1,0]
	v_dot2_f32_bf16 v56, v48, v6, 0
	v_dot2_f32_bf16 v48, v50, v4, 0
	v_dot2_f32_bf16 v56, v52, v10, v56
	v_readlane_b32 s26, v2, 7
	v_dot2_f32_bf16 v48, v54, v8, v48
	v_cvt_scalef32_pk_bf16_fp4 v50, v93, 1.0
	v_cvt_scalef32_pk_bf16_fp4 v52, v93, 1.0 op_sel:[1,0,0]
	v_cvt_scalef32_pk_bf16_fp4 v54, v93, 1.0 op_sel:[0,1,0]
	v_cvt_scalef32_pk_bf16_fp4 v58, v93, 1.0 op_sel:[1,1,0]
	s_lshr_b32 s26, s26, 7
	v_dot2_f32_bf16 v56, v50, v14, v56
	v_dot2_f32_bf16 v48, v52, v12, v48
	s_mov_b32 s27, s86
	v_dot2_f32_bf16 v56, v54, v18, v56
	v_dot2_f32_bf16 v48, v58, v16, v48
	v_cvt_scalef32_pk_bf16_fp4 v50, v94, 1.0
	v_cvt_scalef32_pk_bf16_fp4 v52, v94, 1.0 op_sel:[1,0,0]
	v_cvt_scalef32_pk_bf16_fp4 v54, v94, 1.0 op_sel:[0,1,0]
	v_cvt_scalef32_pk_bf16_fp4 v58, v94, 1.0 op_sel:[1,1,0]
	s_lshl_b64 s[26:27], s[26:27], 10
	v_dot2_f32_bf16 v56, v50, v22, v56
	v_dot2_f32_bf16 v48, v52, v20, v48
	s_add_u32 s26, s13, s26
	v_dot2_f32_bf16 v56, v54, v26, v56
	v_dot2_f32_bf16 v48, v58, v24, v48
	v_cvt_scalef32_pk_bf16_fp4 v50, v95, 1.0
	v_cvt_scalef32_pk_bf16_fp4 v52, v95, 1.0 op_sel:[1,0,0]
	v_cvt_scalef32_pk_bf16_fp4 v54, v95, 1.0 op_sel:[0,1,0]
	v_cvt_scalef32_pk_bf16_fp4 v58, v95, 1.0 op_sel:[1,1,0]
	s_addc_u32 s27, s12, s27
	v_dot2_f32_bf16 v56, v50, v30, v56
	v_dot2_f32_bf16 v48, v52, v28, v48
	v_dot2_f32_bf16 v56, v54, v36, v56
	v_dot2_f32_bf16 v48, v58, v34, v48
	s_nop 2
	v_add_f32_e32 v48, v56, v48
	v_lshl_add_u64 v[50:51], s[26:27], 0, v[32:33]
	global_load_dwordx4 v[92:95], v[50:51], off
	s_waitcnt vmcnt(15)
	v_cvt_scalef32_pk_bf16_fp4 v50, v96, 1.0
	v_cvt_scalef32_pk_bf16_fp4 v52, v96, 1.0 op_sel:[1,0,0]
	v_cvt_scalef32_pk_bf16_fp4 v54, v96, 1.0 op_sel:[0,1,0]
	v_cvt_scalef32_pk_bf16_fp4 v56, v96, 1.0 op_sel:[1,1,0]
	v_readlane_b32 s26, v2, 8
	v_dot2_f32_bf16 v58, v50, v6, 0
	v_dot2_f32_bf16 v50, v52, v4, 0
	v_dot2_f32_bf16 v58, v54, v10, v58
	s_lshr_b32 s26, s26, 7
	v_dot2_f32_bf16 v50, v56, v8, v50
	v_cvt_scalef32_pk_bf16_fp4 v52, v97, 1.0
	v_cvt_scalef32_pk_bf16_fp4 v54, v97, 1.0 op_sel:[1,0,0]
	v_cvt_scalef32_pk_bf16_fp4 v56, v97, 1.0 op_sel:[0,1,0]
	v_cvt_scalef32_pk_bf16_fp4 v60, v97, 1.0 op_sel:[1,1,0]
	s_mov_b32 s27, s86
	v_dot2_f32_bf16 v58, v52, v14, v58
	v_dot2_f32_bf16 v50, v54, v12, v50
	s_lshl_b64 s[26:27], s[26:27], 10
	v_dot2_f32_bf16 v58, v56, v18, v58
	v_dot2_f32_bf16 v50, v60, v16, v50
	v_cvt_scalef32_pk_bf16_fp4 v52, v98, 1.0
	v_cvt_scalef32_pk_bf16_fp4 v54, v98, 1.0 op_sel:[1,0,0]
	v_cvt_scalef32_pk_bf16_fp4 v56, v98, 1.0 op_sel:[0,1,0]
	v_cvt_scalef32_pk_bf16_fp4 v60, v98, 1.0 op_sel:[1,1,0]
	s_add_u32 s26, s13, s26
	v_dot2_f32_bf16 v58, v52, v22, v58
	v_dot2_f32_bf16 v50, v54, v20, v50
	s_addc_u32 s27, s12, s27
	v_dot2_f32_bf16 v58, v56, v26, v58
	v_dot2_f32_bf16 v50, v60, v24, v50
	v_cvt_scalef32_pk_bf16_fp4 v52, v99, 1.0
	v_cvt_scalef32_pk_bf16_fp4 v54, v99, 1.0 op_sel:[1,0,0]
	v_cvt_scalef32_pk_bf16_fp4 v56, v99, 1.0 op_sel:[0,1,0]
	v_cvt_scalef32_pk_bf16_fp4 v60, v99, 1.0 op_sel:[1,1,0]
	v_dot2_f32_bf16 v58, v52, v30, v58
	v_dot2_f32_bf16 v50, v54, v28, v50
	v_dot2_f32_bf16 v58, v56, v36, v58
	v_dot2_f32_bf16 v50, v60, v34, v50
	s_nop 2
	v_add_f32_e32 v49, v58, v50
	v_lshl_add_u64 v[50:51], s[26:27], 0, v[32:33]
	global_load_dwordx4 v[96:99], v[50:51], off
	s_waitcnt vmcnt(15)
; #define P4_FOR16(M) M(0) M(1) M(2) M(3) M(4) M(5) M(6) M(7) M(8) M(9) M(10) M(11) M(12) M(13) M(14) M(15)
; #define P4_U(i) { P4_DOT(b##i, part[i]); const int nk_ = __builtin_amdgcn_readlane(ksel, nb + i); P4_LOAD(b##i, Ug, nk_); }
; #define P4_U(i) { P4_DOT(b##i, part[i]); const int nk_ = __builtin_amdgcn_readlane(kn, i); P4_LOAD(b##i, nbase, nk_); }
; __device__ __forceinline__ void peer_gather_f4p(const float* X, const int* __restrict__ IDX, const float* __restrict__ G, ...
;     ...
;         {
;     ...
;             P4_FOR16(P4_U)
;     ...
;             P4_RED(7);
;         }
	v_cvt_scalef32_pk_bf16_fp4 v50, v104, 1.0
	v_cvt_scalef32_pk_bf16_fp4 v52, v104, 1.0 op_sel:[1,0,0]
	v_cvt_scalef32_pk_bf16_fp4 v54, v104, 1.0 op_sel:[0,1,0]
	v_cvt_scalef32_pk_bf16_fp4 v56, v104, 1.0 op_sel:[1,1,0]
	v_dot2_f32_bf16 v58, v50, v6, 0
	v_dot2_f32_bf16 v50, v52, v4, 0
	v_dot2_f32_bf16 v58, v54, v10, v58
	v_readlane_b32 s26, v2, 9
	v_dot2_f32_bf16 v50, v56, v8, v50
	v_cvt_scalef32_pk_bf16_fp4 v52, v105, 1.0
	v_cvt_scalef32_pk_bf16_fp4 v54, v105, 1.0 op_sel:[1,0,0]
	v_cvt_scalef32_pk_bf16_fp4 v56, v105, 1.0 op_sel:[0,1,0]
	v_cvt_scalef32_pk_bf16_fp4 v60, v105, 1.0 op_sel:[1,1,0]
	s_lshr_b32 s26, s26, 7
	v_dot2_f32_bf16 v58, v52, v14, v58
	v_dot2_f32_bf16 v50, v54, v12, v50
	s_mov_b32 s27, s86
	v_dot2_f32_bf16 v58, v56, v18, v58
	v_dot2_f32_bf16 v50, v60, v16, v50
	v_cvt_scalef32_pk_bf16_fp4 v52, v106, 1.0
	v_cvt_scalef32_pk_bf16_fp4 v54, v106, 1.0 op_sel:[1,0,0]
	v_cvt_scalef32_pk_bf16_fp4 v56, v106, 1.0 op_sel:[0,1,0]
	v_cvt_scalef32_pk_bf16_fp4 v60, v106, 1.0 op_sel:[1,1,0]
	s_lshl_b64 s[26:27], s[26:27], 10
	v_dot2_f32_bf16 v58, v52, v22, v58
	v_dot2_f32_bf16 v50, v54, v20, v50
	s_add_u32 s26, s13, s26
	v_dot2_f32_bf16 v58, v56, v26, v58
	v_dot2_f32_bf16 v50, v60, v24, v50
	v_cvt_scalef32_pk_bf16_fp4 v52, v107, 1.0
	v_cvt_scalef32_pk_bf16_fp4 v54, v107, 1.0 op_sel:[1,0,0]
	v_cvt_scalef32_pk_bf16_fp4 v56, v107, 1.0 op_sel:[0,1,0]
	v_cvt_scalef32_pk_bf16_fp4 v60, v107, 1.0 op_sel:[1,1,0]
	s_addc_u32 s27, s12, s27
	v_dot2_f32_bf16 v58, v52, v30, v58
	v_dot2_f32_bf16 v50, v54, v28, v50
	v_dot2_f32_bf16 v58, v56, v36, v58
	v_dot2_f32_bf16 v50, v60, v34, v50
	s_nop 2
	v_add_f32_e32 v50, v58, v50
	v_lshl_add_u64 v[52:53], s[26:27], 0, v[32:33]
	global_load_dwordx4 v[104:107], v[52:53], off
	s_waitcnt vmcnt(15)
	v_cvt_scalef32_pk_bf16_fp4 v52, v108, 1.0
	v_cvt_scalef32_pk_bf16_fp4 v54, v108, 1.0 op_sel:[1,0,0]
	v_cvt_scalef32_pk_bf16_fp4 v56, v108, 1.0 op_sel:[0,1,0]
	v_cvt_scalef32_pk_bf16_fp4 v58, v108, 1.0 op_sel:[1,1,0]
	v_readlane_b32 s26, v2, 10
	v_dot2_f32_bf16 v60, v52, v6, 0
	v_dot2_f32_bf16 v52, v54, v4, 0
	v_dot2_f32_bf16 v60, v56, v10, v60
	s_lshr_b32 s26, s26, 7
	v_dot2_f32_bf16 v52, v58, v8, v52
	v_cvt_scalef32_pk_bf16_fp4 v54, v109, 1.0
	v_cvt_scalef32_pk_bf16_fp4 v56, v109, 1.0 op_sel:[1,0,0]
	v_cvt_scalef32_pk_bf16_fp4 v58, v109, 1.0 op_sel:[0,1,0]
	v_cvt_scalef32_pk_bf16_fp4 v62, v109, 1.0 op_sel:[1,1,0]
	s_mov_b32 s27, s86
	v_dot2_f32_bf16 v60, v54, v14, v60
	v_dot2_f32_bf16 v52, v56, v12, v52
	s_lshl_b64 s[26:27], s[26:27], 10
	v_dot2_f32_bf16 v60, v58, v18, v60
	v_dot2_f32_bf16 v52, v62, v16, v52
	v_cvt_scalef32_pk_bf16_fp4 v54, v110, 1.0
	v_cvt_scalef32_pk_bf16_fp4 v56, v110, 1.0 op_sel:[1,0,0]
	v_cvt_scalef32_pk_bf16_fp4 v58, v110, 1.0 op_sel:[0,1,0]
	v_cvt_scalef32_pk_bf16_fp4 v62, v110, 1.0 op_sel:[1,1,0]
	s_add_u32 s26, s13, s26
	v_dot2_f32_bf16 v60, v54, v22, v60
	v_dot2_f32_bf16 v52, v56, v20, v52
	s_addc_u32 s27, s12, s27
	v_dot2_f32_bf16 v60, v58, v26, v60
	v_dot2_f32_bf16 v52, v62, v24, v52
	v_cvt_scalef32_pk_bf16_fp4 v54, v111, 1.0
	v_cvt_scalef32_pk_bf16_fp4 v56, v111, 1.0 op_sel:[1,0,0]
	v_cvt_scalef32_pk_bf16_fp4 v58, v111, 1.0 op_sel:[0,1,0]
	v_cvt_scalef32_pk_bf16_fp4 v62, v111, 1.0 op_sel:[1,1,0]
	v_dot2_f32_bf16 v60, v54, v30, v60
	v_dot2_f32_bf16 v52, v56, v28, v52
	v_dot2_f32_bf16 v60, v58, v36, v60
	v_dot2_f32_bf16 v52, v62, v34, v52
	s_nop 2
	v_add_f32_e32 v51, v60, v52
	v_lshl_add_u64 v[52:53], s[26:27], 0, v[32:33]
	global_load_dwordx4 v[108:111], v[52:53], off
	s_waitcnt vmcnt(15)
	v_cvt_scalef32_pk_bf16_fp4 v52, v112, 1.0
	v_cvt_scalef32_pk_bf16_fp4 v54, v112, 1.0 op_sel:[1,0,0]
	v_cvt_scalef32_pk_bf16_fp4 v56, v112, 1.0 op_sel:[0,1,0]
	v_cvt_scalef32_pk_bf16_fp4 v58, v112, 1.0 op_sel:[1,1,0]
	v_dot2_f32_bf16 v60, v52, v6, 0
	v_dot2_f32_bf16 v52, v54, v4, 0
	v_dot2_f32_bf16 v60, v56, v10, v60
	v_readlane_b32 s26, v2, 11
	v_dot2_f32_bf16 v52, v58, v8, v52
	v_cvt_scalef32_pk_bf16_fp4 v54, v113, 1.0
	v_cvt_scalef32_pk_bf16_fp4 v56, v113, 1.0 op_sel:[1,0,0]
	v_cvt_scalef32_pk_bf16_fp4 v58, v113, 1.0 op_sel:[0,1,0]
	v_cvt_scalef32_pk_bf16_fp4 v62, v113, 1.0 op_sel:[1,1,0]
	s_lshr_b32 s26, s26, 7
	v_dot2_f32_bf16 v60, v54, v14, v60
	v_dot2_f32_bf16 v52, v56, v12, v52
	s_mov_b32 s27, s86
	v_dot2_f32_bf16 v60, v58, v18, v60
	v_dot2_f32_bf16 v52, v62, v16, v52
	v_cvt_scalef32_pk_bf16_fp4 v54, v114, 1.0
	v_cvt_scalef32_pk_bf16_fp4 v56, v114, 1.0 op_sel:[1,0,0]
	v_cvt_scalef32_pk_bf16_fp4 v58, v114, 1.0 op_sel:[0,1,0]
	v_cvt_scalef32_pk_bf16_fp4 v62, v114, 1.0 op_sel:[1,1,0]
	s_lshl_b64 s[26:27], s[26:27], 10
	v_dot2_f32_bf16 v60, v54, v22, v60
	v_dot2_f32_bf16 v52, v56, v20, v52
	s_add_u32 s26, s13, s26
	v_dot2_f32_bf16 v60, v58, v26, v60
	v_dot2_f32_bf16 v52, v62, v24, v52
	v_cvt_scalef32_pk_bf16_fp4 v54, v115, 1.0
	v_cvt_scalef32_pk_bf16_fp4 v56, v115, 1.0 op_sel:[1,0,0]
	v_cvt_scalef32_pk_bf16_fp4 v58, v115, 1.0 op_sel:[0,1,0]
	v_cvt_scalef32_pk_bf16_fp4 v62, v115, 1.0 op_sel:[1,1,0]
	s_addc_u32 s27, s12, s27
	v_dot2_f32_bf16 v60, v54, v30, v60
	v_dot2_f32_bf16 v52, v56, v28, v52
	v_dot2_f32_bf16 v60, v58, v36, v60
	v_dot2_f32_bf16 v52, v62, v34, v52
	s_nop 2
	v_add_f32_e32 v100, v60, v52
	v_lshl_add_u64 v[52:53], s[26:27], 0, v[32:33]
	global_load_dwordx4 v[112:115], v[52:53], off
	s_waitcnt vmcnt(15)
; #define P4_FOR16(M) M(0) M(1) M(2) M(3) M(4) M(5) M(6) M(7) M(8) M(9) M(10) M(11) M(12) M(13) M(14) M(15)
; #define P4_U(i) { P4_DOT(b##i, part[i]); const int nk_ = __builtin_amdgcn_readlane(ksel, nb + i); P4_LOAD(b##i, Ug, nk_); }
; #define P4_U(i) { P4_DOT(b##i, part[i]); const int nk_ = __builtin_amdgcn_readlane(kn, i); P4_LOAD(b##i, nbase, nk_); }
; __device__ __forceinline__ void peer_gather_f4p(const float* X, const int* __restrict__ IDX, const float* __restrict__ G, ...
;     ...
;         {
;     ...
;             P4_FOR16(P4_U)
;     ...
;             P4_RED(7);
;         }
	v_cvt_scalef32_pk_bf16_fp4 v52, v116, 1.0
	v_cvt_scalef32_pk_bf16_fp4 v54, v116, 1.0 op_sel:[1,0,0]
	v_cvt_scalef32_pk_bf16_fp4 v56, v116, 1.0 op_sel:[0,1,0]
	v_cvt_scalef32_pk_bf16_fp4 v58, v116, 1.0 op_sel:[1,1,0]
	v_dot2_f32_bf16 v60, v52, v6, 0
	v_dot2_f32_bf16 v52, v54, v4, 0
	v_dot2_f32_bf16 v60, v56, v10, v60
	v_readlane_b32 s26, v2, 12
	v_dot2_f32_bf16 v52, v58, v8, v52
	v_cvt_scalef32_pk_bf16_fp4 v54, v117, 1.0
	v_cvt_scalef32_pk_bf16_fp4 v56, v117, 1.0 op_sel:[1,0,0]
	v_cvt_scalef32_pk_bf16_fp4 v58, v117, 1.0 op_sel:[0,1,0]
	v_cvt_scalef32_pk_bf16_fp4 v62, v117, 1.0 op_sel:[1,1,0]
	s_lshr_b32 s26, s26, 7
	v_dot2_f32_bf16 v60, v54, v14, v60
	v_dot2_f32_bf16 v52, v56, v12, v52
	s_mov_b32 s27, s86
	v_dot2_f32_bf16 v60, v58, v18, v60
	v_dot2_f32_bf16 v52, v62, v16, v52
	v_cvt_scalef32_pk_bf16_fp4 v54, v118, 1.0
	v_cvt_scalef32_pk_bf16_fp4 v56, v118, 1.0 op_sel:[1,0,0]
	v_cvt_scalef32_pk_bf16_fp4 v58, v118, 1.0 op_sel:[0,1,0]
	v_cvt_scalef32_pk_bf16_fp4 v62, v118, 1.0 op_sel:[1,1,0]
	s_lshl_b64 s[26:27], s[26:27], 10
	v_dot2_f32_bf16 v60, v54, v22, v60
	v_dot2_f32_bf16 v52, v56, v20, v52
	s_add_u32 s26, s13, s26
	v_dot2_f32_bf16 v60, v58, v26, v60
	v_dot2_f32_bf16 v52, v62, v24, v52
	v_cvt_scalef32_pk_bf16_fp4 v54, v119, 1.0
	v_cvt_scalef32_pk_bf16_fp4 v56, v119, 1.0 op_sel:[1,0,0]
	v_cvt_scalef32_pk_bf16_fp4 v58, v119, 1.0 op_sel:[0,1,0]
	v_cvt_scalef32_pk_bf16_fp4 v62, v119, 1.0 op_sel:[1,1,0]
	s_addc_u32 s27, s12, s27
	v_dot2_f32_bf16 v60, v54, v30, v60
	v_dot2_f32_bf16 v52, v56, v28, v52
	v_dot2_f32_bf16 v60, v58, v36, v60
	v_dot2_f32_bf16 v52, v62, v34, v52
	s_nop 2
	v_add_f32_e32 v101, v60, v52
	v_lshl_add_u64 v[52:53], s[26:27], 0, v[32:33]
	global_load_dwordx4 v[116:119], v[52:53], off
	s_waitcnt vmcnt(15)
	v_cvt_scalef32_pk_bf16_fp4 v52, v120, 1.0
	v_cvt_scalef32_pk_bf16_fp4 v54, v120, 1.0 op_sel:[1,0,0]
	v_cvt_scalef32_pk_bf16_fp4 v56, v120, 1.0 op_sel:[0,1,0]
	v_cvt_scalef32_pk_bf16_fp4 v58, v120, 1.0 op_sel:[1,1,0]
	v_dot2_f32_bf16 v60, v52, v6, 0
	v_dot2_f32_bf16 v52, v54, v4, 0
	v_dot2_f32_bf16 v60, v56, v10, v60
	v_readlane_b32 s26, v2, 13
	v_dot2_f32_bf16 v52, v58, v8, v52
	v_cvt_scalef32_pk_bf16_fp4 v54, v121, 1.0
	v_cvt_scalef32_pk_bf16_fp4 v56, v121, 1.0 op_sel:[1,0,0]
	v_cvt_scalef32_pk_bf16_fp4 v58, v121, 1.0 op_sel:[0,1,0]
	v_cvt_scalef32_pk_bf16_fp4 v62, v121, 1.0 op_sel:[1,1,0]
	s_lshr_b32 s26, s26, 7
	v_dot2_f32_bf16 v60, v54, v14, v60
	v_dot2_f32_bf16 v52, v56, v12, v52
	s_mov_b32 s27, s86
	v_dot2_f32_bf16 v60, v58, v18, v60
	v_dot2_f32_bf16 v52, v62, v16, v52
	v_cvt_scalef32_pk_bf16_fp4 v54, v122, 1.0
	v_cvt_scalef32_pk_bf16_fp4 v56, v122, 1.0 op_sel:[1,0,0]
	v_cvt_scalef32_pk_bf16_fp4 v58, v122, 1.0 op_sel:[0,1,0]
	v_cvt_scalef32_pk_bf16_fp4 v62, v122, 1.0 op_sel:[1,1,0]
	s_lshl_b64 s[26:27], s[26:27], 10
	v_dot2_f32_bf16 v60, v54, v22, v60
	v_dot2_f32_bf16 v52, v56, v20, v52
	s_add_u32 s26, s13, s26
	v_dot2_f32_bf16 v60, v58, v26, v60
	v_dot2_f32_bf16 v52, v62, v24, v52
	v_cvt_scalef32_pk_bf16_fp4 v54, v123, 1.0
	v_cvt_scalef32_pk_bf16_fp4 v56, v123, 1.0 op_sel:[1,0,0]
	v_cvt_scalef32_pk_bf16_fp4 v58, v123, 1.0 op_sel:[0,1,0]
	v_cvt_scalef32_pk_bf16_fp4 v62, v123, 1.0 op_sel:[1,1,0]
	s_addc_u32 s27, s12, s27
	v_dot2_f32_bf16 v60, v54, v30, v60
	v_dot2_f32_bf16 v52, v56, v28, v52
	v_dot2_f32_bf16 v60, v58, v36, v60
	v_dot2_f32_bf16 v52, v62, v34, v52
	s_nop 2
	v_add_f32_e32 v102, v60, v52
	v_lshl_add_u64 v[52:53], s[26:27], 0, v[32:33]
	global_load_dwordx4 v[120:123], v[52:53], off
	s_waitcnt vmcnt(15)
	v_cvt_scalef32_pk_bf16_fp4 v52, v124, 1.0
	v_cvt_scalef32_pk_bf16_fp4 v54, v124, 1.0 op_sel:[1,0,0]
	v_cvt_scalef32_pk_bf16_fp4 v56, v124, 1.0 op_sel:[0,1,0]
	v_cvt_scalef32_pk_bf16_fp4 v58, v124, 1.0 op_sel:[1,1,0]
	v_dot2_f32_bf16 v60, v52, v6, 0
	v_dot2_f32_bf16 v52, v54, v4, 0
	v_dot2_f32_bf16 v60, v56, v10, v60
	v_readlane_b32 s26, v2, 14
	v_dot2_f32_bf16 v52, v58, v8, v52
	v_cvt_scalef32_pk_bf16_fp4 v54, v125, 1.0
	v_cvt_scalef32_pk_bf16_fp4 v56, v125, 1.0 op_sel:[1,0,0]
	v_cvt_scalef32_pk_bf16_fp4 v58, v125, 1.0 op_sel:[0,1,0]
	v_cvt_scalef32_pk_bf16_fp4 v62, v125, 1.0 op_sel:[1,1,0]
	s_lshr_b32 s26, s26, 7
	v_dot2_f32_bf16 v60, v54, v14, v60
	v_dot2_f32_bf16 v52, v56, v12, v52
	s_mov_b32 s27, s86
	v_dot2_f32_bf16 v60, v58, v18, v60
	v_dot2_f32_bf16 v52, v62, v16, v52
	v_cvt_scalef32_pk_bf16_fp4 v54, v126, 1.0
	v_cvt_scalef32_pk_bf16_fp4 v56, v126, 1.0 op_sel:[1,0,0]
	v_cvt_scalef32_pk_bf16_fp4 v58, v126, 1.0 op_sel:[0,1,0]
	v_cvt_scalef32_pk_bf16_fp4 v62, v126, 1.0 op_sel:[1,1,0]
	s_lshl_b64 s[26:27], s[26:27], 10
	v_dot2_f32_bf16 v60, v54, v22, v60
	v_dot2_f32_bf16 v52, v56, v20, v52
	s_add_u32 s26, s13, s26
	v_dot2_f32_bf16 v60, v58, v26, v60
	v_dot2_f32_bf16 v52, v62, v24, v52
	v_cvt_scalef32_pk_bf16_fp4 v54, v127, 1.0
	v_cvt_scalef32_pk_bf16_fp4 v56, v127, 1.0 op_sel:[1,0,0]
	v_cvt_scalef32_pk_bf16_fp4 v58, v127, 1.0 op_sel:[0,1,0]
	v_cvt_scalef32_pk_bf16_fp4 v62, v127, 1.0 op_sel:[1,1,0]
	s_addc_u32 s27, s12, s27
	v_dot2_f32_bf16 v60, v54, v30, v60
	v_dot2_f32_bf16 v52, v56, v28, v52
	v_dot2_f32_bf16 v60, v58, v36, v60
	v_dot2_f32_bf16 v52, v62, v34, v52
	s_nop 2
	v_add_f32_e32 v62, v60, v52
	v_lshl_add_u64 v[52:53], s[26:27], 0, v[32:33]
	global_load_dwordx4 v[124:127], v[52:53], off
	s_waitcnt vmcnt(15)
; #define P4_FOR16(M) M(0) M(1) M(2) M(3) M(4) M(5) M(6) M(7) M(8) M(9) M(10) M(11) M(12) M(13) M(14) M(15)
; #define P4_U(i) { P4_DOT(b##i, part[i]); const int nk_ = __builtin_amdgcn_readlane(ksel, nb + i); P4_LOAD(b##i, Ug, nk_); }
; #define P4_U(i) { P4_DOT(b##i, part[i]); const int nk_ = __builtin_amdgcn_readlane(kn, i); P4_LOAD(b##i, nbase, nk_); }
; __device__ __forceinline__ float gelu_tanh(float h) {
;     return 0.5f * h * (1.f + tanhf(0.7978845608028654f * (h + 0.044715f * h * h * h)));
; }
; __device__ __forceinline__ void peer_gather_f4p(const float* X, const int* __restrict__ IDX, const float* __restrict__ G, ...
;     ...
;         {
;     ...
;             P4_FOR16(P4_U)
;     ...
;             P4_RED(7);
;         }
	v_cvt_scalef32_pk_bf16_fp4 v52, v128, 1.0
	v_cvt_scalef32_pk_bf16_fp4 v54, v128, 1.0 op_sel:[1,0,0]
	v_cvt_scalef32_pk_bf16_fp4 v56, v128, 1.0 op_sel:[0,1,0]
	v_cvt_scalef32_pk_bf16_fp4 v58, v128, 1.0 op_sel:[1,1,0]
	v_readlane_b32 s26, v2, 15
	v_dot2_f32_bf16 v60, v52, v6, 0
	v_dot2c_f32_bf16_e32 v38, v54, v4
	s_lshr_b32 s26, s26, 7
	v_dot2_f32_bf16 v60, v56, v10, v60
	v_dot2c_f32_bf16_e32 v38, v58, v8
	v_cvt_scalef32_pk_bf16_fp4 v4, v129, 1.0
	v_cvt_scalef32_pk_bf16_fp4 v6, v129, 1.0 op_sel:[1,0,0]
	v_cvt_scalef32_pk_bf16_fp4 v8, v129, 1.0 op_sel:[0,1,0]
	v_cvt_scalef32_pk_bf16_fp4 v10, v129, 1.0 op_sel:[1,1,0]
	s_mov_b32 s27, s86
	v_dot2_f32_bf16 v60, v4, v14, v60
	v_dot2c_f32_bf16_e32 v38, v6, v12
	s_lshl_b64 s[26:27], s[26:27], 10
	v_dot2_f32_bf16 v60, v8, v18, v60
	v_dot2c_f32_bf16_e32 v38, v10, v16
	v_cvt_scalef32_pk_bf16_fp4 v4, v130, 1.0
	v_cvt_scalef32_pk_bf16_fp4 v6, v130, 1.0 op_sel:[1,0,0]
	v_cvt_scalef32_pk_bf16_fp4 v8, v130, 1.0 op_sel:[0,1,0]
	v_cvt_scalef32_pk_bf16_fp4 v10, v130, 1.0 op_sel:[1,1,0]
	s_add_u32 s26, s13, s26
	v_dot2_f32_bf16 v60, v4, v22, v60
	v_dot2c_f32_bf16_e32 v38, v6, v20
	s_addc_u32 s27, s12, s27
	v_dot2_f32_bf16 v60, v8, v26, v60
	v_dot2c_f32_bf16_e32 v38, v10, v24
	v_cvt_scalef32_pk_bf16_fp4 v4, v131, 1.0
	v_cvt_scalef32_pk_bf16_fp4 v6, v131, 1.0 op_sel:[1,0,0]
	v_cvt_scalef32_pk_bf16_fp4 v8, v131, 1.0 op_sel:[0,1,0]
	v_cvt_scalef32_pk_bf16_fp4 v10, v131, 1.0 op_sel:[1,1,0]
	v_cndmask_b32_e64 v2, v49, v41, s[48:49]
	v_dot2_f32_bf16 v60, v4, v30, v60
	v_dot2c_f32_bf16_e32 v38, v6, v28
	v_cndmask_b32_e64 v7, v43, v51, s[48:49]
	v_dot2_f32_bf16 v60, v8, v36, v60
	v_dot2c_f32_bf16_e32 v38, v10, v34
	ds_swizzle_b32 v7, v7 offset:swizzle(SWAP,8)
	s_nop 2
	v_add_f32_e32 v6, v60, v38
	v_lshl_add_u64 v[4:5], s[26:27], 0, v[32:33]
	global_load_dwordx4 v[128:131], v[4:5], off
	v_cndmask_b32_e64 v4, v41, v49, s[48:49]
	ds_swizzle_b32 v4, v4 offset:swizzle(SWAP,8)
	v_cndmask_b32_e64 v5, v42, v50, s[48:49]
	ds_swizzle_b32 v5, v5 offset:swizzle(SWAP,8)
	v_cndmask_b32_e64 v8, v44, v100, s[48:49]
	ds_swizzle_b32 v8, v8 offset:swizzle(SWAP,8)
	v_cndmask_b32_e64 v9, v45, v101, s[48:49]
	ds_swizzle_b32 v9, v9 offset:swizzle(SWAP,8)
	v_cndmask_b32_e64 v10, v46, v102, s[48:49]
	s_waitcnt lgkmcnt(3)
	v_add_f32_e32 v2, v2, v4
	v_cndmask_b32_e64 v4, v50, v42, s[48:49]
	ds_swizzle_b32 v10, v10 offset:swizzle(SWAP,8)
	v_cndmask_b32_e64 v11, v47, v62, s[48:49]
	s_waitcnt lgkmcnt(3)
	v_add_f32_e32 v4, v4, v5
	v_cndmask_b32_e64 v5, v51, v43, s[48:49]
	ds_swizzle_b32 v11, v11 offset:swizzle(SWAP,8)
	v_add_f32_e32 v5, v5, v7
	v_cndmask_b32_e64 v7, v100, v44, s[48:49]
	s_waitcnt lgkmcnt(3)
	v_add_f32_e32 v7, v7, v8
	v_cndmask_b32_e64 v8, v101, v45, s[48:49]
	s_waitcnt lgkmcnt(2)
	v_add_f32_e32 v8, v8, v9
	v_cndmask_b32_e64 v9, v102, v46, s[48:49]
	s_waitcnt lgkmcnt(1)
	v_add_f32_e32 v9, v9, v10
	v_cndmask_b32_e64 v10, v62, v47, s[48:49]
	s_waitcnt lgkmcnt(0)
	v_add_f32_e32 v10, v10, v11
	v_cndmask_b32_e64 v11, v6, v48, s[48:49]
	v_cndmask_b32_e64 v6, v48, v6, s[48:49]
	ds_swizzle_b32 v6, v6 offset:swizzle(SWAP,8)
	s_waitcnt lgkmcnt(0)
	v_add_f32_e32 v6, v11, v6
	v_cndmask_b32_e64 v11, v8, v2, s[46:47]
	v_cndmask_b32_e64 v2, v2, v8, s[46:47]
	v_cndmask_b32_e64 v8, v9, v4, s[46:47]
	v_cndmask_b32_e64 v4, v4, v9, s[46:47]
	ds_swizzle_b32 v4, v4 offset:swizzle(SWAP,4)
	ds_swizzle_b32 v2, v2 offset:swizzle(SWAP,4)
	s_waitcnt lgkmcnt(1)
	v_add_f32_e32 v4, v8, v4
	v_cndmask_b32_e64 v8, v10, v5, s[46:47]
	v_cndmask_b32_e64 v5, v5, v10, s[46:47]
	ds_swizzle_b32 v5, v5 offset:swizzle(SWAP,4)
	s_waitcnt lgkmcnt(1)
	v_add_f32_e32 v2, v11, v2
	s_waitcnt lgkmcnt(0)
	v_add_f32_e32 v5, v8, v5
	v_cndmask_b32_e64 v8, v6, v7, s[46:47]
	v_cndmask_b32_e64 v6, v7, v6, s[46:47]
	ds_swizzle_b32 v6, v6 offset:swizzle(SWAP,4)
	v_cndmask_b32_e64 v7, v5, v2, s[44:45]
	v_cndmask_b32_e64 v2, v2, v5, s[44:45]
	ds_swizzle_b32 v2, v2 offset:swizzle(SWAP,2)
	s_waitcnt lgkmcnt(1)
	v_add_f32_e32 v6, v8, v6
	v_cndmask_b32_e64 v5, v6, v4, s[44:45]
	v_cndmask_b32_e64 v4, v4, v6, s[44:45]
	ds_swizzle_b32 v4, v4 offset:swizzle(SWAP,2)
	s_waitcnt lgkmcnt(1)
	v_add_f32_e32 v2, v7, v2
	s_waitcnt lgkmcnt(0)
	v_add_f32_e32 v4, v5, v4
	v_cndmask_b32_e64 v5, v4, v2, s[42:43]
	v_cndmask_b32_e64 v2, v2, v4, s[42:43]
	ds_swizzle_b32 v2, v2 offset:swizzle(SWAP,1)
	s_waitcnt lgkmcnt(0)
	v_add_f32_e32 v2, v5, v2
	ds_swizzle_b32 v4, v2 offset:swizzle(SWAP,16)
	s_waitcnt lgkmcnt(0)
	v_add_f32_e32 v2, v2, v4
	v_mov_b32_e32 v4, v2
	s_nop 1
	v_permlane32_swap_b32_e32 v2, v4
	v_add_f32_e32 v6, v2, v4
	v_lshl_add_u32 v2, v40, 2, s14
	v_add_u32_e32 v4, 0xc0, v2
	ds_read2st64_b32 v[4:5], v4 offset0:9 offset1:17
	s_waitcnt lgkmcnt(0)
	v_mul_f32_e32 v4, v4, v6
	v_mul_f32_e32 v6, 0x3d372713, v4
	v_mul_f32_e32 v6, v4, v6
	v_fma_f32 v6, v4, v6, v4
	v_mul_f32_e32 v6, 0x3f4c422a, v6
	v_cmp_nlt_f32_e64 s[12:13], |v6|, s25
	s_and_saveexec_b64 s[26:27], s[12:13]
	s_xor_b64 s[12:13], exec, s[26:27]
	s_cbranch_execz .LBB0_543
	v_add_f32_e64 v7, |v6|, |v6|
	v_mul_f32_e32 v8, 0x3fb8aa3b, v7
	v_rndne_f32_e32 v9, v8
	v_sub_f32_e32 v10, v8, v9
	v_fma_f32 v8, v7, s70, -v8
	v_fmac_f32_e32 v8, 0x32a5705f, v7
	v_add_f32_e32 v8, v10, v8
	v_cvt_i32_f32_e32 v9, v9
	v_exp_f32_e32 v8, v8
	v_cmp_ngt_f32_e64 s[42:43], s67, v7
	v_ldexp_f32 v8, v8, v9
	s_nop 0
	v_cndmask_b32_e64 v8, 0, v8, s[42:43]
	v_cmp_nlt_f32_e64 s[42:43], s68, v7
	s_nop 1
	v_cndmask_b32_e64 v7, v205, v8, s[42:43]
	v_add_f32_e32 v7, 1.0, v7
	v_rcp_f32_e32 v7, v7
	s_nop 0
	v_fma_f32 v7, v7, -2.0, 1.0
	s_andn2_saveexec_b64 s[12:13], s[12:13]
	s_cbranch_execnz .LBB0_544

; #define P4_FOR16(M) M(0) M(1) M(2) M(3) M(4) M(5) M(6) M(7) M(8) M(9) M(10) M(11) M(12) M(13) M(14) M(15)
; #define P4_V(i) { const unsigned wu_ = (unsigned)__builtin_amdgcn_readlane((int)__float_as_uint(wreg), i); const unsigned long long wp_ = ((unsigned long long)wu_ << 32) | wu_; \
;               P4_ACC(b##i, wp_); const int nk_ = __builtin_amdgcn_readlane(ksel, nb + i); P4_LOAD(b##i, Vg, nk_); }
; #define P4_V(i) { const unsigned wu_ = (unsigned)__builtin_amdgcn_readlane((int)__float_as_uint(wreg), i); const unsigned long long wp_ = ((unsigned long long)wu_ << 32) | wu_; \
;               P4_ACC(b##i, wp_); const int nk_ = __builtin_amdgcn_readlane(kn, i); P4_LOAD(b##i, Vg, nk_); }
; #define P4_V(i) { const unsigned wu_ = (unsigned)__builtin_amdgcn_readlane((int)__float_as_uint(wreg), i); const unsigned long long wp_ = ((unsigned long long)wu_ << 32) | wu_; \
;               P4_ACC(b##i, wp_); }
; __device__ __forceinline__ void peer_gather_f4p(const float* X, const int* __restrict__ IDX, const float* __restrict__ G, ...
;     ...
; #pragma unroll 1
;         for (int bt = 0; bt < 7; ++bt) {
;             const int ksel = (bt + 1 < 4) ? k0 : k1;
;             const int nb = (16 * (bt + 1)) & 63;
;             const float wreg = wbuf[kt * 128 + bt * 16 + (lane & 15)];
;     ...
;             P4_FOR16(P4_V)
;     ...
;         }
.LBB0_550:
	ds_read_b32 v65, v171
	s_waitcnt vmcnt(15)
	v_cvt_scalef32_pk_f32_fp4 v[66:67], v4, 1.0
	v_cvt_scalef32_pk_f32_fp4 v[68:69], v4, 1.0 op_sel:[1,0,0]
	v_cvt_scalef32_pk_f32_fp4 v[70:71], v4, 1.0 op_sel:[0,1,0]
	s_cmp_lt_u32 s28, 3
	s_waitcnt lgkmcnt(0)
	v_readlane_b32 s16, v65, 0
	s_mov_b32 s17, s16
	v_cvt_scalef32_pk_f32_fp4 v[72:73], v4, 1.0 op_sel:[1,1,0]
	v_pk_fma_f32 v[132:133], s[16:17], v[66:67], v[132:133]
	v_pk_fma_f32 v[162:163], s[16:17], v[68:69], v[162:163]
	v_pk_fma_f32 v[160:161], s[16:17], v[70:71], v[160:161]
	s_cselect_b64 vcc, -1, 0
	v_pk_fma_f32 v[158:159], s[16:17], v[72:73], v[158:159]
	v_cvt_scalef32_pk_f32_fp4 v[66:67], v5, 1.0
	v_cvt_scalef32_pk_f32_fp4 v[68:69], v5, 1.0 op_sel:[1,0,0]
	v_cvt_scalef32_pk_f32_fp4 v[70:71], v5, 1.0 op_sel:[0,1,0]
	v_cvt_scalef32_pk_f32_fp4 v[4:5], v5, 1.0 op_sel:[1,1,0]
	v_cndmask_b32_e32 v64, v167, v166, vcc
	v_pk_fma_f32 v[156:157], s[16:17], v[66:67], v[156:157]
	v_pk_fma_f32 v[154:155], s[16:17], v[68:69], v[154:155]
	v_pk_fma_f32 v[152:153], s[16:17], v[70:71], v[152:153]
	v_pk_fma_f32 v[150:151], s[16:17], v[4:5], v[150:151]
	v_cvt_scalef32_pk_f32_fp4 v[4:5], v6, 1.0
	v_cvt_scalef32_pk_f32_fp4 v[66:67], v6, 1.0 op_sel:[1,0,0]
	v_cvt_scalef32_pk_f32_fp4 v[68:69], v6, 1.0 op_sel:[0,1,0]
	v_cvt_scalef32_pk_f32_fp4 v[70:71], v6, 1.0 op_sel:[1,1,0]
	s_mov_b32 s41, s86
	v_pk_fma_f32 v[148:149], s[16:17], v[4:5], v[148:149]
	v_pk_fma_f32 v[146:147], s[16:17], v[66:67], v[146:147]
	v_pk_fma_f32 v[144:145], s[16:17], v[68:69], v[144:145]
	v_pk_fma_f32 v[142:143], s[16:17], v[70:71], v[142:143]
	v_cvt_scalef32_pk_f32_fp4 v[4:5], v7, 1.0
	v_cvt_scalef32_pk_f32_fp4 v[66:67], v7, 1.0 op_sel:[1,0,0]
	v_cvt_scalef32_pk_f32_fp4 v[68:69], v7, 1.0 op_sel:[0,1,0]
	v_cvt_scalef32_pk_f32_fp4 v[6:7], v7, 1.0 op_sel:[1,1,0]
	s_add_i32 s28, s28, 1
	v_pk_fma_f32 v[140:141], s[16:17], v[4:5], v[140:141]
	v_pk_fma_f32 v[138:139], s[16:17], v[66:67], v[138:139]
	v_pk_fma_f32 v[136:137], s[16:17], v[68:69], v[136:137]
	v_pk_fma_f32 v[134:135], s[16:17], v[6:7], v[134:135]
	s_add_i32 s16, s27, -15
	v_readlane_b32 s16, v64, s16
	s_lshr_b32 s40, s16, 7
	v_readfirstlane_b32 s100, v168
	v_readfirstlane_b32 s101, v169
	v_subrev_u32_e32 v207, s100, v168
	s_lshl_b64 s[16:17], s[40:41], 10
	s_add_u32 s16, s16, s100
	s_addc_u32 s17, s17, s101
	global_load_dwordx4 v[4:7], v207, s[16:17]
	v_readlane_b32 s16, v65, 1
	s_waitcnt vmcnt(15)
	v_cvt_scalef32_pk_f32_fp4 v[66:67], v8, 1.0
	v_cvt_scalef32_pk_f32_fp4 v[68:69], v8, 1.0 op_sel:[1,0,0]
	v_cvt_scalef32_pk_f32_fp4 v[70:71], v8, 1.0 op_sel:[0,1,0]
	s_mov_b32 s17, s16
	v_cvt_scalef32_pk_f32_fp4 v[72:73], v8, 1.0 op_sel:[1,1,0]
	v_pk_fma_f32 v[132:133], s[16:17], v[66:67], v[132:133]
	v_pk_fma_f32 v[162:163], s[16:17], v[68:69], v[162:163]
	v_pk_fma_f32 v[160:161], s[16:17], v[70:71], v[160:161]
	v_add_u32_e32 v171, 64, v171
	v_pk_fma_f32 v[158:159], s[16:17], v[72:73], v[158:159]
	v_cvt_scalef32_pk_f32_fp4 v[66:67], v9, 1.0
	v_cvt_scalef32_pk_f32_fp4 v[68:69], v9, 1.0 op_sel:[1,0,0]
	v_cvt_scalef32_pk_f32_fp4 v[70:71], v9, 1.0 op_sel:[0,1,0]
	v_cvt_scalef32_pk_f32_fp4 v[8:9], v9, 1.0 op_sel:[1,1,0]
	v_pk_fma_f32 v[156:157], s[16:17], v[66:67], v[156:157]
	v_pk_fma_f32 v[154:155], s[16:17], v[68:69], v[154:155]
	v_pk_fma_f32 v[152:153], s[16:17], v[70:71], v[152:153]
	v_pk_fma_f32 v[150:151], s[16:17], v[8:9], v[150:151]
	v_cvt_scalef32_pk_f32_fp4 v[8:9], v10, 1.0
	v_cvt_scalef32_pk_f32_fp4 v[66:67], v10, 1.0 op_sel:[1,0,0]
	v_cvt_scalef32_pk_f32_fp4 v[68:69], v10, 1.0 op_sel:[0,1,0]
	v_cvt_scalef32_pk_f32_fp4 v[70:71], v10, 1.0 op_sel:[1,1,0]
	v_pk_fma_f32 v[148:149], s[16:17], v[8:9], v[148:149]
	v_pk_fma_f32 v[146:147], s[16:17], v[66:67], v[146:147]
	v_pk_fma_f32 v[144:145], s[16:17], v[68:69], v[144:145]
	v_pk_fma_f32 v[142:143], s[16:17], v[70:71], v[142:143]
	v_cvt_scalef32_pk_f32_fp4 v[8:9], v11, 1.0
	v_cvt_scalef32_pk_f32_fp4 v[66:67], v11, 1.0 op_sel:[1,0,0]
	v_cvt_scalef32_pk_f32_fp4 v[68:69], v11, 1.0 op_sel:[0,1,0]
	v_cvt_scalef32_pk_f32_fp4 v[10:11], v11, 1.0 op_sel:[1,1,0]
	v_pk_fma_f32 v[140:141], s[16:17], v[8:9], v[140:141]
	v_pk_fma_f32 v[138:139], s[16:17], v[66:67], v[138:139]
	v_pk_fma_f32 v[136:137], s[16:17], v[68:69], v[136:137]
	v_pk_fma_f32 v[134:135], s[16:17], v[10:11], v[134:135]
	s_add_i32 s16, s27, -14
	v_readlane_b32 s16, v64, s16
	s_lshr_b32 s40, s16, 7
	s_lshl_b64 s[16:17], s[40:41], 10
	s_add_u32 s16, s16, s100
	s_addc_u32 s17, s17, s101
	global_load_dwordx4 v[8:11], v207, s[16:17]
	v_readlane_b32 s16, v65, 2
	s_waitcnt vmcnt(15)
	v_cvt_scalef32_pk_f32_fp4 v[66:67], v12, 1.0
	v_cvt_scalef32_pk_f32_fp4 v[68:69], v12, 1.0 op_sel:[1,0,0]
	v_cvt_scalef32_pk_f32_fp4 v[70:71], v12, 1.0 op_sel:[0,1,0]
	s_mov_b32 s17, s16
	v_cvt_scalef32_pk_f32_fp4 v[72:73], v12, 1.0 op_sel:[1,1,0]
	v_pk_fma_f32 v[132:133], s[16:17], v[66:67], v[132:133]
	v_pk_fma_f32 v[162:163], s[16:17], v[68:69], v[162:163]
	v_pk_fma_f32 v[160:161], s[16:17], v[70:71], v[160:161]
	v_pk_fma_f32 v[158:159], s[16:17], v[72:73], v[158:159]
	v_cvt_scalef32_pk_f32_fp4 v[66:67], v13, 1.0
	v_cvt_scalef32_pk_f32_fp4 v[68:69], v13, 1.0 op_sel:[1,0,0]
	v_cvt_scalef32_pk_f32_fp4 v[70:71], v13, 1.0 op_sel:[0,1,0]
	v_cvt_scalef32_pk_f32_fp4 v[12:13], v13, 1.0 op_sel:[1,1,0]
	v_pk_fma_f32 v[156:157], s[16:17], v[66:67], v[156:157]
	v_pk_fma_f32 v[154:155], s[16:17], v[68:69], v[154:155]
	v_pk_fma_f32 v[152:153], s[16:17], v[70:71], v[152:153]
	v_pk_fma_f32 v[150:151], s[16:17], v[12:13], v[150:151]
	v_cvt_scalef32_pk_f32_fp4 v[12:13], v14, 1.0
	v_cvt_scalef32_pk_f32_fp4 v[66:67], v14, 1.0 op_sel:[1,0,0]
	v_cvt_scalef32_pk_f32_fp4 v[68:69], v14, 1.0 op_sel:[0,1,0]
	v_cvt_scalef32_pk_f32_fp4 v[70:71], v14, 1.0 op_sel:[1,1,0]
	v_pk_fma_f32 v[148:149], s[16:17], v[12:13], v[148:149]
	v_pk_fma_f32 v[146:147], s[16:17], v[66:67], v[146:147]
	v_pk_fma_f32 v[144:145], s[16:17], v[68:69], v[144:145]
	v_pk_fma_f32 v[142:143], s[16:17], v[70:71], v[142:143]
	v_cvt_scalef32_pk_f32_fp4 v[12:13], v15, 1.0
	v_cvt_scalef32_pk_f32_fp4 v[66:67], v15, 1.0 op_sel:[1,0,0]
	v_cvt_scalef32_pk_f32_fp4 v[68:69], v15, 1.0 op_sel:[0,1,0]
	v_cvt_scalef32_pk_f32_fp4 v[14:15], v15, 1.0 op_sel:[1,1,0]
	v_pk_fma_f32 v[140:141], s[16:17], v[12:13], v[140:141]
	v_pk_fma_f32 v[138:139], s[16:17], v[66:67], v[138:139]
	v_pk_fma_f32 v[136:137], s[16:17], v[68:69], v[136:137]
	v_pk_fma_f32 v[134:135], s[16:17], v[14:15], v[134:135]
	s_add_i32 s16, s27, -13
	v_readlane_b32 s16, v64, s16
	s_lshr_b32 s40, s16, 7
	s_lshl_b64 s[16:17], s[40:41], 10
	s_add_u32 s16, s16, s100
	s_addc_u32 s17, s17, s101
	global_load_dwordx4 v[12:15], v207, s[16:17]
	v_readlane_b32 s16, v65, 3
	s_waitcnt vmcnt(15)
; #define P4_FOR16(M) M(0) M(1) M(2) M(3) M(4) M(5) M(6) M(7) M(8) M(9) M(10) M(11) M(12) M(13) M(14) M(15)
; #define P4_V(i) { const unsigned wu_ = (unsigned)__builtin_amdgcn_readlane((int)__float_as_uint(wreg), i); const unsigned long long wp_ = ((unsigned long long)wu_ << 32) | wu_; \
;               P4_ACC(b##i, wp_); const int nk_ = __builtin_amdgcn_readlane(ksel, nb + i); P4_LOAD(b##i, Vg, nk_); }
; #define P4_V(i) { const unsigned wu_ = (unsigned)__builtin_amdgcn_readlane((int)__float_as_uint(wreg), i); const unsigned long long wp_ = ((unsigned long long)wu_ << 32) | wu_; \
;               P4_ACC(b##i, wp_); const int nk_ = __builtin_amdgcn_readlane(kn, i); P4_LOAD(b##i, Vg, nk_); }
; #define P4_V(i) { const unsigned wu_ = (unsigned)__builtin_amdgcn_readlane((int)__float_as_uint(wreg), i); const unsigned long long wp_ = ((unsigned long long)wu_ << 32) | wu_; \
;               P4_ACC(b##i, wp_); }
; __device__ __forceinline__ void peer_gather_f4p(const float* X, const int* __restrict__ IDX, const float* __restrict__ G, ...
;     ...
; #pragma unroll 1
;         for (int bt = 0; bt < 7; ++bt) {
;             const int ksel = (bt + 1 < 4) ? k0 : k1;
;             const int nb = (16 * (bt + 1)) & 63;
;             const float wreg = wbuf[kt * 128 + bt * 16 + (lane & 15)];
;     ...
;             P4_FOR16(P4_V)
;     ...
;         }
	v_cvt_scalef32_pk_f32_fp4 v[66:67], v16, 1.0
	v_cvt_scalef32_pk_f32_fp4 v[68:69], v16, 1.0 op_sel:[1,0,0]
	v_cvt_scalef32_pk_f32_fp4 v[70:71], v16, 1.0 op_sel:[0,1,0]
	s_mov_b32 s17, s16
	v_cvt_scalef32_pk_f32_fp4 v[72:73], v16, 1.0 op_sel:[1,1,0]
	v_pk_fma_f32 v[132:133], s[16:17], v[66:67], v[132:133]
	v_pk_fma_f32 v[162:163], s[16:17], v[68:69], v[162:163]
	v_pk_fma_f32 v[160:161], s[16:17], v[70:71], v[160:161]
	v_pk_fma_f32 v[158:159], s[16:17], v[72:73], v[158:159]
	v_cvt_scalef32_pk_f32_fp4 v[66:67], v17, 1.0
	v_cvt_scalef32_pk_f32_fp4 v[68:69], v17, 1.0 op_sel:[1,0,0]
	v_cvt_scalef32_pk_f32_fp4 v[70:71], v17, 1.0 op_sel:[0,1,0]
	v_cvt_scalef32_pk_f32_fp4 v[16:17], v17, 1.0 op_sel:[1,1,0]
	v_pk_fma_f32 v[156:157], s[16:17], v[66:67], v[156:157]
	v_pk_fma_f32 v[154:155], s[16:17], v[68:69], v[154:155]
	v_pk_fma_f32 v[152:153], s[16:17], v[70:71], v[152:153]
	v_pk_fma_f32 v[150:151], s[16:17], v[16:17], v[150:151]
	v_cvt_scalef32_pk_f32_fp4 v[16:17], v18, 1.0
	v_cvt_scalef32_pk_f32_fp4 v[66:67], v18, 1.0 op_sel:[1,0,0]
	v_cvt_scalef32_pk_f32_fp4 v[68:69], v18, 1.0 op_sel:[0,1,0]
	v_cvt_scalef32_pk_f32_fp4 v[70:71], v18, 1.0 op_sel:[1,1,0]
	v_pk_fma_f32 v[148:149], s[16:17], v[16:17], v[148:149]
	v_pk_fma_f32 v[146:147], s[16:17], v[66:67], v[146:147]
	v_pk_fma_f32 v[144:145], s[16:17], v[68:69], v[144:145]
	v_pk_fma_f32 v[142:143], s[16:17], v[70:71], v[142:143]
	v_cvt_scalef32_pk_f32_fp4 v[16:17], v19, 1.0
	v_cvt_scalef32_pk_f32_fp4 v[66:67], v19, 1.0 op_sel:[1,0,0]
	v_cvt_scalef32_pk_f32_fp4 v[68:69], v19, 1.0 op_sel:[0,1,0]
	v_cvt_scalef32_pk_f32_fp4 v[18:19], v19, 1.0 op_sel:[1,1,0]
	v_pk_fma_f32 v[140:141], s[16:17], v[16:17], v[140:141]
	v_pk_fma_f32 v[138:139], s[16:17], v[66:67], v[138:139]
	v_pk_fma_f32 v[136:137], s[16:17], v[68:69], v[136:137]
	v_pk_fma_f32 v[134:135], s[16:17], v[18:19], v[134:135]
	s_add_i32 s16, s27, -12
	v_readlane_b32 s16, v64, s16
	s_lshr_b32 s40, s16, 7
	s_lshl_b64 s[16:17], s[40:41], 10
	s_add_u32 s16, s16, s100
	s_addc_u32 s17, s17, s101
	global_load_dwordx4 v[16:19], v207, s[16:17]
	v_readlane_b32 s16, v65, 4
	s_waitcnt vmcnt(15)
	v_cvt_scalef32_pk_f32_fp4 v[66:67], v20, 1.0
	v_cvt_scalef32_pk_f32_fp4 v[68:69], v20, 1.0 op_sel:[1,0,0]
	v_cvt_scalef32_pk_f32_fp4 v[70:71], v20, 1.0 op_sel:[0,1,0]
	s_mov_b32 s17, s16
	v_cvt_scalef32_pk_f32_fp4 v[72:73], v20, 1.0 op_sel:[1,1,0]
	v_pk_fma_f32 v[132:133], s[16:17], v[66:67], v[132:133]
	v_pk_fma_f32 v[162:163], s[16:17], v[68:69], v[162:163]
	v_pk_fma_f32 v[160:161], s[16:17], v[70:71], v[160:161]
	v_pk_fma_f32 v[158:159], s[16:17], v[72:73], v[158:159]
	v_cvt_scalef32_pk_f32_fp4 v[66:67], v21, 1.0
	v_cvt_scalef32_pk_f32_fp4 v[68:69], v21, 1.0 op_sel:[1,0,0]
	v_cvt_scalef32_pk_f32_fp4 v[70:71], v21, 1.0 op_sel:[0,1,0]
	v_cvt_scalef32_pk_f32_fp4 v[20:21], v21, 1.0 op_sel:[1,1,0]
	v_pk_fma_f32 v[156:157], s[16:17], v[66:67], v[156:157]
	v_pk_fma_f32 v[154:155], s[16:17], v[68:69], v[154:155]
	v_pk_fma_f32 v[152:153], s[16:17], v[70:71], v[152:153]
	v_pk_fma_f32 v[150:151], s[16:17], v[20:21], v[150:151]
	v_cvt_scalef32_pk_f32_fp4 v[20:21], v22, 1.0
	v_cvt_scalef32_pk_f32_fp4 v[66:67], v22, 1.0 op_sel:[1,0,0]
	v_cvt_scalef32_pk_f32_fp4 v[68:69], v22, 1.0 op_sel:[0,1,0]
	v_cvt_scalef32_pk_f32_fp4 v[70:71], v22, 1.0 op_sel:[1,1,0]
	v_pk_fma_f32 v[148:149], s[16:17], v[20:21], v[148:149]
	v_pk_fma_f32 v[146:147], s[16:17], v[66:67], v[146:147]
	v_pk_fma_f32 v[144:145], s[16:17], v[68:69], v[144:145]
	v_pk_fma_f32 v[142:143], s[16:17], v[70:71], v[142:143]
	v_cvt_scalef32_pk_f32_fp4 v[20:21], v23, 1.0
	v_cvt_scalef32_pk_f32_fp4 v[66:67], v23, 1.0 op_sel:[1,0,0]
	v_cvt_scalef32_pk_f32_fp4 v[68:69], v23, 1.0 op_sel:[0,1,0]
	v_cvt_scalef32_pk_f32_fp4 v[22:23], v23, 1.0 op_sel:[1,1,0]
	v_pk_fma_f32 v[140:141], s[16:17], v[20:21], v[140:141]
	v_pk_fma_f32 v[138:139], s[16:17], v[66:67], v[138:139]
	v_pk_fma_f32 v[136:137], s[16:17], v[68:69], v[136:137]
	v_pk_fma_f32 v[134:135], s[16:17], v[22:23], v[134:135]
	s_add_i32 s16, s27, -11
	v_readlane_b32 s16, v64, s16
	s_lshr_b32 s40, s16, 7
	s_lshl_b64 s[16:17], s[40:41], 10
	s_add_u32 s16, s16, s100
	s_addc_u32 s17, s17, s101
	global_load_dwordx4 v[20:23], v207, s[16:17]
	v_readlane_b32 s16, v65, 5
	s_waitcnt vmcnt(15)
	v_cvt_scalef32_pk_f32_fp4 v[66:67], v24, 1.0
	v_cvt_scalef32_pk_f32_fp4 v[68:69], v24, 1.0 op_sel:[1,0,0]
	v_cvt_scalef32_pk_f32_fp4 v[70:71], v24, 1.0 op_sel:[0,1,0]
	s_mov_b32 s17, s16
	v_cvt_scalef32_pk_f32_fp4 v[72:73], v24, 1.0 op_sel:[1,1,0]
	v_pk_fma_f32 v[132:133], s[16:17], v[66:67], v[132:133]
	v_pk_fma_f32 v[162:163], s[16:17], v[68:69], v[162:163]
	v_pk_fma_f32 v[160:161], s[16:17], v[70:71], v[160:161]
	v_pk_fma_f32 v[158:159], s[16:17], v[72:73], v[158:159]
	v_cvt_scalef32_pk_f32_fp4 v[66:67], v25, 1.0
	v_cvt_scalef32_pk_f32_fp4 v[68:69], v25, 1.0 op_sel:[1,0,0]
	v_cvt_scalef32_pk_f32_fp4 v[70:71], v25, 1.0 op_sel:[0,1,0]
	v_cvt_scalef32_pk_f32_fp4 v[24:25], v25, 1.0 op_sel:[1,1,0]
	v_pk_fma_f32 v[156:157], s[16:17], v[66:67], v[156:157]
	v_pk_fma_f32 v[154:155], s[16:17], v[68:69], v[154:155]
	v_pk_fma_f32 v[152:153], s[16:17], v[70:71], v[152:153]
	v_pk_fma_f32 v[150:151], s[16:17], v[24:25], v[150:151]
	v_cvt_scalef32_pk_f32_fp4 v[24:25], v26, 1.0
	v_cvt_scalef32_pk_f32_fp4 v[66:67], v26, 1.0 op_sel:[1,0,0]
	v_cvt_scalef32_pk_f32_fp4 v[68:69], v26, 1.0 op_sel:[0,1,0]
	v_cvt_scalef32_pk_f32_fp4 v[70:71], v26, 1.0 op_sel:[1,1,0]
	v_pk_fma_f32 v[148:149], s[16:17], v[24:25], v[148:149]
	v_pk_fma_f32 v[146:147], s[16:17], v[66:67], v[146:147]
	v_pk_fma_f32 v[144:145], s[16:17], v[68:69], v[144:145]
	v_pk_fma_f32 v[142:143], s[16:17], v[70:71], v[142:143]
	v_cvt_scalef32_pk_f32_fp4 v[24:25], v27, 1.0
	v_cvt_scalef32_pk_f32_fp4 v[66:67], v27, 1.0 op_sel:[1,0,0]
	v_cvt_scalef32_pk_f32_fp4 v[68:69], v27, 1.0 op_sel:[0,1,0]
	v_cvt_scalef32_pk_f32_fp4 v[26:27], v27, 1.0 op_sel:[1,1,0]
	v_pk_fma_f32 v[140:141], s[16:17], v[24:25], v[140:141]
	v_pk_fma_f32 v[138:139], s[16:17], v[66:67], v[138:139]
	v_pk_fma_f32 v[136:137], s[16:17], v[68:69], v[136:137]
	v_pk_fma_f32 v[134:135], s[16:17], v[26:27], v[134:135]
	s_add_i32 s16, s27, -10
	v_readlane_b32 s16, v64, s16
	s_lshr_b32 s40, s16, 7
	s_lshl_b64 s[16:17], s[40:41], 10
	s_add_u32 s16, s16, s100
	s_addc_u32 s17, s17, s101
	global_load_dwordx4 v[24:27], v207, s[16:17]
	v_readlane_b32 s16, v65, 6
	s_waitcnt vmcnt(15)
; #define P4_FOR16(M) M(0) M(1) M(2) M(3) M(4) M(5) M(6) M(7) M(8) M(9) M(10) M(11) M(12) M(13) M(14) M(15)
; #define P4_V(i) { const unsigned wu_ = (unsigned)__builtin_amdgcn_readlane((int)__float_as_uint(wreg), i); const unsigned long long wp_ = ((unsigned long long)wu_ << 32) | wu_; \
;               P4_ACC(b##i, wp_); const int nk_ = __builtin_amdgcn_readlane(ksel, nb + i); P4_LOAD(b##i, Vg, nk_); }
; #define P4_V(i) { const unsigned wu_ = (unsigned)__builtin_amdgcn_readlane((int)__float_as_uint(wreg), i); const unsigned long long wp_ = ((unsigned long long)wu_ << 32) | wu_; \
;               P4_ACC(b##i, wp_); const int nk_ = __builtin_amdgcn_readlane(kn, i); P4_LOAD(b##i, Vg, nk_); }
; #define P4_V(i) { const unsigned wu_ = (unsigned)__builtin_amdgcn_readlane((int)__float_as_uint(wreg), i); const unsigned long long wp_ = ((unsigned long long)wu_ << 32) | wu_; \
;               P4_ACC(b##i, wp_); }
; __device__ __forceinline__ void peer_gather_f4p(const float* X, const int* __restrict__ IDX, const float* __restrict__ G, ...
;     ...
; #pragma unroll 1
;         for (int bt = 0; bt < 7; ++bt) {
;             const int ksel = (bt + 1 < 4) ? k0 : k1;
;             const int nb = (16 * (bt + 1)) & 63;
;             const float wreg = wbuf[kt * 128 + bt * 16 + (lane & 15)];
;     ...
;             P4_FOR16(P4_V)
;     ...
;         }
	v_cvt_scalef32_pk_f32_fp4 v[66:67], v28, 1.0
	v_cvt_scalef32_pk_f32_fp4 v[68:69], v28, 1.0 op_sel:[1,0,0]
	v_cvt_scalef32_pk_f32_fp4 v[70:71], v28, 1.0 op_sel:[0,1,0]
	s_mov_b32 s17, s16
	v_cvt_scalef32_pk_f32_fp4 v[72:73], v28, 1.0 op_sel:[1,1,0]
	v_pk_fma_f32 v[132:133], s[16:17], v[66:67], v[132:133]
	v_pk_fma_f32 v[162:163], s[16:17], v[68:69], v[162:163]
	v_pk_fma_f32 v[160:161], s[16:17], v[70:71], v[160:161]
	v_pk_fma_f32 v[158:159], s[16:17], v[72:73], v[158:159]
	v_cvt_scalef32_pk_f32_fp4 v[66:67], v29, 1.0
	v_cvt_scalef32_pk_f32_fp4 v[68:69], v29, 1.0 op_sel:[1,0,0]
	v_cvt_scalef32_pk_f32_fp4 v[70:71], v29, 1.0 op_sel:[0,1,0]
	v_cvt_scalef32_pk_f32_fp4 v[28:29], v29, 1.0 op_sel:[1,1,0]
	v_pk_fma_f32 v[156:157], s[16:17], v[66:67], v[156:157]
	v_pk_fma_f32 v[154:155], s[16:17], v[68:69], v[154:155]
	v_pk_fma_f32 v[152:153], s[16:17], v[70:71], v[152:153]
	v_pk_fma_f32 v[150:151], s[16:17], v[28:29], v[150:151]
	v_cvt_scalef32_pk_f32_fp4 v[28:29], v30, 1.0
	v_cvt_scalef32_pk_f32_fp4 v[66:67], v30, 1.0 op_sel:[1,0,0]
	v_cvt_scalef32_pk_f32_fp4 v[68:69], v30, 1.0 op_sel:[0,1,0]
	v_cvt_scalef32_pk_f32_fp4 v[70:71], v30, 1.0 op_sel:[1,1,0]
	v_pk_fma_f32 v[148:149], s[16:17], v[28:29], v[148:149]
	v_pk_fma_f32 v[146:147], s[16:17], v[66:67], v[146:147]
	v_pk_fma_f32 v[144:145], s[16:17], v[68:69], v[144:145]
	v_pk_fma_f32 v[142:143], s[16:17], v[70:71], v[142:143]
	v_cvt_scalef32_pk_f32_fp4 v[28:29], v31, 1.0
	v_cvt_scalef32_pk_f32_fp4 v[66:67], v31, 1.0 op_sel:[1,0,0]
	v_cvt_scalef32_pk_f32_fp4 v[68:69], v31, 1.0 op_sel:[0,1,0]
	v_cvt_scalef32_pk_f32_fp4 v[30:31], v31, 1.0 op_sel:[1,1,0]
	v_pk_fma_f32 v[140:141], s[16:17], v[28:29], v[140:141]
	v_pk_fma_f32 v[138:139], s[16:17], v[66:67], v[138:139]
	v_pk_fma_f32 v[136:137], s[16:17], v[68:69], v[136:137]
	v_pk_fma_f32 v[134:135], s[16:17], v[30:31], v[134:135]
	s_add_i32 s16, s27, -9
	v_readlane_b32 s16, v64, s16
	s_lshr_b32 s40, s16, 7
	s_lshl_b64 s[16:17], s[40:41], 10
	s_add_u32 s16, s16, s100
	s_addc_u32 s17, s17, s101
	global_load_dwordx4 v[28:31], v207, s[16:17]
	v_readlane_b32 s16, v65, 7
	s_waitcnt vmcnt(15)
	v_cvt_scalef32_pk_f32_fp4 v[66:67], v32, 1.0
	v_cvt_scalef32_pk_f32_fp4 v[68:69], v32, 1.0 op_sel:[1,0,0]
	v_cvt_scalef32_pk_f32_fp4 v[70:71], v32, 1.0 op_sel:[0,1,0]
	s_mov_b32 s17, s16
	v_cvt_scalef32_pk_f32_fp4 v[72:73], v32, 1.0 op_sel:[1,1,0]
	v_pk_fma_f32 v[132:133], s[16:17], v[66:67], v[132:133]
	v_pk_fma_f32 v[162:163], s[16:17], v[68:69], v[162:163]
	v_pk_fma_f32 v[160:161], s[16:17], v[70:71], v[160:161]
	v_pk_fma_f32 v[158:159], s[16:17], v[72:73], v[158:159]
	v_cvt_scalef32_pk_f32_fp4 v[66:67], v33, 1.0
	v_cvt_scalef32_pk_f32_fp4 v[68:69], v33, 1.0 op_sel:[1,0,0]
	v_cvt_scalef32_pk_f32_fp4 v[70:71], v33, 1.0 op_sel:[0,1,0]
	v_cvt_scalef32_pk_f32_fp4 v[32:33], v33, 1.0 op_sel:[1,1,0]
	v_pk_fma_f32 v[156:157], s[16:17], v[66:67], v[156:157]
	v_pk_fma_f32 v[154:155], s[16:17], v[68:69], v[154:155]
	v_pk_fma_f32 v[152:153], s[16:17], v[70:71], v[152:153]
	v_pk_fma_f32 v[150:151], s[16:17], v[32:33], v[150:151]
	v_cvt_scalef32_pk_f32_fp4 v[32:33], v34, 1.0
	v_cvt_scalef32_pk_f32_fp4 v[66:67], v34, 1.0 op_sel:[1,0,0]
	v_cvt_scalef32_pk_f32_fp4 v[68:69], v34, 1.0 op_sel:[0,1,0]
	v_cvt_scalef32_pk_f32_fp4 v[70:71], v34, 1.0 op_sel:[1,1,0]
	v_pk_fma_f32 v[148:149], s[16:17], v[32:33], v[148:149]
	v_pk_fma_f32 v[146:147], s[16:17], v[66:67], v[146:147]
	v_pk_fma_f32 v[144:145], s[16:17], v[68:69], v[144:145]
	v_pk_fma_f32 v[142:143], s[16:17], v[70:71], v[142:143]
	v_cvt_scalef32_pk_f32_fp4 v[32:33], v35, 1.0
	v_cvt_scalef32_pk_f32_fp4 v[66:67], v35, 1.0 op_sel:[1,0,0]
	v_cvt_scalef32_pk_f32_fp4 v[68:69], v35, 1.0 op_sel:[0,1,0]
	v_cvt_scalef32_pk_f32_fp4 v[34:35], v35, 1.0 op_sel:[1,1,0]
	v_pk_fma_f32 v[140:141], s[16:17], v[32:33], v[140:141]
	v_pk_fma_f32 v[138:139], s[16:17], v[66:67], v[138:139]
	v_pk_fma_f32 v[136:137], s[16:17], v[68:69], v[136:137]
	v_pk_fma_f32 v[134:135], s[16:17], v[34:35], v[134:135]
	s_add_i32 s16, s27, -8
	v_readlane_b32 s16, v64, s16
	s_lshr_b32 s40, s16, 7
	s_lshl_b64 s[16:17], s[40:41], 10
	s_add_u32 s16, s16, s100
	s_addc_u32 s17, s17, s101
	global_load_dwordx4 v[32:35], v207, s[16:17]
	v_readlane_b32 s16, v65, 8
	s_waitcnt vmcnt(15)
	v_cvt_scalef32_pk_f32_fp4 v[66:67], v36, 1.0
	v_cvt_scalef32_pk_f32_fp4 v[68:69], v36, 1.0 op_sel:[1,0,0]
	v_cvt_scalef32_pk_f32_fp4 v[70:71], v36, 1.0 op_sel:[0,1,0]
	s_mov_b32 s17, s16
	v_cvt_scalef32_pk_f32_fp4 v[72:73], v36, 1.0 op_sel:[1,1,0]
	v_pk_fma_f32 v[132:133], s[16:17], v[66:67], v[132:133]
	v_pk_fma_f32 v[162:163], s[16:17], v[68:69], v[162:163]
	v_pk_fma_f32 v[160:161], s[16:17], v[70:71], v[160:161]
	v_pk_fma_f32 v[158:159], s[16:17], v[72:73], v[158:159]
	v_cvt_scalef32_pk_f32_fp4 v[66:67], v37, 1.0
	v_cvt_scalef32_pk_f32_fp4 v[68:69], v37, 1.0 op_sel:[1,0,0]
	v_cvt_scalef32_pk_f32_fp4 v[70:71], v37, 1.0 op_sel:[0,1,0]
	v_cvt_scalef32_pk_f32_fp4 v[36:37], v37, 1.0 op_sel:[1,1,0]
	v_pk_fma_f32 v[156:157], s[16:17], v[66:67], v[156:157]
	v_pk_fma_f32 v[154:155], s[16:17], v[68:69], v[154:155]
	v_pk_fma_f32 v[152:153], s[16:17], v[70:71], v[152:153]
	v_pk_fma_f32 v[150:151], s[16:17], v[36:37], v[150:151]
	v_cvt_scalef32_pk_f32_fp4 v[36:37], v38, 1.0
	v_cvt_scalef32_pk_f32_fp4 v[66:67], v38, 1.0 op_sel:[1,0,0]
	v_cvt_scalef32_pk_f32_fp4 v[68:69], v38, 1.0 op_sel:[0,1,0]
	v_cvt_scalef32_pk_f32_fp4 v[70:71], v38, 1.0 op_sel:[1,1,0]
	v_pk_fma_f32 v[148:149], s[16:17], v[36:37], v[148:149]
	v_pk_fma_f32 v[146:147], s[16:17], v[66:67], v[146:147]
	v_pk_fma_f32 v[144:145], s[16:17], v[68:69], v[144:145]
	v_pk_fma_f32 v[142:143], s[16:17], v[70:71], v[142:143]
	v_cvt_scalef32_pk_f32_fp4 v[36:37], v39, 1.0
	v_cvt_scalef32_pk_f32_fp4 v[66:67], v39, 1.0 op_sel:[1,0,0]
	v_cvt_scalef32_pk_f32_fp4 v[68:69], v39, 1.0 op_sel:[0,1,0]
	v_cvt_scalef32_pk_f32_fp4 v[38:39], v39, 1.0 op_sel:[1,1,0]
	v_pk_fma_f32 v[140:141], s[16:17], v[36:37], v[140:141]
	v_pk_fma_f32 v[138:139], s[16:17], v[66:67], v[138:139]
	v_pk_fma_f32 v[136:137], s[16:17], v[68:69], v[136:137]
	v_pk_fma_f32 v[134:135], s[16:17], v[38:39], v[134:135]
	s_add_i32 s16, s27, -7
	v_readlane_b32 s16, v64, s16
	s_lshr_b32 s40, s16, 7
	s_lshl_b64 s[16:17], s[40:41], 10
	s_add_u32 s16, s16, s100
	s_addc_u32 s17, s17, s101
	global_load_dwordx4 v[36:39], v207, s[16:17]
	v_readlane_b32 s16, v65, 9
	s_waitcnt vmcnt(15)
; #define P4_FOR16(M) M(0) M(1) M(2) M(3) M(4) M(5) M(6) M(7) M(8) M(9) M(10) M(11) M(12) M(13) M(14) M(15)
; #define P4_V(i) { const unsigned wu_ = (unsigned)__builtin_amdgcn_readlane((int)__float_as_uint(wreg), i); const unsigned long long wp_ = ((unsigned long long)wu_ << 32) | wu_; \
;               P4_ACC(b##i, wp_); const int nk_ = __builtin_amdgcn_readlane(ksel, nb + i); P4_LOAD(b##i, Vg, nk_); }
; #define P4_V(i) { const unsigned wu_ = (unsigned)__builtin_amdgcn_readlane((int)__float_as_uint(wreg), i); const unsigned long long wp_ = ((unsigned long long)wu_ << 32) | wu_; \
;               P4_ACC(b##i, wp_); const int nk_ = __builtin_amdgcn_readlane(kn, i); P4_LOAD(b##i, Vg, nk_); }
; #define P4_V(i) { const unsigned wu_ = (unsigned)__builtin_amdgcn_readlane((int)__float_as_uint(wreg), i); const unsigned long long wp_ = ((unsigned long long)wu_ << 32) | wu_; \
;               P4_ACC(b##i, wp_); }
; __device__ __forceinline__ void peer_gather_f4p(const float* X, const int* __restrict__ IDX, const float* __restrict__ G, ...
;     ...
; #pragma unroll 1
;         for (int bt = 0; bt < 7; ++bt) {
;             const int ksel = (bt + 1 < 4) ? k0 : k1;
;             const int nb = (16 * (bt + 1)) & 63;
;             const float wreg = wbuf[kt * 128 + bt * 16 + (lane & 15)];
;     ...
;             P4_FOR16(P4_V)
;     ...
;         }
	v_cvt_scalef32_pk_f32_fp4 v[66:67], v40, 1.0
	v_cvt_scalef32_pk_f32_fp4 v[68:69], v40, 1.0 op_sel:[1,0,0]
	v_cvt_scalef32_pk_f32_fp4 v[70:71], v40, 1.0 op_sel:[0,1,0]
	s_mov_b32 s17, s16
	v_cvt_scalef32_pk_f32_fp4 v[72:73], v40, 1.0 op_sel:[1,1,0]
	v_pk_fma_f32 v[132:133], s[16:17], v[66:67], v[132:133]
	v_pk_fma_f32 v[162:163], s[16:17], v[68:69], v[162:163]
	v_pk_fma_f32 v[160:161], s[16:17], v[70:71], v[160:161]
	v_pk_fma_f32 v[158:159], s[16:17], v[72:73], v[158:159]
	v_cvt_scalef32_pk_f32_fp4 v[66:67], v41, 1.0
	v_cvt_scalef32_pk_f32_fp4 v[68:69], v41, 1.0 op_sel:[1,0,0]
	v_cvt_scalef32_pk_f32_fp4 v[70:71], v41, 1.0 op_sel:[0,1,0]
	v_cvt_scalef32_pk_f32_fp4 v[40:41], v41, 1.0 op_sel:[1,1,0]
	v_pk_fma_f32 v[156:157], s[16:17], v[66:67], v[156:157]
	v_pk_fma_f32 v[154:155], s[16:17], v[68:69], v[154:155]
	v_pk_fma_f32 v[152:153], s[16:17], v[70:71], v[152:153]
	v_pk_fma_f32 v[150:151], s[16:17], v[40:41], v[150:151]
	v_cvt_scalef32_pk_f32_fp4 v[40:41], v42, 1.0
	v_cvt_scalef32_pk_f32_fp4 v[66:67], v42, 1.0 op_sel:[1,0,0]
	v_cvt_scalef32_pk_f32_fp4 v[68:69], v42, 1.0 op_sel:[0,1,0]
	v_cvt_scalef32_pk_f32_fp4 v[70:71], v42, 1.0 op_sel:[1,1,0]
	v_pk_fma_f32 v[148:149], s[16:17], v[40:41], v[148:149]
	v_pk_fma_f32 v[146:147], s[16:17], v[66:67], v[146:147]
	v_pk_fma_f32 v[144:145], s[16:17], v[68:69], v[144:145]
	v_pk_fma_f32 v[142:143], s[16:17], v[70:71], v[142:143]
	v_cvt_scalef32_pk_f32_fp4 v[40:41], v43, 1.0
	v_cvt_scalef32_pk_f32_fp4 v[66:67], v43, 1.0 op_sel:[1,0,0]
	v_cvt_scalef32_pk_f32_fp4 v[68:69], v43, 1.0 op_sel:[0,1,0]
	v_cvt_scalef32_pk_f32_fp4 v[42:43], v43, 1.0 op_sel:[1,1,0]
	v_pk_fma_f32 v[140:141], s[16:17], v[40:41], v[140:141]
	v_pk_fma_f32 v[138:139], s[16:17], v[66:67], v[138:139]
	v_pk_fma_f32 v[136:137], s[16:17], v[68:69], v[136:137]
	v_pk_fma_f32 v[134:135], s[16:17], v[42:43], v[134:135]
	s_add_i32 s16, s27, -6
	v_readlane_b32 s16, v64, s16
	s_lshr_b32 s40, s16, 7
	s_lshl_b64 s[16:17], s[40:41], 10
	s_add_u32 s16, s16, s100
	s_addc_u32 s17, s17, s101
	global_load_dwordx4 v[40:43], v207, s[16:17]
	v_readlane_b32 s16, v65, 10
	s_waitcnt vmcnt(15)
	v_cvt_scalef32_pk_f32_fp4 v[66:67], v44, 1.0
	v_cvt_scalef32_pk_f32_fp4 v[68:69], v44, 1.0 op_sel:[1,0,0]
	v_cvt_scalef32_pk_f32_fp4 v[70:71], v44, 1.0 op_sel:[0,1,0]
	s_mov_b32 s17, s16
	v_cvt_scalef32_pk_f32_fp4 v[72:73], v44, 1.0 op_sel:[1,1,0]
	v_pk_fma_f32 v[132:133], s[16:17], v[66:67], v[132:133]
	v_pk_fma_f32 v[162:163], s[16:17], v[68:69], v[162:163]
	v_pk_fma_f32 v[160:161], s[16:17], v[70:71], v[160:161]
	v_pk_fma_f32 v[158:159], s[16:17], v[72:73], v[158:159]
	v_cvt_scalef32_pk_f32_fp4 v[66:67], v45, 1.0
	v_cvt_scalef32_pk_f32_fp4 v[68:69], v45, 1.0 op_sel:[1,0,0]
	v_cvt_scalef32_pk_f32_fp4 v[70:71], v45, 1.0 op_sel:[0,1,0]
	v_cvt_scalef32_pk_f32_fp4 v[44:45], v45, 1.0 op_sel:[1,1,0]
	v_pk_fma_f32 v[156:157], s[16:17], v[66:67], v[156:157]
	v_pk_fma_f32 v[154:155], s[16:17], v[68:69], v[154:155]
	v_pk_fma_f32 v[152:153], s[16:17], v[70:71], v[152:153]
	v_pk_fma_f32 v[150:151], s[16:17], v[44:45], v[150:151]
	v_cvt_scalef32_pk_f32_fp4 v[44:45], v46, 1.0
	v_cvt_scalef32_pk_f32_fp4 v[66:67], v46, 1.0 op_sel:[1,0,0]
	v_cvt_scalef32_pk_f32_fp4 v[68:69], v46, 1.0 op_sel:[0,1,0]
	v_cvt_scalef32_pk_f32_fp4 v[70:71], v46, 1.0 op_sel:[1,1,0]
	v_pk_fma_f32 v[148:149], s[16:17], v[44:45], v[148:149]
	v_pk_fma_f32 v[146:147], s[16:17], v[66:67], v[146:147]
	v_pk_fma_f32 v[144:145], s[16:17], v[68:69], v[144:145]
	v_pk_fma_f32 v[142:143], s[16:17], v[70:71], v[142:143]
	v_cvt_scalef32_pk_f32_fp4 v[44:45], v47, 1.0
	v_cvt_scalef32_pk_f32_fp4 v[66:67], v47, 1.0 op_sel:[1,0,0]
	v_cvt_scalef32_pk_f32_fp4 v[68:69], v47, 1.0 op_sel:[0,1,0]
	v_cvt_scalef32_pk_f32_fp4 v[46:47], v47, 1.0 op_sel:[1,1,0]
	v_pk_fma_f32 v[140:141], s[16:17], v[44:45], v[140:141]
	v_pk_fma_f32 v[138:139], s[16:17], v[66:67], v[138:139]
	v_pk_fma_f32 v[136:137], s[16:17], v[68:69], v[136:137]
	v_pk_fma_f32 v[134:135], s[16:17], v[46:47], v[134:135]
	s_add_i32 s16, s27, -5
	v_readlane_b32 s16, v64, s16
	s_lshr_b32 s40, s16, 7
	s_lshl_b64 s[16:17], s[40:41], 10
	s_add_u32 s16, s16, s100
	s_addc_u32 s17, s17, s101
	global_load_dwordx4 v[44:47], v207, s[16:17]
	v_readlane_b32 s16, v65, 11
	s_waitcnt vmcnt(15)
	v_cvt_scalef32_pk_f32_fp4 v[66:67], v48, 1.0
	v_cvt_scalef32_pk_f32_fp4 v[68:69], v48, 1.0 op_sel:[1,0,0]
	v_cvt_scalef32_pk_f32_fp4 v[70:71], v48, 1.0 op_sel:[0,1,0]
	s_mov_b32 s17, s16
	v_cvt_scalef32_pk_f32_fp4 v[72:73], v48, 1.0 op_sel:[1,1,0]
	v_pk_fma_f32 v[132:133], s[16:17], v[66:67], v[132:133]
	v_pk_fma_f32 v[162:163], s[16:17], v[68:69], v[162:163]
	v_pk_fma_f32 v[160:161], s[16:17], v[70:71], v[160:161]
	v_pk_fma_f32 v[158:159], s[16:17], v[72:73], v[158:159]
	v_cvt_scalef32_pk_f32_fp4 v[66:67], v49, 1.0
	v_cvt_scalef32_pk_f32_fp4 v[68:69], v49, 1.0 op_sel:[1,0,0]
	v_cvt_scalef32_pk_f32_fp4 v[70:71], v49, 1.0 op_sel:[0,1,0]
	v_cvt_scalef32_pk_f32_fp4 v[48:49], v49, 1.0 op_sel:[1,1,0]
	v_pk_fma_f32 v[156:157], s[16:17], v[66:67], v[156:157]
	v_pk_fma_f32 v[154:155], s[16:17], v[68:69], v[154:155]
	v_pk_fma_f32 v[152:153], s[16:17], v[70:71], v[152:153]
	v_pk_fma_f32 v[150:151], s[16:17], v[48:49], v[150:151]
	v_cvt_scalef32_pk_f32_fp4 v[48:49], v50, 1.0
	v_cvt_scalef32_pk_f32_fp4 v[66:67], v50, 1.0 op_sel:[1,0,0]
	v_cvt_scalef32_pk_f32_fp4 v[68:69], v50, 1.0 op_sel:[0,1,0]
	v_cvt_scalef32_pk_f32_fp4 v[70:71], v50, 1.0 op_sel:[1,1,0]
	v_pk_fma_f32 v[148:149], s[16:17], v[48:49], v[148:149]
	v_pk_fma_f32 v[146:147], s[16:17], v[66:67], v[146:147]
	v_pk_fma_f32 v[144:145], s[16:17], v[68:69], v[144:145]
	v_pk_fma_f32 v[142:143], s[16:17], v[70:71], v[142:143]
	v_cvt_scalef32_pk_f32_fp4 v[48:49], v51, 1.0
	v_cvt_scalef32_pk_f32_fp4 v[66:67], v51, 1.0 op_sel:[1,0,0]
	v_cvt_scalef32_pk_f32_fp4 v[68:69], v51, 1.0 op_sel:[0,1,0]
	v_cvt_scalef32_pk_f32_fp4 v[50:51], v51, 1.0 op_sel:[1,1,0]
	v_pk_fma_f32 v[140:141], s[16:17], v[48:49], v[140:141]
	v_pk_fma_f32 v[138:139], s[16:17], v[66:67], v[138:139]
	v_pk_fma_f32 v[136:137], s[16:17], v[68:69], v[136:137]
	v_pk_fma_f32 v[134:135], s[16:17], v[50:51], v[134:135]
	s_add_i32 s16, s27, -4
	v_readlane_b32 s16, v64, s16
	s_lshr_b32 s40, s16, 7
	s_lshl_b64 s[16:17], s[40:41], 10
	s_add_u32 s16, s16, s100
	s_addc_u32 s17, s17, s101
	global_load_dwordx4 v[48:51], v207, s[16:17]
	v_readlane_b32 s16, v65, 12
	s_waitcnt vmcnt(15)
; #define P4_FOR16(M) M(0) M(1) M(2) M(3) M(4) M(5) M(6) M(7) M(8) M(9) M(10) M(11) M(12) M(13) M(14) M(15)
; #define P4_V(i) { const unsigned wu_ = (unsigned)__builtin_amdgcn_readlane((int)__float_as_uint(wreg), i); const unsigned long long wp_ = ((unsigned long long)wu_ << 32) | wu_; \
;               P4_ACC(b##i, wp_); const int nk_ = __builtin_amdgcn_readlane(ksel, nb + i); P4_LOAD(b##i, Vg, nk_); }
; #define P4_V(i) { const unsigned wu_ = (unsigned)__builtin_amdgcn_readlane((int)__float_as_uint(wreg), i); const unsigned long long wp_ = ((unsigned long long)wu_ << 32) | wu_; \
;               P4_ACC(b##i, wp_); const int nk_ = __builtin_amdgcn_readlane(kn, i); P4_LOAD(b##i, Vg, nk_); }
; #define P4_V(i) { const unsigned wu_ = (unsigned)__builtin_amdgcn_readlane((int)__float_as_uint(wreg), i); const unsigned long long wp_ = ((unsigned long long)wu_ << 32) | wu_; \
;               P4_ACC(b##i, wp_); }
; __device__ __forceinline__ void peer_gather_f4p(const float* X, const int* __restrict__ IDX, const float* __restrict__ G, ...
;     ...
; #pragma unroll 1
;         for (int bt = 0; bt < 7; ++bt) {
;             const int ksel = (bt + 1 < 4) ? k0 : k1;
;             const int nb = (16 * (bt + 1)) & 63;
;             const float wreg = wbuf[kt * 128 + bt * 16 + (lane & 15)];
;     ...
;             P4_FOR16(P4_V)
;     ...
;         }
	v_cvt_scalef32_pk_f32_fp4 v[66:67], v52, 1.0
	v_cvt_scalef32_pk_f32_fp4 v[68:69], v52, 1.0 op_sel:[1,0,0]
	v_cvt_scalef32_pk_f32_fp4 v[70:71], v52, 1.0 op_sel:[0,1,0]
	s_mov_b32 s17, s16
	v_cvt_scalef32_pk_f32_fp4 v[72:73], v52, 1.0 op_sel:[1,1,0]
	v_pk_fma_f32 v[132:133], s[16:17], v[66:67], v[132:133]
	v_pk_fma_f32 v[162:163], s[16:17], v[68:69], v[162:163]
	v_pk_fma_f32 v[160:161], s[16:17], v[70:71], v[160:161]
	v_pk_fma_f32 v[158:159], s[16:17], v[72:73], v[158:159]
	v_cvt_scalef32_pk_f32_fp4 v[66:67], v53, 1.0
	v_cvt_scalef32_pk_f32_fp4 v[68:69], v53, 1.0 op_sel:[1,0,0]
	v_cvt_scalef32_pk_f32_fp4 v[70:71], v53, 1.0 op_sel:[0,1,0]
	v_cvt_scalef32_pk_f32_fp4 v[52:53], v53, 1.0 op_sel:[1,1,0]
	v_pk_fma_f32 v[156:157], s[16:17], v[66:67], v[156:157]
	v_pk_fma_f32 v[154:155], s[16:17], v[68:69], v[154:155]
	v_pk_fma_f32 v[152:153], s[16:17], v[70:71], v[152:153]
	v_pk_fma_f32 v[150:151], s[16:17], v[52:53], v[150:151]
	v_cvt_scalef32_pk_f32_fp4 v[52:53], v54, 1.0
	v_cvt_scalef32_pk_f32_fp4 v[66:67], v54, 1.0 op_sel:[1,0,0]
	v_cvt_scalef32_pk_f32_fp4 v[68:69], v54, 1.0 op_sel:[0,1,0]
	v_cvt_scalef32_pk_f32_fp4 v[70:71], v54, 1.0 op_sel:[1,1,0]
	v_pk_fma_f32 v[148:149], s[16:17], v[52:53], v[148:149]
	v_pk_fma_f32 v[146:147], s[16:17], v[66:67], v[146:147]
	v_pk_fma_f32 v[144:145], s[16:17], v[68:69], v[144:145]
	v_pk_fma_f32 v[142:143], s[16:17], v[70:71], v[142:143]
	v_cvt_scalef32_pk_f32_fp4 v[52:53], v55, 1.0
	v_cvt_scalef32_pk_f32_fp4 v[66:67], v55, 1.0 op_sel:[1,0,0]
	v_cvt_scalef32_pk_f32_fp4 v[68:69], v55, 1.0 op_sel:[0,1,0]
	v_cvt_scalef32_pk_f32_fp4 v[54:55], v55, 1.0 op_sel:[1,1,0]
	v_pk_fma_f32 v[140:141], s[16:17], v[52:53], v[140:141]
	v_pk_fma_f32 v[138:139], s[16:17], v[66:67], v[138:139]
	v_pk_fma_f32 v[136:137], s[16:17], v[68:69], v[136:137]
	v_pk_fma_f32 v[134:135], s[16:17], v[54:55], v[134:135]
	s_add_i32 s16, s27, -3
	v_readlane_b32 s16, v64, s16
	s_lshr_b32 s40, s16, 7
	s_lshl_b64 s[16:17], s[40:41], 10
	s_add_u32 s16, s16, s100
	s_addc_u32 s17, s17, s101
	global_load_dwordx4 v[52:55], v207, s[16:17]
	v_readlane_b32 s16, v65, 13
	s_waitcnt vmcnt(15)
	v_cvt_scalef32_pk_f32_fp4 v[66:67], v56, 1.0
	v_cvt_scalef32_pk_f32_fp4 v[68:69], v56, 1.0 op_sel:[1,0,0]
	v_cvt_scalef32_pk_f32_fp4 v[70:71], v56, 1.0 op_sel:[0,1,0]
	s_mov_b32 s17, s16
	v_cvt_scalef32_pk_f32_fp4 v[72:73], v56, 1.0 op_sel:[1,1,0]
	v_pk_fma_f32 v[132:133], s[16:17], v[66:67], v[132:133]
	v_pk_fma_f32 v[162:163], s[16:17], v[68:69], v[162:163]
	v_pk_fma_f32 v[160:161], s[16:17], v[70:71], v[160:161]
	v_pk_fma_f32 v[158:159], s[16:17], v[72:73], v[158:159]
	v_cvt_scalef32_pk_f32_fp4 v[66:67], v57, 1.0
	v_cvt_scalef32_pk_f32_fp4 v[68:69], v57, 1.0 op_sel:[1,0,0]
	v_cvt_scalef32_pk_f32_fp4 v[70:71], v57, 1.0 op_sel:[0,1,0]
	v_cvt_scalef32_pk_f32_fp4 v[56:57], v57, 1.0 op_sel:[1,1,0]
	v_pk_fma_f32 v[156:157], s[16:17], v[66:67], v[156:157]
	v_pk_fma_f32 v[154:155], s[16:17], v[68:69], v[154:155]
	v_pk_fma_f32 v[152:153], s[16:17], v[70:71], v[152:153]
	v_pk_fma_f32 v[150:151], s[16:17], v[56:57], v[150:151]
	v_cvt_scalef32_pk_f32_fp4 v[56:57], v58, 1.0
	v_cvt_scalef32_pk_f32_fp4 v[66:67], v58, 1.0 op_sel:[1,0,0]
	v_cvt_scalef32_pk_f32_fp4 v[68:69], v58, 1.0 op_sel:[0,1,0]
	v_cvt_scalef32_pk_f32_fp4 v[70:71], v58, 1.0 op_sel:[1,1,0]
	v_pk_fma_f32 v[148:149], s[16:17], v[56:57], v[148:149]
	v_pk_fma_f32 v[146:147], s[16:17], v[66:67], v[146:147]
	v_pk_fma_f32 v[144:145], s[16:17], v[68:69], v[144:145]
	v_pk_fma_f32 v[142:143], s[16:17], v[70:71], v[142:143]
	v_cvt_scalef32_pk_f32_fp4 v[56:57], v59, 1.0
	v_cvt_scalef32_pk_f32_fp4 v[66:67], v59, 1.0 op_sel:[1,0,0]
	v_cvt_scalef32_pk_f32_fp4 v[68:69], v59, 1.0 op_sel:[0,1,0]
	v_cvt_scalef32_pk_f32_fp4 v[58:59], v59, 1.0 op_sel:[1,1,0]
	v_pk_fma_f32 v[140:141], s[16:17], v[56:57], v[140:141]
	v_pk_fma_f32 v[138:139], s[16:17], v[66:67], v[138:139]
	v_pk_fma_f32 v[136:137], s[16:17], v[68:69], v[136:137]
	v_pk_fma_f32 v[134:135], s[16:17], v[58:59], v[134:135]
	s_add_i32 s16, s27, -2
	v_readlane_b32 s16, v64, s16
	s_lshr_b32 s40, s16, 7
	s_lshl_b64 s[16:17], s[40:41], 10
	s_add_u32 s16, s16, s100
	s_addc_u32 s17, s17, s101
	global_load_dwordx4 v[56:59], v207, s[16:17]
	v_readlane_b32 s16, v65, 14
	s_waitcnt vmcnt(15)
	v_cvt_scalef32_pk_f32_fp4 v[66:67], v60, 1.0
	v_cvt_scalef32_pk_f32_fp4 v[68:69], v60, 1.0 op_sel:[1,0,0]
	v_cvt_scalef32_pk_f32_fp4 v[70:71], v60, 1.0 op_sel:[0,1,0]
	s_mov_b32 s17, s16
	v_cvt_scalef32_pk_f32_fp4 v[72:73], v60, 1.0 op_sel:[1,1,0]
	v_pk_fma_f32 v[132:133], s[16:17], v[66:67], v[132:133]
	v_pk_fma_f32 v[162:163], s[16:17], v[68:69], v[162:163]
	v_pk_fma_f32 v[160:161], s[16:17], v[70:71], v[160:161]
	v_pk_fma_f32 v[158:159], s[16:17], v[72:73], v[158:159]
	v_cvt_scalef32_pk_f32_fp4 v[66:67], v61, 1.0
	v_cvt_scalef32_pk_f32_fp4 v[68:69], v61, 1.0 op_sel:[1,0,0]
	v_cvt_scalef32_pk_f32_fp4 v[70:71], v61, 1.0 op_sel:[0,1,0]
	v_cvt_scalef32_pk_f32_fp4 v[60:61], v61, 1.0 op_sel:[1,1,0]
	v_pk_fma_f32 v[156:157], s[16:17], v[66:67], v[156:157]
	v_pk_fma_f32 v[154:155], s[16:17], v[68:69], v[154:155]
	v_pk_fma_f32 v[152:153], s[16:17], v[70:71], v[152:153]
	v_pk_fma_f32 v[150:151], s[16:17], v[60:61], v[150:151]
	v_cvt_scalef32_pk_f32_fp4 v[60:61], v62, 1.0
	v_cvt_scalef32_pk_f32_fp4 v[66:67], v62, 1.0 op_sel:[1,0,0]
	v_cvt_scalef32_pk_f32_fp4 v[68:69], v62, 1.0 op_sel:[0,1,0]
	v_cvt_scalef32_pk_f32_fp4 v[70:71], v62, 1.0 op_sel:[1,1,0]
	v_pk_fma_f32 v[148:149], s[16:17], v[60:61], v[148:149]
	v_pk_fma_f32 v[146:147], s[16:17], v[66:67], v[146:147]
	v_pk_fma_f32 v[144:145], s[16:17], v[68:69], v[144:145]
	v_pk_fma_f32 v[142:143], s[16:17], v[70:71], v[142:143]
	v_cvt_scalef32_pk_f32_fp4 v[60:61], v63, 1.0
	v_cvt_scalef32_pk_f32_fp4 v[66:67], v63, 1.0 op_sel:[1,0,0]
	v_cvt_scalef32_pk_f32_fp4 v[68:69], v63, 1.0 op_sel:[0,1,0]
	v_cvt_scalef32_pk_f32_fp4 v[62:63], v63, 1.0 op_sel:[1,1,0]
	v_pk_fma_f32 v[140:141], s[16:17], v[60:61], v[140:141]
	v_pk_fma_f32 v[138:139], s[16:17], v[66:67], v[138:139]
	v_pk_fma_f32 v[136:137], s[16:17], v[68:69], v[136:137]
	v_pk_fma_f32 v[134:135], s[16:17], v[62:63], v[134:135]
	s_add_i32 s16, s27, -1
	v_readlane_b32 s16, v64, s16
	s_lshr_b32 s40, s16, 7
	s_lshl_b64 s[16:17], s[40:41], 10
	s_add_u32 s16, s16, s100
	s_addc_u32 s17, s17, s101
	global_load_dwordx4 v[60:63], v207, s[16:17]
	v_readlane_b32 s16, v65, 15
	s_waitcnt vmcnt(15)
; #define P4_FOR16(M) M(0) M(1) M(2) M(3) M(4) M(5) M(6) M(7) M(8) M(9) M(10) M(11) M(12) M(13) M(14) M(15)
; #define P4_V(i) { const unsigned wu_ = (unsigned)__builtin_amdgcn_readlane((int)__float_as_uint(wreg), i); const unsigned long long wp_ = ((unsigned long long)wu_ << 32) | wu_; \
;               P4_ACC(b##i, wp_); const int nk_ = __builtin_amdgcn_readlane(ksel, nb + i); P4_LOAD(b##i, Vg, nk_); }
; #define P4_V(i) { const unsigned wu_ = (unsigned)__builtin_amdgcn_readlane((int)__float_as_uint(wreg), i); const unsigned long long wp_ = ((unsigned long long)wu_ << 32) | wu_; \
;               P4_ACC(b##i, wp_); const int nk_ = __builtin_amdgcn_readlane(kn, i); P4_LOAD(b##i, Vg, nk_); }
; #define P4_V(i) { const unsigned wu_ = (unsigned)__builtin_amdgcn_readlane((int)__float_as_uint(wreg), i); const unsigned long long wp_ = ((unsigned long long)wu_ << 32) | wu_; \
;               P4_ACC(b##i, wp_); }
; __device__ __forceinline__ void peer_gather_f4p(const float* X, const int* __restrict__ IDX, const float* __restrict__ G, ...
;     ...
; #pragma unroll 1
;         for (int bt = 0; bt < 7; ++bt) {
;             const int ksel = (bt + 1 < 4) ? k0 : k1;
;             const int nb = (16 * (bt + 1)) & 63;
;             const float wreg = wbuf[kt * 128 + bt * 16 + (lane & 15)];
;     ...
;             P4_FOR16(P4_V)
;     ...
;         }
;         {
;             const float wreg = wbuf[kt * 128 + 7 * 16 + (lane & 15)];
;             if (kt < 3) {
;     ...
;                 P4_FOR16(P4_V)
	v_cvt_scalef32_pk_f32_fp4 v[66:67], v100, 1.0
	v_cvt_scalef32_pk_f32_fp4 v[68:69], v100, 1.0 op_sel:[1,0,0]
	v_cvt_scalef32_pk_f32_fp4 v[70:71], v100, 1.0 op_sel:[0,1,0]
	v_cvt_scalef32_pk_f32_fp4 v[72:73], v100, 1.0 op_sel:[1,1,0]
	s_mov_b32 s17, s16
	v_pk_fma_f32 v[132:133], s[16:17], v[66:67], v[132:133]
	v_pk_fma_f32 v[162:163], s[16:17], v[68:69], v[162:163]
	v_pk_fma_f32 v[160:161], s[16:17], v[70:71], v[160:161]
	v_pk_fma_f32 v[158:159], s[16:17], v[72:73], v[158:159]
	v_cvt_scalef32_pk_f32_fp4 v[66:67], v101, 1.0
	v_cvt_scalef32_pk_f32_fp4 v[68:69], v101, 1.0 op_sel:[1,0,0]
	v_cvt_scalef32_pk_f32_fp4 v[70:71], v101, 1.0 op_sel:[0,1,0]
	v_cvt_scalef32_pk_f32_fp4 v[72:73], v101, 1.0 op_sel:[1,1,0]
	v_pk_fma_f32 v[156:157], s[16:17], v[66:67], v[156:157]
	v_pk_fma_f32 v[154:155], s[16:17], v[68:69], v[154:155]
	v_pk_fma_f32 v[152:153], s[16:17], v[70:71], v[152:153]
	v_pk_fma_f32 v[150:151], s[16:17], v[72:73], v[150:151]
	v_cvt_scalef32_pk_f32_fp4 v[66:67], v102, 1.0
	v_cvt_scalef32_pk_f32_fp4 v[68:69], v102, 1.0 op_sel:[1,0,0]
	v_cvt_scalef32_pk_f32_fp4 v[70:71], v102, 1.0 op_sel:[0,1,0]
	v_cvt_scalef32_pk_f32_fp4 v[72:73], v102, 1.0 op_sel:[1,1,0]
	v_pk_fma_f32 v[148:149], s[16:17], v[66:67], v[148:149]
	v_pk_fma_f32 v[146:147], s[16:17], v[68:69], v[146:147]
	v_pk_fma_f32 v[144:145], s[16:17], v[70:71], v[144:145]
	v_pk_fma_f32 v[142:143], s[16:17], v[72:73], v[142:143]
	v_cvt_scalef32_pk_f32_fp4 v[66:67], v103, 1.0
	v_cvt_scalef32_pk_f32_fp4 v[68:69], v103, 1.0 op_sel:[1,0,0]
	v_cvt_scalef32_pk_f32_fp4 v[70:71], v103, 1.0 op_sel:[0,1,0]
	v_cvt_scalef32_pk_f32_fp4 v[72:73], v103, 1.0 op_sel:[1,1,0]
	v_pk_fma_f32 v[140:141], s[16:17], v[66:67], v[140:141]
	v_pk_fma_f32 v[138:139], s[16:17], v[68:69], v[138:139]
	v_pk_fma_f32 v[136:137], s[16:17], v[70:71], v[136:137]
	v_pk_fma_f32 v[134:135], s[16:17], v[72:73], v[134:135]
	v_readlane_b32 s16, v64, s27
	s_lshr_b32 s40, s16, 7
	s_lshl_b64 s[40:41], s[40:41], 10
	s_add_u32 s40, s40, s100
	s_addc_u32 s41, s41, s101
	global_load_dwordx4 v[100:103], v207, s[40:41]
	s_add_i32 s27, s27, 16
	s_cmpk_eq_i32 s27, 0x8f
	s_cbranch_scc0 .LBB0_550
	v_lshl_add_u32 v64, v170, 2, s26
	ds_read_b32 v209, v64 offset:4544
	s_cmp_lg_u32 s19, 3
	s_mov_b64 s[40:41], -1
	s_cbranch_scc0 .LBB0_553
	v_readlane_b32 s16, v208, 0
	s_waitcnt lgkmcnt(0)
	v_readlane_b32 s40, v209, 0
	s_waitcnt vmcnt(15)
	v_cvt_scalef32_pk_f32_fp4 v[64:65], v4, 1.0
	v_mov_b64_e32 v[194:195], v[132:133]
	v_mov_b64_e32 v[196:197], v[162:163]
	v_mov_b64_e32 v[190:191], v[160:161]
	v_mov_b64_e32 v[192:193], v[158:159]
	s_lshr_b32 s16, s16, 7
	s_mov_b32 s17, s86
	s_mov_b32 s41, s40
	v_cvt_scalef32_pk_f32_fp4 v[66:67], v4, 1.0 op_sel:[1,0,0]
	v_cvt_scalef32_pk_f32_fp4 v[68:69], v4, 1.0 op_sel:[0,1,0]
	v_cvt_scalef32_pk_f32_fp4 v[70:71], v4, 1.0 op_sel:[1,1,0]
	v_pk_fma_f32 v[194:195], s[40:41], v[64:65], v[194:195]
	v_mov_b64_e32 v[186:187], v[156:157]
	v_pk_fma_f32 v[196:197], s[40:41], v[66:67], v[196:197]
	v_pk_fma_f32 v[190:191], s[40:41], v[68:69], v[190:191]
	v_pk_fma_f32 v[192:193], s[40:41], v[70:71], v[192:193]
	v_cvt_scalef32_pk_f32_fp4 v[64:65], v5, 1.0
	v_mov_b64_e32 v[188:189], v[154:155]
	v_mov_b64_e32 v[182:183], v[152:153]
	v_mov_b64_e32 v[184:185], v[150:151]
	s_lshl_b64 s[16:17], s[16:17], 10
	v_cvt_scalef32_pk_f32_fp4 v[66:67], v5, 1.0 op_sel:[1,0,0]
	v_cvt_scalef32_pk_f32_fp4 v[68:69], v5, 1.0 op_sel:[0,1,0]
	v_cvt_scalef32_pk_f32_fp4 v[70:71], v5, 1.0 op_sel:[1,1,0]
	v_pk_fma_f32 v[186:187], s[40:41], v[64:65], v[186:187]
	v_mov_b64_e32 v[178:179], v[148:149]
	v_pk_fma_f32 v[188:189], s[40:41], v[66:67], v[188:189]
	v_pk_fma_f32 v[182:183], s[40:41], v[68:69], v[182:183]
	v_pk_fma_f32 v[184:185], s[40:41], v[70:71], v[184:185]
	v_cvt_scalef32_pk_f32_fp4 v[64:65], v6, 1.0
	v_mov_b64_e32 v[180:181], v[146:147]
	v_mov_b64_e32 v[174:175], v[144:145]
	v_mov_b64_e32 v[176:177], v[142:143]
	s_add_u32 s16, s52, s16
	v_cvt_scalef32_pk_f32_fp4 v[66:67], v6, 1.0 op_sel:[1,0,0]
	v_cvt_scalef32_pk_f32_fp4 v[68:69], v6, 1.0 op_sel:[0,1,0]
	v_cvt_scalef32_pk_f32_fp4 v[70:71], v6, 1.0 op_sel:[1,1,0]
	v_pk_fma_f32 v[178:179], s[40:41], v[64:65], v[178:179]
	v_mov_b64_e32 v[170:171], v[140:141]
	v_pk_fma_f32 v[180:181], s[40:41], v[66:67], v[180:181]
	v_pk_fma_f32 v[174:175], s[40:41], v[68:69], v[174:175]
	v_pk_fma_f32 v[176:177], s[40:41], v[70:71], v[176:177]
	v_cvt_scalef32_pk_f32_fp4 v[64:65], v7, 1.0
	s_addc_u32 s17, s53, s17
	v_cvt_scalef32_pk_f32_fp4 v[66:67], v7, 1.0 op_sel:[1,0,0]
	v_cvt_scalef32_pk_f32_fp4 v[68:69], v7, 1.0 op_sel:[0,1,0]
	v_cvt_scalef32_pk_f32_fp4 v[70:71], v7, 1.0 op_sel:[1,1,0]
	v_pk_fma_f32 v[170:171], s[40:41], v[64:65], v[170:171]
	v_mov_b64_e32 v[172:173], v[138:139]
	v_mov_b64_e32 v[166:167], v[136:137]
	v_mov_b64_e32 v[168:169], v[134:135]
	v_lshl_add_u64 v[64:65], s[16:17], 0, v[164:165]
	v_readlane_b32 s16, v208, 1
	v_pk_fma_f32 v[172:173], s[40:41], v[66:67], v[172:173]
	v_pk_fma_f32 v[166:167], s[40:41], v[68:69], v[166:167]
	v_pk_fma_f32 v[168:169], s[40:41], v[70:71], v[168:169]
	global_load_dwordx4 v[64:67], v[64:65], off
	v_readlane_b32 s40, v209, 1
	s_waitcnt vmcnt(15)
; #define P4_FOR16(M) M(0) M(1) M(2) M(3) M(4) M(5) M(6) M(7) M(8) M(9) M(10) M(11) M(12) M(13) M(14) M(15)
; #define P4_V(i) { const unsigned wu_ = (unsigned)__builtin_amdgcn_readlane((int)__float_as_uint(wreg), i); const unsigned long long wp_ = ((unsigned long long)wu_ << 32) | wu_; \
;               P4_ACC(b##i, wp_); const int nk_ = __builtin_amdgcn_readlane(ksel, nb + i); P4_LOAD(b##i, Vg, nk_); }
; #define P4_V(i) { const unsigned wu_ = (unsigned)__builtin_amdgcn_readlane((int)__float_as_uint(wreg), i); const unsigned long long wp_ = ((unsigned long long)wu_ << 32) | wu_; \
;               P4_ACC(b##i, wp_); const int nk_ = __builtin_amdgcn_readlane(kn, i); P4_LOAD(b##i, Vg, nk_); }
; #define P4_V(i) { const unsigned wu_ = (unsigned)__builtin_amdgcn_readlane((int)__float_as_uint(wreg), i); const unsigned long long wp_ = ((unsigned long long)wu_ << 32) | wu_; \
;               P4_ACC(b##i, wp_); }
; __device__ __forceinline__ void peer_gather_f4p(const float* X, const int* __restrict__ IDX, const float* __restrict__ G, ...
;     ...
;         {
;             const float wreg = wbuf[kt * 128 + 7 * 16 + (lane & 15)];
;             if (kt < 3) {
;     ...
;                 P4_FOR16(P4_V)
	v_cvt_scalef32_pk_f32_fp4 v[68:69], v8, 1.0
	s_lshr_b32 s16, s16, 7
	s_mov_b32 s17, s86
	s_mov_b32 s41, s40
	v_cvt_scalef32_pk_f32_fp4 v[70:71], v8, 1.0 op_sel:[1,0,0]
	v_cvt_scalef32_pk_f32_fp4 v[72:73], v8, 1.0 op_sel:[0,1,0]
	v_cvt_scalef32_pk_f32_fp4 v[74:75], v8, 1.0 op_sel:[1,1,0]
	v_pk_fma_f32 v[194:195], s[40:41], v[68:69], v[194:195]
	s_lshl_b64 s[16:17], s[16:17], 10
	v_pk_fma_f32 v[196:197], s[40:41], v[70:71], v[196:197]
	v_pk_fma_f32 v[190:191], s[40:41], v[72:73], v[190:191]
	v_pk_fma_f32 v[192:193], s[40:41], v[74:75], v[192:193]
	v_cvt_scalef32_pk_f32_fp4 v[68:69], v9, 1.0
	v_cvt_scalef32_pk_f32_fp4 v[70:71], v9, 1.0 op_sel:[1,0,0]
	v_cvt_scalef32_pk_f32_fp4 v[72:73], v9, 1.0 op_sel:[0,1,0]
	v_cvt_scalef32_pk_f32_fp4 v[74:75], v9, 1.0 op_sel:[1,1,0]
	s_add_u32 s16, s52, s16
	v_pk_fma_f32 v[186:187], s[40:41], v[68:69], v[186:187]
	v_pk_fma_f32 v[188:189], s[40:41], v[70:71], v[188:189]
	v_pk_fma_f32 v[182:183], s[40:41], v[72:73], v[182:183]
	v_pk_fma_f32 v[184:185], s[40:41], v[74:75], v[184:185]
	v_cvt_scalef32_pk_f32_fp4 v[68:69], v10, 1.0
	v_cvt_scalef32_pk_f32_fp4 v[70:71], v10, 1.0 op_sel:[1,0,0]
	v_cvt_scalef32_pk_f32_fp4 v[72:73], v10, 1.0 op_sel:[0,1,0]
	v_cvt_scalef32_pk_f32_fp4 v[74:75], v10, 1.0 op_sel:[1,1,0]
	s_addc_u32 s17, s53, s17
	v_pk_fma_f32 v[178:179], s[40:41], v[68:69], v[178:179]
	v_pk_fma_f32 v[180:181], s[40:41], v[70:71], v[180:181]
	v_pk_fma_f32 v[174:175], s[40:41], v[72:73], v[174:175]
	v_pk_fma_f32 v[176:177], s[40:41], v[74:75], v[176:177]
	v_cvt_scalef32_pk_f32_fp4 v[68:69], v11, 1.0
	v_cvt_scalef32_pk_f32_fp4 v[70:71], v11, 1.0 op_sel:[1,0,0]
	v_cvt_scalef32_pk_f32_fp4 v[72:73], v11, 1.0 op_sel:[0,1,0]
	v_cvt_scalef32_pk_f32_fp4 v[74:75], v11, 1.0 op_sel:[1,1,0]
	v_pk_fma_f32 v[170:171], s[40:41], v[68:69], v[170:171]
	v_lshl_add_u64 v[68:69], s[16:17], 0, v[164:165]
	v_readlane_b32 s16, v208, 2
	v_pk_fma_f32 v[172:173], s[40:41], v[70:71], v[172:173]
	v_pk_fma_f32 v[166:167], s[40:41], v[72:73], v[166:167]
	v_pk_fma_f32 v[168:169], s[40:41], v[74:75], v[168:169]
	global_load_dwordx4 v[68:71], v[68:69], off
	v_readlane_b32 s40, v209, 2
	s_waitcnt vmcnt(15)
	v_cvt_scalef32_pk_f32_fp4 v[72:73], v12, 1.0
	s_lshr_b32 s16, s16, 7
	s_mov_b32 s17, s86
	s_mov_b32 s41, s40
	v_cvt_scalef32_pk_f32_fp4 v[74:75], v12, 1.0 op_sel:[1,0,0]
	v_cvt_scalef32_pk_f32_fp4 v[76:77], v12, 1.0 op_sel:[0,1,0]
	v_cvt_scalef32_pk_f32_fp4 v[78:79], v12, 1.0 op_sel:[1,1,0]
	v_pk_fma_f32 v[194:195], s[40:41], v[72:73], v[194:195]
	s_lshl_b64 s[16:17], s[16:17], 10
	v_pk_fma_f32 v[196:197], s[40:41], v[74:75], v[196:197]
	v_pk_fma_f32 v[190:191], s[40:41], v[76:77], v[190:191]
	v_pk_fma_f32 v[192:193], s[40:41], v[78:79], v[192:193]
	v_cvt_scalef32_pk_f32_fp4 v[72:73], v13, 1.0
	v_cvt_scalef32_pk_f32_fp4 v[74:75], v13, 1.0 op_sel:[1,0,0]
	v_cvt_scalef32_pk_f32_fp4 v[76:77], v13, 1.0 op_sel:[0,1,0]
	v_cvt_scalef32_pk_f32_fp4 v[78:79], v13, 1.0 op_sel:[1,1,0]
	s_add_u32 s16, s52, s16
	v_pk_fma_f32 v[186:187], s[40:41], v[72:73], v[186:187]
	v_pk_fma_f32 v[188:189], s[40:41], v[74:75], v[188:189]
	v_pk_fma_f32 v[182:183], s[40:41], v[76:77], v[182:183]
	v_pk_fma_f32 v[184:185], s[40:41], v[78:79], v[184:185]
	v_cvt_scalef32_pk_f32_fp4 v[72:73], v14, 1.0
	v_cvt_scalef32_pk_f32_fp4 v[74:75], v14, 1.0 op_sel:[1,0,0]
	v_cvt_scalef32_pk_f32_fp4 v[76:77], v14, 1.0 op_sel:[0,1,0]
	v_cvt_scalef32_pk_f32_fp4 v[78:79], v14, 1.0 op_sel:[1,1,0]
	s_addc_u32 s17, s53, s17
	v_pk_fma_f32 v[178:179], s[40:41], v[72:73], v[178:179]
	v_pk_fma_f32 v[180:181], s[40:41], v[74:75], v[180:181]
	v_pk_fma_f32 v[174:175], s[40:41], v[76:77], v[174:175]
	v_pk_fma_f32 v[176:177], s[40:41], v[78:79], v[176:177]
	v_cvt_scalef32_pk_f32_fp4 v[72:73], v15, 1.0
	v_cvt_scalef32_pk_f32_fp4 v[74:75], v15, 1.0 op_sel:[1,0,0]
	v_cvt_scalef32_pk_f32_fp4 v[76:77], v15, 1.0 op_sel:[0,1,0]
	v_cvt_scalef32_pk_f32_fp4 v[78:79], v15, 1.0 op_sel:[1,1,0]
	v_pk_fma_f32 v[170:171], s[40:41], v[72:73], v[170:171]
	v_lshl_add_u64 v[72:73], s[16:17], 0, v[164:165]
	v_readlane_b32 s16, v208, 3
	v_pk_fma_f32 v[172:173], s[40:41], v[74:75], v[172:173]
	v_pk_fma_f32 v[166:167], s[40:41], v[76:77], v[166:167]
	v_pk_fma_f32 v[168:169], s[40:41], v[78:79], v[168:169]
	global_load_dwordx4 v[72:75], v[72:73], off
	v_readlane_b32 s40, v209, 3
	s_waitcnt vmcnt(15)
	v_cvt_scalef32_pk_f32_fp4 v[76:77], v16, 1.0
	s_lshr_b32 s16, s16, 7
	s_mov_b32 s17, s86
	s_mov_b32 s41, s40
	v_cvt_scalef32_pk_f32_fp4 v[78:79], v16, 1.0 op_sel:[1,0,0]
	v_cvt_scalef32_pk_f32_fp4 v[80:81], v16, 1.0 op_sel:[0,1,0]
	v_cvt_scalef32_pk_f32_fp4 v[82:83], v16, 1.0 op_sel:[1,1,0]
	v_pk_fma_f32 v[194:195], s[40:41], v[76:77], v[194:195]
	s_lshl_b64 s[16:17], s[16:17], 10
	v_pk_fma_f32 v[196:197], s[40:41], v[78:79], v[196:197]
	v_pk_fma_f32 v[190:191], s[40:41], v[80:81], v[190:191]
	v_pk_fma_f32 v[192:193], s[40:41], v[82:83], v[192:193]
	v_cvt_scalef32_pk_f32_fp4 v[76:77], v17, 1.0
	v_cvt_scalef32_pk_f32_fp4 v[78:79], v17, 1.0 op_sel:[1,0,0]
	v_cvt_scalef32_pk_f32_fp4 v[80:81], v17, 1.0 op_sel:[0,1,0]
	v_cvt_scalef32_pk_f32_fp4 v[82:83], v17, 1.0 op_sel:[1,1,0]
	s_add_u32 s16, s52, s16
	v_pk_fma_f32 v[186:187], s[40:41], v[76:77], v[186:187]
	v_pk_fma_f32 v[188:189], s[40:41], v[78:79], v[188:189]
	v_pk_fma_f32 v[182:183], s[40:41], v[80:81], v[182:183]
	v_pk_fma_f32 v[184:185], s[40:41], v[82:83], v[184:185]
	v_cvt_scalef32_pk_f32_fp4 v[76:77], v18, 1.0
	v_cvt_scalef32_pk_f32_fp4 v[78:79], v18, 1.0 op_sel:[1,0,0]
	v_cvt_scalef32_pk_f32_fp4 v[80:81], v18, 1.0 op_sel:[0,1,0]
	v_cvt_scalef32_pk_f32_fp4 v[82:83], v18, 1.0 op_sel:[1,1,0]
	s_addc_u32 s17, s53, s17
	v_pk_fma_f32 v[178:179], s[40:41], v[76:77], v[178:179]
	v_pk_fma_f32 v[180:181], s[40:41], v[78:79], v[180:181]
	v_pk_fma_f32 v[174:175], s[40:41], v[80:81], v[174:175]
	v_pk_fma_f32 v[176:177], s[40:41], v[82:83], v[176:177]
	v_cvt_scalef32_pk_f32_fp4 v[76:77], v19, 1.0
	v_cvt_scalef32_pk_f32_fp4 v[78:79], v19, 1.0 op_sel:[1,0,0]
	v_cvt_scalef32_pk_f32_fp4 v[80:81], v19, 1.0 op_sel:[0,1,0]
	v_cvt_scalef32_pk_f32_fp4 v[82:83], v19, 1.0 op_sel:[1,1,0]
	v_pk_fma_f32 v[170:171], s[40:41], v[76:77], v[170:171]
	v_lshl_add_u64 v[76:77], s[16:17], 0, v[164:165]
	v_readlane_b32 s16, v208, 4
	v_pk_fma_f32 v[172:173], s[40:41], v[78:79], v[172:173]
	v_pk_fma_f32 v[166:167], s[40:41], v[80:81], v[166:167]
	v_pk_fma_f32 v[168:169], s[40:41], v[82:83], v[168:169]
	global_load_dwordx4 v[76:79], v[76:77], off
	v_readlane_b32 s40, v209, 4
	s_waitcnt vmcnt(15)
; #define P4_FOR16(M) M(0) M(1) M(2) M(3) M(4) M(5) M(6) M(7) M(8) M(9) M(10) M(11) M(12) M(13) M(14) M(15)
; #define P4_V(i) { const unsigned wu_ = (unsigned)__builtin_amdgcn_readlane((int)__float_as_uint(wreg), i); const unsigned long long wp_ = ((unsigned long long)wu_ << 32) | wu_; \
;               P4_ACC(b##i, wp_); const int nk_ = __builtin_amdgcn_readlane(ksel, nb + i); P4_LOAD(b##i, Vg, nk_); }
; #define P4_V(i) { const unsigned wu_ = (unsigned)__builtin_amdgcn_readlane((int)__float_as_uint(wreg), i); const unsigned long long wp_ = ((unsigned long long)wu_ << 32) | wu_; \
;               P4_ACC(b##i, wp_); const int nk_ = __builtin_amdgcn_readlane(kn, i); P4_LOAD(b##i, Vg, nk_); }
; #define P4_V(i) { const unsigned wu_ = (unsigned)__builtin_amdgcn_readlane((int)__float_as_uint(wreg), i); const unsigned long long wp_ = ((unsigned long long)wu_ << 32) | wu_; \
;               P4_ACC(b##i, wp_); }
; __device__ __forceinline__ void peer_gather_f4p(const float* X, const int* __restrict__ IDX, const float* __restrict__ G, ...
;     ...
;         {
;             const float wreg = wbuf[kt * 128 + 7 * 16 + (lane & 15)];
;             if (kt < 3) {
;     ...
;                 P4_FOR16(P4_V)
	v_cvt_scalef32_pk_f32_fp4 v[80:81], v20, 1.0
	s_lshr_b32 s16, s16, 7
	s_mov_b32 s17, s86
	s_mov_b32 s41, s40
	v_cvt_scalef32_pk_f32_fp4 v[82:83], v20, 1.0 op_sel:[1,0,0]
	v_cvt_scalef32_pk_f32_fp4 v[84:85], v20, 1.0 op_sel:[0,1,0]
	v_cvt_scalef32_pk_f32_fp4 v[86:87], v20, 1.0 op_sel:[1,1,0]
	v_pk_fma_f32 v[194:195], s[40:41], v[80:81], v[194:195]
	s_lshl_b64 s[16:17], s[16:17], 10
	v_pk_fma_f32 v[196:197], s[40:41], v[82:83], v[196:197]
	v_pk_fma_f32 v[190:191], s[40:41], v[84:85], v[190:191]
	v_pk_fma_f32 v[192:193], s[40:41], v[86:87], v[192:193]
	v_cvt_scalef32_pk_f32_fp4 v[80:81], v21, 1.0
	v_cvt_scalef32_pk_f32_fp4 v[82:83], v21, 1.0 op_sel:[1,0,0]
	v_cvt_scalef32_pk_f32_fp4 v[84:85], v21, 1.0 op_sel:[0,1,0]
	v_cvt_scalef32_pk_f32_fp4 v[86:87], v21, 1.0 op_sel:[1,1,0]
	s_add_u32 s16, s52, s16
	v_pk_fma_f32 v[186:187], s[40:41], v[80:81], v[186:187]
	v_pk_fma_f32 v[188:189], s[40:41], v[82:83], v[188:189]
	v_pk_fma_f32 v[182:183], s[40:41], v[84:85], v[182:183]
	v_pk_fma_f32 v[184:185], s[40:41], v[86:87], v[184:185]
	v_cvt_scalef32_pk_f32_fp4 v[80:81], v22, 1.0
	v_cvt_scalef32_pk_f32_fp4 v[82:83], v22, 1.0 op_sel:[1,0,0]
	v_cvt_scalef32_pk_f32_fp4 v[84:85], v22, 1.0 op_sel:[0,1,0]
	v_cvt_scalef32_pk_f32_fp4 v[86:87], v22, 1.0 op_sel:[1,1,0]
	s_addc_u32 s17, s53, s17
	v_pk_fma_f32 v[178:179], s[40:41], v[80:81], v[178:179]
	v_pk_fma_f32 v[180:181], s[40:41], v[82:83], v[180:181]
	v_pk_fma_f32 v[174:175], s[40:41], v[84:85], v[174:175]
	v_pk_fma_f32 v[176:177], s[40:41], v[86:87], v[176:177]
	v_cvt_scalef32_pk_f32_fp4 v[80:81], v23, 1.0
	v_cvt_scalef32_pk_f32_fp4 v[82:83], v23, 1.0 op_sel:[1,0,0]
	v_cvt_scalef32_pk_f32_fp4 v[84:85], v23, 1.0 op_sel:[0,1,0]
	v_cvt_scalef32_pk_f32_fp4 v[86:87], v23, 1.0 op_sel:[1,1,0]
	v_pk_fma_f32 v[170:171], s[40:41], v[80:81], v[170:171]
	v_lshl_add_u64 v[80:81], s[16:17], 0, v[164:165]
	v_readlane_b32 s16, v208, 5
	v_pk_fma_f32 v[172:173], s[40:41], v[82:83], v[172:173]
	v_pk_fma_f32 v[166:167], s[40:41], v[84:85], v[166:167]
	v_pk_fma_f32 v[168:169], s[40:41], v[86:87], v[168:169]
	global_load_dwordx4 v[80:83], v[80:81], off
	v_readlane_b32 s40, v209, 5
	s_waitcnt vmcnt(15)
	v_cvt_scalef32_pk_f32_fp4 v[84:85], v24, 1.0
	s_lshr_b32 s16, s16, 7
	s_mov_b32 s17, s86
	s_mov_b32 s41, s40
	v_cvt_scalef32_pk_f32_fp4 v[86:87], v24, 1.0 op_sel:[1,0,0]
	v_cvt_scalef32_pk_f32_fp4 v[88:89], v24, 1.0 op_sel:[0,1,0]
	v_cvt_scalef32_pk_f32_fp4 v[90:91], v24, 1.0 op_sel:[1,1,0]
	v_pk_fma_f32 v[194:195], s[40:41], v[84:85], v[194:195]
	s_lshl_b64 s[16:17], s[16:17], 10
	v_pk_fma_f32 v[196:197], s[40:41], v[86:87], v[196:197]
	v_pk_fma_f32 v[190:191], s[40:41], v[88:89], v[190:191]
	v_pk_fma_f32 v[192:193], s[40:41], v[90:91], v[192:193]
	v_cvt_scalef32_pk_f32_fp4 v[84:85], v25, 1.0
	v_cvt_scalef32_pk_f32_fp4 v[86:87], v25, 1.0 op_sel:[1,0,0]
	v_cvt_scalef32_pk_f32_fp4 v[88:89], v25, 1.0 op_sel:[0,1,0]
	v_cvt_scalef32_pk_f32_fp4 v[90:91], v25, 1.0 op_sel:[1,1,0]
	s_add_u32 s16, s52, s16
	v_pk_fma_f32 v[186:187], s[40:41], v[84:85], v[186:187]
	v_pk_fma_f32 v[188:189], s[40:41], v[86:87], v[188:189]
	v_pk_fma_f32 v[182:183], s[40:41], v[88:89], v[182:183]
	v_pk_fma_f32 v[184:185], s[40:41], v[90:91], v[184:185]
	v_cvt_scalef32_pk_f32_fp4 v[84:85], v26, 1.0
	v_cvt_scalef32_pk_f32_fp4 v[86:87], v26, 1.0 op_sel:[1,0,0]
	v_cvt_scalef32_pk_f32_fp4 v[88:89], v26, 1.0 op_sel:[0,1,0]
	v_cvt_scalef32_pk_f32_fp4 v[90:91], v26, 1.0 op_sel:[1,1,0]
	s_addc_u32 s17, s53, s17
	v_pk_fma_f32 v[178:179], s[40:41], v[84:85], v[178:179]
	v_pk_fma_f32 v[180:181], s[40:41], v[86:87], v[180:181]
	v_pk_fma_f32 v[174:175], s[40:41], v[88:89], v[174:175]
	v_pk_fma_f32 v[176:177], s[40:41], v[90:91], v[176:177]
	v_cvt_scalef32_pk_f32_fp4 v[84:85], v27, 1.0
	v_cvt_scalef32_pk_f32_fp4 v[86:87], v27, 1.0 op_sel:[1,0,0]
	v_cvt_scalef32_pk_f32_fp4 v[88:89], v27, 1.0 op_sel:[0,1,0]
	v_cvt_scalef32_pk_f32_fp4 v[90:91], v27, 1.0 op_sel:[1,1,0]
	v_pk_fma_f32 v[170:171], s[40:41], v[84:85], v[170:171]
	v_lshl_add_u64 v[84:85], s[16:17], 0, v[164:165]
	v_readlane_b32 s16, v208, 6
	v_pk_fma_f32 v[172:173], s[40:41], v[86:87], v[172:173]
	v_pk_fma_f32 v[166:167], s[40:41], v[88:89], v[166:167]
	v_pk_fma_f32 v[168:169], s[40:41], v[90:91], v[168:169]
	global_load_dwordx4 v[84:87], v[84:85], off
	v_readlane_b32 s40, v209, 6
	s_waitcnt vmcnt(15)
	v_cvt_scalef32_pk_f32_fp4 v[88:89], v28, 1.0
	s_lshr_b32 s16, s16, 7
	s_mov_b32 s17, s86
	s_mov_b32 s41, s40
	v_cvt_scalef32_pk_f32_fp4 v[90:91], v28, 1.0 op_sel:[1,0,0]
	v_cvt_scalef32_pk_f32_fp4 v[92:93], v28, 1.0 op_sel:[0,1,0]
	v_cvt_scalef32_pk_f32_fp4 v[94:95], v28, 1.0 op_sel:[1,1,0]
	v_pk_fma_f32 v[194:195], s[40:41], v[88:89], v[194:195]
	s_lshl_b64 s[16:17], s[16:17], 10
	v_pk_fma_f32 v[196:197], s[40:41], v[90:91], v[196:197]
	v_pk_fma_f32 v[190:191], s[40:41], v[92:93], v[190:191]
	v_pk_fma_f32 v[192:193], s[40:41], v[94:95], v[192:193]
	v_cvt_scalef32_pk_f32_fp4 v[88:89], v29, 1.0
	v_cvt_scalef32_pk_f32_fp4 v[90:91], v29, 1.0 op_sel:[1,0,0]
	v_cvt_scalef32_pk_f32_fp4 v[92:93], v29, 1.0 op_sel:[0,1,0]
	v_cvt_scalef32_pk_f32_fp4 v[94:95], v29, 1.0 op_sel:[1,1,0]
	s_add_u32 s16, s52, s16
	v_pk_fma_f32 v[186:187], s[40:41], v[88:89], v[186:187]
	v_pk_fma_f32 v[188:189], s[40:41], v[90:91], v[188:189]
	v_pk_fma_f32 v[182:183], s[40:41], v[92:93], v[182:183]
	v_pk_fma_f32 v[184:185], s[40:41], v[94:95], v[184:185]
	v_cvt_scalef32_pk_f32_fp4 v[88:89], v30, 1.0
	v_cvt_scalef32_pk_f32_fp4 v[90:91], v30, 1.0 op_sel:[1,0,0]
	v_cvt_scalef32_pk_f32_fp4 v[92:93], v30, 1.0 op_sel:[0,1,0]
	v_cvt_scalef32_pk_f32_fp4 v[94:95], v30, 1.0 op_sel:[1,1,0]
	s_addc_u32 s17, s53, s17
	v_pk_fma_f32 v[178:179], s[40:41], v[88:89], v[178:179]
	v_pk_fma_f32 v[180:181], s[40:41], v[90:91], v[180:181]
	v_pk_fma_f32 v[174:175], s[40:41], v[92:93], v[174:175]
	v_pk_fma_f32 v[176:177], s[40:41], v[94:95], v[176:177]
	v_cvt_scalef32_pk_f32_fp4 v[88:89], v31, 1.0
	v_cvt_scalef32_pk_f32_fp4 v[90:91], v31, 1.0 op_sel:[1,0,0]
	v_cvt_scalef32_pk_f32_fp4 v[92:93], v31, 1.0 op_sel:[0,1,0]
	v_cvt_scalef32_pk_f32_fp4 v[94:95], v31, 1.0 op_sel:[1,1,0]
	v_pk_fma_f32 v[170:171], s[40:41], v[88:89], v[170:171]
	v_lshl_add_u64 v[88:89], s[16:17], 0, v[164:165]
	v_readlane_b32 s16, v208, 7
	v_pk_fma_f32 v[172:173], s[40:41], v[90:91], v[172:173]
	v_pk_fma_f32 v[166:167], s[40:41], v[92:93], v[166:167]
	v_pk_fma_f32 v[168:169], s[40:41], v[94:95], v[168:169]
	global_load_dwordx4 v[88:91], v[88:89], off
	v_readlane_b32 s40, v209, 7
	s_waitcnt vmcnt(15)
; #define P4_FOR16(M) M(0) M(1) M(2) M(3) M(4) M(5) M(6) M(7) M(8) M(9) M(10) M(11) M(12) M(13) M(14) M(15)
; #define P4_V(i) { const unsigned wu_ = (unsigned)__builtin_amdgcn_readlane((int)__float_as_uint(wreg), i); const unsigned long long wp_ = ((unsigned long long)wu_ << 32) | wu_; \
;               P4_ACC(b##i, wp_); const int nk_ = __builtin_amdgcn_readlane(ksel, nb + i); P4_LOAD(b##i, Vg, nk_); }
; #define P4_V(i) { const unsigned wu_ = (unsigned)__builtin_amdgcn_readlane((int)__float_as_uint(wreg), i); const unsigned long long wp_ = ((unsigned long long)wu_ << 32) | wu_; \
;               P4_ACC(b##i, wp_); const int nk_ = __builtin_amdgcn_readlane(kn, i); P4_LOAD(b##i, Vg, nk_); }
; #define P4_V(i) { const unsigned wu_ = (unsigned)__builtin_amdgcn_readlane((int)__float_as_uint(wreg), i); const unsigned long long wp_ = ((unsigned long long)wu_ << 32) | wu_; \
;               P4_ACC(b##i, wp_); }
; __device__ __forceinline__ void peer_gather_f4p(const float* X, const int* __restrict__ IDX, const float* __restrict__ G, ...
;     ...
;         {
;             const float wreg = wbuf[kt * 128 + 7 * 16 + (lane & 15)];
;             if (kt < 3) {
;     ...
;                 P4_FOR16(P4_V)
	v_cvt_scalef32_pk_f32_fp4 v[92:93], v32, 1.0
	s_lshr_b32 s16, s16, 7
	s_mov_b32 s17, s86
	s_mov_b32 s41, s40
	v_cvt_scalef32_pk_f32_fp4 v[94:95], v32, 1.0 op_sel:[1,0,0]
	v_cvt_scalef32_pk_f32_fp4 v[96:97], v32, 1.0 op_sel:[0,1,0]
	v_cvt_scalef32_pk_f32_fp4 v[98:99], v32, 1.0 op_sel:[1,1,0]
	v_pk_fma_f32 v[194:195], s[40:41], v[92:93], v[194:195]
	s_lshl_b64 s[16:17], s[16:17], 10
	v_pk_fma_f32 v[196:197], s[40:41], v[94:95], v[196:197]
	v_pk_fma_f32 v[190:191], s[40:41], v[96:97], v[190:191]
	v_pk_fma_f32 v[192:193], s[40:41], v[98:99], v[192:193]
	v_cvt_scalef32_pk_f32_fp4 v[92:93], v33, 1.0
	v_cvt_scalef32_pk_f32_fp4 v[94:95], v33, 1.0 op_sel:[1,0,0]
	v_cvt_scalef32_pk_f32_fp4 v[96:97], v33, 1.0 op_sel:[0,1,0]
	v_cvt_scalef32_pk_f32_fp4 v[98:99], v33, 1.0 op_sel:[1,1,0]
	s_add_u32 s16, s52, s16
	v_pk_fma_f32 v[186:187], s[40:41], v[92:93], v[186:187]
	v_pk_fma_f32 v[188:189], s[40:41], v[94:95], v[188:189]
	v_pk_fma_f32 v[182:183], s[40:41], v[96:97], v[182:183]
	v_pk_fma_f32 v[184:185], s[40:41], v[98:99], v[184:185]
	v_cvt_scalef32_pk_f32_fp4 v[92:93], v34, 1.0
	v_cvt_scalef32_pk_f32_fp4 v[94:95], v34, 1.0 op_sel:[1,0,0]
	v_cvt_scalef32_pk_f32_fp4 v[96:97], v34, 1.0 op_sel:[0,1,0]
	v_cvt_scalef32_pk_f32_fp4 v[98:99], v34, 1.0 op_sel:[1,1,0]
	s_addc_u32 s17, s53, s17
	v_pk_fma_f32 v[178:179], s[40:41], v[92:93], v[178:179]
	v_pk_fma_f32 v[180:181], s[40:41], v[94:95], v[180:181]
	v_pk_fma_f32 v[174:175], s[40:41], v[96:97], v[174:175]
	v_pk_fma_f32 v[176:177], s[40:41], v[98:99], v[176:177]
	v_cvt_scalef32_pk_f32_fp4 v[92:93], v35, 1.0
	v_cvt_scalef32_pk_f32_fp4 v[94:95], v35, 1.0 op_sel:[1,0,0]
	v_cvt_scalef32_pk_f32_fp4 v[96:97], v35, 1.0 op_sel:[0,1,0]
	v_cvt_scalef32_pk_f32_fp4 v[98:99], v35, 1.0 op_sel:[1,1,0]
	v_pk_fma_f32 v[170:171], s[40:41], v[92:93], v[170:171]
	v_lshl_add_u64 v[92:93], s[16:17], 0, v[164:165]
	v_readlane_b32 s16, v208, 8
	v_pk_fma_f32 v[172:173], s[40:41], v[94:95], v[172:173]
	v_pk_fma_f32 v[166:167], s[40:41], v[96:97], v[166:167]
	v_pk_fma_f32 v[168:169], s[40:41], v[98:99], v[168:169]
	global_load_dwordx4 v[92:95], v[92:93], off
	v_readlane_b32 s40, v209, 8
	s_waitcnt vmcnt(15)
	v_cvt_scalef32_pk_f32_fp4 v[96:97], v36, 1.0
	s_lshr_b32 s16, s16, 7
	s_mov_b32 s17, s86
	s_mov_b32 s41, s40
	v_cvt_scalef32_pk_f32_fp4 v[98:99], v36, 1.0 op_sel:[1,0,0]
	v_cvt_scalef32_pk_f32_fp4 v[104:105], v36, 1.0 op_sel:[0,1,0]
	v_cvt_scalef32_pk_f32_fp4 v[106:107], v36, 1.0 op_sel:[1,1,0]
	v_pk_fma_f32 v[194:195], s[40:41], v[96:97], v[194:195]
	s_lshl_b64 s[16:17], s[16:17], 10
	v_pk_fma_f32 v[196:197], s[40:41], v[98:99], v[196:197]
	v_pk_fma_f32 v[190:191], s[40:41], v[104:105], v[190:191]
	v_pk_fma_f32 v[192:193], s[40:41], v[106:107], v[192:193]
	v_cvt_scalef32_pk_f32_fp4 v[96:97], v37, 1.0
	v_cvt_scalef32_pk_f32_fp4 v[98:99], v37, 1.0 op_sel:[1,0,0]
	v_cvt_scalef32_pk_f32_fp4 v[104:105], v37, 1.0 op_sel:[0,1,0]
	v_cvt_scalef32_pk_f32_fp4 v[106:107], v37, 1.0 op_sel:[1,1,0]
	s_add_u32 s16, s52, s16
	v_pk_fma_f32 v[186:187], s[40:41], v[96:97], v[186:187]
	v_pk_fma_f32 v[188:189], s[40:41], v[98:99], v[188:189]
	v_pk_fma_f32 v[182:183], s[40:41], v[104:105], v[182:183]
	v_pk_fma_f32 v[184:185], s[40:41], v[106:107], v[184:185]
	v_cvt_scalef32_pk_f32_fp4 v[96:97], v38, 1.0
	v_cvt_scalef32_pk_f32_fp4 v[98:99], v38, 1.0 op_sel:[1,0,0]
	v_cvt_scalef32_pk_f32_fp4 v[104:105], v38, 1.0 op_sel:[0,1,0]
	v_cvt_scalef32_pk_f32_fp4 v[106:107], v38, 1.0 op_sel:[1,1,0]
	s_addc_u32 s17, s53, s17
	v_pk_fma_f32 v[178:179], s[40:41], v[96:97], v[178:179]
	v_pk_fma_f32 v[180:181], s[40:41], v[98:99], v[180:181]
	v_pk_fma_f32 v[174:175], s[40:41], v[104:105], v[174:175]
	v_pk_fma_f32 v[176:177], s[40:41], v[106:107], v[176:177]
	v_cvt_scalef32_pk_f32_fp4 v[96:97], v39, 1.0
	v_cvt_scalef32_pk_f32_fp4 v[98:99], v39, 1.0 op_sel:[1,0,0]
	v_cvt_scalef32_pk_f32_fp4 v[104:105], v39, 1.0 op_sel:[0,1,0]
	v_cvt_scalef32_pk_f32_fp4 v[106:107], v39, 1.0 op_sel:[1,1,0]
	v_pk_fma_f32 v[170:171], s[40:41], v[96:97], v[170:171]
	v_lshl_add_u64 v[96:97], s[16:17], 0, v[164:165]
	v_readlane_b32 s16, v208, 9
	v_pk_fma_f32 v[172:173], s[40:41], v[98:99], v[172:173]
	v_pk_fma_f32 v[166:167], s[40:41], v[104:105], v[166:167]
	v_pk_fma_f32 v[168:169], s[40:41], v[106:107], v[168:169]
	global_load_dwordx4 v[96:99], v[96:97], off
	v_readlane_b32 s40, v209, 9
	s_waitcnt vmcnt(15)
	v_cvt_scalef32_pk_f32_fp4 v[104:105], v40, 1.0
	s_lshr_b32 s16, s16, 7
	s_mov_b32 s17, s86
	s_mov_b32 s41, s40
	v_cvt_scalef32_pk_f32_fp4 v[106:107], v40, 1.0 op_sel:[1,0,0]
	v_cvt_scalef32_pk_f32_fp4 v[108:109], v40, 1.0 op_sel:[0,1,0]
	v_cvt_scalef32_pk_f32_fp4 v[110:111], v40, 1.0 op_sel:[1,1,0]
	v_pk_fma_f32 v[194:195], s[40:41], v[104:105], v[194:195]
	s_lshl_b64 s[16:17], s[16:17], 10
	v_pk_fma_f32 v[196:197], s[40:41], v[106:107], v[196:197]
	v_pk_fma_f32 v[190:191], s[40:41], v[108:109], v[190:191]
	v_pk_fma_f32 v[192:193], s[40:41], v[110:111], v[192:193]
	v_cvt_scalef32_pk_f32_fp4 v[104:105], v41, 1.0
	v_cvt_scalef32_pk_f32_fp4 v[106:107], v41, 1.0 op_sel:[1,0,0]
	v_cvt_scalef32_pk_f32_fp4 v[108:109], v41, 1.0 op_sel:[0,1,0]
	v_cvt_scalef32_pk_f32_fp4 v[110:111], v41, 1.0 op_sel:[1,1,0]
	s_add_u32 s16, s52, s16
	v_pk_fma_f32 v[186:187], s[40:41], v[104:105], v[186:187]
	v_pk_fma_f32 v[188:189], s[40:41], v[106:107], v[188:189]
	v_pk_fma_f32 v[182:183], s[40:41], v[108:109], v[182:183]
	v_pk_fma_f32 v[184:185], s[40:41], v[110:111], v[184:185]
	v_cvt_scalef32_pk_f32_fp4 v[104:105], v42, 1.0
	v_cvt_scalef32_pk_f32_fp4 v[106:107], v42, 1.0 op_sel:[1,0,0]
	v_cvt_scalef32_pk_f32_fp4 v[108:109], v42, 1.0 op_sel:[0,1,0]
	v_cvt_scalef32_pk_f32_fp4 v[110:111], v42, 1.0 op_sel:[1,1,0]
	s_addc_u32 s17, s53, s17
	v_pk_fma_f32 v[178:179], s[40:41], v[104:105], v[178:179]
	v_pk_fma_f32 v[180:181], s[40:41], v[106:107], v[180:181]
	v_pk_fma_f32 v[174:175], s[40:41], v[108:109], v[174:175]
	v_pk_fma_f32 v[176:177], s[40:41], v[110:111], v[176:177]
	v_cvt_scalef32_pk_f32_fp4 v[104:105], v43, 1.0
	v_cvt_scalef32_pk_f32_fp4 v[106:107], v43, 1.0 op_sel:[1,0,0]
	v_cvt_scalef32_pk_f32_fp4 v[108:109], v43, 1.0 op_sel:[0,1,0]
	v_cvt_scalef32_pk_f32_fp4 v[110:111], v43, 1.0 op_sel:[1,1,0]
	v_pk_fma_f32 v[170:171], s[40:41], v[104:105], v[170:171]
	v_lshl_add_u64 v[104:105], s[16:17], 0, v[164:165]
	v_readlane_b32 s16, v208, 10
	v_pk_fma_f32 v[172:173], s[40:41], v[106:107], v[172:173]
	v_pk_fma_f32 v[166:167], s[40:41], v[108:109], v[166:167]
	v_pk_fma_f32 v[168:169], s[40:41], v[110:111], v[168:169]
	global_load_dwordx4 v[104:107], v[104:105], off
	v_readlane_b32 s40, v209, 10
	s_waitcnt vmcnt(15)
; #define P4_FOR16(M) M(0) M(1) M(2) M(3) M(4) M(5) M(6) M(7) M(8) M(9) M(10) M(11) M(12) M(13) M(14) M(15)
; #define P4_V(i) { const unsigned wu_ = (unsigned)__builtin_amdgcn_readlane((int)__float_as_uint(wreg), i); const unsigned long long wp_ = ((unsigned long long)wu_ << 32) | wu_; \
;               P4_ACC(b##i, wp_); const int nk_ = __builtin_amdgcn_readlane(ksel, nb + i); P4_LOAD(b##i, Vg, nk_); }
; #define P4_V(i) { const unsigned wu_ = (unsigned)__builtin_amdgcn_readlane((int)__float_as_uint(wreg), i); const unsigned long long wp_ = ((unsigned long long)wu_ << 32) | wu_; \
;               P4_ACC(b##i, wp_); const int nk_ = __builtin_amdgcn_readlane(kn, i); P4_LOAD(b##i, Vg, nk_); }
; #define P4_V(i) { const unsigned wu_ = (unsigned)__builtin_amdgcn_readlane((int)__float_as_uint(wreg), i); const unsigned long long wp_ = ((unsigned long long)wu_ << 32) | wu_; \
;               P4_ACC(b##i, wp_); }
; __device__ __forceinline__ void peer_gather_f4p(const float* X, const int* __restrict__ IDX, const float* __restrict__ G, ...
;     ...
;         for (int bt = 0; bt < 7; ++bt) {
;             const int ksel = (bt + 1 < 4) ? k0 : k1;
;             const int nb = (16 * (bt + 1)) & 63;
;             const float wreg = wbuf[kt * 128 + bt * 16 + (lane & 15)];
;     ...
;             P4_FOR16(P4_V)
;     ...
;         }
	v_cvt_scalef32_pk_f32_fp4 v[108:109], v44, 1.0
	s_lshr_b32 s16, s16, 7
	s_mov_b32 s17, s86
	s_mov_b32 s41, s40
	v_cvt_scalef32_pk_f32_fp4 v[110:111], v44, 1.0 op_sel:[1,0,0]
	v_cvt_scalef32_pk_f32_fp4 v[112:113], v44, 1.0 op_sel:[0,1,0]
	v_cvt_scalef32_pk_f32_fp4 v[114:115], v44, 1.0 op_sel:[1,1,0]
	v_pk_fma_f32 v[194:195], s[40:41], v[108:109], v[194:195]
	s_lshl_b64 s[16:17], s[16:17], 10
	v_pk_fma_f32 v[196:197], s[40:41], v[110:111], v[196:197]
	v_pk_fma_f32 v[190:191], s[40:41], v[112:113], v[190:191]
	v_pk_fma_f32 v[192:193], s[40:41], v[114:115], v[192:193]
	v_cvt_scalef32_pk_f32_fp4 v[108:109], v45, 1.0
	v_cvt_scalef32_pk_f32_fp4 v[110:111], v45, 1.0 op_sel:[1,0,0]
	v_cvt_scalef32_pk_f32_fp4 v[112:113], v45, 1.0 op_sel:[0,1,0]
	v_cvt_scalef32_pk_f32_fp4 v[114:115], v45, 1.0 op_sel:[1,1,0]
	s_add_u32 s16, s52, s16
	v_pk_fma_f32 v[186:187], s[40:41], v[108:109], v[186:187]
	v_pk_fma_f32 v[188:189], s[40:41], v[110:111], v[188:189]
	v_pk_fma_f32 v[182:183], s[40:41], v[112:113], v[182:183]
	v_pk_fma_f32 v[184:185], s[40:41], v[114:115], v[184:185]
	v_cvt_scalef32_pk_f32_fp4 v[108:109], v46, 1.0
	v_cvt_scalef32_pk_f32_fp4 v[110:111], v46, 1.0 op_sel:[1,0,0]
	v_cvt_scalef32_pk_f32_fp4 v[112:113], v46, 1.0 op_sel:[0,1,0]
	v_cvt_scalef32_pk_f32_fp4 v[114:115], v46, 1.0 op_sel:[1,1,0]
	s_addc_u32 s17, s53, s17
	v_pk_fma_f32 v[178:179], s[40:41], v[108:109], v[178:179]
	v_pk_fma_f32 v[180:181], s[40:41], v[110:111], v[180:181]
	v_pk_fma_f32 v[174:175], s[40:41], v[112:113], v[174:175]
	v_pk_fma_f32 v[176:177], s[40:41], v[114:115], v[176:177]
	v_cvt_scalef32_pk_f32_fp4 v[108:109], v47, 1.0
	v_cvt_scalef32_pk_f32_fp4 v[110:111], v47, 1.0 op_sel:[1,0,0]
	v_cvt_scalef32_pk_f32_fp4 v[112:113], v47, 1.0 op_sel:[0,1,0]
	v_cvt_scalef32_pk_f32_fp4 v[114:115], v47, 1.0 op_sel:[1,1,0]
	v_pk_fma_f32 v[170:171], s[40:41], v[108:109], v[170:171]
	v_lshl_add_u64 v[108:109], s[16:17], 0, v[164:165]
	v_readlane_b32 s16, v208, 11
	v_pk_fma_f32 v[172:173], s[40:41], v[110:111], v[172:173]
	v_pk_fma_f32 v[166:167], s[40:41], v[112:113], v[166:167]
	v_pk_fma_f32 v[168:169], s[40:41], v[114:115], v[168:169]
	global_load_dwordx4 v[108:111], v[108:109], off
	v_readlane_b32 s40, v209, 11
	s_waitcnt vmcnt(15)
	v_cvt_scalef32_pk_f32_fp4 v[112:113], v48, 1.0
	s_lshr_b32 s16, s16, 7
	s_mov_b32 s17, s86
	s_mov_b32 s41, s40
	v_cvt_scalef32_pk_f32_fp4 v[114:115], v48, 1.0 op_sel:[1,0,0]
	v_cvt_scalef32_pk_f32_fp4 v[116:117], v48, 1.0 op_sel:[0,1,0]
	v_cvt_scalef32_pk_f32_fp4 v[118:119], v48, 1.0 op_sel:[1,1,0]
	v_pk_fma_f32 v[194:195], s[40:41], v[112:113], v[194:195]
	s_lshl_b64 s[16:17], s[16:17], 10
	v_pk_fma_f32 v[196:197], s[40:41], v[114:115], v[196:197]
	v_pk_fma_f32 v[190:191], s[40:41], v[116:117], v[190:191]
	v_pk_fma_f32 v[192:193], s[40:41], v[118:119], v[192:193]
	v_cvt_scalef32_pk_f32_fp4 v[112:113], v49, 1.0
	v_cvt_scalef32_pk_f32_fp4 v[114:115], v49, 1.0 op_sel:[1,0,0]
	v_cvt_scalef32_pk_f32_fp4 v[116:117], v49, 1.0 op_sel:[0,1,0]
	v_cvt_scalef32_pk_f32_fp4 v[118:119], v49, 1.0 op_sel:[1,1,0]
	s_add_u32 s16, s52, s16
	v_pk_fma_f32 v[186:187], s[40:41], v[112:113], v[186:187]
	v_pk_fma_f32 v[188:189], s[40:41], v[114:115], v[188:189]
	v_pk_fma_f32 v[182:183], s[40:41], v[116:117], v[182:183]
	v_pk_fma_f32 v[184:185], s[40:41], v[118:119], v[184:185]
	v_cvt_scalef32_pk_f32_fp4 v[112:113], v50, 1.0
	v_cvt_scalef32_pk_f32_fp4 v[114:115], v50, 1.0 op_sel:[1,0,0]
	v_cvt_scalef32_pk_f32_fp4 v[116:117], v50, 1.0 op_sel:[0,1,0]
	v_cvt_scalef32_pk_f32_fp4 v[118:119], v50, 1.0 op_sel:[1,1,0]
	s_addc_u32 s17, s53, s17
	v_pk_fma_f32 v[178:179], s[40:41], v[112:113], v[178:179]
	v_pk_fma_f32 v[180:181], s[40:41], v[114:115], v[180:181]
	v_pk_fma_f32 v[174:175], s[40:41], v[116:117], v[174:175]
	v_pk_fma_f32 v[176:177], s[40:41], v[118:119], v[176:177]
	v_cvt_scalef32_pk_f32_fp4 v[112:113], v51, 1.0
	v_cvt_scalef32_pk_f32_fp4 v[114:115], v51, 1.0 op_sel:[1,0,0]
	v_cvt_scalef32_pk_f32_fp4 v[116:117], v51, 1.0 op_sel:[0,1,0]
	v_cvt_scalef32_pk_f32_fp4 v[118:119], v51, 1.0 op_sel:[1,1,0]
	v_pk_fma_f32 v[170:171], s[40:41], v[112:113], v[170:171]
	v_lshl_add_u64 v[112:113], s[16:17], 0, v[164:165]
	v_readlane_b32 s16, v208, 12
	v_pk_fma_f32 v[172:173], s[40:41], v[114:115], v[172:173]
	v_pk_fma_f32 v[166:167], s[40:41], v[116:117], v[166:167]
	v_pk_fma_f32 v[168:169], s[40:41], v[118:119], v[168:169]
	global_load_dwordx4 v[112:115], v[112:113], off
	v_readlane_b32 s40, v209, 12
	s_waitcnt vmcnt(15)
	v_cvt_scalef32_pk_f32_fp4 v[116:117], v52, 1.0
	s_lshr_b32 s16, s16, 7
	s_mov_b32 s17, s86
	s_mov_b32 s41, s40
	v_cvt_scalef32_pk_f32_fp4 v[118:119], v52, 1.0 op_sel:[1,0,0]
	v_cvt_scalef32_pk_f32_fp4 v[120:121], v52, 1.0 op_sel:[0,1,0]
	v_cvt_scalef32_pk_f32_fp4 v[122:123], v52, 1.0 op_sel:[1,1,0]
	v_pk_fma_f32 v[194:195], s[40:41], v[116:117], v[194:195]
	s_lshl_b64 s[16:17], s[16:17], 10
	v_pk_fma_f32 v[196:197], s[40:41], v[118:119], v[196:197]
	v_pk_fma_f32 v[190:191], s[40:41], v[120:121], v[190:191]
	v_pk_fma_f32 v[192:193], s[40:41], v[122:123], v[192:193]
	v_cvt_scalef32_pk_f32_fp4 v[116:117], v53, 1.0
	v_cvt_scalef32_pk_f32_fp4 v[118:119], v53, 1.0 op_sel:[1,0,0]
	v_cvt_scalef32_pk_f32_fp4 v[120:121], v53, 1.0 op_sel:[0,1,0]
	v_cvt_scalef32_pk_f32_fp4 v[122:123], v53, 1.0 op_sel:[1,1,0]
	s_add_u32 s16, s52, s16
	v_pk_fma_f32 v[186:187], s[40:41], v[116:117], v[186:187]
	v_pk_fma_f32 v[188:189], s[40:41], v[118:119], v[188:189]
	v_pk_fma_f32 v[182:183], s[40:41], v[120:121], v[182:183]
	v_pk_fma_f32 v[184:185], s[40:41], v[122:123], v[184:185]
	v_cvt_scalef32_pk_f32_fp4 v[116:117], v54, 1.0
	v_cvt_scalef32_pk_f32_fp4 v[118:119], v54, 1.0 op_sel:[1,0,0]
	v_cvt_scalef32_pk_f32_fp4 v[120:121], v54, 1.0 op_sel:[0,1,0]
	v_cvt_scalef32_pk_f32_fp4 v[122:123], v54, 1.0 op_sel:[1,1,0]
	s_addc_u32 s17, s53, s17
	v_pk_fma_f32 v[178:179], s[40:41], v[116:117], v[178:179]
	v_pk_fma_f32 v[180:181], s[40:41], v[118:119], v[180:181]
	v_pk_fma_f32 v[174:175], s[40:41], v[120:121], v[174:175]
	v_pk_fma_f32 v[176:177], s[40:41], v[122:123], v[176:177]
	v_cvt_scalef32_pk_f32_fp4 v[116:117], v55, 1.0
	v_cvt_scalef32_pk_f32_fp4 v[118:119], v55, 1.0 op_sel:[1,0,0]
	v_cvt_scalef32_pk_f32_fp4 v[120:121], v55, 1.0 op_sel:[0,1,0]
	v_cvt_scalef32_pk_f32_fp4 v[122:123], v55, 1.0 op_sel:[1,1,0]
	v_pk_fma_f32 v[170:171], s[40:41], v[116:117], v[170:171]
	v_lshl_add_u64 v[116:117], s[16:17], 0, v[164:165]
	v_readlane_b32 s16, v208, 13
	v_pk_fma_f32 v[172:173], s[40:41], v[118:119], v[172:173]
	v_pk_fma_f32 v[166:167], s[40:41], v[120:121], v[166:167]
	v_pk_fma_f32 v[168:169], s[40:41], v[122:123], v[168:169]
	global_load_dwordx4 v[116:119], v[116:117], off
	v_readlane_b32 s40, v209, 13
	s_waitcnt vmcnt(15)
; #define P4_FOR16(M) M(0) M(1) M(2) M(3) M(4) M(5) M(6) M(7) M(8) M(9) M(10) M(11) M(12) M(13) M(14) M(15)
; #define P4_V(i) { const unsigned wu_ = (unsigned)__builtin_amdgcn_readlane((int)__float_as_uint(wreg), i); const unsigned long long wp_ = ((unsigned long long)wu_ << 32) | wu_; \
;               P4_ACC(b##i, wp_); const int nk_ = __builtin_amdgcn_readlane(ksel, nb + i); P4_LOAD(b##i, Vg, nk_); }
; #define P4_V(i) { const unsigned wu_ = (unsigned)__builtin_amdgcn_readlane((int)__float_as_uint(wreg), i); const unsigned long long wp_ = ((unsigned long long)wu_ << 32) | wu_; \
;               P4_ACC(b##i, wp_); const int nk_ = __builtin_amdgcn_readlane(kn, i); P4_LOAD(b##i, Vg, nk_); }
; #define P4_V(i) { const unsigned wu_ = (unsigned)__builtin_amdgcn_readlane((int)__float_as_uint(wreg), i); const unsigned long long wp_ = ((unsigned long long)wu_ << 32) | wu_; \
;               P4_ACC(b##i, wp_); }
; __device__ __forceinline__ void peer_gather_f4p(const float* X, const int* __restrict__ IDX, const float* __restrict__ G, ...
;     ...
;         for (int bt = 0; bt < 7; ++bt) {
;             const int ksel = (bt + 1 < 4) ? k0 : k1;
;             const int nb = (16 * (bt + 1)) & 63;
;             const float wreg = wbuf[kt * 128 + bt * 16 + (lane & 15)];
;     ...
;             P4_FOR16(P4_V)
;     ...
;         }
	v_cvt_scalef32_pk_f32_fp4 v[120:121], v56, 1.0
	s_lshr_b32 s16, s16, 7
	s_mov_b32 s17, s86
	s_mov_b32 s41, s40
	v_cvt_scalef32_pk_f32_fp4 v[122:123], v56, 1.0 op_sel:[1,0,0]
	v_cvt_scalef32_pk_f32_fp4 v[124:125], v56, 1.0 op_sel:[0,1,0]
	v_cvt_scalef32_pk_f32_fp4 v[126:127], v56, 1.0 op_sel:[1,1,0]
	v_pk_fma_f32 v[194:195], s[40:41], v[120:121], v[194:195]
	s_lshl_b64 s[16:17], s[16:17], 10
	v_pk_fma_f32 v[196:197], s[40:41], v[122:123], v[196:197]
	v_pk_fma_f32 v[190:191], s[40:41], v[124:125], v[190:191]
	v_pk_fma_f32 v[192:193], s[40:41], v[126:127], v[192:193]
	v_cvt_scalef32_pk_f32_fp4 v[120:121], v57, 1.0
	v_cvt_scalef32_pk_f32_fp4 v[122:123], v57, 1.0 op_sel:[1,0,0]
	v_cvt_scalef32_pk_f32_fp4 v[124:125], v57, 1.0 op_sel:[0,1,0]
	v_cvt_scalef32_pk_f32_fp4 v[126:127], v57, 1.0 op_sel:[1,1,0]
	s_add_u32 s16, s52, s16
	v_pk_fma_f32 v[186:187], s[40:41], v[120:121], v[186:187]
	v_pk_fma_f32 v[188:189], s[40:41], v[122:123], v[188:189]
	v_pk_fma_f32 v[182:183], s[40:41], v[124:125], v[182:183]
	v_pk_fma_f32 v[184:185], s[40:41], v[126:127], v[184:185]
	v_cvt_scalef32_pk_f32_fp4 v[120:121], v58, 1.0
	v_cvt_scalef32_pk_f32_fp4 v[122:123], v58, 1.0 op_sel:[1,0,0]
	v_cvt_scalef32_pk_f32_fp4 v[124:125], v58, 1.0 op_sel:[0,1,0]
	v_cvt_scalef32_pk_f32_fp4 v[126:127], v58, 1.0 op_sel:[1,1,0]
	s_addc_u32 s17, s53, s17
	v_pk_fma_f32 v[178:179], s[40:41], v[120:121], v[178:179]
	v_pk_fma_f32 v[180:181], s[40:41], v[122:123], v[180:181]
	v_pk_fma_f32 v[174:175], s[40:41], v[124:125], v[174:175]
	v_pk_fma_f32 v[176:177], s[40:41], v[126:127], v[176:177]
	v_cvt_scalef32_pk_f32_fp4 v[120:121], v59, 1.0
	v_cvt_scalef32_pk_f32_fp4 v[122:123], v59, 1.0 op_sel:[1,0,0]
	v_cvt_scalef32_pk_f32_fp4 v[124:125], v59, 1.0 op_sel:[0,1,0]
	v_cvt_scalef32_pk_f32_fp4 v[126:127], v59, 1.0 op_sel:[1,1,0]
	v_pk_fma_f32 v[170:171], s[40:41], v[120:121], v[170:171]
	v_lshl_add_u64 v[120:121], s[16:17], 0, v[164:165]
	v_readlane_b32 s16, v208, 14
	v_pk_fma_f32 v[172:173], s[40:41], v[122:123], v[172:173]
	v_pk_fma_f32 v[166:167], s[40:41], v[124:125], v[166:167]
	v_pk_fma_f32 v[168:169], s[40:41], v[126:127], v[168:169]
	global_load_dwordx4 v[120:123], v[120:121], off
	v_readlane_b32 s40, v209, 14
	s_waitcnt vmcnt(15)
	v_cvt_scalef32_pk_f32_fp4 v[124:125], v60, 1.0
	s_lshr_b32 s16, s16, 7
	s_mov_b32 s17, s86
	s_mov_b32 s41, s40
	v_cvt_scalef32_pk_f32_fp4 v[126:127], v60, 1.0 op_sel:[1,0,0]
	v_cvt_scalef32_pk_f32_fp4 v[128:129], v60, 1.0 op_sel:[0,1,0]
	v_cvt_scalef32_pk_f32_fp4 v[130:131], v60, 1.0 op_sel:[1,1,0]
	v_pk_fma_f32 v[194:195], s[40:41], v[124:125], v[194:195]
	s_lshl_b64 s[16:17], s[16:17], 10
	v_pk_fma_f32 v[196:197], s[40:41], v[126:127], v[196:197]
	v_pk_fma_f32 v[190:191], s[40:41], v[128:129], v[190:191]
	v_pk_fma_f32 v[192:193], s[40:41], v[130:131], v[192:193]
	v_cvt_scalef32_pk_f32_fp4 v[124:125], v61, 1.0
	v_cvt_scalef32_pk_f32_fp4 v[126:127], v61, 1.0 op_sel:[1,0,0]
	v_cvt_scalef32_pk_f32_fp4 v[128:129], v61, 1.0 op_sel:[0,1,0]
	v_cvt_scalef32_pk_f32_fp4 v[130:131], v61, 1.0 op_sel:[1,1,0]
	s_add_u32 s16, s52, s16
	v_pk_fma_f32 v[186:187], s[40:41], v[124:125], v[186:187]
	v_pk_fma_f32 v[188:189], s[40:41], v[126:127], v[188:189]
	v_pk_fma_f32 v[182:183], s[40:41], v[128:129], v[182:183]
	v_pk_fma_f32 v[184:185], s[40:41], v[130:131], v[184:185]
	v_cvt_scalef32_pk_f32_fp4 v[124:125], v62, 1.0
	v_cvt_scalef32_pk_f32_fp4 v[126:127], v62, 1.0 op_sel:[1,0,0]
	v_cvt_scalef32_pk_f32_fp4 v[128:129], v62, 1.0 op_sel:[0,1,0]
	v_cvt_scalef32_pk_f32_fp4 v[130:131], v62, 1.0 op_sel:[1,1,0]
	s_addc_u32 s17, s53, s17
	v_pk_fma_f32 v[178:179], s[40:41], v[124:125], v[178:179]
	v_pk_fma_f32 v[180:181], s[40:41], v[126:127], v[180:181]
	v_pk_fma_f32 v[174:175], s[40:41], v[128:129], v[174:175]
	v_pk_fma_f32 v[176:177], s[40:41], v[130:131], v[176:177]
	v_cvt_scalef32_pk_f32_fp4 v[124:125], v63, 1.0
	v_cvt_scalef32_pk_f32_fp4 v[126:127], v63, 1.0 op_sel:[1,0,0]
	v_cvt_scalef32_pk_f32_fp4 v[128:129], v63, 1.0 op_sel:[0,1,0]
	v_cvt_scalef32_pk_f32_fp4 v[130:131], v63, 1.0 op_sel:[1,1,0]
	v_pk_fma_f32 v[170:171], s[40:41], v[124:125], v[170:171]
	v_lshl_add_u64 v[124:125], s[16:17], 0, v[164:165]
	v_readlane_b32 s16, v208, 15
	v_pk_fma_f32 v[172:173], s[40:41], v[126:127], v[172:173]
	v_pk_fma_f32 v[166:167], s[40:41], v[128:129], v[166:167]
	v_pk_fma_f32 v[168:169], s[40:41], v[130:131], v[168:169]
	global_load_dwordx4 v[124:127], v[124:125], off
	v_readlane_b32 s40, v209, 15
	s_waitcnt vmcnt(15)
	v_cvt_scalef32_pk_f32_fp4 v[128:129], v100, 1.0
	s_lshr_b32 s16, s16, 7
	s_mov_b32 s17, s86
	s_mov_b32 s41, s40
	v_cvt_scalef32_pk_f32_fp4 v[130:131], v100, 1.0 op_sel:[1,0,0]
	v_cvt_scalef32_pk_f32_fp4 v[210:211], v100, 1.0 op_sel:[0,1,0]
	v_cvt_scalef32_pk_f32_fp4 v[212:213], v100, 1.0 op_sel:[1,1,0]
	v_pk_fma_f32 v[194:195], s[40:41], v[128:129], v[194:195]
	s_lshl_b64 s[16:17], s[16:17], 10
	v_pk_fma_f32 v[196:197], s[40:41], v[130:131], v[196:197]
	v_pk_fma_f32 v[190:191], s[40:41], v[210:211], v[190:191]
	v_pk_fma_f32 v[192:193], s[40:41], v[212:213], v[192:193]
	v_cvt_scalef32_pk_f32_fp4 v[128:129], v101, 1.0
	v_cvt_scalef32_pk_f32_fp4 v[130:131], v101, 1.0 op_sel:[1,0,0]
	v_cvt_scalef32_pk_f32_fp4 v[210:211], v101, 1.0 op_sel:[0,1,0]
	v_cvt_scalef32_pk_f32_fp4 v[212:213], v101, 1.0 op_sel:[1,1,0]
	s_add_u32 s16, s52, s16
	v_pk_fma_f32 v[186:187], s[40:41], v[128:129], v[186:187]
	v_pk_fma_f32 v[188:189], s[40:41], v[130:131], v[188:189]
	v_pk_fma_f32 v[182:183], s[40:41], v[210:211], v[182:183]
	v_pk_fma_f32 v[184:185], s[40:41], v[212:213], v[184:185]
	v_cvt_scalef32_pk_f32_fp4 v[128:129], v102, 1.0
	v_cvt_scalef32_pk_f32_fp4 v[130:131], v102, 1.0 op_sel:[1,0,0]
	v_cvt_scalef32_pk_f32_fp4 v[210:211], v102, 1.0 op_sel:[0,1,0]
	v_cvt_scalef32_pk_f32_fp4 v[212:213], v102, 1.0 op_sel:[1,1,0]
	s_addc_u32 s17, s53, s17
	v_pk_fma_f32 v[178:179], s[40:41], v[128:129], v[178:179]
	v_pk_fma_f32 v[180:181], s[40:41], v[130:131], v[180:181]
	v_pk_fma_f32 v[174:175], s[40:41], v[210:211], v[174:175]
	v_pk_fma_f32 v[176:177], s[40:41], v[212:213], v[176:177]
	v_cvt_scalef32_pk_f32_fp4 v[128:129], v103, 1.0
	v_cvt_scalef32_pk_f32_fp4 v[130:131], v103, 1.0 op_sel:[1,0,0]
	v_cvt_scalef32_pk_f32_fp4 v[210:211], v103, 1.0 op_sel:[0,1,0]
	v_cvt_scalef32_pk_f32_fp4 v[212:213], v103, 1.0 op_sel:[1,1,0]
	v_pk_fma_f32 v[170:171], s[40:41], v[128:129], v[170:171]
	v_lshl_add_u64 v[128:129], s[16:17], 0, v[164:165]
	v_pk_fma_f32 v[172:173], s[40:41], v[130:131], v[172:173]
	v_pk_fma_f32 v[166:167], s[40:41], v[210:211], v[166:167]
	v_pk_fma_f32 v[168:169], s[40:41], v[212:213], v[168:169]
	global_load_dwordx4 v[128:131], v[128:129], off
	s_mov_b64 s[40:41], 0
; #define P4_FOR16(M) M(0) M(1) M(2) M(3) M(4) M(5) M(6) M(7) M(8) M(9) M(10) M(11) M(12) M(13) M(14) M(15)
; #define P4_V(i) { const unsigned wu_ = (unsigned)__builtin_amdgcn_readlane((int)__float_as_uint(wreg), i); const unsigned long long wp_ = ((unsigned long long)wu_ << 32) | wu_; \
;               P4_ACC(b##i, wp_); const int nk_ = __builtin_amdgcn_readlane(ksel, nb + i); P4_LOAD(b##i, Vg, nk_); }
; #define P4_V(i) { const unsigned wu_ = (unsigned)__builtin_amdgcn_readlane((int)__float_as_uint(wreg), i); const unsigned long long wp_ = ((unsigned long long)wu_ << 32) | wu_; \
;               P4_ACC(b##i, wp_); const int nk_ = __builtin_amdgcn_readlane(kn, i); P4_LOAD(b##i, Vg, nk_); }
; #define P4_V(i) { const unsigned wu_ = (unsigned)__builtin_amdgcn_readlane((int)__float_as_uint(wreg), i); const unsigned long long wp_ = ((unsigned long long)wu_ << 32) | wu_; \
;               P4_ACC(b##i, wp_); }
; __device__ __forceinline__ void peer_gather_f4p(const float* X, const int* __restrict__ IDX, const float* __restrict__ G, ...
;     ...
;         {
;             const float wreg = wbuf[kt * 128 + 7 * 16 + (lane & 15)];
;             if (kt < 3) {
;     ...
;                 P4_FOR16(P4_V)
;     ...
;             } else {
;     ...
;                 P4_FOR16(P4_V)
;     ...
;             }
.LBB0_553:
	s_andn2_b64 vcc, exec, s[40:41]
	s_cbranch_vccnz .LBB0_548
	s_waitcnt lgkmcnt(0)
	v_readlane_b32 s40, v209, 0
	s_waitcnt vmcnt(15)
	v_cvt_scalef32_pk_f32_fp4 v[64:65], v4, 1.0
	v_cvt_scalef32_pk_f32_fp4 v[66:67], v4, 1.0 op_sel:[1,0,0]
	s_waitcnt vmcnt(14)
	v_cvt_scalef32_pk_f32_fp4 v[68:69], v4, 1.0 op_sel:[0,1,0]
	v_cvt_scalef32_pk_f32_fp4 v[70:71], v4, 1.0 op_sel:[1,1,0]
	s_mov_b32 s41, s40
	v_pk_fma_f32 v[132:133], s[40:41], v[64:65], v[132:133]
	v_pk_fma_f32 v[162:163], s[40:41], v[66:67], v[162:163]
	v_pk_fma_f32 v[160:161], s[40:41], v[68:69], v[160:161]
	v_pk_fma_f32 v[158:159], s[40:41], v[70:71], v[158:159]
	v_cvt_scalef32_pk_f32_fp4 v[64:65], v5, 1.0
	v_cvt_scalef32_pk_f32_fp4 v[66:67], v5, 1.0 op_sel:[1,0,0]
	v_cvt_scalef32_pk_f32_fp4 v[68:69], v5, 1.0 op_sel:[0,1,0]
	v_cvt_scalef32_pk_f32_fp4 v[70:71], v5, 1.0 op_sel:[1,1,0]
	s_waitcnt vmcnt(0)
	v_mov_b64_e32 v[130:131], v[102:103]
	v_pk_fma_f32 v[156:157], s[40:41], v[64:65], v[156:157]
	v_pk_fma_f32 v[154:155], s[40:41], v[66:67], v[154:155]
	v_pk_fma_f32 v[152:153], s[40:41], v[68:69], v[152:153]
	v_pk_fma_f32 v[150:151], s[40:41], v[70:71], v[150:151]
	v_cvt_scalef32_pk_f32_fp4 v[64:65], v6, 1.0
	v_cvt_scalef32_pk_f32_fp4 v[66:67], v6, 1.0 op_sel:[1,0,0]
	v_cvt_scalef32_pk_f32_fp4 v[68:69], v6, 1.0 op_sel:[0,1,0]
	v_cvt_scalef32_pk_f32_fp4 v[70:71], v6, 1.0 op_sel:[1,1,0]
	v_mov_b64_e32 v[126:127], v[62:63]
	v_pk_fma_f32 v[148:149], s[40:41], v[64:65], v[148:149]
	v_pk_fma_f32 v[146:147], s[40:41], v[66:67], v[146:147]
	v_pk_fma_f32 v[144:145], s[40:41], v[68:69], v[144:145]
	v_pk_fma_f32 v[142:143], s[40:41], v[70:71], v[142:143]
	v_cvt_scalef32_pk_f32_fp4 v[64:65], v7, 1.0
	v_cvt_scalef32_pk_f32_fp4 v[66:67], v7, 1.0 op_sel:[1,0,0]
	v_cvt_scalef32_pk_f32_fp4 v[68:69], v7, 1.0 op_sel:[0,1,0]
	v_cvt_scalef32_pk_f32_fp4 v[70:71], v7, 1.0 op_sel:[1,1,0]
	v_mov_b64_e32 v[122:123], v[58:59]
	v_pk_fma_f32 v[140:141], s[40:41], v[64:65], v[140:141]
	v_pk_fma_f32 v[138:139], s[40:41], v[66:67], v[138:139]
	v_pk_fma_f32 v[136:137], s[40:41], v[68:69], v[136:137]
	v_pk_fma_f32 v[134:135], s[40:41], v[70:71], v[134:135]
	v_readlane_b32 s40, v209, 1
	v_cvt_scalef32_pk_f32_fp4 v[64:65], v8, 1.0
	v_cvt_scalef32_pk_f32_fp4 v[66:67], v8, 1.0 op_sel:[1,0,0]
	v_cvt_scalef32_pk_f32_fp4 v[68:69], v8, 1.0 op_sel:[0,1,0]
	v_cvt_scalef32_pk_f32_fp4 v[70:71], v8, 1.0 op_sel:[1,1,0]
	s_mov_b32 s41, s40
	v_pk_fma_f32 v[132:133], s[40:41], v[64:65], v[132:133]
	v_pk_fma_f32 v[162:163], s[40:41], v[66:67], v[162:163]
	v_pk_fma_f32 v[160:161], s[40:41], v[68:69], v[160:161]
	v_pk_fma_f32 v[158:159], s[40:41], v[70:71], v[158:159]
	v_cvt_scalef32_pk_f32_fp4 v[64:65], v9, 1.0
	v_cvt_scalef32_pk_f32_fp4 v[66:67], v9, 1.0 op_sel:[1,0,0]
	v_cvt_scalef32_pk_f32_fp4 v[68:69], v9, 1.0 op_sel:[0,1,0]
	v_cvt_scalef32_pk_f32_fp4 v[70:71], v9, 1.0 op_sel:[1,1,0]
	v_mov_b64_e32 v[118:119], v[54:55]
	v_pk_fma_f32 v[156:157], s[40:41], v[64:65], v[156:157]
	v_pk_fma_f32 v[154:155], s[40:41], v[66:67], v[154:155]
	v_pk_fma_f32 v[152:153], s[40:41], v[68:69], v[152:153]
	v_pk_fma_f32 v[150:151], s[40:41], v[70:71], v[150:151]
	v_cvt_scalef32_pk_f32_fp4 v[64:65], v10, 1.0
	v_cvt_scalef32_pk_f32_fp4 v[66:67], v10, 1.0 op_sel:[1,0,0]
	v_cvt_scalef32_pk_f32_fp4 v[68:69], v10, 1.0 op_sel:[0,1,0]
	v_cvt_scalef32_pk_f32_fp4 v[70:71], v10, 1.0 op_sel:[1,1,0]
	v_mov_b64_e32 v[114:115], v[50:51]
	v_pk_fma_f32 v[148:149], s[40:41], v[64:65], v[148:149]
	v_pk_fma_f32 v[146:147], s[40:41], v[66:67], v[146:147]
	v_pk_fma_f32 v[144:145], s[40:41], v[68:69], v[144:145]
	v_pk_fma_f32 v[142:143], s[40:41], v[70:71], v[142:143]
	v_cvt_scalef32_pk_f32_fp4 v[64:65], v11, 1.0
	v_cvt_scalef32_pk_f32_fp4 v[66:67], v11, 1.0 op_sel:[1,0,0]
	v_cvt_scalef32_pk_f32_fp4 v[68:69], v11, 1.0 op_sel:[0,1,0]
	v_cvt_scalef32_pk_f32_fp4 v[70:71], v11, 1.0 op_sel:[1,1,0]
	v_mov_b64_e32 v[110:111], v[46:47]
	v_pk_fma_f32 v[140:141], s[40:41], v[64:65], v[140:141]
	v_pk_fma_f32 v[138:139], s[40:41], v[66:67], v[138:139]
	v_pk_fma_f32 v[136:137], s[40:41], v[68:69], v[136:137]
	v_pk_fma_f32 v[134:135], s[40:41], v[70:71], v[134:135]
	v_readlane_b32 s40, v209, 2
	v_cvt_scalef32_pk_f32_fp4 v[64:65], v12, 1.0
	v_cvt_scalef32_pk_f32_fp4 v[66:67], v12, 1.0 op_sel:[1,0,0]
	v_cvt_scalef32_pk_f32_fp4 v[68:69], v12, 1.0 op_sel:[0,1,0]
	v_cvt_scalef32_pk_f32_fp4 v[70:71], v12, 1.0 op_sel:[1,1,0]
	s_mov_b32 s41, s40
	v_pk_fma_f32 v[132:133], s[40:41], v[64:65], v[132:133]
	v_pk_fma_f32 v[162:163], s[40:41], v[66:67], v[162:163]
	v_pk_fma_f32 v[160:161], s[40:41], v[68:69], v[160:161]
	v_pk_fma_f32 v[158:159], s[40:41], v[70:71], v[158:159]
	v_cvt_scalef32_pk_f32_fp4 v[64:65], v13, 1.0
	v_cvt_scalef32_pk_f32_fp4 v[66:67], v13, 1.0 op_sel:[1,0,0]
	v_cvt_scalef32_pk_f32_fp4 v[68:69], v13, 1.0 op_sel:[0,1,0]
	v_cvt_scalef32_pk_f32_fp4 v[70:71], v13, 1.0 op_sel:[1,1,0]
	v_mov_b64_e32 v[106:107], v[42:43]
	v_pk_fma_f32 v[156:157], s[40:41], v[64:65], v[156:157]
	v_pk_fma_f32 v[154:155], s[40:41], v[66:67], v[154:155]
	v_pk_fma_f32 v[152:153], s[40:41], v[68:69], v[152:153]
	v_pk_fma_f32 v[150:151], s[40:41], v[70:71], v[150:151]
	v_cvt_scalef32_pk_f32_fp4 v[64:65], v14, 1.0
	v_cvt_scalef32_pk_f32_fp4 v[66:67], v14, 1.0 op_sel:[1,0,0]
	v_cvt_scalef32_pk_f32_fp4 v[68:69], v14, 1.0 op_sel:[0,1,0]
	v_cvt_scalef32_pk_f32_fp4 v[70:71], v14, 1.0 op_sel:[1,1,0]
	v_mov_b64_e32 v[98:99], v[38:39]
	v_pk_fma_f32 v[148:149], s[40:41], v[64:65], v[148:149]
	v_pk_fma_f32 v[146:147], s[40:41], v[66:67], v[146:147]
	v_pk_fma_f32 v[144:145], s[40:41], v[68:69], v[144:145]
	v_pk_fma_f32 v[142:143], s[40:41], v[70:71], v[142:143]
	v_cvt_scalef32_pk_f32_fp4 v[64:65], v15, 1.0
; #define P4_FOR16(M) M(0) M(1) M(2) M(3) M(4) M(5) M(6) M(7) M(8) M(9) M(10) M(11) M(12) M(13) M(14) M(15)
; #define P4_V(i) { const unsigned wu_ = (unsigned)__builtin_amdgcn_readlane((int)__float_as_uint(wreg), i); const unsigned long long wp_ = ((unsigned long long)wu_ << 32) | wu_; \
;               P4_ACC(b##i, wp_); const int nk_ = __builtin_amdgcn_readlane(ksel, nb + i); P4_LOAD(b##i, Vg, nk_); }
; #define P4_V(i) { const unsigned wu_ = (unsigned)__builtin_amdgcn_readlane((int)__float_as_uint(wreg), i); const unsigned long long wp_ = ((unsigned long long)wu_ << 32) | wu_; \
;               P4_ACC(b##i, wp_); const int nk_ = __builtin_amdgcn_readlane(kn, i); P4_LOAD(b##i, Vg, nk_); }
; #define P4_V(i) { const unsigned wu_ = (unsigned)__builtin_amdgcn_readlane((int)__float_as_uint(wreg), i); const unsigned long long wp_ = ((unsigned long long)wu_ << 32) | wu_; \
;               P4_ACC(b##i, wp_); }
; __device__ __forceinline__ void peer_gather_f4p(const float* X, const int* __restrict__ IDX, const float* __restrict__ G, ...
;     ...
;         {
;             const float wreg = wbuf[kt * 128 + 7 * 16 + (lane & 15)];
;             if (kt < 3) {
;     ...
;                 P4_FOR16(P4_V)
;     ...
;             } else {
;     ...
;                 P4_FOR16(P4_V)
;     ...
;             }
	v_cvt_scalef32_pk_f32_fp4 v[66:67], v15, 1.0 op_sel:[1,0,0]
	v_cvt_scalef32_pk_f32_fp4 v[68:69], v15, 1.0 op_sel:[0,1,0]
	v_cvt_scalef32_pk_f32_fp4 v[70:71], v15, 1.0 op_sel:[1,1,0]
	v_mov_b64_e32 v[94:95], v[34:35]
	v_pk_fma_f32 v[140:141], s[40:41], v[64:65], v[140:141]
	v_pk_fma_f32 v[138:139], s[40:41], v[66:67], v[138:139]
	v_pk_fma_f32 v[136:137], s[40:41], v[68:69], v[136:137]
	v_pk_fma_f32 v[134:135], s[40:41], v[70:71], v[134:135]
	v_readlane_b32 s40, v209, 3
	v_cvt_scalef32_pk_f32_fp4 v[64:65], v16, 1.0
	v_cvt_scalef32_pk_f32_fp4 v[66:67], v16, 1.0 op_sel:[1,0,0]
	v_cvt_scalef32_pk_f32_fp4 v[68:69], v16, 1.0 op_sel:[0,1,0]
	v_cvt_scalef32_pk_f32_fp4 v[70:71], v16, 1.0 op_sel:[1,1,0]
	s_mov_b32 s41, s40
	v_pk_fma_f32 v[132:133], s[40:41], v[64:65], v[132:133]
	v_pk_fma_f32 v[162:163], s[40:41], v[66:67], v[162:163]
	v_pk_fma_f32 v[160:161], s[40:41], v[68:69], v[160:161]
	v_pk_fma_f32 v[158:159], s[40:41], v[70:71], v[158:159]
	v_cvt_scalef32_pk_f32_fp4 v[64:65], v17, 1.0
	v_cvt_scalef32_pk_f32_fp4 v[66:67], v17, 1.0 op_sel:[1,0,0]
	v_cvt_scalef32_pk_f32_fp4 v[68:69], v17, 1.0 op_sel:[0,1,0]
	v_cvt_scalef32_pk_f32_fp4 v[70:71], v17, 1.0 op_sel:[1,1,0]
	v_mov_b64_e32 v[90:91], v[30:31]
	v_pk_fma_f32 v[156:157], s[40:41], v[64:65], v[156:157]
	v_pk_fma_f32 v[154:155], s[40:41], v[66:67], v[154:155]
	v_pk_fma_f32 v[152:153], s[40:41], v[68:69], v[152:153]
	v_pk_fma_f32 v[150:151], s[40:41], v[70:71], v[150:151]
	v_cvt_scalef32_pk_f32_fp4 v[64:65], v18, 1.0
	v_cvt_scalef32_pk_f32_fp4 v[66:67], v18, 1.0 op_sel:[1,0,0]
	v_cvt_scalef32_pk_f32_fp4 v[68:69], v18, 1.0 op_sel:[0,1,0]
	v_cvt_scalef32_pk_f32_fp4 v[70:71], v18, 1.0 op_sel:[1,1,0]
	v_mov_b64_e32 v[86:87], v[26:27]
	v_pk_fma_f32 v[148:149], s[40:41], v[64:65], v[148:149]
	v_pk_fma_f32 v[146:147], s[40:41], v[66:67], v[146:147]
	v_pk_fma_f32 v[144:145], s[40:41], v[68:69], v[144:145]
	v_pk_fma_f32 v[142:143], s[40:41], v[70:71], v[142:143]
	v_cvt_scalef32_pk_f32_fp4 v[64:65], v19, 1.0
	v_cvt_scalef32_pk_f32_fp4 v[66:67], v19, 1.0 op_sel:[1,0,0]
	v_cvt_scalef32_pk_f32_fp4 v[68:69], v19, 1.0 op_sel:[0,1,0]
	v_cvt_scalef32_pk_f32_fp4 v[70:71], v19, 1.0 op_sel:[1,1,0]
	v_mov_b64_e32 v[82:83], v[22:23]
	v_pk_fma_f32 v[140:141], s[40:41], v[64:65], v[140:141]
	v_pk_fma_f32 v[138:139], s[40:41], v[66:67], v[138:139]
	v_pk_fma_f32 v[136:137], s[40:41], v[68:69], v[136:137]
	v_pk_fma_f32 v[134:135], s[40:41], v[70:71], v[134:135]
	v_readlane_b32 s40, v209, 4
	v_cvt_scalef32_pk_f32_fp4 v[64:65], v20, 1.0
	v_cvt_scalef32_pk_f32_fp4 v[66:67], v20, 1.0 op_sel:[1,0,0]
	v_cvt_scalef32_pk_f32_fp4 v[68:69], v20, 1.0 op_sel:[0,1,0]
	v_cvt_scalef32_pk_f32_fp4 v[70:71], v20, 1.0 op_sel:[1,1,0]
	s_mov_b32 s41, s40
	v_pk_fma_f32 v[132:133], s[40:41], v[64:65], v[132:133]
	v_pk_fma_f32 v[162:163], s[40:41], v[66:67], v[162:163]
	v_pk_fma_f32 v[160:161], s[40:41], v[68:69], v[160:161]
	v_pk_fma_f32 v[158:159], s[40:41], v[70:71], v[158:159]
	v_cvt_scalef32_pk_f32_fp4 v[64:65], v21, 1.0
	v_cvt_scalef32_pk_f32_fp4 v[66:67], v21, 1.0 op_sel:[1,0,0]
	v_cvt_scalef32_pk_f32_fp4 v[68:69], v21, 1.0 op_sel:[0,1,0]
	v_cvt_scalef32_pk_f32_fp4 v[70:71], v21, 1.0 op_sel:[1,1,0]
	v_mov_b64_e32 v[78:79], v[18:19]
	v_pk_fma_f32 v[156:157], s[40:41], v[64:65], v[156:157]
	v_pk_fma_f32 v[154:155], s[40:41], v[66:67], v[154:155]
	v_pk_fma_f32 v[152:153], s[40:41], v[68:69], v[152:153]
	v_pk_fma_f32 v[150:151], s[40:41], v[70:71], v[150:151]
	v_cvt_scalef32_pk_f32_fp4 v[64:65], v22, 1.0
	v_cvt_scalef32_pk_f32_fp4 v[66:67], v22, 1.0 op_sel:[1,0,0]
	v_cvt_scalef32_pk_f32_fp4 v[68:69], v22, 1.0 op_sel:[0,1,0]
	v_cvt_scalef32_pk_f32_fp4 v[70:71], v22, 1.0 op_sel:[1,1,0]
	v_mov_b64_e32 v[74:75], v[14:15]
	v_pk_fma_f32 v[148:149], s[40:41], v[64:65], v[148:149]
	v_pk_fma_f32 v[146:147], s[40:41], v[66:67], v[146:147]
	v_pk_fma_f32 v[144:145], s[40:41], v[68:69], v[144:145]
	v_pk_fma_f32 v[142:143], s[40:41], v[70:71], v[142:143]
	v_cvt_scalef32_pk_f32_fp4 v[64:65], v23, 1.0
	v_cvt_scalef32_pk_f32_fp4 v[66:67], v23, 1.0 op_sel:[1,0,0]
	v_cvt_scalef32_pk_f32_fp4 v[68:69], v23, 1.0 op_sel:[0,1,0]
	v_cvt_scalef32_pk_f32_fp4 v[70:71], v23, 1.0 op_sel:[1,1,0]
	v_mov_b64_e32 v[128:129], v[100:101]
	v_pk_fma_f32 v[140:141], s[40:41], v[64:65], v[140:141]
	v_pk_fma_f32 v[138:139], s[40:41], v[66:67], v[138:139]
	v_pk_fma_f32 v[136:137], s[40:41], v[68:69], v[136:137]
	v_pk_fma_f32 v[134:135], s[40:41], v[70:71], v[134:135]
	v_readlane_b32 s40, v209, 5
	v_cvt_scalef32_pk_f32_fp4 v[64:65], v24, 1.0
	v_cvt_scalef32_pk_f32_fp4 v[66:67], v24, 1.0 op_sel:[1,0,0]
	v_cvt_scalef32_pk_f32_fp4 v[68:69], v24, 1.0 op_sel:[0,1,0]
	v_cvt_scalef32_pk_f32_fp4 v[70:71], v24, 1.0 op_sel:[1,1,0]
	s_mov_b32 s41, s40
	v_pk_fma_f32 v[132:133], s[40:41], v[64:65], v[132:133]
	v_pk_fma_f32 v[162:163], s[40:41], v[66:67], v[162:163]
	v_pk_fma_f32 v[160:161], s[40:41], v[68:69], v[160:161]
	v_pk_fma_f32 v[158:159], s[40:41], v[70:71], v[158:159]
	v_cvt_scalef32_pk_f32_fp4 v[64:65], v25, 1.0
	v_cvt_scalef32_pk_f32_fp4 v[66:67], v25, 1.0 op_sel:[1,0,0]
	v_cvt_scalef32_pk_f32_fp4 v[68:69], v25, 1.0 op_sel:[0,1,0]
	v_cvt_scalef32_pk_f32_fp4 v[70:71], v25, 1.0 op_sel:[1,1,0]
	v_mov_b64_e32 v[124:125], v[60:61]
	v_pk_fma_f32 v[156:157], s[40:41], v[64:65], v[156:157]
	v_pk_fma_f32 v[154:155], s[40:41], v[66:67], v[154:155]
	v_pk_fma_f32 v[152:153], s[40:41], v[68:69], v[152:153]
	v_pk_fma_f32 v[150:151], s[40:41], v[70:71], v[150:151]
	v_cvt_scalef32_pk_f32_fp4 v[64:65], v26, 1.0
	v_cvt_scalef32_pk_f32_fp4 v[66:67], v26, 1.0 op_sel:[1,0,0]
	v_cvt_scalef32_pk_f32_fp4 v[68:69], v26, 1.0 op_sel:[0,1,0]
	v_cvt_scalef32_pk_f32_fp4 v[70:71], v26, 1.0 op_sel:[1,1,0]
; #define P4_FOR16(M) M(0) M(1) M(2) M(3) M(4) M(5) M(6) M(7) M(8) M(9) M(10) M(11) M(12) M(13) M(14) M(15)
; #define P4_V(i) { const unsigned wu_ = (unsigned)__builtin_amdgcn_readlane((int)__float_as_uint(wreg), i); const unsigned long long wp_ = ((unsigned long long)wu_ << 32) | wu_; \
;               P4_ACC(b##i, wp_); const int nk_ = __builtin_amdgcn_readlane(ksel, nb + i); P4_LOAD(b##i, Vg, nk_); }
; #define P4_V(i) { const unsigned wu_ = (unsigned)__builtin_amdgcn_readlane((int)__float_as_uint(wreg), i); const unsigned long long wp_ = ((unsigned long long)wu_ << 32) | wu_; \
;               P4_ACC(b##i, wp_); const int nk_ = __builtin_amdgcn_readlane(kn, i); P4_LOAD(b##i, Vg, nk_); }
; #define P4_V(i) { const unsigned wu_ = (unsigned)__builtin_amdgcn_readlane((int)__float_as_uint(wreg), i); const unsigned long long wp_ = ((unsigned long long)wu_ << 32) | wu_; \
;               P4_ACC(b##i, wp_); }
; __device__ __forceinline__ void peer_gather_f4p(const float* X, const int* __restrict__ IDX, const float* __restrict__ G, ...
;     ...
;         {
;             const float wreg = wbuf[kt * 128 + 7 * 16 + (lane & 15)];
;             if (kt < 3) {
;     ...
;                 P4_FOR16(P4_V)
;     ...
;             } else {
;     ...
;                 P4_FOR16(P4_V)
;     ...
;             }
	v_mov_b64_e32 v[120:121], v[56:57]
	v_pk_fma_f32 v[148:149], s[40:41], v[64:65], v[148:149]
	v_pk_fma_f32 v[146:147], s[40:41], v[66:67], v[146:147]
	v_pk_fma_f32 v[144:145], s[40:41], v[68:69], v[144:145]
	v_pk_fma_f32 v[142:143], s[40:41], v[70:71], v[142:143]
	v_cvt_scalef32_pk_f32_fp4 v[64:65], v27, 1.0
	v_cvt_scalef32_pk_f32_fp4 v[66:67], v27, 1.0 op_sel:[1,0,0]
	v_cvt_scalef32_pk_f32_fp4 v[68:69], v27, 1.0 op_sel:[0,1,0]
	v_cvt_scalef32_pk_f32_fp4 v[70:71], v27, 1.0 op_sel:[1,1,0]
	v_mov_b64_e32 v[116:117], v[52:53]
	v_pk_fma_f32 v[140:141], s[40:41], v[64:65], v[140:141]
	v_pk_fma_f32 v[138:139], s[40:41], v[66:67], v[138:139]
	v_pk_fma_f32 v[136:137], s[40:41], v[68:69], v[136:137]
	v_pk_fma_f32 v[134:135], s[40:41], v[70:71], v[134:135]
	v_readlane_b32 s40, v209, 6
	v_cvt_scalef32_pk_f32_fp4 v[64:65], v28, 1.0
	v_cvt_scalef32_pk_f32_fp4 v[66:67], v28, 1.0 op_sel:[1,0,0]
	v_cvt_scalef32_pk_f32_fp4 v[68:69], v28, 1.0 op_sel:[0,1,0]
	v_cvt_scalef32_pk_f32_fp4 v[70:71], v28, 1.0 op_sel:[1,1,0]
	s_mov_b32 s41, s40
	v_pk_fma_f32 v[132:133], s[40:41], v[64:65], v[132:133]
	v_pk_fma_f32 v[162:163], s[40:41], v[66:67], v[162:163]
	v_pk_fma_f32 v[160:161], s[40:41], v[68:69], v[160:161]
	v_pk_fma_f32 v[158:159], s[40:41], v[70:71], v[158:159]
	v_cvt_scalef32_pk_f32_fp4 v[64:65], v29, 1.0
	v_cvt_scalef32_pk_f32_fp4 v[66:67], v29, 1.0 op_sel:[1,0,0]
	v_cvt_scalef32_pk_f32_fp4 v[68:69], v29, 1.0 op_sel:[0,1,0]
	v_cvt_scalef32_pk_f32_fp4 v[70:71], v29, 1.0 op_sel:[1,1,0]
	v_mov_b64_e32 v[112:113], v[48:49]
	v_pk_fma_f32 v[156:157], s[40:41], v[64:65], v[156:157]
	v_pk_fma_f32 v[154:155], s[40:41], v[66:67], v[154:155]
	v_pk_fma_f32 v[152:153], s[40:41], v[68:69], v[152:153]
	v_pk_fma_f32 v[150:151], s[40:41], v[70:71], v[150:151]
	v_cvt_scalef32_pk_f32_fp4 v[64:65], v30, 1.0
	v_cvt_scalef32_pk_f32_fp4 v[66:67], v30, 1.0 op_sel:[1,0,0]
	v_cvt_scalef32_pk_f32_fp4 v[68:69], v30, 1.0 op_sel:[0,1,0]
	v_cvt_scalef32_pk_f32_fp4 v[70:71], v30, 1.0 op_sel:[1,1,0]
	v_mov_b64_e32 v[108:109], v[44:45]
	v_pk_fma_f32 v[148:149], s[40:41], v[64:65], v[148:149]
	v_pk_fma_f32 v[146:147], s[40:41], v[66:67], v[146:147]
	v_pk_fma_f32 v[144:145], s[40:41], v[68:69], v[144:145]
	v_pk_fma_f32 v[142:143], s[40:41], v[70:71], v[142:143]
	v_cvt_scalef32_pk_f32_fp4 v[64:65], v31, 1.0
	v_cvt_scalef32_pk_f32_fp4 v[66:67], v31, 1.0 op_sel:[1,0,0]
	v_cvt_scalef32_pk_f32_fp4 v[68:69], v31, 1.0 op_sel:[0,1,0]
	v_cvt_scalef32_pk_f32_fp4 v[70:71], v31, 1.0 op_sel:[1,1,0]
	v_mov_b64_e32 v[104:105], v[40:41]
	v_pk_fma_f32 v[140:141], s[40:41], v[64:65], v[140:141]
	v_pk_fma_f32 v[138:139], s[40:41], v[66:67], v[138:139]
	v_pk_fma_f32 v[136:137], s[40:41], v[68:69], v[136:137]
	v_pk_fma_f32 v[134:135], s[40:41], v[70:71], v[134:135]
	v_readlane_b32 s40, v209, 7
	v_cvt_scalef32_pk_f32_fp4 v[64:65], v32, 1.0
	v_cvt_scalef32_pk_f32_fp4 v[66:67], v32, 1.0 op_sel:[1,0,0]
	v_cvt_scalef32_pk_f32_fp4 v[68:69], v32, 1.0 op_sel:[0,1,0]
	v_cvt_scalef32_pk_f32_fp4 v[70:71], v32, 1.0 op_sel:[1,1,0]
	s_mov_b32 s41, s40
	v_pk_fma_f32 v[132:133], s[40:41], v[64:65], v[132:133]
	v_pk_fma_f32 v[162:163], s[40:41], v[66:67], v[162:163]
	v_pk_fma_f32 v[160:161], s[40:41], v[68:69], v[160:161]
	v_pk_fma_f32 v[158:159], s[40:41], v[70:71], v[158:159]
	v_cvt_scalef32_pk_f32_fp4 v[64:65], v33, 1.0
	v_cvt_scalef32_pk_f32_fp4 v[66:67], v33, 1.0 op_sel:[1,0,0]
	v_cvt_scalef32_pk_f32_fp4 v[68:69], v33, 1.0 op_sel:[0,1,0]
	v_cvt_scalef32_pk_f32_fp4 v[70:71], v33, 1.0 op_sel:[1,1,0]
	v_mov_b64_e32 v[96:97], v[36:37]
	v_pk_fma_f32 v[156:157], s[40:41], v[64:65], v[156:157]
	v_pk_fma_f32 v[154:155], s[40:41], v[66:67], v[154:155]
	v_pk_fma_f32 v[152:153], s[40:41], v[68:69], v[152:153]
	v_pk_fma_f32 v[150:151], s[40:41], v[70:71], v[150:151]
	v_cvt_scalef32_pk_f32_fp4 v[64:65], v34, 1.0
	v_cvt_scalef32_pk_f32_fp4 v[66:67], v34, 1.0 op_sel:[1,0,0]
	v_cvt_scalef32_pk_f32_fp4 v[68:69], v34, 1.0 op_sel:[0,1,0]
	v_cvt_scalef32_pk_f32_fp4 v[70:71], v34, 1.0 op_sel:[1,1,0]
	v_mov_b64_e32 v[92:93], v[32:33]
	v_pk_fma_f32 v[148:149], s[40:41], v[64:65], v[148:149]
	v_pk_fma_f32 v[146:147], s[40:41], v[66:67], v[146:147]
	v_pk_fma_f32 v[144:145], s[40:41], v[68:69], v[144:145]
	v_pk_fma_f32 v[142:143], s[40:41], v[70:71], v[142:143]
	v_cvt_scalef32_pk_f32_fp4 v[64:65], v35, 1.0
	v_cvt_scalef32_pk_f32_fp4 v[66:67], v35, 1.0 op_sel:[1,0,0]
	v_cvt_scalef32_pk_f32_fp4 v[68:69], v35, 1.0 op_sel:[0,1,0]
	v_cvt_scalef32_pk_f32_fp4 v[70:71], v35, 1.0 op_sel:[1,1,0]
	v_mov_b64_e32 v[88:89], v[28:29]
	v_pk_fma_f32 v[140:141], s[40:41], v[64:65], v[140:141]
	v_pk_fma_f32 v[138:139], s[40:41], v[66:67], v[138:139]
	v_pk_fma_f32 v[136:137], s[40:41], v[68:69], v[136:137]
	v_pk_fma_f32 v[134:135], s[40:41], v[70:71], v[134:135]
	v_readlane_b32 s40, v209, 8
	v_cvt_scalef32_pk_f32_fp4 v[64:65], v36, 1.0
	v_cvt_scalef32_pk_f32_fp4 v[66:67], v36, 1.0 op_sel:[1,0,0]
	v_cvt_scalef32_pk_f32_fp4 v[68:69], v36, 1.0 op_sel:[0,1,0]
	v_cvt_scalef32_pk_f32_fp4 v[70:71], v36, 1.0 op_sel:[1,1,0]
	s_mov_b32 s41, s40
	v_pk_fma_f32 v[132:133], s[40:41], v[64:65], v[132:133]
	v_pk_fma_f32 v[162:163], s[40:41], v[66:67], v[162:163]
	v_pk_fma_f32 v[160:161], s[40:41], v[68:69], v[160:161]
	v_pk_fma_f32 v[158:159], s[40:41], v[70:71], v[158:159]
	v_cvt_scalef32_pk_f32_fp4 v[64:65], v37, 1.0
	v_cvt_scalef32_pk_f32_fp4 v[66:67], v37, 1.0 op_sel:[1,0,0]
	v_cvt_scalef32_pk_f32_fp4 v[68:69], v37, 1.0 op_sel:[0,1,0]
	v_cvt_scalef32_pk_f32_fp4 v[70:71], v37, 1.0 op_sel:[1,1,0]
	v_mov_b64_e32 v[84:85], v[24:25]
	v_pk_fma_f32 v[156:157], s[40:41], v[64:65], v[156:157]
	v_pk_fma_f32 v[154:155], s[40:41], v[66:67], v[154:155]
	v_pk_fma_f32 v[152:153], s[40:41], v[68:69], v[152:153]
; #define P4_FOR16(M) M(0) M(1) M(2) M(3) M(4) M(5) M(6) M(7) M(8) M(9) M(10) M(11) M(12) M(13) M(14) M(15)
; #define P4_V(i) { const unsigned wu_ = (unsigned)__builtin_amdgcn_readlane((int)__float_as_uint(wreg), i); const unsigned long long wp_ = ((unsigned long long)wu_ << 32) | wu_; \
;               P4_ACC(b##i, wp_); const int nk_ = __builtin_amdgcn_readlane(ksel, nb + i); P4_LOAD(b##i, Vg, nk_); }
; #define P4_V(i) { const unsigned wu_ = (unsigned)__builtin_amdgcn_readlane((int)__float_as_uint(wreg), i); const unsigned long long wp_ = ((unsigned long long)wu_ << 32) | wu_; \
;               P4_ACC(b##i, wp_); const int nk_ = __builtin_amdgcn_readlane(kn, i); P4_LOAD(b##i, Vg, nk_); }
; #define P4_V(i) { const unsigned wu_ = (unsigned)__builtin_amdgcn_readlane((int)__float_as_uint(wreg), i); const unsigned long long wp_ = ((unsigned long long)wu_ << 32) | wu_; \
;               P4_ACC(b##i, wp_); }
; __device__ __forceinline__ void peer_gather_f4p(const float* X, const int* __restrict__ IDX, const float* __restrict__ G, ...
;     ...
;         {
;             const float wreg = wbuf[kt * 128 + 7 * 16 + (lane & 15)];
;             if (kt < 3) {
;     ...
;                 P4_FOR16(P4_V)
;     ...
;             } else {
;     ...
;                 P4_FOR16(P4_V)
;     ...
;             }
	v_pk_fma_f32 v[150:151], s[40:41], v[70:71], v[150:151]
	v_cvt_scalef32_pk_f32_fp4 v[64:65], v38, 1.0
	v_cvt_scalef32_pk_f32_fp4 v[66:67], v38, 1.0 op_sel:[1,0,0]
	v_cvt_scalef32_pk_f32_fp4 v[68:69], v38, 1.0 op_sel:[0,1,0]
	v_cvt_scalef32_pk_f32_fp4 v[70:71], v38, 1.0 op_sel:[1,1,0]
	v_mov_b64_e32 v[80:81], v[20:21]
	v_pk_fma_f32 v[148:149], s[40:41], v[64:65], v[148:149]
	v_pk_fma_f32 v[146:147], s[40:41], v[66:67], v[146:147]
	v_pk_fma_f32 v[144:145], s[40:41], v[68:69], v[144:145]
	v_pk_fma_f32 v[142:143], s[40:41], v[70:71], v[142:143]
	v_cvt_scalef32_pk_f32_fp4 v[64:65], v39, 1.0
	v_cvt_scalef32_pk_f32_fp4 v[66:67], v39, 1.0 op_sel:[1,0,0]
	v_cvt_scalef32_pk_f32_fp4 v[68:69], v39, 1.0 op_sel:[0,1,0]
	v_cvt_scalef32_pk_f32_fp4 v[70:71], v39, 1.0 op_sel:[1,1,0]
	v_mov_b64_e32 v[76:77], v[16:17]
	v_pk_fma_f32 v[140:141], s[40:41], v[64:65], v[140:141]
	v_pk_fma_f32 v[138:139], s[40:41], v[66:67], v[138:139]
	v_pk_fma_f32 v[136:137], s[40:41], v[68:69], v[136:137]
	v_pk_fma_f32 v[134:135], s[40:41], v[70:71], v[134:135]
	v_readlane_b32 s40, v209, 9
	v_cvt_scalef32_pk_f32_fp4 v[64:65], v40, 1.0
	v_cvt_scalef32_pk_f32_fp4 v[66:67], v40, 1.0 op_sel:[1,0,0]
	v_cvt_scalef32_pk_f32_fp4 v[68:69], v40, 1.0 op_sel:[0,1,0]
	v_cvt_scalef32_pk_f32_fp4 v[70:71], v40, 1.0 op_sel:[1,1,0]
	s_mov_b32 s41, s40
	v_pk_fma_f32 v[132:133], s[40:41], v[64:65], v[132:133]
	v_pk_fma_f32 v[162:163], s[40:41], v[66:67], v[162:163]
	v_pk_fma_f32 v[160:161], s[40:41], v[68:69], v[160:161]
	v_pk_fma_f32 v[158:159], s[40:41], v[70:71], v[158:159]
	v_cvt_scalef32_pk_f32_fp4 v[64:65], v41, 1.0
	v_cvt_scalef32_pk_f32_fp4 v[66:67], v41, 1.0 op_sel:[1,0,0]
	v_cvt_scalef32_pk_f32_fp4 v[68:69], v41, 1.0 op_sel:[0,1,0]
	v_cvt_scalef32_pk_f32_fp4 v[70:71], v41, 1.0 op_sel:[1,1,0]
	v_mov_b64_e32 v[72:73], v[12:13]
	v_pk_fma_f32 v[156:157], s[40:41], v[64:65], v[156:157]
	v_pk_fma_f32 v[154:155], s[40:41], v[66:67], v[154:155]
	v_pk_fma_f32 v[152:153], s[40:41], v[68:69], v[152:153]
	v_pk_fma_f32 v[150:151], s[40:41], v[70:71], v[150:151]
	v_cvt_scalef32_pk_f32_fp4 v[64:65], v42, 1.0
	v_cvt_scalef32_pk_f32_fp4 v[66:67], v42, 1.0 op_sel:[1,0,0]
	v_cvt_scalef32_pk_f32_fp4 v[68:69], v42, 1.0 op_sel:[0,1,0]
	v_cvt_scalef32_pk_f32_fp4 v[70:71], v42, 1.0 op_sel:[1,1,0]
	v_pk_fma_f32 v[148:149], s[40:41], v[64:65], v[148:149]
	v_pk_fma_f32 v[146:147], s[40:41], v[66:67], v[146:147]
	v_pk_fma_f32 v[144:145], s[40:41], v[68:69], v[144:145]
	v_pk_fma_f32 v[142:143], s[40:41], v[70:71], v[142:143]
	v_cvt_scalef32_pk_f32_fp4 v[64:65], v43, 1.0
	v_cvt_scalef32_pk_f32_fp4 v[66:67], v43, 1.0 op_sel:[1,0,0]
	v_cvt_scalef32_pk_f32_fp4 v[68:69], v43, 1.0 op_sel:[0,1,0]
	v_cvt_scalef32_pk_f32_fp4 v[70:71], v43, 1.0 op_sel:[1,1,0]
	v_pk_fma_f32 v[140:141], s[40:41], v[64:65], v[140:141]
	v_pk_fma_f32 v[138:139], s[40:41], v[66:67], v[138:139]
	v_pk_fma_f32 v[136:137], s[40:41], v[68:69], v[136:137]
	v_pk_fma_f32 v[134:135], s[40:41], v[70:71], v[134:135]
	v_readlane_b32 s40, v209, 10
	v_cvt_scalef32_pk_f32_fp4 v[64:65], v44, 1.0
	v_cvt_scalef32_pk_f32_fp4 v[66:67], v44, 1.0 op_sel:[1,0,0]
	v_cvt_scalef32_pk_f32_fp4 v[68:69], v44, 1.0 op_sel:[0,1,0]
	v_cvt_scalef32_pk_f32_fp4 v[70:71], v44, 1.0 op_sel:[1,1,0]
	s_mov_b32 s41, s40
	v_pk_fma_f32 v[132:133], s[40:41], v[64:65], v[132:133]
	v_pk_fma_f32 v[162:163], s[40:41], v[66:67], v[162:163]
	v_pk_fma_f32 v[160:161], s[40:41], v[68:69], v[160:161]
	v_pk_fma_f32 v[158:159], s[40:41], v[70:71], v[158:159]
	v_cvt_scalef32_pk_f32_fp4 v[64:65], v45, 1.0
	v_cvt_scalef32_pk_f32_fp4 v[66:67], v45, 1.0 op_sel:[1,0,0]
	v_cvt_scalef32_pk_f32_fp4 v[68:69], v45, 1.0 op_sel:[0,1,0]
	v_cvt_scalef32_pk_f32_fp4 v[70:71], v45, 1.0 op_sel:[1,1,0]
	v_pk_fma_f32 v[156:157], s[40:41], v[64:65], v[156:157]
	v_pk_fma_f32 v[154:155], s[40:41], v[66:67], v[154:155]
	v_pk_fma_f32 v[152:153], s[40:41], v[68:69], v[152:153]
	v_pk_fma_f32 v[150:151], s[40:41], v[70:71], v[150:151]
	v_cvt_scalef32_pk_f32_fp4 v[64:65], v46, 1.0
	v_cvt_scalef32_pk_f32_fp4 v[66:67], v46, 1.0 op_sel:[1,0,0]
	v_cvt_scalef32_pk_f32_fp4 v[68:69], v46, 1.0 op_sel:[0,1,0]
	v_cvt_scalef32_pk_f32_fp4 v[70:71], v46, 1.0 op_sel:[1,1,0]
	v_pk_fma_f32 v[148:149], s[40:41], v[64:65], v[148:149]
	v_pk_fma_f32 v[146:147], s[40:41], v[66:67], v[146:147]
	v_pk_fma_f32 v[144:145], s[40:41], v[68:69], v[144:145]
	v_pk_fma_f32 v[142:143], s[40:41], v[70:71], v[142:143]
	v_cvt_scalef32_pk_f32_fp4 v[64:65], v47, 1.0
	v_cvt_scalef32_pk_f32_fp4 v[66:67], v47, 1.0 op_sel:[1,0,0]
	v_cvt_scalef32_pk_f32_fp4 v[68:69], v47, 1.0 op_sel:[0,1,0]
	v_cvt_scalef32_pk_f32_fp4 v[70:71], v47, 1.0 op_sel:[1,1,0]
	v_pk_fma_f32 v[140:141], s[40:41], v[64:65], v[140:141]
	v_pk_fma_f32 v[138:139], s[40:41], v[66:67], v[138:139]
	v_pk_fma_f32 v[136:137], s[40:41], v[68:69], v[136:137]
	v_pk_fma_f32 v[134:135], s[40:41], v[70:71], v[134:135]
	v_readlane_b32 s40, v209, 11
	v_cvt_scalef32_pk_f32_fp4 v[64:65], v48, 1.0
	v_cvt_scalef32_pk_f32_fp4 v[66:67], v48, 1.0 op_sel:[1,0,0]
	v_cvt_scalef32_pk_f32_fp4 v[68:69], v48, 1.0 op_sel:[0,1,0]
	v_cvt_scalef32_pk_f32_fp4 v[70:71], v48, 1.0 op_sel:[1,1,0]
	s_mov_b32 s41, s40
	v_pk_fma_f32 v[132:133], s[40:41], v[64:65], v[132:133]
	v_pk_fma_f32 v[162:163], s[40:41], v[66:67], v[162:163]
	v_pk_fma_f32 v[160:161], s[40:41], v[68:69], v[160:161]
	v_pk_fma_f32 v[158:159], s[40:41], v[70:71], v[158:159]
	v_cvt_scalef32_pk_f32_fp4 v[64:65], v49, 1.0
	v_cvt_scalef32_pk_f32_fp4 v[66:67], v49, 1.0 op_sel:[1,0,0]
	v_cvt_scalef32_pk_f32_fp4 v[68:69], v49, 1.0 op_sel:[0,1,0]
	v_cvt_scalef32_pk_f32_fp4 v[70:71], v49, 1.0 op_sel:[1,1,0]
	v_pk_fma_f32 v[156:157], s[40:41], v[64:65], v[156:157]
; #define P4_FOR16(M) M(0) M(1) M(2) M(3) M(4) M(5) M(6) M(7) M(8) M(9) M(10) M(11) M(12) M(13) M(14) M(15)
; #define P4_V(i) { const unsigned wu_ = (unsigned)__builtin_amdgcn_readlane((int)__float_as_uint(wreg), i); const unsigned long long wp_ = ((unsigned long long)wu_ << 32) | wu_; \
;               P4_ACC(b##i, wp_); const int nk_ = __builtin_amdgcn_readlane(ksel, nb + i); P4_LOAD(b##i, Vg, nk_); }
; #define P4_V(i) { const unsigned wu_ = (unsigned)__builtin_amdgcn_readlane((int)__float_as_uint(wreg), i); const unsigned long long wp_ = ((unsigned long long)wu_ << 32) | wu_; \
;               P4_ACC(b##i, wp_); const int nk_ = __builtin_amdgcn_readlane(kn, i); P4_LOAD(b##i, Vg, nk_); }
; #define P4_V(i) { const unsigned wu_ = (unsigned)__builtin_amdgcn_readlane((int)__float_as_uint(wreg), i); const unsigned long long wp_ = ((unsigned long long)wu_ << 32) | wu_; \
;               P4_ACC(b##i, wp_); }
; __device__ __forceinline__ void peer_gather_f4p(const float* X, const int* __restrict__ IDX, const float* __restrict__ G, ...
;     ...
;         {
;             const float wreg = wbuf[kt * 128 + 7 * 16 + (lane & 15)];
;             if (kt < 3) {
;     ...
;                 P4_FOR16(P4_V)
;     ...
;             } else {
;     ...
;                 P4_FOR16(P4_V)
;     ...
;             }
	v_pk_fma_f32 v[154:155], s[40:41], v[66:67], v[154:155]
	v_pk_fma_f32 v[152:153], s[40:41], v[68:69], v[152:153]
	v_pk_fma_f32 v[150:151], s[40:41], v[70:71], v[150:151]
	v_cvt_scalef32_pk_f32_fp4 v[64:65], v50, 1.0
	v_cvt_scalef32_pk_f32_fp4 v[66:67], v50, 1.0 op_sel:[1,0,0]
	v_cvt_scalef32_pk_f32_fp4 v[68:69], v50, 1.0 op_sel:[0,1,0]
	v_cvt_scalef32_pk_f32_fp4 v[70:71], v50, 1.0 op_sel:[1,1,0]
	v_pk_fma_f32 v[148:149], s[40:41], v[64:65], v[148:149]
	v_pk_fma_f32 v[146:147], s[40:41], v[66:67], v[146:147]
	v_pk_fma_f32 v[144:145], s[40:41], v[68:69], v[144:145]
	v_pk_fma_f32 v[142:143], s[40:41], v[70:71], v[142:143]
	v_cvt_scalef32_pk_f32_fp4 v[64:65], v51, 1.0
	v_cvt_scalef32_pk_f32_fp4 v[66:67], v51, 1.0 op_sel:[1,0,0]
	v_cvt_scalef32_pk_f32_fp4 v[68:69], v51, 1.0 op_sel:[0,1,0]
	v_cvt_scalef32_pk_f32_fp4 v[70:71], v51, 1.0 op_sel:[1,1,0]
	v_pk_fma_f32 v[140:141], s[40:41], v[64:65], v[140:141]
	v_pk_fma_f32 v[138:139], s[40:41], v[66:67], v[138:139]
	v_pk_fma_f32 v[136:137], s[40:41], v[68:69], v[136:137]
	v_pk_fma_f32 v[134:135], s[40:41], v[70:71], v[134:135]
	v_readlane_b32 s40, v209, 12
	v_cvt_scalef32_pk_f32_fp4 v[64:65], v52, 1.0
	v_cvt_scalef32_pk_f32_fp4 v[66:67], v52, 1.0 op_sel:[1,0,0]
	v_cvt_scalef32_pk_f32_fp4 v[68:69], v52, 1.0 op_sel:[0,1,0]
	v_cvt_scalef32_pk_f32_fp4 v[70:71], v52, 1.0 op_sel:[1,1,0]
	s_mov_b32 s41, s40
	v_pk_fma_f32 v[132:133], s[40:41], v[64:65], v[132:133]
	v_pk_fma_f32 v[162:163], s[40:41], v[66:67], v[162:163]
	v_pk_fma_f32 v[160:161], s[40:41], v[68:69], v[160:161]
	v_pk_fma_f32 v[158:159], s[40:41], v[70:71], v[158:159]
	v_cvt_scalef32_pk_f32_fp4 v[64:65], v53, 1.0
	v_cvt_scalef32_pk_f32_fp4 v[66:67], v53, 1.0 op_sel:[1,0,0]
	v_cvt_scalef32_pk_f32_fp4 v[68:69], v53, 1.0 op_sel:[0,1,0]
	v_cvt_scalef32_pk_f32_fp4 v[70:71], v53, 1.0 op_sel:[1,1,0]
	v_pk_fma_f32 v[156:157], s[40:41], v[64:65], v[156:157]
	v_pk_fma_f32 v[154:155], s[40:41], v[66:67], v[154:155]
	v_pk_fma_f32 v[152:153], s[40:41], v[68:69], v[152:153]
	v_pk_fma_f32 v[150:151], s[40:41], v[70:71], v[150:151]
	v_cvt_scalef32_pk_f32_fp4 v[64:65], v54, 1.0
	v_cvt_scalef32_pk_f32_fp4 v[66:67], v54, 1.0 op_sel:[1,0,0]
	v_cvt_scalef32_pk_f32_fp4 v[68:69], v54, 1.0 op_sel:[0,1,0]
	v_cvt_scalef32_pk_f32_fp4 v[70:71], v54, 1.0 op_sel:[1,1,0]
	v_pk_fma_f32 v[148:149], s[40:41], v[64:65], v[148:149]
	v_pk_fma_f32 v[146:147], s[40:41], v[66:67], v[146:147]
	v_pk_fma_f32 v[144:145], s[40:41], v[68:69], v[144:145]
	v_pk_fma_f32 v[142:143], s[40:41], v[70:71], v[142:143]
	v_cvt_scalef32_pk_f32_fp4 v[64:65], v55, 1.0
	v_cvt_scalef32_pk_f32_fp4 v[66:67], v55, 1.0 op_sel:[1,0,0]
	v_cvt_scalef32_pk_f32_fp4 v[68:69], v55, 1.0 op_sel:[0,1,0]
	v_cvt_scalef32_pk_f32_fp4 v[70:71], v55, 1.0 op_sel:[1,1,0]
	v_pk_fma_f32 v[140:141], s[40:41], v[64:65], v[140:141]
	v_pk_fma_f32 v[138:139], s[40:41], v[66:67], v[138:139]
	v_pk_fma_f32 v[136:137], s[40:41], v[68:69], v[136:137]
	v_pk_fma_f32 v[134:135], s[40:41], v[70:71], v[134:135]
	v_readlane_b32 s40, v209, 13
	v_cvt_scalef32_pk_f32_fp4 v[64:65], v56, 1.0
	v_cvt_scalef32_pk_f32_fp4 v[66:67], v56, 1.0 op_sel:[1,0,0]
	v_cvt_scalef32_pk_f32_fp4 v[68:69], v56, 1.0 op_sel:[0,1,0]
	v_cvt_scalef32_pk_f32_fp4 v[70:71], v56, 1.0 op_sel:[1,1,0]
	s_mov_b32 s41, s40
	v_pk_fma_f32 v[132:133], s[40:41], v[64:65], v[132:133]
	v_pk_fma_f32 v[162:163], s[40:41], v[66:67], v[162:163]
	v_pk_fma_f32 v[160:161], s[40:41], v[68:69], v[160:161]
	v_pk_fma_f32 v[158:159], s[40:41], v[70:71], v[158:159]
	v_cvt_scalef32_pk_f32_fp4 v[64:65], v57, 1.0
	v_cvt_scalef32_pk_f32_fp4 v[66:67], v57, 1.0 op_sel:[1,0,0]
	v_cvt_scalef32_pk_f32_fp4 v[68:69], v57, 1.0 op_sel:[0,1,0]
	v_cvt_scalef32_pk_f32_fp4 v[70:71], v57, 1.0 op_sel:[1,1,0]
	v_pk_fma_f32 v[156:157], s[40:41], v[64:65], v[156:157]
	v_pk_fma_f32 v[154:155], s[40:41], v[66:67], v[154:155]
	v_pk_fma_f32 v[152:153], s[40:41], v[68:69], v[152:153]
	v_pk_fma_f32 v[150:151], s[40:41], v[70:71], v[150:151]
	v_cvt_scalef32_pk_f32_fp4 v[64:65], v58, 1.0
	v_cvt_scalef32_pk_f32_fp4 v[66:67], v58, 1.0 op_sel:[1,0,0]
	v_cvt_scalef32_pk_f32_fp4 v[68:69], v58, 1.0 op_sel:[0,1,0]
	v_cvt_scalef32_pk_f32_fp4 v[70:71], v58, 1.0 op_sel:[1,1,0]
	v_pk_fma_f32 v[148:149], s[40:41], v[64:65], v[148:149]
	v_pk_fma_f32 v[146:147], s[40:41], v[66:67], v[146:147]
	v_pk_fma_f32 v[144:145], s[40:41], v[68:69], v[144:145]
	v_pk_fma_f32 v[142:143], s[40:41], v[70:71], v[142:143]
	v_cvt_scalef32_pk_f32_fp4 v[64:65], v59, 1.0
	v_cvt_scalef32_pk_f32_fp4 v[66:67], v59, 1.0 op_sel:[1,0,0]
	v_cvt_scalef32_pk_f32_fp4 v[68:69], v59, 1.0 op_sel:[0,1,0]
	v_cvt_scalef32_pk_f32_fp4 v[70:71], v59, 1.0 op_sel:[1,1,0]
	v_pk_fma_f32 v[140:141], s[40:41], v[64:65], v[140:141]
	v_pk_fma_f32 v[138:139], s[40:41], v[66:67], v[138:139]
	v_pk_fma_f32 v[136:137], s[40:41], v[68:69], v[136:137]
; #define P4_FOR16(M) M(0) M(1) M(2) M(3) M(4) M(5) M(6) M(7) M(8) M(9) M(10) M(11) M(12) M(13) M(14) M(15)
; #define P4_V(i) { const unsigned wu_ = (unsigned)__builtin_amdgcn_readlane((int)__float_as_uint(wreg), i); const unsigned long long wp_ = ((unsigned long long)wu_ << 32) | wu_; \
;               P4_ACC(b##i, wp_); const int nk_ = __builtin_amdgcn_readlane(ksel, nb + i); P4_LOAD(b##i, Vg, nk_); }
; #define P4_V(i) { const unsigned wu_ = (unsigned)__builtin_amdgcn_readlane((int)__float_as_uint(wreg), i); const unsigned long long wp_ = ((unsigned long long)wu_ << 32) | wu_; \
;               P4_ACC(b##i, wp_); const int nk_ = __builtin_amdgcn_readlane(kn, i); P4_LOAD(b##i, Vg, nk_); }
; #define P4_V(i) { const unsigned wu_ = (unsigned)__builtin_amdgcn_readlane((int)__float_as_uint(wreg), i); const unsigned long long wp_ = ((unsigned long long)wu_ << 32) | wu_; \
;               P4_ACC(b##i, wp_); }
; __device__ __forceinline__ void peer_gather_f4p(const float* X, const int* __restrict__ IDX, const float* __restrict__ G, ...
;     ...
;         {
;             const float wreg = wbuf[kt * 128 + 7 * 16 + (lane & 15)];
;             if (kt < 3) {
;     ...
;                 P4_FOR16(P4_V)
;     ...
;             } else {
;     ...
;                 P4_FOR16(P4_V)
;     ...
;             }
	v_pk_fma_f32 v[134:135], s[40:41], v[70:71], v[134:135]
	v_readlane_b32 s40, v209, 14
	v_cvt_scalef32_pk_f32_fp4 v[64:65], v60, 1.0
	v_cvt_scalef32_pk_f32_fp4 v[66:67], v60, 1.0 op_sel:[1,0,0]
	v_cvt_scalef32_pk_f32_fp4 v[68:69], v60, 1.0 op_sel:[0,1,0]
	v_cvt_scalef32_pk_f32_fp4 v[70:71], v60, 1.0 op_sel:[1,1,0]
	s_mov_b32 s41, s40
	v_pk_fma_f32 v[132:133], s[40:41], v[64:65], v[132:133]
	v_pk_fma_f32 v[162:163], s[40:41], v[66:67], v[162:163]
	v_pk_fma_f32 v[160:161], s[40:41], v[68:69], v[160:161]
	v_pk_fma_f32 v[158:159], s[40:41], v[70:71], v[158:159]
	v_cvt_scalef32_pk_f32_fp4 v[64:65], v61, 1.0
	v_cvt_scalef32_pk_f32_fp4 v[66:67], v61, 1.0 op_sel:[1,0,0]
	v_cvt_scalef32_pk_f32_fp4 v[68:69], v61, 1.0 op_sel:[0,1,0]
	v_cvt_scalef32_pk_f32_fp4 v[70:71], v61, 1.0 op_sel:[1,1,0]
	v_pk_fma_f32 v[156:157], s[40:41], v[64:65], v[156:157]
	v_pk_fma_f32 v[154:155], s[40:41], v[66:67], v[154:155]
	v_pk_fma_f32 v[152:153], s[40:41], v[68:69], v[152:153]
	v_pk_fma_f32 v[150:151], s[40:41], v[70:71], v[150:151]
	v_cvt_scalef32_pk_f32_fp4 v[64:65], v62, 1.0
	v_cvt_scalef32_pk_f32_fp4 v[66:67], v62, 1.0 op_sel:[1,0,0]
	v_cvt_scalef32_pk_f32_fp4 v[68:69], v62, 1.0 op_sel:[0,1,0]
	v_cvt_scalef32_pk_f32_fp4 v[70:71], v62, 1.0 op_sel:[1,1,0]
	v_pk_fma_f32 v[148:149], s[40:41], v[64:65], v[148:149]
	v_pk_fma_f32 v[146:147], s[40:41], v[66:67], v[146:147]
	v_pk_fma_f32 v[144:145], s[40:41], v[68:69], v[144:145]
	v_pk_fma_f32 v[142:143], s[40:41], v[70:71], v[142:143]
	v_cvt_scalef32_pk_f32_fp4 v[64:65], v63, 1.0
	v_cvt_scalef32_pk_f32_fp4 v[66:67], v63, 1.0 op_sel:[1,0,0]
	v_cvt_scalef32_pk_f32_fp4 v[68:69], v63, 1.0 op_sel:[0,1,0]
	v_cvt_scalef32_pk_f32_fp4 v[70:71], v63, 1.0 op_sel:[1,1,0]
	v_pk_fma_f32 v[140:141], s[40:41], v[64:65], v[140:141]
	v_pk_fma_f32 v[138:139], s[40:41], v[66:67], v[138:139]
	v_pk_fma_f32 v[136:137], s[40:41], v[68:69], v[136:137]
	v_pk_fma_f32 v[134:135], s[40:41], v[70:71], v[134:135]
	v_readlane_b32 s40, v209, 15
	v_cvt_scalef32_pk_f32_fp4 v[64:65], v100, 1.0
	v_cvt_scalef32_pk_f32_fp4 v[66:67], v100, 1.0 op_sel:[1,0,0]
	v_cvt_scalef32_pk_f32_fp4 v[68:69], v100, 1.0 op_sel:[0,1,0]
	v_cvt_scalef32_pk_f32_fp4 v[70:71], v100, 1.0 op_sel:[1,1,0]
	s_mov_b32 s41, s40
	v_pk_fma_f32 v[132:133], s[40:41], v[64:65], v[132:133]
	v_pk_fma_f32 v[162:163], s[40:41], v[66:67], v[162:163]
	v_pk_fma_f32 v[160:161], s[40:41], v[68:69], v[160:161]
	v_pk_fma_f32 v[158:159], s[40:41], v[70:71], v[158:159]
	v_cvt_scalef32_pk_f32_fp4 v[64:65], v101, 1.0
	v_cvt_scalef32_pk_f32_fp4 v[66:67], v101, 1.0 op_sel:[1,0,0]
	v_cvt_scalef32_pk_f32_fp4 v[68:69], v101, 1.0 op_sel:[0,1,0]
	v_cvt_scalef32_pk_f32_fp4 v[70:71], v101, 1.0 op_sel:[1,1,0]
	s_nop 0
	v_mov_b32_e32 v194, v132
	v_pk_fma_f32 v[156:157], s[40:41], v[64:65], v[156:157]
	v_pk_fma_f32 v[154:155], s[40:41], v[66:67], v[154:155]
	v_pk_fma_f32 v[152:153], s[40:41], v[68:69], v[152:153]
	v_pk_fma_f32 v[150:151], s[40:41], v[70:71], v[150:151]
	v_cvt_scalef32_pk_f32_fp4 v[64:65], v102, 1.0
	v_cvt_scalef32_pk_f32_fp4 v[66:67], v102, 1.0 op_sel:[1,0,0]
	v_cvt_scalef32_pk_f32_fp4 v[68:69], v102, 1.0 op_sel:[0,1,0]
	v_cvt_scalef32_pk_f32_fp4 v[70:71], v102, 1.0 op_sel:[1,1,0]
	v_mov_b32_e32 v195, v133
	v_pk_fma_f32 v[148:149], s[40:41], v[64:65], v[148:149]
	v_pk_fma_f32 v[146:147], s[40:41], v[66:67], v[146:147]
	v_pk_fma_f32 v[144:145], s[40:41], v[68:69], v[144:145]
	v_pk_fma_f32 v[142:143], s[40:41], v[70:71], v[142:143]
	v_cvt_scalef32_pk_f32_fp4 v[64:65], v103, 1.0
	v_cvt_scalef32_pk_f32_fp4 v[66:67], v103, 1.0 op_sel:[1,0,0]
	v_cvt_scalef32_pk_f32_fp4 v[68:69], v103, 1.0 op_sel:[0,1,0]
	v_cvt_scalef32_pk_f32_fp4 v[70:71], v103, 1.0 op_sel:[1,1,0]
	v_mov_b32_e32 v196, v162
	v_pk_fma_f32 v[140:141], s[40:41], v[64:65], v[140:141]
	v_pk_fma_f32 v[138:139], s[40:41], v[66:67], v[138:139]
	v_pk_fma_f32 v[136:137], s[40:41], v[68:69], v[136:137]
	v_pk_fma_f32 v[134:135], s[40:41], v[70:71], v[134:135]
	v_mov_b64_e32 v[70:71], v[10:11]
	v_mov_b64_e32 v[66:67], v[6:7]
	v_mov_b64_e32 v[68:69], v[8:9]
	v_mov_b64_e32 v[64:65], v[4:5]
	v_mov_b32_e32 v197, v163
	v_mov_b32_e32 v190, v160
	v_mov_b32_e32 v191, v161
	v_mov_b32_e32 v192, v158
	v_mov_b32_e32 v193, v159
	v_mov_b32_e32 v186, v156
	v_mov_b32_e32 v187, v157
	v_mov_b32_e32 v188, v154
	v_mov_b32_e32 v189, v155
	v_mov_b32_e32 v182, v152
	v_mov_b32_e32 v183, v153
	v_mov_b32_e32 v184, v150
	v_mov_b32_e32 v185, v151
	v_mov_b32_e32 v178, v148
	v_mov_b32_e32 v179, v149
	v_mov_b32_e32 v180, v146
	v_mov_b32_e32 v181, v147
	v_mov_b32_e32 v174, v144
	v_mov_b32_e32 v175, v145
	v_mov_b32_e32 v176, v142
	v_mov_b32_e32 v177, v143
	v_mov_b32_e32 v170, v140
	v_mov_b32_e32 v171, v141
	v_mov_b32_e32 v172, v138
	v_mov_b32_e32 v173, v139
	v_mov_b32_e32 v166, v136
	v_mov_b32_e32 v167, v137
	v_mov_b32_e32 v168, v134
	v_mov_b32_e32 v169, v135
	s_branch .LBB0_548

; #define P4_FOR16(M) M(0) M(1) M(2) M(3) M(4) M(5) M(6) M(7) M(8) M(9) M(10) M(11) M(12) M(13) M(14) M(15)
; #define P4_U(i) { P4_DOT(b##i, part[i]); const int nk_ = __builtin_amdgcn_readlane(ksel, nb + i); P4_LOAD(b##i, Ug, nk_); }
; #define P4_U(i) { P4_DOT(b##i, part[i]); const int nk_ = __builtin_amdgcn_readlane(kn, i); P4_LOAD(b##i, nbase, nk_); }
; __device__ __forceinline__ void peer_gather_f4p(const float* X, const int* __restrict__ IDX, const float* __restrict__ G, ...
;     ...
; #pragma unroll 1
;         for (int bt = 0; bt < 7; ++bt) {
;             const int ksel = (bt + 1 < 4) ? k0 : k1;
;             const int nb = (16 * (bt + 1)) & 63;
;     ...
;             P4_FOR16(P4_U)
;     ...
;             P4_RED(bt);
;         }
.LBB0_1230:
	s_mov_b32 s87, s86
	s_waitcnt vmcnt(15)
	v_cvt_scalef32_pk_bf16_fp4 v48, v64, 1.0
	v_cvt_scalef32_pk_bf16_fp4 v50, v64, 1.0 op_sel:[1,0,0]
	v_cvt_scalef32_pk_bf16_fp4 v52, v64, 1.0 op_sel:[0,1,0]
	v_cvt_scalef32_pk_bf16_fp4 v54, v64, 1.0 op_sel:[1,1,0]
	v_dot2_f32_bf16 v56, v48, v6, 0
	v_dot2_f32_bf16 v48, v50, v4, 0
	v_dot2_f32_bf16 v56, v52, v10, v56
	s_cmp_lt_u32 s29, 3
	v_dot2_f32_bf16 v48, v54, v8, v48
	v_cvt_scalef32_pk_bf16_fp4 v50, v65, 1.0
	v_cvt_scalef32_pk_bf16_fp4 v52, v65, 1.0 op_sel:[1,0,0]
	v_cvt_scalef32_pk_bf16_fp4 v54, v65, 1.0 op_sel:[0,1,0]
	v_cvt_scalef32_pk_bf16_fp4 v58, v65, 1.0 op_sel:[1,1,0]
	s_cselect_b64 s[48:49], -1, 0
	v_dot2_f32_bf16 v56, v50, v14, v56
	v_dot2_f32_bf16 v48, v52, v12, v48
	s_waitcnt lgkmcnt(1)
	v_cndmask_b32_e64 v46, v39, v38, s[48:49]
	v_dot2_f32_bf16 v56, v54, v18, v56
	v_dot2_f32_bf16 v48, v58, v16, v48
	v_cvt_scalef32_pk_bf16_fp4 v50, v66, 1.0
	v_cvt_scalef32_pk_bf16_fp4 v52, v66, 1.0 op_sel:[1,0,0]
	v_cvt_scalef32_pk_bf16_fp4 v54, v66, 1.0 op_sel:[0,1,0]
	v_cvt_scalef32_pk_bf16_fp4 v58, v66, 1.0 op_sel:[1,1,0]
	s_add_i32 s12, s28, -15
	v_dot2_f32_bf16 v56, v50, v22, v56
	v_dot2_f32_bf16 v48, v52, v20, v48
	v_readlane_b32 s12, v46, s12
	v_dot2_f32_bf16 v56, v54, v26, v56
	v_dot2_f32_bf16 v48, v58, v24, v48
	v_cvt_scalef32_pk_bf16_fp4 v50, v67, 1.0
	v_cvt_scalef32_pk_bf16_fp4 v52, v67, 1.0 op_sel:[1,0,0]
	v_cvt_scalef32_pk_bf16_fp4 v54, v67, 1.0 op_sel:[0,1,0]
	v_cvt_scalef32_pk_bf16_fp4 v58, v67, 1.0 op_sel:[1,1,0]
	s_lshr_b32 s12, s12, 7
	v_dot2_f32_bf16 v56, v50, v30, v56
	v_dot2_f32_bf16 v48, v52, v28, v48
	s_mov_b32 s13, s86
	v_dot2_f32_bf16 v56, v54, v36, v56
	v_dot2_f32_bf16 v48, v58, v34, v48
	s_lshl_b64 s[12:13], s[12:13], 10
	s_nop 2
	v_readfirstlane_b32 s100, v40
	v_readfirstlane_b32 s101, v41
	v_subrev_u32_e32 v207, s100, v40
	v_add_f32_e32 v47, v56, v48
	s_add_u32 s12, s12, s100
	s_addc_u32 s13, s13, s101
	global_load_dwordx4 v[64:67], v207, s[12:13]
	s_waitcnt vmcnt(15)
	v_cvt_scalef32_pk_bf16_fp4 v48, v68, 1.0
	v_cvt_scalef32_pk_bf16_fp4 v50, v68, 1.0 op_sel:[1,0,0]
	v_cvt_scalef32_pk_bf16_fp4 v52, v68, 1.0 op_sel:[0,1,0]
	v_cvt_scalef32_pk_bf16_fp4 v54, v68, 1.0 op_sel:[1,1,0]
	v_dot2_f32_bf16 v56, v48, v6, 0
	v_dot2_f32_bf16 v48, v50, v4, 0
	v_dot2_f32_bf16 v56, v52, v10, v56
	s_add_i32 s12, s28, -14
	v_dot2_f32_bf16 v48, v54, v8, v48
	v_cvt_scalef32_pk_bf16_fp4 v50, v69, 1.0
	v_cvt_scalef32_pk_bf16_fp4 v52, v69, 1.0 op_sel:[1,0,0]
	v_cvt_scalef32_pk_bf16_fp4 v54, v69, 1.0 op_sel:[0,1,0]
	v_cvt_scalef32_pk_bf16_fp4 v58, v69, 1.0 op_sel:[1,1,0]
	v_readlane_b32 s12, v46, s12
	v_dot2_f32_bf16 v56, v50, v14, v56
	v_dot2_f32_bf16 v48, v52, v12, v48
	s_lshr_b32 s12, s12, 7
	v_dot2_f32_bf16 v56, v54, v18, v56
	v_dot2_f32_bf16 v48, v58, v16, v48
	v_cvt_scalef32_pk_bf16_fp4 v50, v70, 1.0
	v_cvt_scalef32_pk_bf16_fp4 v52, v70, 1.0 op_sel:[1,0,0]
	v_cvt_scalef32_pk_bf16_fp4 v54, v70, 1.0 op_sel:[0,1,0]
	v_cvt_scalef32_pk_bf16_fp4 v58, v70, 1.0 op_sel:[1,1,0]
	s_mov_b32 s13, s86
	v_dot2_f32_bf16 v56, v50, v22, v56
	v_dot2_f32_bf16 v48, v52, v20, v48
	s_lshl_b64 s[12:13], s[12:13], 10
	v_dot2_f32_bf16 v56, v54, v26, v56
	v_dot2_f32_bf16 v48, v58, v24, v48
	v_cvt_scalef32_pk_bf16_fp4 v50, v71, 1.0
	v_cvt_scalef32_pk_bf16_fp4 v52, v71, 1.0 op_sel:[1,0,0]
	v_cvt_scalef32_pk_bf16_fp4 v54, v71, 1.0 op_sel:[0,1,0]
	v_cvt_scalef32_pk_bf16_fp4 v58, v71, 1.0 op_sel:[1,1,0]
	v_mov_b32_e32 v42, 0
	v_dot2_f32_bf16 v56, v50, v30, v56
	v_dot2_f32_bf16 v48, v52, v28, v48
	v_dot2_f32_bf16 v56, v54, v36, v56
	v_dot2_f32_bf16 v48, v58, v34, v48
	s_nop 2
	v_add_f32_e32 v48, v56, v48
	s_add_u32 s12, s12, s100
	s_addc_u32 s13, s13, s101
	global_load_dwordx4 v[68:71], v207, s[12:13]
	s_waitcnt vmcnt(15)
	v_cvt_scalef32_pk_bf16_fp4 v50, v72, 1.0
	v_cvt_scalef32_pk_bf16_fp4 v52, v72, 1.0 op_sel:[1,0,0]
	v_cvt_scalef32_pk_bf16_fp4 v54, v72, 1.0 op_sel:[0,1,0]
	v_cvt_scalef32_pk_bf16_fp4 v56, v72, 1.0 op_sel:[1,1,0]
	s_add_i32 s12, s28, -13
	v_dot2_f32_bf16 v58, v50, v6, 0
	v_dot2_f32_bf16 v50, v52, v4, 0
	v_dot2_f32_bf16 v58, v54, v10, v58
	v_readlane_b32 s12, v46, s12
	v_dot2_f32_bf16 v50, v56, v8, v50
	v_cvt_scalef32_pk_bf16_fp4 v52, v73, 1.0
	v_cvt_scalef32_pk_bf16_fp4 v54, v73, 1.0 op_sel:[1,0,0]
	v_cvt_scalef32_pk_bf16_fp4 v56, v73, 1.0 op_sel:[0,1,0]
	v_cvt_scalef32_pk_bf16_fp4 v60, v73, 1.0 op_sel:[1,1,0]
	s_lshr_b32 s12, s12, 7
	v_dot2_f32_bf16 v58, v52, v14, v58
	v_dot2_f32_bf16 v50, v54, v12, v50
	s_mov_b32 s13, s86
	v_dot2_f32_bf16 v58, v56, v18, v58
	v_dot2_f32_bf16 v50, v60, v16, v50
	v_cvt_scalef32_pk_bf16_fp4 v52, v74, 1.0
	v_cvt_scalef32_pk_bf16_fp4 v54, v74, 1.0 op_sel:[1,0,0]
	v_cvt_scalef32_pk_bf16_fp4 v56, v74, 1.0 op_sel:[0,1,0]
	v_cvt_scalef32_pk_bf16_fp4 v60, v74, 1.0 op_sel:[1,1,0]
	s_lshl_b64 s[12:13], s[12:13], 10
	v_dot2_f32_bf16 v58, v52, v22, v58
	v_dot2_f32_bf16 v50, v54, v20, v50
	v_dot2_f32_bf16 v58, v56, v26, v58
	v_dot2_f32_bf16 v50, v60, v24, v50
	v_cvt_scalef32_pk_bf16_fp4 v52, v75, 1.0
	v_cvt_scalef32_pk_bf16_fp4 v54, v75, 1.0 op_sel:[1,0,0]
	v_cvt_scalef32_pk_bf16_fp4 v56, v75, 1.0 op_sel:[0,1,0]
	v_cvt_scalef32_pk_bf16_fp4 v60, v75, 1.0 op_sel:[1,1,0]
	v_dot2_f32_bf16 v58, v52, v30, v58
	v_dot2_f32_bf16 v50, v54, v28, v50
	v_dot2_f32_bf16 v58, v56, v36, v58
	v_dot2_f32_bf16 v50, v60, v34, v50
	s_nop 2
	v_add_f32_e32 v49, v58, v50
	s_add_u32 s12, s12, s100
	s_addc_u32 s13, s13, s101
	global_load_dwordx4 v[72:75], v207, s[12:13]
	s_waitcnt vmcnt(15)
; #define P4_FOR16(M) M(0) M(1) M(2) M(3) M(4) M(5) M(6) M(7) M(8) M(9) M(10) M(11) M(12) M(13) M(14) M(15)
; #define P4_U(i) { P4_DOT(b##i, part[i]); const int nk_ = __builtin_amdgcn_readlane(ksel, nb + i); P4_LOAD(b##i, Ug, nk_); }
; #define P4_U(i) { P4_DOT(b##i, part[i]); const int nk_ = __builtin_amdgcn_readlane(kn, i); P4_LOAD(b##i, nbase, nk_); }
; __device__ __forceinline__ void peer_gather_f4p(const float* X, const int* __restrict__ IDX, const float* __restrict__ G, ...
;     ...
; #pragma unroll 1
;         for (int bt = 0; bt < 7; ++bt) {
;             const int ksel = (bt + 1 < 4) ? k0 : k1;
;             const int nb = (16 * (bt + 1)) & 63;
;     ...
;             P4_FOR16(P4_U)
;     ...
;             P4_RED(bt);
;         }
	v_cvt_scalef32_pk_bf16_fp4 v50, v76, 1.0
	v_cvt_scalef32_pk_bf16_fp4 v52, v76, 1.0 op_sel:[1,0,0]
	v_cvt_scalef32_pk_bf16_fp4 v54, v76, 1.0 op_sel:[0,1,0]
	v_cvt_scalef32_pk_bf16_fp4 v56, v76, 1.0 op_sel:[1,1,0]
	v_dot2_f32_bf16 v58, v50, v6, 0
	v_dot2_f32_bf16 v50, v52, v4, 0
	v_dot2_f32_bf16 v58, v54, v10, v58
	s_add_i32 s12, s28, -12
	v_dot2_f32_bf16 v50, v56, v8, v50
	v_cvt_scalef32_pk_bf16_fp4 v52, v77, 1.0
	v_cvt_scalef32_pk_bf16_fp4 v54, v77, 1.0 op_sel:[1,0,0]
	v_cvt_scalef32_pk_bf16_fp4 v56, v77, 1.0 op_sel:[0,1,0]
	v_cvt_scalef32_pk_bf16_fp4 v60, v77, 1.0 op_sel:[1,1,0]
	v_readlane_b32 s12, v46, s12
	v_dot2_f32_bf16 v58, v52, v14, v58
	v_dot2_f32_bf16 v50, v54, v12, v50
	s_lshr_b32 s12, s12, 7
	v_dot2_f32_bf16 v58, v56, v18, v58
	v_dot2_f32_bf16 v50, v60, v16, v50
	v_cvt_scalef32_pk_bf16_fp4 v52, v78, 1.0
	v_cvt_scalef32_pk_bf16_fp4 v54, v78, 1.0 op_sel:[1,0,0]
	v_cvt_scalef32_pk_bf16_fp4 v56, v78, 1.0 op_sel:[0,1,0]
	v_cvt_scalef32_pk_bf16_fp4 v60, v78, 1.0 op_sel:[1,1,0]
	s_mov_b32 s13, s86
	v_dot2_f32_bf16 v58, v52, v22, v58
	v_dot2_f32_bf16 v50, v54, v20, v50
	s_lshl_b64 s[12:13], s[12:13], 10
	v_dot2_f32_bf16 v58, v56, v26, v58
	v_dot2_f32_bf16 v50, v60, v24, v50
	v_cvt_scalef32_pk_bf16_fp4 v52, v79, 1.0
	v_cvt_scalef32_pk_bf16_fp4 v54, v79, 1.0 op_sel:[1,0,0]
	v_cvt_scalef32_pk_bf16_fp4 v56, v79, 1.0 op_sel:[0,1,0]
	v_cvt_scalef32_pk_bf16_fp4 v60, v79, 1.0 op_sel:[1,1,0]
	v_dot2_f32_bf16 v58, v52, v30, v58
	v_dot2_f32_bf16 v50, v54, v28, v50
	v_dot2_f32_bf16 v58, v56, v36, v58
	v_dot2_f32_bf16 v50, v60, v34, v50
	s_nop 2
	v_add_f32_e32 v50, v58, v50
	s_add_u32 s12, s12, s100
	s_addc_u32 s13, s13, s101
	global_load_dwordx4 v[76:79], v207, s[12:13]
	s_waitcnt vmcnt(15)
	v_cvt_scalef32_pk_bf16_fp4 v52, v84, 1.0
	v_cvt_scalef32_pk_bf16_fp4 v54, v84, 1.0 op_sel:[1,0,0]
	v_cvt_scalef32_pk_bf16_fp4 v56, v84, 1.0 op_sel:[0,1,0]
	v_cvt_scalef32_pk_bf16_fp4 v58, v84, 1.0 op_sel:[1,1,0]
	s_add_i32 s12, s28, -11
	v_dot2_f32_bf16 v60, v52, v6, 0
	v_dot2_f32_bf16 v52, v54, v4, 0
	v_dot2_f32_bf16 v60, v56, v10, v60
	v_readlane_b32 s12, v46, s12
	v_dot2_f32_bf16 v52, v58, v8, v52
	v_cvt_scalef32_pk_bf16_fp4 v54, v85, 1.0
	v_cvt_scalef32_pk_bf16_fp4 v56, v85, 1.0 op_sel:[1,0,0]
	v_cvt_scalef32_pk_bf16_fp4 v58, v85, 1.0 op_sel:[0,1,0]
	v_cvt_scalef32_pk_bf16_fp4 v62, v85, 1.0 op_sel:[1,1,0]
	s_lshr_b32 s12, s12, 7
	v_dot2_f32_bf16 v60, v54, v14, v60
	v_dot2_f32_bf16 v52, v56, v12, v52
	s_mov_b32 s13, s86
	v_dot2_f32_bf16 v60, v58, v18, v60
	v_dot2_f32_bf16 v52, v62, v16, v52
	v_cvt_scalef32_pk_bf16_fp4 v54, v86, 1.0
	v_cvt_scalef32_pk_bf16_fp4 v56, v86, 1.0 op_sel:[1,0,0]
	v_cvt_scalef32_pk_bf16_fp4 v58, v86, 1.0 op_sel:[0,1,0]
	v_cvt_scalef32_pk_bf16_fp4 v62, v86, 1.0 op_sel:[1,1,0]
	s_lshl_b64 s[12:13], s[12:13], 10
	v_dot2_f32_bf16 v60, v54, v22, v60
	v_dot2_f32_bf16 v52, v56, v20, v52
	v_dot2_f32_bf16 v60, v58, v26, v60
	v_dot2_f32_bf16 v52, v62, v24, v52
	v_cvt_scalef32_pk_bf16_fp4 v54, v87, 1.0
	v_cvt_scalef32_pk_bf16_fp4 v56, v87, 1.0 op_sel:[1,0,0]
	v_cvt_scalef32_pk_bf16_fp4 v58, v87, 1.0 op_sel:[0,1,0]
	v_cvt_scalef32_pk_bf16_fp4 v62, v87, 1.0 op_sel:[1,1,0]
	v_dot2_f32_bf16 v60, v54, v30, v60
	v_dot2_f32_bf16 v52, v56, v28, v52
	v_dot2_f32_bf16 v60, v58, v36, v60
	v_dot2_f32_bf16 v52, v62, v34, v52
	s_nop 2
	v_add_f32_e32 v51, v60, v52
	s_add_u32 s12, s12, s100
	s_addc_u32 s13, s13, s101
	global_load_dwordx4 v[84:87], v207, s[12:13]
	s_waitcnt vmcnt(15)
	v_cvt_scalef32_pk_bf16_fp4 v52, v88, 1.0
	v_cvt_scalef32_pk_bf16_fp4 v54, v88, 1.0 op_sel:[1,0,0]
	v_cvt_scalef32_pk_bf16_fp4 v56, v88, 1.0 op_sel:[0,1,0]
	v_cvt_scalef32_pk_bf16_fp4 v58, v88, 1.0 op_sel:[1,1,0]
	v_dot2_f32_bf16 v60, v52, v6, 0
	v_dot2_f32_bf16 v52, v54, v4, 0
	v_dot2_f32_bf16 v60, v56, v10, v60
	s_add_i32 s12, s28, -10
	v_dot2_f32_bf16 v52, v58, v8, v52
	v_cvt_scalef32_pk_bf16_fp4 v54, v89, 1.0
	v_cvt_scalef32_pk_bf16_fp4 v56, v89, 1.0 op_sel:[1,0,0]
	v_cvt_scalef32_pk_bf16_fp4 v58, v89, 1.0 op_sel:[0,1,0]
	v_cvt_scalef32_pk_bf16_fp4 v62, v89, 1.0 op_sel:[1,1,0]
	v_readlane_b32 s12, v46, s12
	v_dot2_f32_bf16 v60, v54, v14, v60
	v_dot2_f32_bf16 v52, v56, v12, v52
	s_lshr_b32 s12, s12, 7
	v_dot2_f32_bf16 v60, v58, v18, v60
	v_dot2_f32_bf16 v52, v62, v16, v52
	v_cvt_scalef32_pk_bf16_fp4 v54, v90, 1.0
	v_cvt_scalef32_pk_bf16_fp4 v56, v90, 1.0 op_sel:[1,0,0]
	v_cvt_scalef32_pk_bf16_fp4 v58, v90, 1.0 op_sel:[0,1,0]
	v_cvt_scalef32_pk_bf16_fp4 v62, v90, 1.0 op_sel:[1,1,0]
	s_mov_b32 s13, s86
	v_dot2_f32_bf16 v60, v54, v22, v60
	v_dot2_f32_bf16 v52, v56, v20, v52
	s_lshl_b64 s[12:13], s[12:13], 10
	v_dot2_f32_bf16 v60, v58, v26, v60
	v_dot2_f32_bf16 v52, v62, v24, v52
	v_cvt_scalef32_pk_bf16_fp4 v54, v91, 1.0
	v_cvt_scalef32_pk_bf16_fp4 v56, v91, 1.0 op_sel:[1,0,0]
	v_cvt_scalef32_pk_bf16_fp4 v58, v91, 1.0 op_sel:[0,1,0]
	v_cvt_scalef32_pk_bf16_fp4 v62, v91, 1.0 op_sel:[1,1,0]
	v_dot2_f32_bf16 v60, v54, v30, v60
	v_dot2_f32_bf16 v52, v56, v28, v52
	v_dot2_f32_bf16 v60, v58, v36, v60
	v_dot2_f32_bf16 v52, v62, v34, v52
	s_nop 2
	v_add_f32_e32 v52, v60, v52
	s_add_u32 s12, s12, s100
	s_addc_u32 s13, s13, s101
	global_load_dwordx4 v[88:91], v207, s[12:13]
	s_waitcnt vmcnt(15)
; #define P4_FOR16(M) M(0) M(1) M(2) M(3) M(4) M(5) M(6) M(7) M(8) M(9) M(10) M(11) M(12) M(13) M(14) M(15)
; #define P4_U(i) { P4_DOT(b##i, part[i]); const int nk_ = __builtin_amdgcn_readlane(ksel, nb + i); P4_LOAD(b##i, Ug, nk_); }
; #define P4_U(i) { P4_DOT(b##i, part[i]); const int nk_ = __builtin_amdgcn_readlane(kn, i); P4_LOAD(b##i, nbase, nk_); }
; __device__ __forceinline__ void peer_gather_f4p(const float* X, const int* __restrict__ IDX, const float* __restrict__ G, ...
;     ...
; #pragma unroll 1
;         for (int bt = 0; bt < 7; ++bt) {
;             const int ksel = (bt + 1 < 4) ? k0 : k1;
;             const int nb = (16 * (bt + 1)) & 63;
;     ...
;             P4_FOR16(P4_U)
;     ...
;             P4_RED(bt);
;         }
	v_cvt_scalef32_pk_bf16_fp4 v54, v92, 1.0
	v_cvt_scalef32_pk_bf16_fp4 v56, v92, 1.0 op_sel:[1,0,0]
	v_cvt_scalef32_pk_bf16_fp4 v58, v92, 1.0 op_sel:[0,1,0]
	v_cvt_scalef32_pk_bf16_fp4 v60, v92, 1.0 op_sel:[1,1,0]
	s_add_i32 s12, s28, -9
	v_dot2_f32_bf16 v62, v54, v6, 0
	v_dot2_f32_bf16 v54, v56, v4, 0
	v_dot2_f32_bf16 v62, v58, v10, v62
	v_readlane_b32 s12, v46, s12
	v_dot2_f32_bf16 v54, v60, v8, v54
	v_cvt_scalef32_pk_bf16_fp4 v56, v93, 1.0
	v_cvt_scalef32_pk_bf16_fp4 v58, v93, 1.0 op_sel:[1,0,0]
	v_cvt_scalef32_pk_bf16_fp4 v60, v93, 1.0 op_sel:[0,1,0]
	v_cvt_scalef32_pk_bf16_fp4 v80, v93, 1.0 op_sel:[1,1,0]
	s_lshr_b32 s12, s12, 7
	v_dot2_f32_bf16 v62, v56, v14, v62
	v_dot2_f32_bf16 v54, v58, v12, v54
	s_mov_b32 s13, s86
	v_dot2_f32_bf16 v62, v60, v18, v62
	v_dot2_f32_bf16 v54, v80, v16, v54
	v_cvt_scalef32_pk_bf16_fp4 v56, v94, 1.0
	v_cvt_scalef32_pk_bf16_fp4 v58, v94, 1.0 op_sel:[1,0,0]
	v_cvt_scalef32_pk_bf16_fp4 v60, v94, 1.0 op_sel:[0,1,0]
	v_cvt_scalef32_pk_bf16_fp4 v80, v94, 1.0 op_sel:[1,1,0]
	s_lshl_b64 s[12:13], s[12:13], 10
	v_dot2_f32_bf16 v62, v56, v22, v62
	v_dot2_f32_bf16 v54, v58, v20, v54
	v_dot2_f32_bf16 v62, v60, v26, v62
	v_dot2_f32_bf16 v54, v80, v24, v54
	v_cvt_scalef32_pk_bf16_fp4 v56, v95, 1.0
	v_cvt_scalef32_pk_bf16_fp4 v58, v95, 1.0 op_sel:[1,0,0]
	v_cvt_scalef32_pk_bf16_fp4 v60, v95, 1.0 op_sel:[0,1,0]
	v_cvt_scalef32_pk_bf16_fp4 v80, v95, 1.0 op_sel:[1,1,0]
	v_dot2_f32_bf16 v62, v56, v30, v62
	v_dot2_f32_bf16 v54, v58, v28, v54
	v_dot2_f32_bf16 v62, v60, v36, v62
	v_dot2_f32_bf16 v54, v80, v34, v54
	s_nop 2
	v_add_f32_e32 v53, v62, v54
	s_add_u32 s12, s12, s100
	s_addc_u32 s13, s13, s101
	global_load_dwordx4 v[92:95], v207, s[12:13]
	s_waitcnt vmcnt(15)
	v_cvt_scalef32_pk_bf16_fp4 v54, v96, 1.0
	v_cvt_scalef32_pk_bf16_fp4 v56, v96, 1.0 op_sel:[1,0,0]
	v_cvt_scalef32_pk_bf16_fp4 v58, v96, 1.0 op_sel:[0,1,0]
	v_cvt_scalef32_pk_bf16_fp4 v60, v96, 1.0 op_sel:[1,1,0]
	v_dot2_f32_bf16 v62, v54, v6, 0
	v_dot2_f32_bf16 v54, v56, v4, 0
	v_dot2_f32_bf16 v62, v58, v10, v62
	s_add_i32 s12, s28, -8
	v_dot2_f32_bf16 v54, v60, v8, v54
	v_cvt_scalef32_pk_bf16_fp4 v56, v97, 1.0
	v_cvt_scalef32_pk_bf16_fp4 v58, v97, 1.0 op_sel:[1,0,0]
	v_cvt_scalef32_pk_bf16_fp4 v60, v97, 1.0 op_sel:[0,1,0]
	v_cvt_scalef32_pk_bf16_fp4 v80, v97, 1.0 op_sel:[1,1,0]
	v_readlane_b32 s12, v46, s12
	v_dot2_f32_bf16 v62, v56, v14, v62
	v_dot2_f32_bf16 v54, v58, v12, v54
	s_lshr_b32 s12, s12, 7
	v_dot2_f32_bf16 v62, v60, v18, v62
	v_dot2_f32_bf16 v54, v80, v16, v54
	v_cvt_scalef32_pk_bf16_fp4 v56, v98, 1.0
	v_cvt_scalef32_pk_bf16_fp4 v58, v98, 1.0 op_sel:[1,0,0]
	v_cvt_scalef32_pk_bf16_fp4 v60, v98, 1.0 op_sel:[0,1,0]
	v_cvt_scalef32_pk_bf16_fp4 v80, v98, 1.0 op_sel:[1,1,0]
	s_mov_b32 s13, s86
	v_dot2_f32_bf16 v62, v56, v22, v62
	v_dot2_f32_bf16 v54, v58, v20, v54
	s_lshl_b64 s[12:13], s[12:13], 10
	v_dot2_f32_bf16 v62, v60, v26, v62
	v_dot2_f32_bf16 v54, v80, v24, v54
	v_cvt_scalef32_pk_bf16_fp4 v56, v99, 1.0
	v_cvt_scalef32_pk_bf16_fp4 v58, v99, 1.0 op_sel:[1,0,0]
	v_cvt_scalef32_pk_bf16_fp4 v60, v99, 1.0 op_sel:[0,1,0]
	v_cvt_scalef32_pk_bf16_fp4 v80, v99, 1.0 op_sel:[1,1,0]
	v_dot2_f32_bf16 v62, v56, v30, v62
	v_dot2_f32_bf16 v54, v58, v28, v54
	v_dot2_f32_bf16 v62, v60, v36, v62
	v_dot2_f32_bf16 v54, v80, v34, v54
	s_nop 2
	v_add_f32_e32 v54, v62, v54
	s_add_u32 s12, s12, s100
	s_addc_u32 s13, s13, s101
	global_load_dwordx4 v[96:99], v207, s[12:13]
	s_waitcnt vmcnt(15)
	v_cvt_scalef32_pk_bf16_fp4 v56, v100, 1.0
	v_cvt_scalef32_pk_bf16_fp4 v58, v100, 1.0 op_sel:[1,0,0]
	v_cvt_scalef32_pk_bf16_fp4 v60, v100, 1.0 op_sel:[0,1,0]
	v_cvt_scalef32_pk_bf16_fp4 v62, v100, 1.0 op_sel:[1,1,0]
	s_add_i32 s12, s28, -7
	v_dot2_f32_bf16 v80, v56, v6, 0
	v_dot2_f32_bf16 v56, v58, v4, 0
	v_dot2_f32_bf16 v80, v60, v10, v80
	v_readlane_b32 s12, v46, s12
	v_dot2_f32_bf16 v56, v62, v8, v56
	v_cvt_scalef32_pk_bf16_fp4 v58, v101, 1.0
	v_cvt_scalef32_pk_bf16_fp4 v60, v101, 1.0 op_sel:[1,0,0]
	v_cvt_scalef32_pk_bf16_fp4 v62, v101, 1.0 op_sel:[0,1,0]
	v_cvt_scalef32_pk_bf16_fp4 v82, v101, 1.0 op_sel:[1,1,0]
	s_lshr_b32 s12, s12, 7
	v_dot2_f32_bf16 v80, v58, v14, v80
	v_dot2_f32_bf16 v56, v60, v12, v56
	s_mov_b32 s13, s86
	v_dot2_f32_bf16 v80, v62, v18, v80
	v_dot2_f32_bf16 v56, v82, v16, v56
	v_cvt_scalef32_pk_bf16_fp4 v58, v102, 1.0
	v_cvt_scalef32_pk_bf16_fp4 v60, v102, 1.0 op_sel:[1,0,0]
	v_cvt_scalef32_pk_bf16_fp4 v62, v102, 1.0 op_sel:[0,1,0]
	v_cvt_scalef32_pk_bf16_fp4 v82, v102, 1.0 op_sel:[1,1,0]
	s_lshl_b64 s[12:13], s[12:13], 10
	v_dot2_f32_bf16 v80, v58, v22, v80
	v_dot2_f32_bf16 v56, v60, v20, v56
	v_dot2_f32_bf16 v80, v62, v26, v80
	v_dot2_f32_bf16 v56, v82, v24, v56
	v_cvt_scalef32_pk_bf16_fp4 v58, v103, 1.0
	v_cvt_scalef32_pk_bf16_fp4 v60, v103, 1.0 op_sel:[1,0,0]
	v_cvt_scalef32_pk_bf16_fp4 v62, v103, 1.0 op_sel:[0,1,0]
	v_cvt_scalef32_pk_bf16_fp4 v82, v103, 1.0 op_sel:[1,1,0]
	v_dot2_f32_bf16 v80, v58, v30, v80
	v_dot2_f32_bf16 v56, v60, v28, v56
	v_dot2_f32_bf16 v80, v62, v36, v80
	v_dot2_f32_bf16 v56, v82, v34, v56
	s_nop 2
	v_add_f32_e32 v55, v80, v56
	s_add_u32 s12, s12, s100
	s_addc_u32 s13, s13, s101
	global_load_dwordx4 v[100:103], v207, s[12:13]
	s_waitcnt vmcnt(15)
; #define P4_FOR16(M) M(0) M(1) M(2) M(3) M(4) M(5) M(6) M(7) M(8) M(9) M(10) M(11) M(12) M(13) M(14) M(15)
; #define P4_U(i) { P4_DOT(b##i, part[i]); const int nk_ = __builtin_amdgcn_readlane(ksel, nb + i); P4_LOAD(b##i, Ug, nk_); }
; #define P4_U(i) { P4_DOT(b##i, part[i]); const int nk_ = __builtin_amdgcn_readlane(kn, i); P4_LOAD(b##i, nbase, nk_); }
; __device__ __forceinline__ void peer_gather_f4p(const float* X, const int* __restrict__ IDX, const float* __restrict__ G, ...
;     ...
; #pragma unroll 1
;         for (int bt = 0; bt < 7; ++bt) {
;             const int ksel = (bt + 1 < 4) ? k0 : k1;
;             const int nb = (16 * (bt + 1)) & 63;
;     ...
;             P4_FOR16(P4_U)
;     ...
;             P4_RED(bt);
;         }
	v_cvt_scalef32_pk_bf16_fp4 v56, v104, 1.0
	v_cvt_scalef32_pk_bf16_fp4 v58, v104, 1.0 op_sel:[1,0,0]
	v_cvt_scalef32_pk_bf16_fp4 v60, v104, 1.0 op_sel:[0,1,0]
	v_cvt_scalef32_pk_bf16_fp4 v62, v104, 1.0 op_sel:[1,1,0]
	v_dot2_f32_bf16 v80, v56, v6, 0
	v_dot2_f32_bf16 v56, v58, v4, 0
	v_dot2_f32_bf16 v80, v60, v10, v80
	s_add_i32 s12, s28, -6
	v_dot2_f32_bf16 v56, v62, v8, v56
	v_cvt_scalef32_pk_bf16_fp4 v58, v105, 1.0
	v_cvt_scalef32_pk_bf16_fp4 v60, v105, 1.0 op_sel:[1,0,0]
	v_cvt_scalef32_pk_bf16_fp4 v62, v105, 1.0 op_sel:[0,1,0]
	v_cvt_scalef32_pk_bf16_fp4 v82, v105, 1.0 op_sel:[1,1,0]
	v_readlane_b32 s12, v46, s12
	v_dot2_f32_bf16 v80, v58, v14, v80
	v_dot2_f32_bf16 v56, v60, v12, v56
	s_lshr_b32 s12, s12, 7
	v_dot2_f32_bf16 v80, v62, v18, v80
	v_dot2_f32_bf16 v56, v82, v16, v56
	v_cvt_scalef32_pk_bf16_fp4 v58, v106, 1.0
	v_cvt_scalef32_pk_bf16_fp4 v60, v106, 1.0 op_sel:[1,0,0]
	v_cvt_scalef32_pk_bf16_fp4 v62, v106, 1.0 op_sel:[0,1,0]
	v_cvt_scalef32_pk_bf16_fp4 v82, v106, 1.0 op_sel:[1,1,0]
	s_mov_b32 s13, s86
	v_dot2_f32_bf16 v80, v58, v22, v80
	v_dot2_f32_bf16 v56, v60, v20, v56
	s_lshl_b64 s[12:13], s[12:13], 10
	v_dot2_f32_bf16 v80, v62, v26, v80
	v_dot2_f32_bf16 v56, v82, v24, v56
	v_cvt_scalef32_pk_bf16_fp4 v58, v107, 1.0
	v_cvt_scalef32_pk_bf16_fp4 v60, v107, 1.0 op_sel:[1,0,0]
	v_cvt_scalef32_pk_bf16_fp4 v62, v107, 1.0 op_sel:[0,1,0]
	v_cvt_scalef32_pk_bf16_fp4 v82, v107, 1.0 op_sel:[1,1,0]
	v_dot2_f32_bf16 v80, v58, v30, v80
	v_dot2_f32_bf16 v56, v60, v28, v56
	v_dot2_f32_bf16 v80, v62, v36, v80
	v_dot2_f32_bf16 v56, v82, v34, v56
	s_nop 2
	v_add_f32_e32 v56, v80, v56
	s_add_u32 s12, s12, s100
	s_addc_u32 s13, s13, s101
	global_load_dwordx4 v[104:107], v207, s[12:13]
	s_waitcnt vmcnt(15)
	v_cvt_scalef32_pk_bf16_fp4 v58, v108, 1.0
	v_cvt_scalef32_pk_bf16_fp4 v60, v108, 1.0 op_sel:[1,0,0]
	v_cvt_scalef32_pk_bf16_fp4 v62, v108, 1.0 op_sel:[0,1,0]
	v_cvt_scalef32_pk_bf16_fp4 v80, v108, 1.0 op_sel:[1,1,0]
	s_add_i32 s12, s28, -5
	v_dot2_f32_bf16 v82, v58, v6, 0
	v_dot2_f32_bf16 v58, v60, v4, 0
	v_dot2_f32_bf16 v82, v62, v10, v82
	v_readlane_b32 s12, v46, s12
	v_dot2_f32_bf16 v58, v80, v8, v58
	v_cvt_scalef32_pk_bf16_fp4 v60, v109, 1.0
	v_cvt_scalef32_pk_bf16_fp4 v62, v109, 1.0 op_sel:[1,0,0]
	v_cvt_scalef32_pk_bf16_fp4 v80, v109, 1.0 op_sel:[0,1,0]
	v_cvt_scalef32_pk_bf16_fp4 v108, v109, 1.0 op_sel:[1,1,0]
	s_lshr_b32 s12, s12, 7
	v_dot2_f32_bf16 v82, v60, v14, v82
	v_dot2_f32_bf16 v58, v62, v12, v58
	s_mov_b32 s13, s86
	v_dot2_f32_bf16 v82, v80, v18, v82
	v_dot2_f32_bf16 v58, v108, v16, v58
	v_cvt_scalef32_pk_bf16_fp4 v60, v110, 1.0
	v_cvt_scalef32_pk_bf16_fp4 v62, v110, 1.0 op_sel:[1,0,0]
	v_cvt_scalef32_pk_bf16_fp4 v80, v110, 1.0 op_sel:[0,1,0]
	v_cvt_scalef32_pk_bf16_fp4 v108, v110, 1.0 op_sel:[1,1,0]
	s_lshl_b64 s[12:13], s[12:13], 10
	v_dot2_f32_bf16 v82, v60, v22, v82
	v_dot2_f32_bf16 v58, v62, v20, v58
	v_dot2_f32_bf16 v82, v80, v26, v82
	v_dot2_f32_bf16 v58, v108, v24, v58
	v_cvt_scalef32_pk_bf16_fp4 v60, v111, 1.0
	v_cvt_scalef32_pk_bf16_fp4 v62, v111, 1.0 op_sel:[1,0,0]
	v_cvt_scalef32_pk_bf16_fp4 v80, v111, 1.0 op_sel:[0,1,0]
	v_cvt_scalef32_pk_bf16_fp4 v108, v111, 1.0 op_sel:[1,1,0]
	v_dot2_f32_bf16 v82, v60, v30, v82
	v_dot2_f32_bf16 v58, v62, v28, v58
	v_dot2_f32_bf16 v82, v80, v36, v82
	v_dot2_f32_bf16 v58, v108, v34, v58
	s_nop 2
	v_add_f32_e32 v57, v82, v58
	s_add_u32 s12, s12, s100
	s_addc_u32 s13, s13, s101
	global_load_dwordx4 v[108:111], v207, s[12:13]
	s_waitcnt vmcnt(15)
	v_cvt_scalef32_pk_bf16_fp4 v58, v112, 1.0
	v_cvt_scalef32_pk_bf16_fp4 v60, v112, 1.0 op_sel:[1,0,0]
	v_cvt_scalef32_pk_bf16_fp4 v62, v112, 1.0 op_sel:[0,1,0]
	v_cvt_scalef32_pk_bf16_fp4 v80, v112, 1.0 op_sel:[1,1,0]
	v_dot2_f32_bf16 v82, v58, v6, 0
	v_dot2_f32_bf16 v58, v60, v4, 0
	v_dot2_f32_bf16 v82, v62, v10, v82
	s_add_i32 s12, s28, -4
	v_dot2_f32_bf16 v58, v80, v8, v58
	v_cvt_scalef32_pk_bf16_fp4 v60, v113, 1.0
	v_cvt_scalef32_pk_bf16_fp4 v62, v113, 1.0 op_sel:[1,0,0]
	v_cvt_scalef32_pk_bf16_fp4 v80, v113, 1.0 op_sel:[0,1,0]
	v_cvt_scalef32_pk_bf16_fp4 v112, v113, 1.0 op_sel:[1,1,0]
	v_readlane_b32 s12, v46, s12
	v_dot2_f32_bf16 v82, v60, v14, v82
	v_dot2_f32_bf16 v58, v62, v12, v58
	s_lshr_b32 s12, s12, 7
	v_dot2_f32_bf16 v82, v80, v18, v82
	v_dot2_f32_bf16 v58, v112, v16, v58
	v_cvt_scalef32_pk_bf16_fp4 v60, v114, 1.0
	v_cvt_scalef32_pk_bf16_fp4 v62, v114, 1.0 op_sel:[1,0,0]
	v_cvt_scalef32_pk_bf16_fp4 v80, v114, 1.0 op_sel:[0,1,0]
	v_cvt_scalef32_pk_bf16_fp4 v112, v114, 1.0 op_sel:[1,1,0]
	s_mov_b32 s13, s86
	v_dot2_f32_bf16 v82, v60, v22, v82
	v_dot2_f32_bf16 v58, v62, v20, v58
	s_lshl_b64 s[12:13], s[12:13], 10
	v_dot2_f32_bf16 v82, v80, v26, v82
	v_dot2_f32_bf16 v58, v112, v24, v58
	v_cvt_scalef32_pk_bf16_fp4 v60, v115, 1.0
	v_cvt_scalef32_pk_bf16_fp4 v62, v115, 1.0 op_sel:[1,0,0]
	v_cvt_scalef32_pk_bf16_fp4 v80, v115, 1.0 op_sel:[0,1,0]
	v_cvt_scalef32_pk_bf16_fp4 v112, v115, 1.0 op_sel:[1,1,0]
	v_dot2_f32_bf16 v82, v60, v30, v82
	v_dot2_f32_bf16 v58, v62, v28, v58
	v_dot2_f32_bf16 v82, v80, v36, v82
	v_dot2_f32_bf16 v58, v112, v34, v58
	s_nop 2
	v_add_f32_e32 v132, v82, v58
	s_add_u32 s12, s12, s100
	s_addc_u32 s13, s13, s101
	global_load_dwordx4 v[112:115], v207, s[12:13]
	s_waitcnt vmcnt(15)
; #define P4_FOR16(M) M(0) M(1) M(2) M(3) M(4) M(5) M(6) M(7) M(8) M(9) M(10) M(11) M(12) M(13) M(14) M(15)
; #define P4_U(i) { P4_DOT(b##i, part[i]); const int nk_ = __builtin_amdgcn_readlane(ksel, nb + i); P4_LOAD(b##i, Ug, nk_); }
; #define P4_U(i) { P4_DOT(b##i, part[i]); const int nk_ = __builtin_amdgcn_readlane(kn, i); P4_LOAD(b##i, nbase, nk_); }
; __device__ __forceinline__ void peer_gather_f4p(const float* X, const int* __restrict__ IDX, const float* __restrict__ G, ...
;     ...
; #pragma unroll 1
;         for (int bt = 0; bt < 7; ++bt) {
;             const int ksel = (bt + 1 < 4) ? k0 : k1;
;             const int nb = (16 * (bt + 1)) & 63;
;     ...
;             P4_FOR16(P4_U)
;     ...
;             P4_RED(bt);
;         }
	v_cvt_scalef32_pk_bf16_fp4 v58, v116, 1.0
	v_cvt_scalef32_pk_bf16_fp4 v60, v116, 1.0 op_sel:[1,0,0]
	v_cvt_scalef32_pk_bf16_fp4 v62, v116, 1.0 op_sel:[0,1,0]
	v_cvt_scalef32_pk_bf16_fp4 v80, v116, 1.0 op_sel:[1,1,0]
	v_dot2_f32_bf16 v82, v58, v6, 0
	v_dot2_f32_bf16 v58, v60, v4, 0
	v_dot2_f32_bf16 v82, v62, v10, v82
	s_add_i32 s12, s28, -3
	v_dot2_f32_bf16 v58, v80, v8, v58
	v_cvt_scalef32_pk_bf16_fp4 v60, v117, 1.0
	v_cvt_scalef32_pk_bf16_fp4 v62, v117, 1.0 op_sel:[1,0,0]
	v_cvt_scalef32_pk_bf16_fp4 v80, v117, 1.0 op_sel:[0,1,0]
	v_cvt_scalef32_pk_bf16_fp4 v116, v117, 1.0 op_sel:[1,1,0]
	v_readlane_b32 s12, v46, s12
	v_dot2_f32_bf16 v82, v60, v14, v82
	v_dot2_f32_bf16 v58, v62, v12, v58
	s_lshr_b32 s12, s12, 7
	v_dot2_f32_bf16 v82, v80, v18, v82
	v_dot2_f32_bf16 v58, v116, v16, v58
	v_cvt_scalef32_pk_bf16_fp4 v60, v118, 1.0
	v_cvt_scalef32_pk_bf16_fp4 v62, v118, 1.0 op_sel:[1,0,0]
	v_cvt_scalef32_pk_bf16_fp4 v80, v118, 1.0 op_sel:[0,1,0]
	v_cvt_scalef32_pk_bf16_fp4 v116, v118, 1.0 op_sel:[1,1,0]
	s_mov_b32 s13, s86
	v_dot2_f32_bf16 v82, v60, v22, v82
	v_dot2_f32_bf16 v58, v62, v20, v58
	s_lshl_b64 s[12:13], s[12:13], 10
	v_dot2_f32_bf16 v82, v80, v26, v82
	v_dot2_f32_bf16 v58, v116, v24, v58
	v_cvt_scalef32_pk_bf16_fp4 v60, v119, 1.0
	v_cvt_scalef32_pk_bf16_fp4 v62, v119, 1.0 op_sel:[1,0,0]
	v_cvt_scalef32_pk_bf16_fp4 v80, v119, 1.0 op_sel:[0,1,0]
	v_cvt_scalef32_pk_bf16_fp4 v116, v119, 1.0 op_sel:[1,1,0]
	v_dot2_f32_bf16 v82, v60, v30, v82
	v_dot2_f32_bf16 v58, v62, v28, v58
	v_dot2_f32_bf16 v82, v80, v36, v82
	v_dot2_f32_bf16 v58, v116, v34, v58
	s_nop 2
	v_add_f32_e32 v133, v82, v58
	s_add_u32 s12, s12, s100
	s_addc_u32 s13, s13, s101
	global_load_dwordx4 v[116:119], v207, s[12:13]
	s_waitcnt vmcnt(15)
	v_cvt_scalef32_pk_bf16_fp4 v58, v120, 1.0
	v_cvt_scalef32_pk_bf16_fp4 v60, v120, 1.0 op_sel:[1,0,0]
	v_cvt_scalef32_pk_bf16_fp4 v62, v120, 1.0 op_sel:[0,1,0]
	v_cvt_scalef32_pk_bf16_fp4 v80, v120, 1.0 op_sel:[1,1,0]
	v_dot2_f32_bf16 v82, v58, v6, 0
	v_dot2_f32_bf16 v58, v60, v4, 0
	v_dot2_f32_bf16 v82, v62, v10, v82
	s_add_i32 s12, s28, -2
	v_dot2_f32_bf16 v58, v80, v8, v58
	v_cvt_scalef32_pk_bf16_fp4 v60, v121, 1.0
	v_cvt_scalef32_pk_bf16_fp4 v62, v121, 1.0 op_sel:[1,0,0]
	v_cvt_scalef32_pk_bf16_fp4 v80, v121, 1.0 op_sel:[0,1,0]
	v_cvt_scalef32_pk_bf16_fp4 v120, v121, 1.0 op_sel:[1,1,0]
	v_readlane_b32 s12, v46, s12
	v_dot2_f32_bf16 v82, v60, v14, v82
	v_dot2_f32_bf16 v58, v62, v12, v58
	s_lshr_b32 s12, s12, 7
	v_dot2_f32_bf16 v82, v80, v18, v82
	v_dot2_f32_bf16 v58, v120, v16, v58
	v_cvt_scalef32_pk_bf16_fp4 v60, v122, 1.0
	v_cvt_scalef32_pk_bf16_fp4 v62, v122, 1.0 op_sel:[1,0,0]
	v_cvt_scalef32_pk_bf16_fp4 v80, v122, 1.0 op_sel:[0,1,0]
	v_cvt_scalef32_pk_bf16_fp4 v120, v122, 1.0 op_sel:[1,1,0]
	s_mov_b32 s13, s86
	v_dot2_f32_bf16 v82, v60, v22, v82
	v_dot2_f32_bf16 v58, v62, v20, v58
	s_lshl_b64 s[12:13], s[12:13], 10
	v_dot2_f32_bf16 v82, v80, v26, v82
	v_dot2_f32_bf16 v58, v120, v24, v58
	v_cvt_scalef32_pk_bf16_fp4 v60, v123, 1.0
	v_cvt_scalef32_pk_bf16_fp4 v62, v123, 1.0 op_sel:[1,0,0]
	v_cvt_scalef32_pk_bf16_fp4 v80, v123, 1.0 op_sel:[0,1,0]
	v_cvt_scalef32_pk_bf16_fp4 v120, v123, 1.0 op_sel:[1,1,0]
	v_dot2_f32_bf16 v82, v60, v30, v82
	v_dot2_f32_bf16 v58, v62, v28, v58
	v_dot2_f32_bf16 v82, v80, v36, v82
	v_dot2_f32_bf16 v58, v120, v34, v58
	s_nop 2
	v_add_f32_e32 v134, v82, v58
	s_add_u32 s12, s12, s100
	s_addc_u32 s13, s13, s101
	global_load_dwordx4 v[120:123], v207, s[12:13]
	s_waitcnt vmcnt(15)
	v_cvt_scalef32_pk_bf16_fp4 v58, v124, 1.0
	v_cvt_scalef32_pk_bf16_fp4 v60, v124, 1.0 op_sel:[1,0,0]
	v_cvt_scalef32_pk_bf16_fp4 v62, v124, 1.0 op_sel:[0,1,0]
	v_cvt_scalef32_pk_bf16_fp4 v80, v124, 1.0 op_sel:[1,1,0]
	v_dot2_f32_bf16 v82, v58, v6, 0
	v_dot2_f32_bf16 v58, v60, v4, 0
	v_dot2_f32_bf16 v82, v62, v10, v82
	s_add_i32 s12, s28, -1
	v_dot2_f32_bf16 v58, v80, v8, v58
	v_cvt_scalef32_pk_bf16_fp4 v60, v125, 1.0
	v_cvt_scalef32_pk_bf16_fp4 v62, v125, 1.0 op_sel:[1,0,0]
	v_cvt_scalef32_pk_bf16_fp4 v80, v125, 1.0 op_sel:[0,1,0]
	v_cvt_scalef32_pk_bf16_fp4 v124, v125, 1.0 op_sel:[1,1,0]
	v_readlane_b32 s12, v46, s12
	v_dot2_f32_bf16 v82, v60, v14, v82
	v_dot2_f32_bf16 v58, v62, v12, v58
	s_lshr_b32 s12, s12, 7
	v_dot2_f32_bf16 v82, v80, v18, v82
	v_dot2_f32_bf16 v58, v124, v16, v58
	v_cvt_scalef32_pk_bf16_fp4 v60, v126, 1.0
	v_cvt_scalef32_pk_bf16_fp4 v62, v126, 1.0 op_sel:[1,0,0]
	v_cvt_scalef32_pk_bf16_fp4 v80, v126, 1.0 op_sel:[0,1,0]
	v_cvt_scalef32_pk_bf16_fp4 v124, v126, 1.0 op_sel:[1,1,0]
	s_mov_b32 s13, s86
	v_dot2_f32_bf16 v82, v60, v22, v82
	v_dot2_f32_bf16 v58, v62, v20, v58
	s_lshl_b64 s[12:13], s[12:13], 10
	v_dot2_f32_bf16 v82, v80, v26, v82
	v_dot2_f32_bf16 v58, v124, v24, v58
	v_cvt_scalef32_pk_bf16_fp4 v60, v127, 1.0
	v_cvt_scalef32_pk_bf16_fp4 v62, v127, 1.0 op_sel:[1,0,0]
	v_cvt_scalef32_pk_bf16_fp4 v80, v127, 1.0 op_sel:[0,1,0]
	v_cvt_scalef32_pk_bf16_fp4 v124, v127, 1.0 op_sel:[1,1,0]
	v_dot2_f32_bf16 v82, v60, v30, v82
	v_dot2_f32_bf16 v58, v62, v28, v58
	v_dot2_f32_bf16 v82, v80, v36, v82
	v_dot2_f32_bf16 v58, v124, v34, v58
	s_nop 2
	v_add_f32_e32 v135, v82, v58
	s_add_u32 s12, s12, s100
	s_addc_u32 s13, s13, s101
	global_load_dwordx4 v[124:127], v207, s[12:13]
	s_waitcnt vmcnt(15)
; #define P4_FOR16(M) M(0) M(1) M(2) M(3) M(4) M(5) M(6) M(7) M(8) M(9) M(10) M(11) M(12) M(13) M(14) M(15)
; #define P4_U(i) { P4_DOT(b##i, part[i]); const int nk_ = __builtin_amdgcn_readlane(ksel, nb + i); P4_LOAD(b##i, Ug, nk_); }
; #define P4_U(i) { P4_DOT(b##i, part[i]); const int nk_ = __builtin_amdgcn_readlane(kn, i); P4_LOAD(b##i, nbase, nk_); }
; __device__ __forceinline__ float gelu_tanh(float h) {
;     return 0.5f * h * (1.f + tanhf(0.7978845608028654f * (h + 0.044715f * h * h * h)));
; }
; __device__ __forceinline__ void peer_gather_f4p(const float* X, const int* __restrict__ IDX, const float* __restrict__ G, ...
;     ...
; #pragma unroll 1
;         for (int bt = 0; bt < 7; ++bt) {
;             const int ksel = (bt + 1 < 4) ? k0 : k1;
;             const int nb = (16 * (bt + 1)) & 63;
;     ...
;             P4_FOR16(P4_U)
;     ...
;             P4_RED(bt);
;         }
	v_cvt_scalef32_pk_bf16_fp4 v58, v128, 1.0
	v_cvt_scalef32_pk_bf16_fp4 v60, v128, 1.0 op_sel:[1,0,0]
	v_cvt_scalef32_pk_bf16_fp4 v62, v128, 1.0 op_sel:[0,1,0]
	v_cvt_scalef32_pk_bf16_fp4 v80, v128, 1.0 op_sel:[1,1,0]
	v_readlane_b32 s12, v46, s28
	v_dot2_f32_bf16 v82, v58, v6, 0
	v_dot2c_f32_bf16_e32 v42, v60, v4
	s_lshr_b32 s12, s12, 7
	v_dot2_f32_bf16 v82, v62, v10, v82
	v_dot2c_f32_bf16_e32 v42, v80, v8
	v_cvt_scalef32_pk_bf16_fp4 v58, v129, 1.0
	v_cvt_scalef32_pk_bf16_fp4 v60, v129, 1.0 op_sel:[1,0,0]
	v_cvt_scalef32_pk_bf16_fp4 v62, v129, 1.0 op_sel:[0,1,0]
	v_cvt_scalef32_pk_bf16_fp4 v80, v129, 1.0 op_sel:[1,1,0]
	s_mov_b32 s13, s86
	v_dot2_f32_bf16 v82, v58, v14, v82
	v_dot2c_f32_bf16_e32 v42, v60, v12
	s_lshl_b64 s[12:13], s[12:13], 10
	v_dot2_f32_bf16 v82, v62, v18, v82
	v_dot2c_f32_bf16_e32 v42, v80, v16
	v_cvt_scalef32_pk_bf16_fp4 v58, v130, 1.0
	v_cvt_scalef32_pk_bf16_fp4 v60, v130, 1.0 op_sel:[1,0,0]
	v_cvt_scalef32_pk_bf16_fp4 v62, v130, 1.0 op_sel:[0,1,0]
	v_cvt_scalef32_pk_bf16_fp4 v80, v130, 1.0 op_sel:[1,1,0]
	v_cndmask_b32_e64 v46, v48, v56, s[46:47]
	v_dot2_f32_bf16 v82, v58, v22, v82
	v_dot2c_f32_bf16_e32 v42, v60, v20
	ds_swizzle_b32 v46, v46 offset:swizzle(SWAP,8)
	v_dot2_f32_bf16 v82, v62, v26, v82
	v_dot2c_f32_bf16_e32 v42, v80, v24
	v_cvt_scalef32_pk_bf16_fp4 v58, v131, 1.0
	v_cvt_scalef32_pk_bf16_fp4 v60, v131, 1.0 op_sel:[1,0,0]
	v_cvt_scalef32_pk_bf16_fp4 v62, v131, 1.0 op_sel:[0,1,0]
	v_cvt_scalef32_pk_bf16_fp4 v80, v131, 1.0 op_sel:[1,1,0]
	v_dot2_f32_bf16 v82, v58, v30, v82
	v_dot2c_f32_bf16_e32 v42, v60, v28
	v_dot2_f32_bf16 v82, v62, v36, v82
	v_dot2c_f32_bf16_e32 v42, v80, v34
	s_nop 2
	v_add_f32_e32 v58, v82, v42
	v_lshl_add_u64 v[42:43], v[40:41], 0, s[12:13]
	global_load_dwordx4 v[128:131], v[42:43], off
	v_cndmask_b32_e64 v43, v47, v55, s[46:47]
	ds_swizzle_b32 v43, v43 offset:swizzle(SWAP,8)
	v_cndmask_b32_e64 v42, v55, v47, s[46:47]
	v_cndmask_b32_e64 v47, v49, v57, s[46:47]
	ds_swizzle_b32 v47, v47 offset:swizzle(SWAP,8)
	s_waitcnt lgkmcnt(1)
	v_add_f32_e32 v42, v42, v43
	v_cndmask_b32_e64 v43, v56, v48, s[46:47]
	v_cndmask_b32_e64 v48, v50, v132, s[46:47]
	v_add_f32_e32 v43, v43, v46
	v_cndmask_b32_e64 v46, v57, v49, s[46:47]
	ds_swizzle_b32 v48, v48 offset:swizzle(SWAP,8)
	v_cndmask_b32_e64 v49, v51, v133, s[46:47]
	ds_swizzle_b32 v49, v49 offset:swizzle(SWAP,8)
	s_waitcnt lgkmcnt(2)
	v_add_f32_e32 v46, v46, v47
	v_cndmask_b32_e64 v47, v132, v50, s[46:47]
	v_cndmask_b32_e64 v50, v52, v134, s[46:47]
	ds_swizzle_b32 v50, v50 offset:swizzle(SWAP,8)
	s_waitcnt lgkmcnt(2)
	v_add_f32_e32 v47, v47, v48
	v_cndmask_b32_e64 v48, v133, v51, s[46:47]
	v_cndmask_b32_e64 v51, v53, v135, s[46:47]
	s_waitcnt lgkmcnt(1)
	v_add_f32_e32 v48, v48, v49
	v_cndmask_b32_e64 v49, v134, v52, s[46:47]
	ds_swizzle_b32 v51, v51 offset:swizzle(SWAP,8)
	v_cndmask_b32_e64 v52, v54, v58, s[46:47]
	ds_swizzle_b32 v52, v52 offset:swizzle(SWAP,8)
	s_waitcnt lgkmcnt(2)
	v_add_f32_e32 v49, v49, v50
	v_cndmask_b32_e64 v50, v135, v53, s[46:47]
	s_waitcnt lgkmcnt(1)
	v_add_f32_e32 v50, v50, v51
	v_cndmask_b32_e64 v51, v58, v54, s[46:47]
	s_waitcnt lgkmcnt(0)
	v_add_f32_e32 v51, v51, v52
	v_cndmask_b32_e64 v53, v42, v48, s[44:45]
	v_cndmask_b32_e64 v42, v48, v42, s[44:45]
	v_cndmask_b32_e64 v48, v49, v43, s[44:45]
	v_cndmask_b32_e64 v43, v43, v49, s[44:45]
	v_cndmask_b32_e64 v49, v46, v50, s[44:45]
	v_cndmask_b32_e64 v52, v47, v51, s[44:45]
	ds_swizzle_b32 v53, v53 offset:swizzle(SWAP,4)
	ds_swizzle_b32 v43, v43 offset:swizzle(SWAP,4)
	ds_swizzle_b32 v49, v49 offset:swizzle(SWAP,4)
	ds_swizzle_b32 v52, v52 offset:swizzle(SWAP,4)
	v_cndmask_b32_e64 v46, v50, v46, s[44:45]
	v_cndmask_b32_e64 v47, v51, v47, s[44:45]
	s_waitcnt lgkmcnt(3)
	v_add_f32_e32 v42, v42, v53
	s_waitcnt lgkmcnt(2)
	v_add_f32_e32 v43, v48, v43
	s_waitcnt lgkmcnt(1)
	v_add_f32_e32 v46, v46, v49
	s_waitcnt lgkmcnt(0)
	v_add_f32_e32 v47, v47, v52
	v_cndmask_b32_e64 v48, v42, v46, s[42:43]
	v_cndmask_b32_e64 v49, v43, v47, s[42:43]
	ds_swizzle_b32 v48, v48 offset:swizzle(SWAP,2)
	ds_swizzle_b32 v49, v49 offset:swizzle(SWAP,2)
	v_cndmask_b32_e64 v42, v46, v42, s[42:43]
	v_cndmask_b32_e64 v43, v47, v43, s[42:43]
	s_waitcnt lgkmcnt(1)
	v_add_f32_e32 v42, v42, v48
	s_waitcnt lgkmcnt(0)
	v_add_f32_e32 v43, v43, v49
	v_cndmask_b32_e64 v46, v42, v43, s[40:41]
	ds_swizzle_b32 v46, v46 offset:swizzle(SWAP,1)
	v_cndmask_b32_e64 v42, v43, v42, s[40:41]
	s_waitcnt lgkmcnt(0)
	v_add_f32_e32 v42, v42, v46
	ds_swizzle_b32 v43, v42 offset:swizzle(SWAP,16)
	s_waitcnt lgkmcnt(0)
	v_add_f32_e32 v46, v42, v43
	ds_read2st64_b32 v[42:43], v45 offset1:8
	v_mov_b32_e32 v47, v46
	s_nop 1
	v_permlane32_swap_b32_e32 v46, v47
	v_add_f32_e32 v46, v46, v47
	s_waitcnt lgkmcnt(0)
	v_mul_f32_e32 v42, v42, v46
	v_mul_f32_e32 v46, 0x3d372713, v42
	v_mul_f32_e32 v46, v42, v46
	v_fma_f32 v46, v42, v46, v42
	v_mul_f32_e32 v46, 0x3f4c422a, v46
	v_cmp_nlt_f32_e64 s[12:13], |v46|, s25
	s_and_saveexec_b64 s[48:49], s[12:13]
	s_xor_b64 s[12:13], exec, s[48:49]
	s_cbranch_execz .LBB0_1233
	v_add_f32_e64 v47, |v46|, |v46|
	v_mul_f32_e32 v48, 0x3fb8aa3b, v47
	v_rndne_f32_e32 v49, v48
	v_sub_f32_e32 v50, v48, v49
	v_fma_f32 v48, v47, s70, -v48
	v_fmac_f32_e32 v48, 0x32a5705f, v47
	v_add_f32_e32 v48, v50, v48
	v_cvt_i32_f32_e32 v49, v49
	v_exp_f32_e32 v48, v48
	v_cmp_ngt_f32_e64 s[48:49], s67, v47
	v_ldexp_f32 v48, v48, v49
	s_nop 0
	v_cndmask_b32_e64 v48, 0, v48, s[48:49]
	v_cmp_nlt_f32_e64 s[48:49], s68, v47
	s_nop 1
	v_cndmask_b32_e64 v47, v205, v48, s[48:49]
	v_add_f32_e32 v47, 1.0, v47
	v_rcp_f32_e32 v47, v47
	s_nop 0
	v_fma_f32 v47, v47, -2.0, 1.0
	s_andn2_saveexec_b64 s[12:13], s[12:13]
	s_cbranch_execnz .LBB0_1234

; #define P4_FOR16(M) M(0) M(1) M(2) M(3) M(4) M(5) M(6) M(7) M(8) M(9) M(10) M(11) M(12) M(13) M(14) M(15)
; #define P4_U(i) { P4_DOT(b##i, part[i]); const int nk_ = __builtin_amdgcn_readlane(ksel, nb + i); P4_LOAD(b##i, Ug, nk_); }
; #define P4_U(i) { P4_DOT(b##i, part[i]); const int nk_ = __builtin_amdgcn_readlane(kn, i); P4_LOAD(b##i, nbase, nk_); }
; __device__ __forceinline__ void peer_gather_f4p(const float* X, const int* __restrict__ IDX, const float* __restrict__ G, ...
;     ...
;         {
;     ...
;             P4_FOR16(P4_U)
;     ...
;             P4_RED(7);
;         }
.LBB0_1236:
	s_mov_b32 s87, s86
	s_waitcnt vmcnt(15)
	v_cvt_scalef32_pk_bf16_fp4 v42, v64, 1.0
	v_or_b32_e32 v40, s27, v44
	v_cvt_scalef32_pk_bf16_fp4 v44, v64, 1.0 op_sel:[1,0,0]
	v_cvt_scalef32_pk_bf16_fp4 v46, v64, 1.0 op_sel:[0,1,0]
	v_cvt_scalef32_pk_bf16_fp4 v48, v64, 1.0 op_sel:[1,1,0]
	v_dot2_f32_bf16 v50, v42, v6, 0
	v_dot2_f32_bf16 v42, v44, v4, 0
	v_dot2_f32_bf16 v50, v46, v10, v50
	s_cmp_eq_u32 s26, 3
	v_dot2_f32_bf16 v42, v48, v8, v42
	v_cvt_scalef32_pk_bf16_fp4 v44, v65, 1.0
	v_cvt_scalef32_pk_bf16_fp4 v46, v65, 1.0 op_sel:[1,0,0]
	v_cvt_scalef32_pk_bf16_fp4 v48, v65, 1.0 op_sel:[0,1,0]
	v_cvt_scalef32_pk_bf16_fp4 v52, v65, 1.0 op_sel:[1,1,0]
	v_readlane_b32 s26, v2, 0
	v_dot2_f32_bf16 v50, v44, v14, v50
	v_dot2_f32_bf16 v42, v46, v12, v42
	s_cselect_b32 s12, s53, s51
	v_dot2_f32_bf16 v50, v48, v18, v50
	v_dot2_f32_bf16 v42, v52, v16, v42
	v_cvt_scalef32_pk_bf16_fp4 v44, v66, 1.0
	v_cvt_scalef32_pk_bf16_fp4 v46, v66, 1.0 op_sel:[1,0,0]
	v_cvt_scalef32_pk_bf16_fp4 v48, v66, 1.0 op_sel:[0,1,0]
	v_cvt_scalef32_pk_bf16_fp4 v52, v66, 1.0 op_sel:[1,1,0]
	s_cselect_b32 s13, s52, s50
	v_dot2_f32_bf16 v50, v44, v22, v50
	v_dot2_f32_bf16 v42, v46, v20, v42
	s_lshr_b32 s26, s26, 7
	v_dot2_f32_bf16 v50, v48, v26, v50
	v_dot2_f32_bf16 v42, v52, v24, v42
	s_mov_b32 s27, s86
	v_cvt_scalef32_pk_bf16_fp4 v44, v67, 1.0
	v_cvt_scalef32_pk_bf16_fp4 v46, v67, 1.0 op_sel:[1,0,0]
	v_cvt_scalef32_pk_bf16_fp4 v48, v67, 1.0 op_sel:[0,1,0]
	v_cvt_scalef32_pk_bf16_fp4 v52, v67, 1.0 op_sel:[1,1,0]
	s_lshl_b64 s[26:27], s[26:27], 10
	v_dot2_f32_bf16 v50, v44, v30, v50
	v_dot2_f32_bf16 v42, v46, v28, v42
	s_add_u32 s26, s13, s26
	v_dot2_f32_bf16 v50, v48, v36, v50
	v_dot2_f32_bf16 v42, v52, v34, v42
	s_addc_u32 s27, s12, s27
	s_nop 2
	v_add_f32_e32 v41, v50, v42
	v_lshl_add_u64 v[42:43], s[26:27], 0, v[32:33]
	global_load_dwordx4 v[64:67], v[42:43], off
	s_waitcnt vmcnt(15)
	v_cvt_scalef32_pk_bf16_fp4 v42, v68, 1.0
	v_cvt_scalef32_pk_bf16_fp4 v44, v68, 1.0 op_sel:[1,0,0]
	v_cvt_scalef32_pk_bf16_fp4 v46, v68, 1.0 op_sel:[0,1,0]
	v_cvt_scalef32_pk_bf16_fp4 v48, v68, 1.0 op_sel:[1,1,0]
	v_dot2_f32_bf16 v50, v42, v6, 0
	v_dot2_f32_bf16 v42, v44, v4, 0
	v_dot2_f32_bf16 v50, v46, v10, v50
	v_readlane_b32 s26, v2, 1
	v_dot2_f32_bf16 v42, v48, v8, v42
	v_cvt_scalef32_pk_bf16_fp4 v44, v69, 1.0
	v_cvt_scalef32_pk_bf16_fp4 v46, v69, 1.0 op_sel:[1,0,0]
	v_cvt_scalef32_pk_bf16_fp4 v48, v69, 1.0 op_sel:[0,1,0]
	v_cvt_scalef32_pk_bf16_fp4 v52, v69, 1.0 op_sel:[1,1,0]
	s_lshr_b32 s26, s26, 7
	v_dot2_f32_bf16 v50, v44, v14, v50
	v_dot2_f32_bf16 v42, v46, v12, v42
	s_mov_b32 s27, s86
	v_dot2_f32_bf16 v50, v48, v18, v50
	v_dot2_f32_bf16 v42, v52, v16, v42
	v_cvt_scalef32_pk_bf16_fp4 v44, v70, 1.0
	v_cvt_scalef32_pk_bf16_fp4 v46, v70, 1.0 op_sel:[1,0,0]
	v_cvt_scalef32_pk_bf16_fp4 v48, v70, 1.0 op_sel:[0,1,0]
	v_cvt_scalef32_pk_bf16_fp4 v52, v70, 1.0 op_sel:[1,1,0]
	s_lshl_b64 s[26:27], s[26:27], 10
	v_dot2_f32_bf16 v50, v44, v22, v50
	v_dot2_f32_bf16 v42, v46, v20, v42
	s_add_u32 s26, s13, s26
	v_dot2_f32_bf16 v50, v48, v26, v50
	v_dot2_f32_bf16 v42, v52, v24, v42
	v_cvt_scalef32_pk_bf16_fp4 v44, v71, 1.0
	v_cvt_scalef32_pk_bf16_fp4 v46, v71, 1.0 op_sel:[1,0,0]
	v_cvt_scalef32_pk_bf16_fp4 v48, v71, 1.0 op_sel:[0,1,0]
	v_cvt_scalef32_pk_bf16_fp4 v52, v71, 1.0 op_sel:[1,1,0]
	s_addc_u32 s27, s12, s27
	v_dot2_f32_bf16 v50, v44, v30, v50
	v_dot2_f32_bf16 v42, v46, v28, v42
	v_mov_b32_e32 v38, 0
	v_dot2_f32_bf16 v50, v48, v36, v50
	v_dot2_f32_bf16 v42, v52, v34, v42
	s_nop 2
	v_add_f32_e32 v42, v50, v42
	v_lshl_add_u64 v[44:45], s[26:27], 0, v[32:33]
	global_load_dwordx4 v[68:71], v[44:45], off
	s_waitcnt vmcnt(15)
	v_cvt_scalef32_pk_bf16_fp4 v44, v72, 1.0
	v_cvt_scalef32_pk_bf16_fp4 v46, v72, 1.0 op_sel:[1,0,0]
	v_cvt_scalef32_pk_bf16_fp4 v48, v72, 1.0 op_sel:[0,1,0]
	v_cvt_scalef32_pk_bf16_fp4 v50, v72, 1.0 op_sel:[1,1,0]
	v_readlane_b32 s26, v2, 2
	v_dot2_f32_bf16 v52, v44, v6, 0
	v_dot2_f32_bf16 v44, v46, v4, 0
	v_dot2_f32_bf16 v52, v48, v10, v52
	s_lshr_b32 s26, s26, 7
	v_dot2_f32_bf16 v44, v50, v8, v44
	v_cvt_scalef32_pk_bf16_fp4 v46, v73, 1.0
	v_cvt_scalef32_pk_bf16_fp4 v48, v73, 1.0 op_sel:[1,0,0]
	v_cvt_scalef32_pk_bf16_fp4 v50, v73, 1.0 op_sel:[0,1,0]
	v_cvt_scalef32_pk_bf16_fp4 v54, v73, 1.0 op_sel:[1,1,0]
	s_mov_b32 s27, s86
	v_dot2_f32_bf16 v52, v46, v14, v52
	v_dot2_f32_bf16 v44, v48, v12, v44
	s_lshl_b64 s[26:27], s[26:27], 10
	v_dot2_f32_bf16 v52, v50, v18, v52
	v_dot2_f32_bf16 v44, v54, v16, v44
	v_cvt_scalef32_pk_bf16_fp4 v46, v74, 1.0
	v_cvt_scalef32_pk_bf16_fp4 v48, v74, 1.0 op_sel:[1,0,0]
	v_cvt_scalef32_pk_bf16_fp4 v50, v74, 1.0 op_sel:[0,1,0]
	v_cvt_scalef32_pk_bf16_fp4 v54, v74, 1.0 op_sel:[1,1,0]
	s_add_u32 s26, s13, s26
	v_dot2_f32_bf16 v52, v46, v22, v52
	v_dot2_f32_bf16 v44, v48, v20, v44
	s_addc_u32 s27, s12, s27
	v_dot2_f32_bf16 v52, v50, v26, v52
	v_dot2_f32_bf16 v44, v54, v24, v44
	v_cvt_scalef32_pk_bf16_fp4 v46, v75, 1.0
	v_cvt_scalef32_pk_bf16_fp4 v48, v75, 1.0 op_sel:[1,0,0]
	v_cvt_scalef32_pk_bf16_fp4 v50, v75, 1.0 op_sel:[0,1,0]
	v_cvt_scalef32_pk_bf16_fp4 v54, v75, 1.0 op_sel:[1,1,0]
	v_dot2_f32_bf16 v52, v46, v30, v52
	v_dot2_f32_bf16 v44, v48, v28, v44
	v_dot2_f32_bf16 v52, v50, v36, v52
	v_dot2_f32_bf16 v44, v54, v34, v44
	s_nop 2
	v_add_f32_e32 v43, v52, v44
	v_lshl_add_u64 v[44:45], s[26:27], 0, v[32:33]
	global_load_dwordx4 v[72:75], v[44:45], off
	s_waitcnt vmcnt(15)
; #define P4_FOR16(M) M(0) M(1) M(2) M(3) M(4) M(5) M(6) M(7) M(8) M(9) M(10) M(11) M(12) M(13) M(14) M(15)
; #define P4_U(i) { P4_DOT(b##i, part[i]); const int nk_ = __builtin_amdgcn_readlane(ksel, nb + i); P4_LOAD(b##i, Ug, nk_); }
; #define P4_U(i) { P4_DOT(b##i, part[i]); const int nk_ = __builtin_amdgcn_readlane(kn, i); P4_LOAD(b##i, nbase, nk_); }
; __device__ __forceinline__ void peer_gather_f4p(const float* X, const int* __restrict__ IDX, const float* __restrict__ G, ...
;     ...
;         {
;     ...
;             P4_FOR16(P4_U)
;     ...
;             P4_RED(7);
;         }
	v_cvt_scalef32_pk_bf16_fp4 v44, v76, 1.0
	v_cvt_scalef32_pk_bf16_fp4 v46, v76, 1.0 op_sel:[1,0,0]
	v_cvt_scalef32_pk_bf16_fp4 v48, v76, 1.0 op_sel:[0,1,0]
	v_cvt_scalef32_pk_bf16_fp4 v50, v76, 1.0 op_sel:[1,1,0]
	v_dot2_f32_bf16 v52, v44, v6, 0
	v_dot2_f32_bf16 v44, v46, v4, 0
	v_dot2_f32_bf16 v52, v48, v10, v52
	v_readlane_b32 s26, v2, 3
	v_dot2_f32_bf16 v44, v50, v8, v44
	v_cvt_scalef32_pk_bf16_fp4 v46, v77, 1.0
	v_cvt_scalef32_pk_bf16_fp4 v48, v77, 1.0 op_sel:[1,0,0]
	v_cvt_scalef32_pk_bf16_fp4 v50, v77, 1.0 op_sel:[0,1,0]
	v_cvt_scalef32_pk_bf16_fp4 v54, v77, 1.0 op_sel:[1,1,0]
	s_lshr_b32 s26, s26, 7
	v_dot2_f32_bf16 v52, v46, v14, v52
	v_dot2_f32_bf16 v44, v48, v12, v44
	s_mov_b32 s27, s86
	v_dot2_f32_bf16 v52, v50, v18, v52
	v_dot2_f32_bf16 v44, v54, v16, v44
	v_cvt_scalef32_pk_bf16_fp4 v46, v78, 1.0
	v_cvt_scalef32_pk_bf16_fp4 v48, v78, 1.0 op_sel:[1,0,0]
	v_cvt_scalef32_pk_bf16_fp4 v50, v78, 1.0 op_sel:[0,1,0]
	v_cvt_scalef32_pk_bf16_fp4 v54, v78, 1.0 op_sel:[1,1,0]
	s_lshl_b64 s[26:27], s[26:27], 10
	v_dot2_f32_bf16 v52, v46, v22, v52
	v_dot2_f32_bf16 v44, v48, v20, v44
	s_add_u32 s26, s13, s26
	v_dot2_f32_bf16 v52, v50, v26, v52
	v_dot2_f32_bf16 v44, v54, v24, v44
	v_cvt_scalef32_pk_bf16_fp4 v46, v79, 1.0
	v_cvt_scalef32_pk_bf16_fp4 v48, v79, 1.0 op_sel:[1,0,0]
	v_cvt_scalef32_pk_bf16_fp4 v50, v79, 1.0 op_sel:[0,1,0]
	v_cvt_scalef32_pk_bf16_fp4 v54, v79, 1.0 op_sel:[1,1,0]
	s_addc_u32 s27, s12, s27
	v_dot2_f32_bf16 v52, v46, v30, v52
	v_dot2_f32_bf16 v44, v48, v28, v44
	v_dot2_f32_bf16 v52, v50, v36, v52
	v_dot2_f32_bf16 v44, v54, v34, v44
	s_nop 2
	v_add_f32_e32 v44, v52, v44
	v_lshl_add_u64 v[46:47], s[26:27], 0, v[32:33]
	global_load_dwordx4 v[76:79], v[46:47], off
	s_waitcnt vmcnt(15)
	v_cvt_scalef32_pk_bf16_fp4 v46, v84, 1.0
	v_cvt_scalef32_pk_bf16_fp4 v48, v84, 1.0 op_sel:[1,0,0]
	v_cvt_scalef32_pk_bf16_fp4 v50, v84, 1.0 op_sel:[0,1,0]
	v_cvt_scalef32_pk_bf16_fp4 v52, v84, 1.0 op_sel:[1,1,0]
	v_readlane_b32 s26, v2, 4
	v_dot2_f32_bf16 v54, v46, v6, 0
	v_dot2_f32_bf16 v46, v48, v4, 0
	v_dot2_f32_bf16 v54, v50, v10, v54
	s_lshr_b32 s26, s26, 7
	v_dot2_f32_bf16 v46, v52, v8, v46
	v_cvt_scalef32_pk_bf16_fp4 v48, v85, 1.0
	v_cvt_scalef32_pk_bf16_fp4 v50, v85, 1.0 op_sel:[1,0,0]
	v_cvt_scalef32_pk_bf16_fp4 v52, v85, 1.0 op_sel:[0,1,0]
	v_cvt_scalef32_pk_bf16_fp4 v56, v85, 1.0 op_sel:[1,1,0]
	s_mov_b32 s27, s86
	v_dot2_f32_bf16 v54, v48, v14, v54
	v_dot2_f32_bf16 v46, v50, v12, v46
	s_lshl_b64 s[26:27], s[26:27], 10
	v_dot2_f32_bf16 v54, v52, v18, v54
	v_dot2_f32_bf16 v46, v56, v16, v46
	v_cvt_scalef32_pk_bf16_fp4 v48, v86, 1.0
	v_cvt_scalef32_pk_bf16_fp4 v50, v86, 1.0 op_sel:[1,0,0]
	v_cvt_scalef32_pk_bf16_fp4 v52, v86, 1.0 op_sel:[0,1,0]
	v_cvt_scalef32_pk_bf16_fp4 v56, v86, 1.0 op_sel:[1,1,0]
	s_add_u32 s26, s13, s26
	v_dot2_f32_bf16 v54, v48, v22, v54
	v_dot2_f32_bf16 v46, v50, v20, v46
	s_addc_u32 s27, s12, s27
	v_dot2_f32_bf16 v54, v52, v26, v54
	v_dot2_f32_bf16 v46, v56, v24, v46
	v_cvt_scalef32_pk_bf16_fp4 v48, v87, 1.0
	v_cvt_scalef32_pk_bf16_fp4 v50, v87, 1.0 op_sel:[1,0,0]
	v_cvt_scalef32_pk_bf16_fp4 v52, v87, 1.0 op_sel:[0,1,0]
	v_cvt_scalef32_pk_bf16_fp4 v56, v87, 1.0 op_sel:[1,1,0]
	v_dot2_f32_bf16 v54, v48, v30, v54
	v_dot2_f32_bf16 v46, v50, v28, v46
	v_dot2_f32_bf16 v54, v52, v36, v54
	v_dot2_f32_bf16 v46, v56, v34, v46
	s_nop 2
	v_add_f32_e32 v45, v54, v46
	v_lshl_add_u64 v[46:47], s[26:27], 0, v[32:33]
	global_load_dwordx4 v[84:87], v[46:47], off
	s_waitcnt vmcnt(15)
	v_cvt_scalef32_pk_bf16_fp4 v46, v88, 1.0
	v_cvt_scalef32_pk_bf16_fp4 v48, v88, 1.0 op_sel:[1,0,0]
	v_cvt_scalef32_pk_bf16_fp4 v50, v88, 1.0 op_sel:[0,1,0]
	v_cvt_scalef32_pk_bf16_fp4 v52, v88, 1.0 op_sel:[1,1,0]
	v_dot2_f32_bf16 v54, v46, v6, 0
	v_dot2_f32_bf16 v46, v48, v4, 0
	v_dot2_f32_bf16 v54, v50, v10, v54
	v_readlane_b32 s26, v2, 5
	v_dot2_f32_bf16 v46, v52, v8, v46
	v_cvt_scalef32_pk_bf16_fp4 v48, v89, 1.0
	v_cvt_scalef32_pk_bf16_fp4 v50, v89, 1.0 op_sel:[1,0,0]
	v_cvt_scalef32_pk_bf16_fp4 v52, v89, 1.0 op_sel:[0,1,0]
	v_cvt_scalef32_pk_bf16_fp4 v56, v89, 1.0 op_sel:[1,1,0]
	s_lshr_b32 s26, s26, 7
	v_dot2_f32_bf16 v54, v48, v14, v54
	v_dot2_f32_bf16 v46, v50, v12, v46
	s_mov_b32 s27, s86
	v_dot2_f32_bf16 v54, v52, v18, v54
	v_dot2_f32_bf16 v46, v56, v16, v46
	v_cvt_scalef32_pk_bf16_fp4 v48, v90, 1.0
	v_cvt_scalef32_pk_bf16_fp4 v50, v90, 1.0 op_sel:[1,0,0]
	v_cvt_scalef32_pk_bf16_fp4 v52, v90, 1.0 op_sel:[0,1,0]
	v_cvt_scalef32_pk_bf16_fp4 v56, v90, 1.0 op_sel:[1,1,0]
	s_lshl_b64 s[26:27], s[26:27], 10
	v_dot2_f32_bf16 v54, v48, v22, v54
	v_dot2_f32_bf16 v46, v50, v20, v46
	s_add_u32 s26, s13, s26
	v_dot2_f32_bf16 v54, v52, v26, v54
	v_dot2_f32_bf16 v46, v56, v24, v46
	v_cvt_scalef32_pk_bf16_fp4 v48, v91, 1.0
	v_cvt_scalef32_pk_bf16_fp4 v50, v91, 1.0 op_sel:[1,0,0]
	v_cvt_scalef32_pk_bf16_fp4 v52, v91, 1.0 op_sel:[0,1,0]
	v_cvt_scalef32_pk_bf16_fp4 v56, v91, 1.0 op_sel:[1,1,0]
	s_addc_u32 s27, s12, s27
	v_dot2_f32_bf16 v54, v48, v30, v54
	v_dot2_f32_bf16 v46, v50, v28, v46
	v_dot2_f32_bf16 v54, v52, v36, v54
	v_dot2_f32_bf16 v46, v56, v34, v46
	s_nop 2
	v_add_f32_e32 v46, v54, v46
	v_lshl_add_u64 v[48:49], s[26:27], 0, v[32:33]
	global_load_dwordx4 v[88:91], v[48:49], off
	s_waitcnt vmcnt(15)
; #define P4_FOR16(M) M(0) M(1) M(2) M(3) M(4) M(5) M(6) M(7) M(8) M(9) M(10) M(11) M(12) M(13) M(14) M(15)
; #define P4_U(i) { P4_DOT(b##i, part[i]); const int nk_ = __builtin_amdgcn_readlane(ksel, nb + i); P4_LOAD(b##i, Ug, nk_); }
; #define P4_U(i) { P4_DOT(b##i, part[i]); const int nk_ = __builtin_amdgcn_readlane(kn, i); P4_LOAD(b##i, nbase, nk_); }
; __device__ __forceinline__ void peer_gather_f4p(const float* X, const int* __restrict__ IDX, const float* __restrict__ G, ...
;     ...
;         {
;     ...
;             P4_FOR16(P4_U)
;     ...
;             P4_RED(7);
;         }
	v_cvt_scalef32_pk_bf16_fp4 v48, v92, 1.0
	v_cvt_scalef32_pk_bf16_fp4 v50, v92, 1.0 op_sel:[1,0,0]
	v_cvt_scalef32_pk_bf16_fp4 v52, v92, 1.0 op_sel:[0,1,0]
	v_cvt_scalef32_pk_bf16_fp4 v54, v92, 1.0 op_sel:[1,1,0]
	v_readlane_b32 s26, v2, 6
	v_dot2_f32_bf16 v56, v48, v6, 0
	v_dot2_f32_bf16 v48, v50, v4, 0
	v_dot2_f32_bf16 v56, v52, v10, v56
	s_lshr_b32 s26, s26, 7
	v_dot2_f32_bf16 v48, v54, v8, v48
	v_cvt_scalef32_pk_bf16_fp4 v50, v93, 1.0
	v_cvt_scalef32_pk_bf16_fp4 v52, v93, 1.0 op_sel:[1,0,0]
	v_cvt_scalef32_pk_bf16_fp4 v54, v93, 1.0 op_sel:[0,1,0]
	v_cvt_scalef32_pk_bf16_fp4 v58, v93, 1.0 op_sel:[1,1,0]
	s_mov_b32 s27, s86
	v_dot2_f32_bf16 v56, v50, v14, v56
	v_dot2_f32_bf16 v48, v52, v12, v48
	s_lshl_b64 s[26:27], s[26:27], 10
	v_dot2_f32_bf16 v56, v54, v18, v56
	v_dot2_f32_bf16 v48, v58, v16, v48
	v_cvt_scalef32_pk_bf16_fp4 v50, v94, 1.0
	v_cvt_scalef32_pk_bf16_fp4 v52, v94, 1.0 op_sel:[1,0,0]
	v_cvt_scalef32_pk_bf16_fp4 v54, v94, 1.0 op_sel:[0,1,0]
	v_cvt_scalef32_pk_bf16_fp4 v58, v94, 1.0 op_sel:[1,1,0]
	s_add_u32 s26, s13, s26
	v_dot2_f32_bf16 v56, v50, v22, v56
	v_dot2_f32_bf16 v48, v52, v20, v48
	s_addc_u32 s27, s12, s27
	v_dot2_f32_bf16 v56, v54, v26, v56
	v_dot2_f32_bf16 v48, v58, v24, v48
	v_cvt_scalef32_pk_bf16_fp4 v50, v95, 1.0
	v_cvt_scalef32_pk_bf16_fp4 v52, v95, 1.0 op_sel:[1,0,0]
	v_cvt_scalef32_pk_bf16_fp4 v54, v95, 1.0 op_sel:[0,1,0]
	v_cvt_scalef32_pk_bf16_fp4 v58, v95, 1.0 op_sel:[1,1,0]
	v_dot2_f32_bf16 v56, v50, v30, v56
	v_dot2_f32_bf16 v48, v52, v28, v48
	v_dot2_f32_bf16 v56, v54, v36, v56
	v_dot2_f32_bf16 v48, v58, v34, v48
	s_nop 2
	v_add_f32_e32 v47, v56, v48
	v_lshl_add_u64 v[48:49], s[26:27], 0, v[32:33]
	global_load_dwordx4 v[92:95], v[48:49], off
	s_waitcnt vmcnt(15)
	v_cvt_scalef32_pk_bf16_fp4 v48, v96, 1.0
	v_cvt_scalef32_pk_bf16_fp4 v50, v96, 1.0 op_sel:[1,0,0]
	v_cvt_scalef32_pk_bf16_fp4 v52, v96, 1.0 op_sel:[0,1,0]
	v_cvt_scalef32_pk_bf16_fp4 v54, v96, 1.0 op_sel:[1,1,0]
	v_dot2_f32_bf16 v56, v48, v6, 0
	v_dot2_f32_bf16 v48, v50, v4, 0
	v_dot2_f32_bf16 v56, v52, v10, v56
	v_readlane_b32 s26, v2, 7
	v_dot2_f32_bf16 v48, v54, v8, v48
	v_cvt_scalef32_pk_bf16_fp4 v50, v97, 1.0
	v_cvt_scalef32_pk_bf16_fp4 v52, v97, 1.0 op_sel:[1,0,0]
	v_cvt_scalef32_pk_bf16_fp4 v54, v97, 1.0 op_sel:[0,1,0]
	v_cvt_scalef32_pk_bf16_fp4 v58, v97, 1.0 op_sel:[1,1,0]
	s_lshr_b32 s26, s26, 7
	v_dot2_f32_bf16 v56, v50, v14, v56
	v_dot2_f32_bf16 v48, v52, v12, v48
	s_mov_b32 s27, s86
	v_dot2_f32_bf16 v56, v54, v18, v56
	v_dot2_f32_bf16 v48, v58, v16, v48
	v_cvt_scalef32_pk_bf16_fp4 v50, v98, 1.0
	v_cvt_scalef32_pk_bf16_fp4 v52, v98, 1.0 op_sel:[1,0,0]
	v_cvt_scalef32_pk_bf16_fp4 v54, v98, 1.0 op_sel:[0,1,0]
	v_cvt_scalef32_pk_bf16_fp4 v58, v98, 1.0 op_sel:[1,1,0]
	s_lshl_b64 s[26:27], s[26:27], 10
	v_dot2_f32_bf16 v56, v50, v22, v56
	v_dot2_f32_bf16 v48, v52, v20, v48
	s_add_u32 s26, s13, s26
	v_dot2_f32_bf16 v56, v54, v26, v56
	v_dot2_f32_bf16 v48, v58, v24, v48
	v_cvt_scalef32_pk_bf16_fp4 v50, v99, 1.0
	v_cvt_scalef32_pk_bf16_fp4 v52, v99, 1.0 op_sel:[1,0,0]
	v_cvt_scalef32_pk_bf16_fp4 v54, v99, 1.0 op_sel:[0,1,0]
	v_cvt_scalef32_pk_bf16_fp4 v58, v99, 1.0 op_sel:[1,1,0]
	s_addc_u32 s27, s12, s27
	v_dot2_f32_bf16 v56, v50, v30, v56
	v_dot2_f32_bf16 v48, v52, v28, v48
	v_dot2_f32_bf16 v56, v54, v36, v56
	v_dot2_f32_bf16 v48, v58, v34, v48
	s_nop 2
	v_add_f32_e32 v48, v56, v48
	v_lshl_add_u64 v[50:51], s[26:27], 0, v[32:33]
	global_load_dwordx4 v[96:99], v[50:51], off
	s_waitcnt vmcnt(15)
	v_cvt_scalef32_pk_bf16_fp4 v50, v100, 1.0
	v_cvt_scalef32_pk_bf16_fp4 v52, v100, 1.0 op_sel:[1,0,0]
	v_cvt_scalef32_pk_bf16_fp4 v54, v100, 1.0 op_sel:[0,1,0]
	v_cvt_scalef32_pk_bf16_fp4 v56, v100, 1.0 op_sel:[1,1,0]
	v_readlane_b32 s26, v2, 8
	v_dot2_f32_bf16 v58, v50, v6, 0
	v_dot2_f32_bf16 v50, v52, v4, 0
	v_dot2_f32_bf16 v58, v54, v10, v58
	s_lshr_b32 s26, s26, 7
	v_dot2_f32_bf16 v50, v56, v8, v50
	v_cvt_scalef32_pk_bf16_fp4 v52, v101, 1.0
	v_cvt_scalef32_pk_bf16_fp4 v54, v101, 1.0 op_sel:[1,0,0]
	v_cvt_scalef32_pk_bf16_fp4 v56, v101, 1.0 op_sel:[0,1,0]
	v_cvt_scalef32_pk_bf16_fp4 v60, v101, 1.0 op_sel:[1,1,0]
	s_mov_b32 s27, s86
	v_dot2_f32_bf16 v58, v52, v14, v58
	v_dot2_f32_bf16 v50, v54, v12, v50
	s_lshl_b64 s[26:27], s[26:27], 10
	v_dot2_f32_bf16 v58, v56, v18, v58
	v_dot2_f32_bf16 v50, v60, v16, v50
	v_cvt_scalef32_pk_bf16_fp4 v52, v102, 1.0
	v_cvt_scalef32_pk_bf16_fp4 v54, v102, 1.0 op_sel:[1,0,0]
	v_cvt_scalef32_pk_bf16_fp4 v56, v102, 1.0 op_sel:[0,1,0]
	v_cvt_scalef32_pk_bf16_fp4 v60, v102, 1.0 op_sel:[1,1,0]
	s_add_u32 s26, s13, s26
	v_dot2_f32_bf16 v58, v52, v22, v58
	v_dot2_f32_bf16 v50, v54, v20, v50
	s_addc_u32 s27, s12, s27
	v_dot2_f32_bf16 v58, v56, v26, v58
	v_dot2_f32_bf16 v50, v60, v24, v50
	v_cvt_scalef32_pk_bf16_fp4 v52, v103, 1.0
	v_cvt_scalef32_pk_bf16_fp4 v54, v103, 1.0 op_sel:[1,0,0]
	v_cvt_scalef32_pk_bf16_fp4 v56, v103, 1.0 op_sel:[0,1,0]
	v_cvt_scalef32_pk_bf16_fp4 v60, v103, 1.0 op_sel:[1,1,0]
	v_dot2_f32_bf16 v58, v52, v30, v58
	v_dot2_f32_bf16 v50, v54, v28, v50
	v_dot2_f32_bf16 v58, v56, v36, v58
	v_dot2_f32_bf16 v50, v60, v34, v50
	s_nop 2
	v_add_f32_e32 v49, v58, v50
	v_lshl_add_u64 v[50:51], s[26:27], 0, v[32:33]
	global_load_dwordx4 v[100:103], v[50:51], off
	s_waitcnt vmcnt(15)
; #define P4_FOR16(M) M(0) M(1) M(2) M(3) M(4) M(5) M(6) M(7) M(8) M(9) M(10) M(11) M(12) M(13) M(14) M(15)
; #define P4_U(i) { P4_DOT(b##i, part[i]); const int nk_ = __builtin_amdgcn_readlane(ksel, nb + i); P4_LOAD(b##i, Ug, nk_); }
; #define P4_U(i) { P4_DOT(b##i, part[i]); const int nk_ = __builtin_amdgcn_readlane(kn, i); P4_LOAD(b##i, nbase, nk_); }
; __device__ __forceinline__ void peer_gather_f4p(const float* X, const int* __restrict__ IDX, const float* __restrict__ G, ...
;     ...
;         {
;     ...
;             P4_FOR16(P4_U)
;     ...
;             P4_RED(7);
;         }
	v_cvt_scalef32_pk_bf16_fp4 v50, v104, 1.0
	v_cvt_scalef32_pk_bf16_fp4 v52, v104, 1.0 op_sel:[1,0,0]
	v_cvt_scalef32_pk_bf16_fp4 v54, v104, 1.0 op_sel:[0,1,0]
	v_cvt_scalef32_pk_bf16_fp4 v56, v104, 1.0 op_sel:[1,1,0]
	v_dot2_f32_bf16 v58, v50, v6, 0
	v_dot2_f32_bf16 v50, v52, v4, 0
	v_dot2_f32_bf16 v58, v54, v10, v58
	v_readlane_b32 s26, v2, 9
	v_dot2_f32_bf16 v50, v56, v8, v50
	v_cvt_scalef32_pk_bf16_fp4 v52, v105, 1.0
	v_cvt_scalef32_pk_bf16_fp4 v54, v105, 1.0 op_sel:[1,0,0]
	v_cvt_scalef32_pk_bf16_fp4 v56, v105, 1.0 op_sel:[0,1,0]
	v_cvt_scalef32_pk_bf16_fp4 v60, v105, 1.0 op_sel:[1,1,0]
	s_lshr_b32 s26, s26, 7
	v_dot2_f32_bf16 v58, v52, v14, v58
	v_dot2_f32_bf16 v50, v54, v12, v50
	s_mov_b32 s27, s86
	v_dot2_f32_bf16 v58, v56, v18, v58
	v_dot2_f32_bf16 v50, v60, v16, v50
	v_cvt_scalef32_pk_bf16_fp4 v52, v106, 1.0
	v_cvt_scalef32_pk_bf16_fp4 v54, v106, 1.0 op_sel:[1,0,0]
	v_cvt_scalef32_pk_bf16_fp4 v56, v106, 1.0 op_sel:[0,1,0]
	v_cvt_scalef32_pk_bf16_fp4 v60, v106, 1.0 op_sel:[1,1,0]
	s_lshl_b64 s[26:27], s[26:27], 10
	v_dot2_f32_bf16 v58, v52, v22, v58
	v_dot2_f32_bf16 v50, v54, v20, v50
	s_add_u32 s26, s13, s26
	v_dot2_f32_bf16 v58, v56, v26, v58
	v_dot2_f32_bf16 v50, v60, v24, v50
	v_cvt_scalef32_pk_bf16_fp4 v52, v107, 1.0
	v_cvt_scalef32_pk_bf16_fp4 v54, v107, 1.0 op_sel:[1,0,0]
	v_cvt_scalef32_pk_bf16_fp4 v56, v107, 1.0 op_sel:[0,1,0]
	v_cvt_scalef32_pk_bf16_fp4 v60, v107, 1.0 op_sel:[1,1,0]
	s_addc_u32 s27, s12, s27
	v_dot2_f32_bf16 v58, v52, v30, v58
	v_dot2_f32_bf16 v50, v54, v28, v50
	v_dot2_f32_bf16 v58, v56, v36, v58
	v_dot2_f32_bf16 v50, v60, v34, v50
	s_nop 2
	v_add_f32_e32 v50, v58, v50
	v_lshl_add_u64 v[52:53], s[26:27], 0, v[32:33]
	global_load_dwordx4 v[104:107], v[52:53], off
	s_waitcnt vmcnt(15)
	v_cvt_scalef32_pk_bf16_fp4 v52, v108, 1.0
	v_cvt_scalef32_pk_bf16_fp4 v54, v108, 1.0 op_sel:[1,0,0]
	v_cvt_scalef32_pk_bf16_fp4 v56, v108, 1.0 op_sel:[0,1,0]
	v_cvt_scalef32_pk_bf16_fp4 v58, v108, 1.0 op_sel:[1,1,0]
	v_readlane_b32 s26, v2, 10
	v_dot2_f32_bf16 v60, v52, v6, 0
	v_dot2_f32_bf16 v52, v54, v4, 0
	v_dot2_f32_bf16 v60, v56, v10, v60
	s_lshr_b32 s26, s26, 7
	v_dot2_f32_bf16 v52, v58, v8, v52
	v_cvt_scalef32_pk_bf16_fp4 v54, v109, 1.0
	v_cvt_scalef32_pk_bf16_fp4 v56, v109, 1.0 op_sel:[1,0,0]
	v_cvt_scalef32_pk_bf16_fp4 v58, v109, 1.0 op_sel:[0,1,0]
	v_cvt_scalef32_pk_bf16_fp4 v62, v109, 1.0 op_sel:[1,1,0]
	s_mov_b32 s27, s86
	v_dot2_f32_bf16 v60, v54, v14, v60
	v_dot2_f32_bf16 v52, v56, v12, v52
	s_lshl_b64 s[26:27], s[26:27], 10
	v_dot2_f32_bf16 v60, v58, v18, v60
	v_dot2_f32_bf16 v52, v62, v16, v52
	v_cvt_scalef32_pk_bf16_fp4 v54, v110, 1.0
	v_cvt_scalef32_pk_bf16_fp4 v56, v110, 1.0 op_sel:[1,0,0]
	v_cvt_scalef32_pk_bf16_fp4 v58, v110, 1.0 op_sel:[0,1,0]
	v_cvt_scalef32_pk_bf16_fp4 v62, v110, 1.0 op_sel:[1,1,0]
	s_add_u32 s26, s13, s26
	v_dot2_f32_bf16 v60, v54, v22, v60
	v_dot2_f32_bf16 v52, v56, v20, v52
	s_addc_u32 s27, s12, s27
	v_dot2_f32_bf16 v60, v58, v26, v60
	v_dot2_f32_bf16 v52, v62, v24, v52
	v_cvt_scalef32_pk_bf16_fp4 v54, v111, 1.0
	v_cvt_scalef32_pk_bf16_fp4 v56, v111, 1.0 op_sel:[1,0,0]
	v_cvt_scalef32_pk_bf16_fp4 v58, v111, 1.0 op_sel:[0,1,0]
	v_cvt_scalef32_pk_bf16_fp4 v62, v111, 1.0 op_sel:[1,1,0]
	v_dot2_f32_bf16 v60, v54, v30, v60
	v_dot2_f32_bf16 v52, v56, v28, v52
	v_dot2_f32_bf16 v60, v58, v36, v60
	v_dot2_f32_bf16 v52, v62, v34, v52
	s_nop 2
	v_add_f32_e32 v51, v60, v52
	v_lshl_add_u64 v[52:53], s[26:27], 0, v[32:33]
	global_load_dwordx4 v[108:111], v[52:53], off
	s_waitcnt vmcnt(15)
	v_cvt_scalef32_pk_bf16_fp4 v52, v112, 1.0
	v_cvt_scalef32_pk_bf16_fp4 v54, v112, 1.0 op_sel:[1,0,0]
	v_cvt_scalef32_pk_bf16_fp4 v56, v112, 1.0 op_sel:[0,1,0]
	v_cvt_scalef32_pk_bf16_fp4 v58, v112, 1.0 op_sel:[1,1,0]
	v_dot2_f32_bf16 v60, v52, v6, 0
	v_dot2_f32_bf16 v52, v54, v4, 0
	v_dot2_f32_bf16 v60, v56, v10, v60
	v_readlane_b32 s26, v2, 11
	v_dot2_f32_bf16 v52, v58, v8, v52
	v_cvt_scalef32_pk_bf16_fp4 v54, v113, 1.0
	v_cvt_scalef32_pk_bf16_fp4 v56, v113, 1.0 op_sel:[1,0,0]
	v_cvt_scalef32_pk_bf16_fp4 v58, v113, 1.0 op_sel:[0,1,0]
	v_cvt_scalef32_pk_bf16_fp4 v62, v113, 1.0 op_sel:[1,1,0]
	s_lshr_b32 s26, s26, 7
	v_dot2_f32_bf16 v60, v54, v14, v60
	v_dot2_f32_bf16 v52, v56, v12, v52
	s_mov_b32 s27, s86
	v_dot2_f32_bf16 v60, v58, v18, v60
	v_dot2_f32_bf16 v52, v62, v16, v52
	v_cvt_scalef32_pk_bf16_fp4 v54, v114, 1.0
	v_cvt_scalef32_pk_bf16_fp4 v56, v114, 1.0 op_sel:[1,0,0]
	v_cvt_scalef32_pk_bf16_fp4 v58, v114, 1.0 op_sel:[0,1,0]
	v_cvt_scalef32_pk_bf16_fp4 v62, v114, 1.0 op_sel:[1,1,0]
	s_lshl_b64 s[26:27], s[26:27], 10
	v_dot2_f32_bf16 v60, v54, v22, v60
	v_dot2_f32_bf16 v52, v56, v20, v52
	s_add_u32 s26, s13, s26
	v_dot2_f32_bf16 v60, v58, v26, v60
	v_dot2_f32_bf16 v52, v62, v24, v52
	v_cvt_scalef32_pk_bf16_fp4 v54, v115, 1.0
	v_cvt_scalef32_pk_bf16_fp4 v56, v115, 1.0 op_sel:[1,0,0]
	v_cvt_scalef32_pk_bf16_fp4 v58, v115, 1.0 op_sel:[0,1,0]
	v_cvt_scalef32_pk_bf16_fp4 v62, v115, 1.0 op_sel:[1,1,0]
	s_addc_u32 s27, s12, s27
	v_dot2_f32_bf16 v60, v54, v30, v60
	v_dot2_f32_bf16 v52, v56, v28, v52
	v_dot2_f32_bf16 v60, v58, v36, v60
	v_dot2_f32_bf16 v52, v62, v34, v52
	s_nop 2
	v_add_f32_e32 v80, v60, v52
	v_lshl_add_u64 v[52:53], s[26:27], 0, v[32:33]
	global_load_dwordx4 v[112:115], v[52:53], off
	s_waitcnt vmcnt(15)
; #define P4_FOR16(M) M(0) M(1) M(2) M(3) M(4) M(5) M(6) M(7) M(8) M(9) M(10) M(11) M(12) M(13) M(14) M(15)
; #define P4_U(i) { P4_DOT(b##i, part[i]); const int nk_ = __builtin_amdgcn_readlane(ksel, nb + i); P4_LOAD(b##i, Ug, nk_); }
; #define P4_U(i) { P4_DOT(b##i, part[i]); const int nk_ = __builtin_amdgcn_readlane(kn, i); P4_LOAD(b##i, nbase, nk_); }
; __device__ __forceinline__ void peer_gather_f4p(const float* X, const int* __restrict__ IDX, const float* __restrict__ G, ...
;     ...
;         {
;     ...
;             P4_FOR16(P4_U)
;     ...
;             P4_RED(7);
;         }
	v_cvt_scalef32_pk_bf16_fp4 v52, v116, 1.0
	v_cvt_scalef32_pk_bf16_fp4 v54, v116, 1.0 op_sel:[1,0,0]
	v_cvt_scalef32_pk_bf16_fp4 v56, v116, 1.0 op_sel:[0,1,0]
	v_cvt_scalef32_pk_bf16_fp4 v58, v116, 1.0 op_sel:[1,1,0]
	v_dot2_f32_bf16 v60, v52, v6, 0
	v_dot2_f32_bf16 v52, v54, v4, 0
	v_dot2_f32_bf16 v60, v56, v10, v60
	v_readlane_b32 s26, v2, 12
	v_dot2_f32_bf16 v52, v58, v8, v52
	v_cvt_scalef32_pk_bf16_fp4 v54, v117, 1.0
	v_cvt_scalef32_pk_bf16_fp4 v56, v117, 1.0 op_sel:[1,0,0]
	v_cvt_scalef32_pk_bf16_fp4 v58, v117, 1.0 op_sel:[0,1,0]
	v_cvt_scalef32_pk_bf16_fp4 v62, v117, 1.0 op_sel:[1,1,0]
	s_lshr_b32 s26, s26, 7
	v_dot2_f32_bf16 v60, v54, v14, v60
	v_dot2_f32_bf16 v52, v56, v12, v52
	s_mov_b32 s27, s86
	v_dot2_f32_bf16 v60, v58, v18, v60
	v_dot2_f32_bf16 v52, v62, v16, v52
	v_cvt_scalef32_pk_bf16_fp4 v54, v118, 1.0
	v_cvt_scalef32_pk_bf16_fp4 v56, v118, 1.0 op_sel:[1,0,0]
	v_cvt_scalef32_pk_bf16_fp4 v58, v118, 1.0 op_sel:[0,1,0]
	v_cvt_scalef32_pk_bf16_fp4 v62, v118, 1.0 op_sel:[1,1,0]
	s_lshl_b64 s[26:27], s[26:27], 10
	v_dot2_f32_bf16 v60, v54, v22, v60
	v_dot2_f32_bf16 v52, v56, v20, v52
	s_add_u32 s26, s13, s26
	v_dot2_f32_bf16 v60, v58, v26, v60
	v_dot2_f32_bf16 v52, v62, v24, v52
	v_cvt_scalef32_pk_bf16_fp4 v54, v119, 1.0
	v_cvt_scalef32_pk_bf16_fp4 v56, v119, 1.0 op_sel:[1,0,0]
	v_cvt_scalef32_pk_bf16_fp4 v58, v119, 1.0 op_sel:[0,1,0]
	v_cvt_scalef32_pk_bf16_fp4 v62, v119, 1.0 op_sel:[1,1,0]
	s_addc_u32 s27, s12, s27
	v_dot2_f32_bf16 v60, v54, v30, v60
	v_dot2_f32_bf16 v52, v56, v28, v52
	v_dot2_f32_bf16 v60, v58, v36, v60
	v_dot2_f32_bf16 v52, v62, v34, v52
	s_nop 2
	v_add_f32_e32 v81, v60, v52
	v_lshl_add_u64 v[52:53], s[26:27], 0, v[32:33]
	global_load_dwordx4 v[116:119], v[52:53], off
	s_waitcnt vmcnt(15)
	v_cvt_scalef32_pk_bf16_fp4 v52, v120, 1.0
	v_cvt_scalef32_pk_bf16_fp4 v54, v120, 1.0 op_sel:[1,0,0]
	v_cvt_scalef32_pk_bf16_fp4 v56, v120, 1.0 op_sel:[0,1,0]
	v_cvt_scalef32_pk_bf16_fp4 v58, v120, 1.0 op_sel:[1,1,0]
	v_dot2_f32_bf16 v60, v52, v6, 0
	v_dot2_f32_bf16 v52, v54, v4, 0
	v_dot2_f32_bf16 v60, v56, v10, v60
	v_readlane_b32 s26, v2, 13
	v_dot2_f32_bf16 v52, v58, v8, v52
	v_cvt_scalef32_pk_bf16_fp4 v54, v121, 1.0
	v_cvt_scalef32_pk_bf16_fp4 v56, v121, 1.0 op_sel:[1,0,0]
	v_cvt_scalef32_pk_bf16_fp4 v58, v121, 1.0 op_sel:[0,1,0]
	v_cvt_scalef32_pk_bf16_fp4 v62, v121, 1.0 op_sel:[1,1,0]
	s_lshr_b32 s26, s26, 7
	v_dot2_f32_bf16 v60, v54, v14, v60
	v_dot2_f32_bf16 v52, v56, v12, v52
	s_mov_b32 s27, s86
	v_dot2_f32_bf16 v60, v58, v18, v60
	v_dot2_f32_bf16 v52, v62, v16, v52
	v_cvt_scalef32_pk_bf16_fp4 v54, v122, 1.0
	v_cvt_scalef32_pk_bf16_fp4 v56, v122, 1.0 op_sel:[1,0,0]
	v_cvt_scalef32_pk_bf16_fp4 v58, v122, 1.0 op_sel:[0,1,0]
	v_cvt_scalef32_pk_bf16_fp4 v62, v122, 1.0 op_sel:[1,1,0]
	s_lshl_b64 s[26:27], s[26:27], 10
	v_dot2_f32_bf16 v60, v54, v22, v60
	v_dot2_f32_bf16 v52, v56, v20, v52
	s_add_u32 s26, s13, s26
	v_dot2_f32_bf16 v60, v58, v26, v60
	v_dot2_f32_bf16 v52, v62, v24, v52
	v_cvt_scalef32_pk_bf16_fp4 v54, v123, 1.0
	v_cvt_scalef32_pk_bf16_fp4 v56, v123, 1.0 op_sel:[1,0,0]
	v_cvt_scalef32_pk_bf16_fp4 v58, v123, 1.0 op_sel:[0,1,0]
	v_cvt_scalef32_pk_bf16_fp4 v62, v123, 1.0 op_sel:[1,1,0]
	s_addc_u32 s27, s12, s27
	v_dot2_f32_bf16 v60, v54, v30, v60
	v_dot2_f32_bf16 v52, v56, v28, v52
	v_dot2_f32_bf16 v60, v58, v36, v60
	v_dot2_f32_bf16 v52, v62, v34, v52
	s_nop 2
	v_add_f32_e32 v82, v60, v52
	v_lshl_add_u64 v[52:53], s[26:27], 0, v[32:33]
	global_load_dwordx4 v[120:123], v[52:53], off
	s_waitcnt vmcnt(15)
	v_cvt_scalef32_pk_bf16_fp4 v52, v124, 1.0
	v_cvt_scalef32_pk_bf16_fp4 v54, v124, 1.0 op_sel:[1,0,0]
	v_cvt_scalef32_pk_bf16_fp4 v56, v124, 1.0 op_sel:[0,1,0]
	v_cvt_scalef32_pk_bf16_fp4 v58, v124, 1.0 op_sel:[1,1,0]
	v_dot2_f32_bf16 v60, v52, v6, 0
	v_dot2_f32_bf16 v52, v54, v4, 0
	v_dot2_f32_bf16 v60, v56, v10, v60
	v_readlane_b32 s26, v2, 14
	v_dot2_f32_bf16 v52, v58, v8, v52
	v_cvt_scalef32_pk_bf16_fp4 v54, v125, 1.0
	v_cvt_scalef32_pk_bf16_fp4 v56, v125, 1.0 op_sel:[1,0,0]
	v_cvt_scalef32_pk_bf16_fp4 v58, v125, 1.0 op_sel:[0,1,0]
	v_cvt_scalef32_pk_bf16_fp4 v62, v125, 1.0 op_sel:[1,1,0]
	s_lshr_b32 s26, s26, 7
	v_dot2_f32_bf16 v60, v54, v14, v60
	v_dot2_f32_bf16 v52, v56, v12, v52
	s_mov_b32 s27, s86
	v_dot2_f32_bf16 v60, v58, v18, v60
	v_dot2_f32_bf16 v52, v62, v16, v52
	v_cvt_scalef32_pk_bf16_fp4 v54, v126, 1.0
	v_cvt_scalef32_pk_bf16_fp4 v56, v126, 1.0 op_sel:[1,0,0]
	v_cvt_scalef32_pk_bf16_fp4 v58, v126, 1.0 op_sel:[0,1,0]
	v_cvt_scalef32_pk_bf16_fp4 v62, v126, 1.0 op_sel:[1,1,0]
	s_lshl_b64 s[26:27], s[26:27], 10
	v_dot2_f32_bf16 v60, v54, v22, v60
	v_dot2_f32_bf16 v52, v56, v20, v52
	s_add_u32 s26, s13, s26
	v_dot2_f32_bf16 v60, v58, v26, v60
	v_dot2_f32_bf16 v52, v62, v24, v52
	v_cvt_scalef32_pk_bf16_fp4 v54, v127, 1.0
	v_cvt_scalef32_pk_bf16_fp4 v56, v127, 1.0 op_sel:[1,0,0]
	v_cvt_scalef32_pk_bf16_fp4 v58, v127, 1.0 op_sel:[0,1,0]
	v_cvt_scalef32_pk_bf16_fp4 v62, v127, 1.0 op_sel:[1,1,0]
	s_addc_u32 s27, s12, s27
	v_dot2_f32_bf16 v60, v54, v30, v60
	v_dot2_f32_bf16 v52, v56, v28, v52
	v_dot2_f32_bf16 v60, v58, v36, v60
	v_dot2_f32_bf16 v52, v62, v34, v52
	s_nop 2
	v_add_f32_e32 v62, v60, v52
	v_lshl_add_u64 v[52:53], s[26:27], 0, v[32:33]
	global_load_dwordx4 v[124:127], v[52:53], off
	s_waitcnt vmcnt(15)
; #define P4_FOR16(M) M(0) M(1) M(2) M(3) M(4) M(5) M(6) M(7) M(8) M(9) M(10) M(11) M(12) M(13) M(14) M(15)
; #define P4_U(i) { P4_DOT(b##i, part[i]); const int nk_ = __builtin_amdgcn_readlane(ksel, nb + i); P4_LOAD(b##i, Ug, nk_); }
; #define P4_U(i) { P4_DOT(b##i, part[i]); const int nk_ = __builtin_amdgcn_readlane(kn, i); P4_LOAD(b##i, nbase, nk_); }
; __device__ __forceinline__ void peer_gather_f4p(const float* X, const int* __restrict__ IDX, const float* __restrict__ G, ...
;     ...
; #pragma unroll 1
;         for (int bt = 0; bt < 7; ++bt) {
;             const int ksel = (bt + 1 < 4) ? k0 : k1;
;             const int nb = (16 * (bt + 1)) & 63;
;     ...
;             P4_FOR16(P4_U)
;     ...
;             P4_RED(bt);
;         }
;         {
;     ...
;             P4_FOR16(P4_U)
;     ...
;             P4_RED(7);
;         }
	v_cvt_scalef32_pk_bf16_fp4 v52, v128, 1.0
	v_cvt_scalef32_pk_bf16_fp4 v54, v128, 1.0 op_sel:[1,0,0]
	v_cvt_scalef32_pk_bf16_fp4 v56, v128, 1.0 op_sel:[0,1,0]
	v_cvt_scalef32_pk_bf16_fp4 v58, v128, 1.0 op_sel:[1,1,0]
	v_readlane_b32 s26, v2, 15
	v_dot2_f32_bf16 v60, v52, v6, 0
	v_dot2c_f32_bf16_e32 v38, v54, v4
	s_lshr_b32 s26, s26, 7
	v_dot2_f32_bf16 v60, v56, v10, v60
	v_dot2c_f32_bf16_e32 v38, v58, v8
	v_cvt_scalef32_pk_bf16_fp4 v4, v129, 1.0
	v_cvt_scalef32_pk_bf16_fp4 v6, v129, 1.0 op_sel:[1,0,0]
	v_cvt_scalef32_pk_bf16_fp4 v8, v129, 1.0 op_sel:[0,1,0]
	v_cvt_scalef32_pk_bf16_fp4 v10, v129, 1.0 op_sel:[1,1,0]
	s_mov_b32 s27, s86
	v_dot2_f32_bf16 v60, v4, v14, v60
	v_dot2c_f32_bf16_e32 v38, v6, v12
	s_lshl_b64 s[26:27], s[26:27], 10
	v_dot2_f32_bf16 v60, v8, v18, v60
	v_dot2c_f32_bf16_e32 v38, v10, v16
	v_cvt_scalef32_pk_bf16_fp4 v4, v130, 1.0
	v_cvt_scalef32_pk_bf16_fp4 v6, v130, 1.0 op_sel:[1,0,0]
	v_cvt_scalef32_pk_bf16_fp4 v8, v130, 1.0 op_sel:[0,1,0]
	v_cvt_scalef32_pk_bf16_fp4 v10, v130, 1.0 op_sel:[1,1,0]
	s_add_u32 s26, s13, s26
	v_dot2_f32_bf16 v60, v4, v22, v60
	v_dot2c_f32_bf16_e32 v38, v6, v20
	s_addc_u32 s27, s12, s27
	v_dot2_f32_bf16 v60, v8, v26, v60
	v_dot2c_f32_bf16_e32 v38, v10, v24
	v_cvt_scalef32_pk_bf16_fp4 v4, v131, 1.0
	v_cvt_scalef32_pk_bf16_fp4 v6, v131, 1.0 op_sel:[1,0,0]
	v_cvt_scalef32_pk_bf16_fp4 v8, v131, 1.0 op_sel:[0,1,0]
	v_cvt_scalef32_pk_bf16_fp4 v10, v131, 1.0 op_sel:[1,1,0]
	v_cndmask_b32_e64 v2, v49, v41, s[46:47]
	v_dot2_f32_bf16 v60, v4, v30, v60
	v_dot2c_f32_bf16_e32 v38, v6, v28
	v_cndmask_b32_e64 v7, v43, v51, s[46:47]
	v_dot2_f32_bf16 v60, v8, v36, v60
	v_dot2c_f32_bf16_e32 v38, v10, v34
	ds_swizzle_b32 v7, v7 offset:swizzle(SWAP,8)
	s_nop 2
	v_add_f32_e32 v6, v60, v38
	v_lshl_add_u64 v[4:5], s[26:27], 0, v[32:33]
	global_load_dwordx4 v[128:131], v[4:5], off
	v_cndmask_b32_e64 v4, v41, v49, s[46:47]
	ds_swizzle_b32 v4, v4 offset:swizzle(SWAP,8)
	v_cndmask_b32_e64 v5, v42, v50, s[46:47]
	ds_swizzle_b32 v5, v5 offset:swizzle(SWAP,8)
	v_cndmask_b32_e64 v8, v44, v80, s[46:47]
	ds_swizzle_b32 v8, v8 offset:swizzle(SWAP,8)
	v_cndmask_b32_e64 v9, v45, v81, s[46:47]
	ds_swizzle_b32 v9, v9 offset:swizzle(SWAP,8)
	v_cndmask_b32_e64 v10, v46, v82, s[46:47]
	s_waitcnt lgkmcnt(3)
	v_add_f32_e32 v2, v2, v4
	v_cndmask_b32_e64 v4, v50, v42, s[46:47]
	ds_swizzle_b32 v10, v10 offset:swizzle(SWAP,8)
	v_cndmask_b32_e64 v11, v47, v62, s[46:47]
	s_waitcnt lgkmcnt(3)
	v_add_f32_e32 v4, v4, v5
	v_cndmask_b32_e64 v5, v51, v43, s[46:47]
	ds_swizzle_b32 v11, v11 offset:swizzle(SWAP,8)
	v_add_f32_e32 v5, v5, v7
	v_cndmask_b32_e64 v7, v80, v44, s[46:47]
	s_waitcnt lgkmcnt(3)
	v_add_f32_e32 v7, v7, v8
	v_cndmask_b32_e64 v8, v81, v45, s[46:47]
	s_waitcnt lgkmcnt(2)
	v_add_f32_e32 v8, v8, v9
	v_cndmask_b32_e64 v9, v82, v46, s[46:47]
	s_waitcnt lgkmcnt(1)
	v_add_f32_e32 v9, v9, v10
	v_cndmask_b32_e64 v10, v62, v47, s[46:47]
	s_waitcnt lgkmcnt(0)
	v_add_f32_e32 v10, v10, v11
	v_cndmask_b32_e64 v11, v6, v48, s[46:47]
	v_cndmask_b32_e64 v6, v48, v6, s[46:47]
	ds_swizzle_b32 v6, v6 offset:swizzle(SWAP,8)
	s_waitcnt lgkmcnt(0)
	v_add_f32_e32 v6, v11, v6
	v_cndmask_b32_e64 v11, v8, v2, s[44:45]
	v_cndmask_b32_e64 v2, v2, v8, s[44:45]
	v_cndmask_b32_e64 v8, v9, v4, s[44:45]
	v_cndmask_b32_e64 v4, v4, v9, s[44:45]
	ds_swizzle_b32 v4, v4 offset:swizzle(SWAP,4)
	ds_swizzle_b32 v2, v2 offset:swizzle(SWAP,4)
	s_waitcnt lgkmcnt(1)
	v_add_f32_e32 v4, v8, v4
	v_cndmask_b32_e64 v8, v10, v5, s[44:45]
	v_cndmask_b32_e64 v5, v5, v10, s[44:45]
	ds_swizzle_b32 v5, v5 offset:swizzle(SWAP,4)
	s_waitcnt lgkmcnt(1)
	v_add_f32_e32 v2, v11, v2
	s_waitcnt lgkmcnt(0)
	v_add_f32_e32 v5, v8, v5
	v_cndmask_b32_e64 v8, v6, v7, s[44:45]
	v_cndmask_b32_e64 v6, v7, v6, s[44:45]
	ds_swizzle_b32 v6, v6 offset:swizzle(SWAP,4)
	v_cndmask_b32_e64 v7, v5, v2, s[42:43]
	v_cndmask_b32_e64 v2, v2, v5, s[42:43]
	ds_swizzle_b32 v2, v2 offset:swizzle(SWAP,2)
	s_waitcnt lgkmcnt(1)
	v_add_f32_e32 v6, v8, v6
	v_cndmask_b32_e64 v5, v6, v4, s[42:43]
	v_cndmask_b32_e64 v4, v4, v6, s[42:43]
	ds_swizzle_b32 v4, v4 offset:swizzle(SWAP,2)
	s_waitcnt lgkmcnt(1)
	v_add_f32_e32 v2, v7, v2
	s_waitcnt lgkmcnt(0)
	v_add_f32_e32 v4, v5, v4
	v_cndmask_b32_e64 v5, v4, v2, s[40:41]
	v_cndmask_b32_e64 v2, v2, v4, s[40:41]
	ds_swizzle_b32 v2, v2 offset:swizzle(SWAP,1)
	s_waitcnt lgkmcnt(0)
	v_add_f32_e32 v2, v5, v2
	ds_swizzle_b32 v4, v2 offset:swizzle(SWAP,16)
	s_waitcnt lgkmcnt(0)
	v_add_f32_e32 v2, v2, v4
	v_mov_b32_e32 v4, v2
	s_nop 1
	v_permlane32_swap_b32_e32 v2, v4
	v_add_f32_e32 v6, v2, v4
	v_lshl_add_u32 v2, v40, 2, s14
	v_add_u32_e32 v4, 0xc0, v2
	ds_read2st64_b32 v[4:5], v4 offset0:9 offset1:17
	s_waitcnt lgkmcnt(0)
	v_mul_f32_e32 v4, v4, v6
	v_mul_f32_e32 v6, 0x3d372713, v4
	v_mul_f32_e32 v6, v4, v6
	v_fma_f32 v6, v4, v6, v4
	v_mul_f32_e32 v6, 0x3f4c422a, v6
	v_cmp_nlt_f32_e64 s[12:13], |v6|, s25
	s_and_saveexec_b64 s[26:27], s[12:13]
	s_xor_b64 s[12:13], exec, s[26:27]
	s_cbranch_execz .LBB0_1240
	v_add_f32_e64 v7, |v6|, |v6|
	v_mul_f32_e32 v8, 0x3fb8aa3b, v7
	v_rndne_f32_e32 v9, v8
	v_sub_f32_e32 v10, v8, v9
	v_fma_f32 v8, v7, s70, -v8
	v_fmac_f32_e32 v8, 0x32a5705f, v7
	v_add_f32_e32 v8, v10, v8
	v_cvt_i32_f32_e32 v9, v9
	v_exp_f32_e32 v8, v8
	v_cmp_ngt_f32_e64 s[40:41], s67, v7
	v_ldexp_f32 v8, v8, v9
	s_nop 0
	v_cndmask_b32_e64 v8, 0, v8, s[40:41]
	v_cmp_nlt_f32_e64 s[40:41], s68, v7
	s_nop 1
	v_cndmask_b32_e64 v7, v205, v8, s[40:41]
	v_add_f32_e32 v7, 1.0, v7
	v_rcp_f32_e32 v7, v7
	s_nop 0
	v_fma_f32 v7, v7, -2.0, 1.0
	s_andn2_saveexec_b64 s[12:13], s[12:13]
	s_cbranch_execnz .LBB0_1241

; #define P4_FOR16(M) M(0) M(1) M(2) M(3) M(4) M(5) M(6) M(7) M(8) M(9) M(10) M(11) M(12) M(13) M(14) M(15)
; #define P4_V(i) { const unsigned wu_ = (unsigned)__builtin_amdgcn_readlane((int)__float_as_uint(wreg), i); const unsigned long long wp_ = ((unsigned long long)wu_ << 32) | wu_; \
;               P4_ACC(b##i, wp_); const int nk_ = __builtin_amdgcn_readlane(ksel, nb + i); P4_LOAD(b##i, Vg, nk_); }
; #define P4_V(i) { const unsigned wu_ = (unsigned)__builtin_amdgcn_readlane((int)__float_as_uint(wreg), i); const unsigned long long wp_ = ((unsigned long long)wu_ << 32) | wu_; \
;               P4_ACC(b##i, wp_); const int nk_ = __builtin_amdgcn_readlane(kn, i); P4_LOAD(b##i, Vg, nk_); }
; #define P4_V(i) { const unsigned wu_ = (unsigned)__builtin_amdgcn_readlane((int)__float_as_uint(wreg), i); const unsigned long long wp_ = ((unsigned long long)wu_ << 32) | wu_; \
;               P4_ACC(b##i, wp_); }
; __device__ __forceinline__ void peer_gather_f4p(const float* X, const int* __restrict__ IDX, const float* __restrict__ G, ...
;     ...
;         for (int bt = 0; bt < 7; ++bt) {
;             const int ksel = (bt + 1 < 4) ? k0 : k1;
;             const int nb = (16 * (bt + 1)) & 63;
;             const float wreg = wbuf[kt * 128 + bt * 16 + (lane & 15)];
;     ...
;             P4_FOR16(P4_V)
;     ...
;         }
.LBB0_1247:
	ds_read_b32 v65, v171
	s_waitcnt vmcnt(15)
	v_cvt_scalef32_pk_f32_fp4 v[66:67], v4, 1.0
	v_cvt_scalef32_pk_f32_fp4 v[68:69], v4, 1.0 op_sel:[1,0,0]
	v_cvt_scalef32_pk_f32_fp4 v[70:71], v4, 1.0 op_sel:[0,1,0]
	s_cmp_lt_u32 s28, 3
	s_waitcnt lgkmcnt(0)
	v_readlane_b32 s16, v65, 0
	s_mov_b32 s17, s16
	v_cvt_scalef32_pk_f32_fp4 v[72:73], v4, 1.0 op_sel:[1,1,0]
	v_pk_fma_f32 v[132:133], s[16:17], v[66:67], v[132:133]
	v_pk_fma_f32 v[162:163], s[16:17], v[68:69], v[162:163]
	v_pk_fma_f32 v[160:161], s[16:17], v[70:71], v[160:161]
	s_cselect_b64 vcc, -1, 0
	v_pk_fma_f32 v[158:159], s[16:17], v[72:73], v[158:159]
	v_cvt_scalef32_pk_f32_fp4 v[66:67], v5, 1.0
	v_cvt_scalef32_pk_f32_fp4 v[68:69], v5, 1.0 op_sel:[1,0,0]
	v_cvt_scalef32_pk_f32_fp4 v[70:71], v5, 1.0 op_sel:[0,1,0]
	v_cvt_scalef32_pk_f32_fp4 v[4:5], v5, 1.0 op_sel:[1,1,0]
	v_cndmask_b32_e32 v64, v167, v166, vcc
	v_pk_fma_f32 v[156:157], s[16:17], v[66:67], v[156:157]
	v_pk_fma_f32 v[154:155], s[16:17], v[68:69], v[154:155]
	v_pk_fma_f32 v[152:153], s[16:17], v[70:71], v[152:153]
	v_pk_fma_f32 v[150:151], s[16:17], v[4:5], v[150:151]
	v_cvt_scalef32_pk_f32_fp4 v[4:5], v6, 1.0
	v_cvt_scalef32_pk_f32_fp4 v[66:67], v6, 1.0 op_sel:[1,0,0]
	v_cvt_scalef32_pk_f32_fp4 v[68:69], v6, 1.0 op_sel:[0,1,0]
	v_cvt_scalef32_pk_f32_fp4 v[70:71], v6, 1.0 op_sel:[1,1,0]
	s_mov_b32 s41, s86
	v_pk_fma_f32 v[148:149], s[16:17], v[4:5], v[148:149]
	v_pk_fma_f32 v[146:147], s[16:17], v[66:67], v[146:147]
	v_pk_fma_f32 v[144:145], s[16:17], v[68:69], v[144:145]
	v_pk_fma_f32 v[142:143], s[16:17], v[70:71], v[142:143]
	v_cvt_scalef32_pk_f32_fp4 v[4:5], v7, 1.0
	v_cvt_scalef32_pk_f32_fp4 v[66:67], v7, 1.0 op_sel:[1,0,0]
	v_cvt_scalef32_pk_f32_fp4 v[68:69], v7, 1.0 op_sel:[0,1,0]
	v_cvt_scalef32_pk_f32_fp4 v[6:7], v7, 1.0 op_sel:[1,1,0]
	s_add_i32 s28, s28, 1
	v_pk_fma_f32 v[140:141], s[16:17], v[4:5], v[140:141]
	v_pk_fma_f32 v[138:139], s[16:17], v[66:67], v[138:139]
	v_pk_fma_f32 v[136:137], s[16:17], v[68:69], v[136:137]
	v_pk_fma_f32 v[134:135], s[16:17], v[6:7], v[134:135]
	s_add_i32 s16, s27, -15
	v_readlane_b32 s16, v64, s16
	s_lshr_b32 s40, s16, 7
	v_readfirstlane_b32 s100, v168
	v_readfirstlane_b32 s101, v169
	v_subrev_u32_e32 v207, s100, v168
	s_lshl_b64 s[16:17], s[40:41], 10
	s_add_u32 s16, s16, s100
	s_addc_u32 s17, s17, s101
	global_load_dwordx4 v[4:7], v207, s[16:17]
	v_readlane_b32 s16, v65, 1
	s_waitcnt vmcnt(15)
	v_cvt_scalef32_pk_f32_fp4 v[66:67], v8, 1.0
	v_cvt_scalef32_pk_f32_fp4 v[68:69], v8, 1.0 op_sel:[1,0,0]
	v_cvt_scalef32_pk_f32_fp4 v[70:71], v8, 1.0 op_sel:[0,1,0]
	s_mov_b32 s17, s16
	v_cvt_scalef32_pk_f32_fp4 v[72:73], v8, 1.0 op_sel:[1,1,0]
	v_pk_fma_f32 v[132:133], s[16:17], v[66:67], v[132:133]
	v_pk_fma_f32 v[162:163], s[16:17], v[68:69], v[162:163]
	v_pk_fma_f32 v[160:161], s[16:17], v[70:71], v[160:161]
	v_add_u32_e32 v171, 64, v171
	v_pk_fma_f32 v[158:159], s[16:17], v[72:73], v[158:159]
	v_cvt_scalef32_pk_f32_fp4 v[66:67], v9, 1.0
	v_cvt_scalef32_pk_f32_fp4 v[68:69], v9, 1.0 op_sel:[1,0,0]
	v_cvt_scalef32_pk_f32_fp4 v[70:71], v9, 1.0 op_sel:[0,1,0]
	v_cvt_scalef32_pk_f32_fp4 v[8:9], v9, 1.0 op_sel:[1,1,0]
	v_pk_fma_f32 v[156:157], s[16:17], v[66:67], v[156:157]
	v_pk_fma_f32 v[154:155], s[16:17], v[68:69], v[154:155]
	v_pk_fma_f32 v[152:153], s[16:17], v[70:71], v[152:153]
	v_pk_fma_f32 v[150:151], s[16:17], v[8:9], v[150:151]
	v_cvt_scalef32_pk_f32_fp4 v[8:9], v10, 1.0
	v_cvt_scalef32_pk_f32_fp4 v[66:67], v10, 1.0 op_sel:[1,0,0]
	v_cvt_scalef32_pk_f32_fp4 v[68:69], v10, 1.0 op_sel:[0,1,0]
	v_cvt_scalef32_pk_f32_fp4 v[70:71], v10, 1.0 op_sel:[1,1,0]
	v_pk_fma_f32 v[148:149], s[16:17], v[8:9], v[148:149]
	v_pk_fma_f32 v[146:147], s[16:17], v[66:67], v[146:147]
	v_pk_fma_f32 v[144:145], s[16:17], v[68:69], v[144:145]
	v_pk_fma_f32 v[142:143], s[16:17], v[70:71], v[142:143]
	v_cvt_scalef32_pk_f32_fp4 v[8:9], v11, 1.0
	v_cvt_scalef32_pk_f32_fp4 v[66:67], v11, 1.0 op_sel:[1,0,0]
	v_cvt_scalef32_pk_f32_fp4 v[68:69], v11, 1.0 op_sel:[0,1,0]
	v_cvt_scalef32_pk_f32_fp4 v[10:11], v11, 1.0 op_sel:[1,1,0]
	v_pk_fma_f32 v[140:141], s[16:17], v[8:9], v[140:141]
	v_pk_fma_f32 v[138:139], s[16:17], v[66:67], v[138:139]
	v_pk_fma_f32 v[136:137], s[16:17], v[68:69], v[136:137]
	v_pk_fma_f32 v[134:135], s[16:17], v[10:11], v[134:135]
	s_add_i32 s16, s27, -14
	v_readlane_b32 s16, v64, s16
	s_lshr_b32 s40, s16, 7
	s_lshl_b64 s[16:17], s[40:41], 10
	s_add_u32 s16, s16, s100
	s_addc_u32 s17, s17, s101
	global_load_dwordx4 v[8:11], v207, s[16:17]
	v_readlane_b32 s16, v65, 2
	s_waitcnt vmcnt(15)
	v_cvt_scalef32_pk_f32_fp4 v[66:67], v12, 1.0
	v_cvt_scalef32_pk_f32_fp4 v[68:69], v12, 1.0 op_sel:[1,0,0]
	v_cvt_scalef32_pk_f32_fp4 v[70:71], v12, 1.0 op_sel:[0,1,0]
	s_mov_b32 s17, s16
	v_cvt_scalef32_pk_f32_fp4 v[72:73], v12, 1.0 op_sel:[1,1,0]
	v_pk_fma_f32 v[132:133], s[16:17], v[66:67], v[132:133]
	v_pk_fma_f32 v[162:163], s[16:17], v[68:69], v[162:163]
	v_pk_fma_f32 v[160:161], s[16:17], v[70:71], v[160:161]
	v_pk_fma_f32 v[158:159], s[16:17], v[72:73], v[158:159]
	v_cvt_scalef32_pk_f32_fp4 v[66:67], v13, 1.0
	v_cvt_scalef32_pk_f32_fp4 v[68:69], v13, 1.0 op_sel:[1,0,0]
	v_cvt_scalef32_pk_f32_fp4 v[70:71], v13, 1.0 op_sel:[0,1,0]
	v_cvt_scalef32_pk_f32_fp4 v[12:13], v13, 1.0 op_sel:[1,1,0]
	v_pk_fma_f32 v[156:157], s[16:17], v[66:67], v[156:157]
	v_pk_fma_f32 v[154:155], s[16:17], v[68:69], v[154:155]
	v_pk_fma_f32 v[152:153], s[16:17], v[70:71], v[152:153]
	v_pk_fma_f32 v[150:151], s[16:17], v[12:13], v[150:151]
	v_cvt_scalef32_pk_f32_fp4 v[12:13], v14, 1.0
	v_cvt_scalef32_pk_f32_fp4 v[66:67], v14, 1.0 op_sel:[1,0,0]
	v_cvt_scalef32_pk_f32_fp4 v[68:69], v14, 1.0 op_sel:[0,1,0]
	v_cvt_scalef32_pk_f32_fp4 v[70:71], v14, 1.0 op_sel:[1,1,0]
	v_pk_fma_f32 v[148:149], s[16:17], v[12:13], v[148:149]
	v_pk_fma_f32 v[146:147], s[16:17], v[66:67], v[146:147]
	v_pk_fma_f32 v[144:145], s[16:17], v[68:69], v[144:145]
	v_pk_fma_f32 v[142:143], s[16:17], v[70:71], v[142:143]
	v_cvt_scalef32_pk_f32_fp4 v[12:13], v15, 1.0
	v_cvt_scalef32_pk_f32_fp4 v[66:67], v15, 1.0 op_sel:[1,0,0]
	v_cvt_scalef32_pk_f32_fp4 v[68:69], v15, 1.0 op_sel:[0,1,0]
	v_cvt_scalef32_pk_f32_fp4 v[14:15], v15, 1.0 op_sel:[1,1,0]
	v_pk_fma_f32 v[140:141], s[16:17], v[12:13], v[140:141]
	v_pk_fma_f32 v[138:139], s[16:17], v[66:67], v[138:139]
	v_pk_fma_f32 v[136:137], s[16:17], v[68:69], v[136:137]
	v_pk_fma_f32 v[134:135], s[16:17], v[14:15], v[134:135]
	s_add_i32 s16, s27, -13
	v_readlane_b32 s16, v64, s16
	s_lshr_b32 s40, s16, 7
	s_lshl_b64 s[16:17], s[40:41], 10
	s_add_u32 s16, s16, s100
	s_addc_u32 s17, s17, s101
	global_load_dwordx4 v[12:15], v207, s[16:17]
	v_readlane_b32 s16, v65, 3
	s_waitcnt vmcnt(15)
; #define P4_FOR16(M) M(0) M(1) M(2) M(3) M(4) M(5) M(6) M(7) M(8) M(9) M(10) M(11) M(12) M(13) M(14) M(15)
; #define P4_V(i) { const unsigned wu_ = (unsigned)__builtin_amdgcn_readlane((int)__float_as_uint(wreg), i); const unsigned long long wp_ = ((unsigned long long)wu_ << 32) | wu_; \
;               P4_ACC(b##i, wp_); const int nk_ = __builtin_amdgcn_readlane(ksel, nb + i); P4_LOAD(b##i, Vg, nk_); }
; #define P4_V(i) { const unsigned wu_ = (unsigned)__builtin_amdgcn_readlane((int)__float_as_uint(wreg), i); const unsigned long long wp_ = ((unsigned long long)wu_ << 32) | wu_; \
;               P4_ACC(b##i, wp_); const int nk_ = __builtin_amdgcn_readlane(kn, i); P4_LOAD(b##i, Vg, nk_); }
; #define P4_V(i) { const unsigned wu_ = (unsigned)__builtin_amdgcn_readlane((int)__float_as_uint(wreg), i); const unsigned long long wp_ = ((unsigned long long)wu_ << 32) | wu_; \
;               P4_ACC(b##i, wp_); }
; __device__ __forceinline__ void peer_gather_f4p(const float* X, const int* __restrict__ IDX, const float* __restrict__ G, ...
;     ...
;         for (int bt = 0; bt < 7; ++bt) {
;             const int ksel = (bt + 1 < 4) ? k0 : k1;
;             const int nb = (16 * (bt + 1)) & 63;
;             const float wreg = wbuf[kt * 128 + bt * 16 + (lane & 15)];
;     ...
;             P4_FOR16(P4_V)
;     ...
;         }
	v_cvt_scalef32_pk_f32_fp4 v[66:67], v16, 1.0
	v_cvt_scalef32_pk_f32_fp4 v[68:69], v16, 1.0 op_sel:[1,0,0]
	v_cvt_scalef32_pk_f32_fp4 v[70:71], v16, 1.0 op_sel:[0,1,0]
	s_mov_b32 s17, s16
	v_cvt_scalef32_pk_f32_fp4 v[72:73], v16, 1.0 op_sel:[1,1,0]
	v_pk_fma_f32 v[132:133], s[16:17], v[66:67], v[132:133]
	v_pk_fma_f32 v[162:163], s[16:17], v[68:69], v[162:163]
	v_pk_fma_f32 v[160:161], s[16:17], v[70:71], v[160:161]
	v_pk_fma_f32 v[158:159], s[16:17], v[72:73], v[158:159]
	v_cvt_scalef32_pk_f32_fp4 v[66:67], v17, 1.0
	v_cvt_scalef32_pk_f32_fp4 v[68:69], v17, 1.0 op_sel:[1,0,0]
	v_cvt_scalef32_pk_f32_fp4 v[70:71], v17, 1.0 op_sel:[0,1,0]
	v_cvt_scalef32_pk_f32_fp4 v[16:17], v17, 1.0 op_sel:[1,1,0]
	v_pk_fma_f32 v[156:157], s[16:17], v[66:67], v[156:157]
	v_pk_fma_f32 v[154:155], s[16:17], v[68:69], v[154:155]
	v_pk_fma_f32 v[152:153], s[16:17], v[70:71], v[152:153]
	v_pk_fma_f32 v[150:151], s[16:17], v[16:17], v[150:151]
	v_cvt_scalef32_pk_f32_fp4 v[16:17], v18, 1.0
	v_cvt_scalef32_pk_f32_fp4 v[66:67], v18, 1.0 op_sel:[1,0,0]
	v_cvt_scalef32_pk_f32_fp4 v[68:69], v18, 1.0 op_sel:[0,1,0]
	v_cvt_scalef32_pk_f32_fp4 v[70:71], v18, 1.0 op_sel:[1,1,0]
	v_pk_fma_f32 v[148:149], s[16:17], v[16:17], v[148:149]
	v_pk_fma_f32 v[146:147], s[16:17], v[66:67], v[146:147]
	v_pk_fma_f32 v[144:145], s[16:17], v[68:69], v[144:145]
	v_pk_fma_f32 v[142:143], s[16:17], v[70:71], v[142:143]
	v_cvt_scalef32_pk_f32_fp4 v[16:17], v19, 1.0
	v_cvt_scalef32_pk_f32_fp4 v[66:67], v19, 1.0 op_sel:[1,0,0]
	v_cvt_scalef32_pk_f32_fp4 v[68:69], v19, 1.0 op_sel:[0,1,0]
	v_cvt_scalef32_pk_f32_fp4 v[18:19], v19, 1.0 op_sel:[1,1,0]
	v_pk_fma_f32 v[140:141], s[16:17], v[16:17], v[140:141]
	v_pk_fma_f32 v[138:139], s[16:17], v[66:67], v[138:139]
	v_pk_fma_f32 v[136:137], s[16:17], v[68:69], v[136:137]
	v_pk_fma_f32 v[134:135], s[16:17], v[18:19], v[134:135]
	s_add_i32 s16, s27, -12
	v_readlane_b32 s16, v64, s16
	s_lshr_b32 s40, s16, 7
	s_lshl_b64 s[16:17], s[40:41], 10
	s_add_u32 s16, s16, s100
	s_addc_u32 s17, s17, s101
	global_load_dwordx4 v[16:19], v207, s[16:17]
	v_readlane_b32 s16, v65, 4
	s_waitcnt vmcnt(15)
	v_cvt_scalef32_pk_f32_fp4 v[66:67], v20, 1.0
	v_cvt_scalef32_pk_f32_fp4 v[68:69], v20, 1.0 op_sel:[1,0,0]
	v_cvt_scalef32_pk_f32_fp4 v[70:71], v20, 1.0 op_sel:[0,1,0]
	s_mov_b32 s17, s16
	v_cvt_scalef32_pk_f32_fp4 v[72:73], v20, 1.0 op_sel:[1,1,0]
	v_pk_fma_f32 v[132:133], s[16:17], v[66:67], v[132:133]
	v_pk_fma_f32 v[162:163], s[16:17], v[68:69], v[162:163]
	v_pk_fma_f32 v[160:161], s[16:17], v[70:71], v[160:161]
	v_pk_fma_f32 v[158:159], s[16:17], v[72:73], v[158:159]
	v_cvt_scalef32_pk_f32_fp4 v[66:67], v21, 1.0
	v_cvt_scalef32_pk_f32_fp4 v[68:69], v21, 1.0 op_sel:[1,0,0]
	v_cvt_scalef32_pk_f32_fp4 v[70:71], v21, 1.0 op_sel:[0,1,0]
	v_cvt_scalef32_pk_f32_fp4 v[20:21], v21, 1.0 op_sel:[1,1,0]
	v_pk_fma_f32 v[156:157], s[16:17], v[66:67], v[156:157]
	v_pk_fma_f32 v[154:155], s[16:17], v[68:69], v[154:155]
	v_pk_fma_f32 v[152:153], s[16:17], v[70:71], v[152:153]
	v_pk_fma_f32 v[150:151], s[16:17], v[20:21], v[150:151]
	v_cvt_scalef32_pk_f32_fp4 v[20:21], v22, 1.0
	v_cvt_scalef32_pk_f32_fp4 v[66:67], v22, 1.0 op_sel:[1,0,0]
	v_cvt_scalef32_pk_f32_fp4 v[68:69], v22, 1.0 op_sel:[0,1,0]
	v_cvt_scalef32_pk_f32_fp4 v[70:71], v22, 1.0 op_sel:[1,1,0]
	v_pk_fma_f32 v[148:149], s[16:17], v[20:21], v[148:149]
	v_pk_fma_f32 v[146:147], s[16:17], v[66:67], v[146:147]
	v_pk_fma_f32 v[144:145], s[16:17], v[68:69], v[144:145]
	v_pk_fma_f32 v[142:143], s[16:17], v[70:71], v[142:143]
	v_cvt_scalef32_pk_f32_fp4 v[20:21], v23, 1.0
	v_cvt_scalef32_pk_f32_fp4 v[66:67], v23, 1.0 op_sel:[1,0,0]
	v_cvt_scalef32_pk_f32_fp4 v[68:69], v23, 1.0 op_sel:[0,1,0]
	v_cvt_scalef32_pk_f32_fp4 v[22:23], v23, 1.0 op_sel:[1,1,0]
	v_pk_fma_f32 v[140:141], s[16:17], v[20:21], v[140:141]
	v_pk_fma_f32 v[138:139], s[16:17], v[66:67], v[138:139]
	v_pk_fma_f32 v[136:137], s[16:17], v[68:69], v[136:137]
	v_pk_fma_f32 v[134:135], s[16:17], v[22:23], v[134:135]
	s_add_i32 s16, s27, -11
	v_readlane_b32 s16, v64, s16
	s_lshr_b32 s40, s16, 7
	s_lshl_b64 s[16:17], s[40:41], 10
	s_add_u32 s16, s16, s100
	s_addc_u32 s17, s17, s101
	global_load_dwordx4 v[20:23], v207, s[16:17]
	v_readlane_b32 s16, v65, 5
	s_waitcnt vmcnt(15)
	v_cvt_scalef32_pk_f32_fp4 v[66:67], v24, 1.0
	v_cvt_scalef32_pk_f32_fp4 v[68:69], v24, 1.0 op_sel:[1,0,0]
	v_cvt_scalef32_pk_f32_fp4 v[70:71], v24, 1.0 op_sel:[0,1,0]
	s_mov_b32 s17, s16
	v_cvt_scalef32_pk_f32_fp4 v[72:73], v24, 1.0 op_sel:[1,1,0]
	v_pk_fma_f32 v[132:133], s[16:17], v[66:67], v[132:133]
	v_pk_fma_f32 v[162:163], s[16:17], v[68:69], v[162:163]
	v_pk_fma_f32 v[160:161], s[16:17], v[70:71], v[160:161]
	v_pk_fma_f32 v[158:159], s[16:17], v[72:73], v[158:159]
	v_cvt_scalef32_pk_f32_fp4 v[66:67], v25, 1.0
	v_cvt_scalef32_pk_f32_fp4 v[68:69], v25, 1.0 op_sel:[1,0,0]
	v_cvt_scalef32_pk_f32_fp4 v[70:71], v25, 1.0 op_sel:[0,1,0]
	v_cvt_scalef32_pk_f32_fp4 v[24:25], v25, 1.0 op_sel:[1,1,0]
	v_pk_fma_f32 v[156:157], s[16:17], v[66:67], v[156:157]
	v_pk_fma_f32 v[154:155], s[16:17], v[68:69], v[154:155]
	v_pk_fma_f32 v[152:153], s[16:17], v[70:71], v[152:153]
	v_pk_fma_f32 v[150:151], s[16:17], v[24:25], v[150:151]
	v_cvt_scalef32_pk_f32_fp4 v[24:25], v26, 1.0
	v_cvt_scalef32_pk_f32_fp4 v[66:67], v26, 1.0 op_sel:[1,0,0]
	v_cvt_scalef32_pk_f32_fp4 v[68:69], v26, 1.0 op_sel:[0,1,0]
	v_cvt_scalef32_pk_f32_fp4 v[70:71], v26, 1.0 op_sel:[1,1,0]
	v_pk_fma_f32 v[148:149], s[16:17], v[24:25], v[148:149]
	v_pk_fma_f32 v[146:147], s[16:17], v[66:67], v[146:147]
	v_pk_fma_f32 v[144:145], s[16:17], v[68:69], v[144:145]
	v_pk_fma_f32 v[142:143], s[16:17], v[70:71], v[142:143]
	v_cvt_scalef32_pk_f32_fp4 v[24:25], v27, 1.0
	v_cvt_scalef32_pk_f32_fp4 v[66:67], v27, 1.0 op_sel:[1,0,0]
	v_cvt_scalef32_pk_f32_fp4 v[68:69], v27, 1.0 op_sel:[0,1,0]
	v_cvt_scalef32_pk_f32_fp4 v[26:27], v27, 1.0 op_sel:[1,1,0]
	v_pk_fma_f32 v[140:141], s[16:17], v[24:25], v[140:141]
	v_pk_fma_f32 v[138:139], s[16:17], v[66:67], v[138:139]
	v_pk_fma_f32 v[136:137], s[16:17], v[68:69], v[136:137]
	v_pk_fma_f32 v[134:135], s[16:17], v[26:27], v[134:135]
	s_add_i32 s16, s27, -10
	v_readlane_b32 s16, v64, s16
	s_lshr_b32 s40, s16, 7
	s_lshl_b64 s[16:17], s[40:41], 10
	s_add_u32 s16, s16, s100
	s_addc_u32 s17, s17, s101
	global_load_dwordx4 v[24:27], v207, s[16:17]
	v_readlane_b32 s16, v65, 6
	s_waitcnt vmcnt(15)
; #define P4_FOR16(M) M(0) M(1) M(2) M(3) M(4) M(5) M(6) M(7) M(8) M(9) M(10) M(11) M(12) M(13) M(14) M(15)
; #define P4_V(i) { const unsigned wu_ = (unsigned)__builtin_amdgcn_readlane((int)__float_as_uint(wreg), i); const unsigned long long wp_ = ((unsigned long long)wu_ << 32) | wu_; \
;               P4_ACC(b##i, wp_); const int nk_ = __builtin_amdgcn_readlane(ksel, nb + i); P4_LOAD(b##i, Vg, nk_); }
; #define P4_V(i) { const unsigned wu_ = (unsigned)__builtin_amdgcn_readlane((int)__float_as_uint(wreg), i); const unsigned long long wp_ = ((unsigned long long)wu_ << 32) | wu_; \
;               P4_ACC(b##i, wp_); const int nk_ = __builtin_amdgcn_readlane(kn, i); P4_LOAD(b##i, Vg, nk_); }
; #define P4_V(i) { const unsigned wu_ = (unsigned)__builtin_amdgcn_readlane((int)__float_as_uint(wreg), i); const unsigned long long wp_ = ((unsigned long long)wu_ << 32) | wu_; \
;               P4_ACC(b##i, wp_); }
; __device__ __forceinline__ void peer_gather_f4p(const float* X, const int* __restrict__ IDX, const float* __restrict__ G, ...
;     ...
;         for (int bt = 0; bt < 7; ++bt) {
;             const int ksel = (bt + 1 < 4) ? k0 : k1;
;             const int nb = (16 * (bt + 1)) & 63;
;             const float wreg = wbuf[kt * 128 + bt * 16 + (lane & 15)];
;     ...
;             P4_FOR16(P4_V)
	v_cvt_scalef32_pk_f32_fp4 v[66:67], v28, 1.0
	v_cvt_scalef32_pk_f32_fp4 v[68:69], v28, 1.0 op_sel:[1,0,0]
	v_cvt_scalef32_pk_f32_fp4 v[70:71], v28, 1.0 op_sel:[0,1,0]
	s_mov_b32 s17, s16
	v_cvt_scalef32_pk_f32_fp4 v[72:73], v28, 1.0 op_sel:[1,1,0]
	v_pk_fma_f32 v[132:133], s[16:17], v[66:67], v[132:133]
	v_pk_fma_f32 v[162:163], s[16:17], v[68:69], v[162:163]
	v_pk_fma_f32 v[160:161], s[16:17], v[70:71], v[160:161]
	v_pk_fma_f32 v[158:159], s[16:17], v[72:73], v[158:159]
	v_cvt_scalef32_pk_f32_fp4 v[66:67], v29, 1.0
	v_cvt_scalef32_pk_f32_fp4 v[68:69], v29, 1.0 op_sel:[1,0,0]
	v_cvt_scalef32_pk_f32_fp4 v[70:71], v29, 1.0 op_sel:[0,1,0]
	v_cvt_scalef32_pk_f32_fp4 v[28:29], v29, 1.0 op_sel:[1,1,0]
	v_pk_fma_f32 v[156:157], s[16:17], v[66:67], v[156:157]
	v_pk_fma_f32 v[154:155], s[16:17], v[68:69], v[154:155]
	v_pk_fma_f32 v[152:153], s[16:17], v[70:71], v[152:153]
	v_pk_fma_f32 v[150:151], s[16:17], v[28:29], v[150:151]
	v_cvt_scalef32_pk_f32_fp4 v[28:29], v30, 1.0
	v_cvt_scalef32_pk_f32_fp4 v[66:67], v30, 1.0 op_sel:[1,0,0]
	v_cvt_scalef32_pk_f32_fp4 v[68:69], v30, 1.0 op_sel:[0,1,0]
	v_cvt_scalef32_pk_f32_fp4 v[70:71], v30, 1.0 op_sel:[1,1,0]
	v_pk_fma_f32 v[148:149], s[16:17], v[28:29], v[148:149]
	v_pk_fma_f32 v[146:147], s[16:17], v[66:67], v[146:147]
	v_pk_fma_f32 v[144:145], s[16:17], v[68:69], v[144:145]
	v_pk_fma_f32 v[142:143], s[16:17], v[70:71], v[142:143]
	v_cvt_scalef32_pk_f32_fp4 v[28:29], v31, 1.0
	v_cvt_scalef32_pk_f32_fp4 v[66:67], v31, 1.0 op_sel:[1,0,0]
	v_cvt_scalef32_pk_f32_fp4 v[68:69], v31, 1.0 op_sel:[0,1,0]
	v_cvt_scalef32_pk_f32_fp4 v[30:31], v31, 1.0 op_sel:[1,1,0]
	v_pk_fma_f32 v[140:141], s[16:17], v[28:29], v[140:141]
	v_pk_fma_f32 v[138:139], s[16:17], v[66:67], v[138:139]
	v_pk_fma_f32 v[136:137], s[16:17], v[68:69], v[136:137]
	v_pk_fma_f32 v[134:135], s[16:17], v[30:31], v[134:135]
	s_add_i32 s16, s27, -9
	v_readlane_b32 s16, v64, s16
	s_lshr_b32 s40, s16, 7
	s_lshl_b64 s[16:17], s[40:41], 10
	s_add_u32 s16, s16, s100
	s_addc_u32 s17, s17, s101
	global_load_dwordx4 v[28:31], v207, s[16:17]
	v_readlane_b32 s16, v65, 7
	s_waitcnt vmcnt(15)
	v_cvt_scalef32_pk_f32_fp4 v[66:67], v32, 1.0
	v_cvt_scalef32_pk_f32_fp4 v[68:69], v32, 1.0 op_sel:[1,0,0]
	v_cvt_scalef32_pk_f32_fp4 v[70:71], v32, 1.0 op_sel:[0,1,0]
	s_mov_b32 s17, s16
	v_cvt_scalef32_pk_f32_fp4 v[72:73], v32, 1.0 op_sel:[1,1,0]
	v_pk_fma_f32 v[132:133], s[16:17], v[66:67], v[132:133]
	v_pk_fma_f32 v[162:163], s[16:17], v[68:69], v[162:163]
	v_pk_fma_f32 v[160:161], s[16:17], v[70:71], v[160:161]
	v_pk_fma_f32 v[158:159], s[16:17], v[72:73], v[158:159]
	v_cvt_scalef32_pk_f32_fp4 v[66:67], v33, 1.0
	v_cvt_scalef32_pk_f32_fp4 v[68:69], v33, 1.0 op_sel:[1,0,0]
	v_cvt_scalef32_pk_f32_fp4 v[70:71], v33, 1.0 op_sel:[0,1,0]
	v_cvt_scalef32_pk_f32_fp4 v[32:33], v33, 1.0 op_sel:[1,1,0]
	v_pk_fma_f32 v[156:157], s[16:17], v[66:67], v[156:157]
	v_pk_fma_f32 v[154:155], s[16:17], v[68:69], v[154:155]
	v_pk_fma_f32 v[152:153], s[16:17], v[70:71], v[152:153]
	v_pk_fma_f32 v[150:151], s[16:17], v[32:33], v[150:151]
	v_cvt_scalef32_pk_f32_fp4 v[32:33], v34, 1.0
	v_cvt_scalef32_pk_f32_fp4 v[66:67], v34, 1.0 op_sel:[1,0,0]
	v_cvt_scalef32_pk_f32_fp4 v[68:69], v34, 1.0 op_sel:[0,1,0]
	v_cvt_scalef32_pk_f32_fp4 v[70:71], v34, 1.0 op_sel:[1,1,0]
	v_pk_fma_f32 v[148:149], s[16:17], v[32:33], v[148:149]
	v_pk_fma_f32 v[146:147], s[16:17], v[66:67], v[146:147]
	v_pk_fma_f32 v[144:145], s[16:17], v[68:69], v[144:145]
	v_pk_fma_f32 v[142:143], s[16:17], v[70:71], v[142:143]
	v_cvt_scalef32_pk_f32_fp4 v[32:33], v35, 1.0
	v_cvt_scalef32_pk_f32_fp4 v[66:67], v35, 1.0 op_sel:[1,0,0]
	v_cvt_scalef32_pk_f32_fp4 v[68:69], v35, 1.0 op_sel:[0,1,0]
	v_cvt_scalef32_pk_f32_fp4 v[34:35], v35, 1.0 op_sel:[1,1,0]
	v_pk_fma_f32 v[140:141], s[16:17], v[32:33], v[140:141]
	v_pk_fma_f32 v[138:139], s[16:17], v[66:67], v[138:139]
	v_pk_fma_f32 v[136:137], s[16:17], v[68:69], v[136:137]
	v_pk_fma_f32 v[134:135], s[16:17], v[34:35], v[134:135]
	s_add_i32 s16, s27, -8
	v_readlane_b32 s16, v64, s16
	s_lshr_b32 s40, s16, 7
	s_lshl_b64 s[16:17], s[40:41], 10
	s_add_u32 s16, s16, s100
	s_addc_u32 s17, s17, s101
	global_load_dwordx4 v[32:35], v207, s[16:17]
	v_readlane_b32 s16, v65, 8
	s_waitcnt vmcnt(15)
	v_cvt_scalef32_pk_f32_fp4 v[66:67], v36, 1.0
	v_cvt_scalef32_pk_f32_fp4 v[68:69], v36, 1.0 op_sel:[1,0,0]
	v_cvt_scalef32_pk_f32_fp4 v[70:71], v36, 1.0 op_sel:[0,1,0]
	s_mov_b32 s17, s16
	v_cvt_scalef32_pk_f32_fp4 v[72:73], v36, 1.0 op_sel:[1,1,0]
	v_pk_fma_f32 v[132:133], s[16:17], v[66:67], v[132:133]
	v_pk_fma_f32 v[162:163], s[16:17], v[68:69], v[162:163]
	v_pk_fma_f32 v[160:161], s[16:17], v[70:71], v[160:161]
	v_pk_fma_f32 v[158:159], s[16:17], v[72:73], v[158:159]
	v_cvt_scalef32_pk_f32_fp4 v[66:67], v37, 1.0
	v_cvt_scalef32_pk_f32_fp4 v[68:69], v37, 1.0 op_sel:[1,0,0]
	v_cvt_scalef32_pk_f32_fp4 v[70:71], v37, 1.0 op_sel:[0,1,0]
	v_cvt_scalef32_pk_f32_fp4 v[36:37], v37, 1.0 op_sel:[1,1,0]
	v_pk_fma_f32 v[156:157], s[16:17], v[66:67], v[156:157]
	v_pk_fma_f32 v[154:155], s[16:17], v[68:69], v[154:155]
	v_pk_fma_f32 v[152:153], s[16:17], v[70:71], v[152:153]
	v_pk_fma_f32 v[150:151], s[16:17], v[36:37], v[150:151]
	v_cvt_scalef32_pk_f32_fp4 v[36:37], v38, 1.0
	v_cvt_scalef32_pk_f32_fp4 v[66:67], v38, 1.0 op_sel:[1,0,0]
	v_cvt_scalef32_pk_f32_fp4 v[68:69], v38, 1.0 op_sel:[0,1,0]
	v_cvt_scalef32_pk_f32_fp4 v[70:71], v38, 1.0 op_sel:[1,1,0]
	v_pk_fma_f32 v[148:149], s[16:17], v[36:37], v[148:149]
	v_pk_fma_f32 v[146:147], s[16:17], v[66:67], v[146:147]
	v_pk_fma_f32 v[144:145], s[16:17], v[68:69], v[144:145]
	v_pk_fma_f32 v[142:143], s[16:17], v[70:71], v[142:143]
	v_cvt_scalef32_pk_f32_fp4 v[36:37], v39, 1.0
	v_cvt_scalef32_pk_f32_fp4 v[66:67], v39, 1.0 op_sel:[1,0,0]
	v_cvt_scalef32_pk_f32_fp4 v[68:69], v39, 1.0 op_sel:[0,1,0]
	v_cvt_scalef32_pk_f32_fp4 v[38:39], v39, 1.0 op_sel:[1,1,0]
	v_pk_fma_f32 v[140:141], s[16:17], v[36:37], v[140:141]
	v_pk_fma_f32 v[138:139], s[16:17], v[66:67], v[138:139]
	v_pk_fma_f32 v[136:137], s[16:17], v[68:69], v[136:137]
	v_pk_fma_f32 v[134:135], s[16:17], v[38:39], v[134:135]
	s_add_i32 s16, s27, -7
	v_readlane_b32 s16, v64, s16
	s_lshr_b32 s40, s16, 7
	s_lshl_b64 s[16:17], s[40:41], 10
	s_add_u32 s16, s16, s100
	s_addc_u32 s17, s17, s101
	global_load_dwordx4 v[36:39], v207, s[16:17]
	v_readlane_b32 s16, v65, 9
	s_waitcnt vmcnt(15)
; #define P4_FOR16(M) M(0) M(1) M(2) M(3) M(4) M(5) M(6) M(7) M(8) M(9) M(10) M(11) M(12) M(13) M(14) M(15)
; #define P4_V(i) { const unsigned wu_ = (unsigned)__builtin_amdgcn_readlane((int)__float_as_uint(wreg), i); const unsigned long long wp_ = ((unsigned long long)wu_ << 32) | wu_; \
;               P4_ACC(b##i, wp_); const int nk_ = __builtin_amdgcn_readlane(ksel, nb + i); P4_LOAD(b##i, Vg, nk_); }
; #define P4_V(i) { const unsigned wu_ = (unsigned)__builtin_amdgcn_readlane((int)__float_as_uint(wreg), i); const unsigned long long wp_ = ((unsigned long long)wu_ << 32) | wu_; \
;               P4_ACC(b##i, wp_); const int nk_ = __builtin_amdgcn_readlane(kn, i); P4_LOAD(b##i, Vg, nk_); }
; #define P4_V(i) { const unsigned wu_ = (unsigned)__builtin_amdgcn_readlane((int)__float_as_uint(wreg), i); const unsigned long long wp_ = ((unsigned long long)wu_ << 32) | wu_; \
;               P4_ACC(b##i, wp_); }
; __device__ __forceinline__ void peer_gather_f4p(const float* X, const int* __restrict__ IDX, const float* __restrict__ G, ...
;     ...
;         for (int bt = 0; bt < 7; ++bt) {
;             const int ksel = (bt + 1 < 4) ? k0 : k1;
;             const int nb = (16 * (bt + 1)) & 63;
;             const float wreg = wbuf[kt * 128 + bt * 16 + (lane & 15)];
;     ...
;             P4_FOR16(P4_V)
	v_cvt_scalef32_pk_f32_fp4 v[66:67], v40, 1.0
	v_cvt_scalef32_pk_f32_fp4 v[68:69], v40, 1.0 op_sel:[1,0,0]
	v_cvt_scalef32_pk_f32_fp4 v[70:71], v40, 1.0 op_sel:[0,1,0]
	s_mov_b32 s17, s16
	v_cvt_scalef32_pk_f32_fp4 v[72:73], v40, 1.0 op_sel:[1,1,0]
	v_pk_fma_f32 v[132:133], s[16:17], v[66:67], v[132:133]
	v_pk_fma_f32 v[162:163], s[16:17], v[68:69], v[162:163]
	v_pk_fma_f32 v[160:161], s[16:17], v[70:71], v[160:161]
	v_pk_fma_f32 v[158:159], s[16:17], v[72:73], v[158:159]
	v_cvt_scalef32_pk_f32_fp4 v[66:67], v41, 1.0
	v_cvt_scalef32_pk_f32_fp4 v[68:69], v41, 1.0 op_sel:[1,0,0]
	v_cvt_scalef32_pk_f32_fp4 v[70:71], v41, 1.0 op_sel:[0,1,0]
	v_cvt_scalef32_pk_f32_fp4 v[40:41], v41, 1.0 op_sel:[1,1,0]
	v_pk_fma_f32 v[156:157], s[16:17], v[66:67], v[156:157]
	v_pk_fma_f32 v[154:155], s[16:17], v[68:69], v[154:155]
	v_pk_fma_f32 v[152:153], s[16:17], v[70:71], v[152:153]
	v_pk_fma_f32 v[150:151], s[16:17], v[40:41], v[150:151]
	v_cvt_scalef32_pk_f32_fp4 v[40:41], v42, 1.0
	v_cvt_scalef32_pk_f32_fp4 v[66:67], v42, 1.0 op_sel:[1,0,0]
	v_cvt_scalef32_pk_f32_fp4 v[68:69], v42, 1.0 op_sel:[0,1,0]
	v_cvt_scalef32_pk_f32_fp4 v[70:71], v42, 1.0 op_sel:[1,1,0]
	v_pk_fma_f32 v[148:149], s[16:17], v[40:41], v[148:149]
	v_pk_fma_f32 v[146:147], s[16:17], v[66:67], v[146:147]
	v_pk_fma_f32 v[144:145], s[16:17], v[68:69], v[144:145]
	v_pk_fma_f32 v[142:143], s[16:17], v[70:71], v[142:143]
	v_cvt_scalef32_pk_f32_fp4 v[40:41], v43, 1.0
	v_cvt_scalef32_pk_f32_fp4 v[66:67], v43, 1.0 op_sel:[1,0,0]
	v_cvt_scalef32_pk_f32_fp4 v[68:69], v43, 1.0 op_sel:[0,1,0]
	v_cvt_scalef32_pk_f32_fp4 v[42:43], v43, 1.0 op_sel:[1,1,0]
	v_pk_fma_f32 v[140:141], s[16:17], v[40:41], v[140:141]
	v_pk_fma_f32 v[138:139], s[16:17], v[66:67], v[138:139]
	v_pk_fma_f32 v[136:137], s[16:17], v[68:69], v[136:137]
	v_pk_fma_f32 v[134:135], s[16:17], v[42:43], v[134:135]
	s_add_i32 s16, s27, -6
	v_readlane_b32 s16, v64, s16
	s_lshr_b32 s40, s16, 7
	s_lshl_b64 s[16:17], s[40:41], 10
	s_add_u32 s16, s16, s100
	s_addc_u32 s17, s17, s101
	global_load_dwordx4 v[40:43], v207, s[16:17]
	v_readlane_b32 s16, v65, 10
	s_waitcnt vmcnt(15)
	v_cvt_scalef32_pk_f32_fp4 v[66:67], v44, 1.0
	v_cvt_scalef32_pk_f32_fp4 v[68:69], v44, 1.0 op_sel:[1,0,0]
	v_cvt_scalef32_pk_f32_fp4 v[70:71], v44, 1.0 op_sel:[0,1,0]
	s_mov_b32 s17, s16
	v_cvt_scalef32_pk_f32_fp4 v[72:73], v44, 1.0 op_sel:[1,1,0]
	v_pk_fma_f32 v[132:133], s[16:17], v[66:67], v[132:133]
	v_pk_fma_f32 v[162:163], s[16:17], v[68:69], v[162:163]
	v_pk_fma_f32 v[160:161], s[16:17], v[70:71], v[160:161]
	v_pk_fma_f32 v[158:159], s[16:17], v[72:73], v[158:159]
	v_cvt_scalef32_pk_f32_fp4 v[66:67], v45, 1.0
	v_cvt_scalef32_pk_f32_fp4 v[68:69], v45, 1.0 op_sel:[1,0,0]
	v_cvt_scalef32_pk_f32_fp4 v[70:71], v45, 1.0 op_sel:[0,1,0]
	v_cvt_scalef32_pk_f32_fp4 v[44:45], v45, 1.0 op_sel:[1,1,0]
	v_pk_fma_f32 v[156:157], s[16:17], v[66:67], v[156:157]
	v_pk_fma_f32 v[154:155], s[16:17], v[68:69], v[154:155]
	v_pk_fma_f32 v[152:153], s[16:17], v[70:71], v[152:153]
	v_pk_fma_f32 v[150:151], s[16:17], v[44:45], v[150:151]
	v_cvt_scalef32_pk_f32_fp4 v[44:45], v46, 1.0
	v_cvt_scalef32_pk_f32_fp4 v[66:67], v46, 1.0 op_sel:[1,0,0]
	v_cvt_scalef32_pk_f32_fp4 v[68:69], v46, 1.0 op_sel:[0,1,0]
	v_cvt_scalef32_pk_f32_fp4 v[70:71], v46, 1.0 op_sel:[1,1,0]
	v_pk_fma_f32 v[148:149], s[16:17], v[44:45], v[148:149]
	v_pk_fma_f32 v[146:147], s[16:17], v[66:67], v[146:147]
	v_pk_fma_f32 v[144:145], s[16:17], v[68:69], v[144:145]
	v_pk_fma_f32 v[142:143], s[16:17], v[70:71], v[142:143]
	v_cvt_scalef32_pk_f32_fp4 v[44:45], v47, 1.0
	v_cvt_scalef32_pk_f32_fp4 v[66:67], v47, 1.0 op_sel:[1,0,0]
	v_cvt_scalef32_pk_f32_fp4 v[68:69], v47, 1.0 op_sel:[0,1,0]
	v_cvt_scalef32_pk_f32_fp4 v[46:47], v47, 1.0 op_sel:[1,1,0]
	v_pk_fma_f32 v[140:141], s[16:17], v[44:45], v[140:141]
	v_pk_fma_f32 v[138:139], s[16:17], v[66:67], v[138:139]
	v_pk_fma_f32 v[136:137], s[16:17], v[68:69], v[136:137]
	v_pk_fma_f32 v[134:135], s[16:17], v[46:47], v[134:135]
	s_add_i32 s16, s27, -5
	v_readlane_b32 s16, v64, s16
	s_lshr_b32 s40, s16, 7
	s_lshl_b64 s[16:17], s[40:41], 10
	s_add_u32 s16, s16, s100
	s_addc_u32 s17, s17, s101
	global_load_dwordx4 v[44:47], v207, s[16:17]
	v_readlane_b32 s16, v65, 11
	s_waitcnt vmcnt(15)
	v_cvt_scalef32_pk_f32_fp4 v[66:67], v48, 1.0
	v_cvt_scalef32_pk_f32_fp4 v[68:69], v48, 1.0 op_sel:[1,0,0]
	v_cvt_scalef32_pk_f32_fp4 v[70:71], v48, 1.0 op_sel:[0,1,0]
	s_mov_b32 s17, s16
	v_cvt_scalef32_pk_f32_fp4 v[72:73], v48, 1.0 op_sel:[1,1,0]
	v_pk_fma_f32 v[132:133], s[16:17], v[66:67], v[132:133]
	v_pk_fma_f32 v[162:163], s[16:17], v[68:69], v[162:163]
	v_pk_fma_f32 v[160:161], s[16:17], v[70:71], v[160:161]
	v_pk_fma_f32 v[158:159], s[16:17], v[72:73], v[158:159]
	v_cvt_scalef32_pk_f32_fp4 v[66:67], v49, 1.0
	v_cvt_scalef32_pk_f32_fp4 v[68:69], v49, 1.0 op_sel:[1,0,0]
	v_cvt_scalef32_pk_f32_fp4 v[70:71], v49, 1.0 op_sel:[0,1,0]
	v_cvt_scalef32_pk_f32_fp4 v[48:49], v49, 1.0 op_sel:[1,1,0]
	v_pk_fma_f32 v[156:157], s[16:17], v[66:67], v[156:157]
	v_pk_fma_f32 v[154:155], s[16:17], v[68:69], v[154:155]
	v_pk_fma_f32 v[152:153], s[16:17], v[70:71], v[152:153]
	v_pk_fma_f32 v[150:151], s[16:17], v[48:49], v[150:151]
	v_cvt_scalef32_pk_f32_fp4 v[48:49], v50, 1.0
	v_cvt_scalef32_pk_f32_fp4 v[66:67], v50, 1.0 op_sel:[1,0,0]
	v_cvt_scalef32_pk_f32_fp4 v[68:69], v50, 1.0 op_sel:[0,1,0]
	v_cvt_scalef32_pk_f32_fp4 v[70:71], v50, 1.0 op_sel:[1,1,0]
	v_pk_fma_f32 v[148:149], s[16:17], v[48:49], v[148:149]
	v_pk_fma_f32 v[146:147], s[16:17], v[66:67], v[146:147]
	v_pk_fma_f32 v[144:145], s[16:17], v[68:69], v[144:145]
	v_pk_fma_f32 v[142:143], s[16:17], v[70:71], v[142:143]
	v_cvt_scalef32_pk_f32_fp4 v[48:49], v51, 1.0
	v_cvt_scalef32_pk_f32_fp4 v[66:67], v51, 1.0 op_sel:[1,0,0]
	v_cvt_scalef32_pk_f32_fp4 v[68:69], v51, 1.0 op_sel:[0,1,0]
	v_cvt_scalef32_pk_f32_fp4 v[50:51], v51, 1.0 op_sel:[1,1,0]
	v_pk_fma_f32 v[140:141], s[16:17], v[48:49], v[140:141]
	v_pk_fma_f32 v[138:139], s[16:17], v[66:67], v[138:139]
	v_pk_fma_f32 v[136:137], s[16:17], v[68:69], v[136:137]
	v_pk_fma_f32 v[134:135], s[16:17], v[50:51], v[134:135]
	s_add_i32 s16, s27, -4
	v_readlane_b32 s16, v64, s16
	s_lshr_b32 s40, s16, 7
	s_lshl_b64 s[16:17], s[40:41], 10
	s_add_u32 s16, s16, s100
	s_addc_u32 s17, s17, s101
	global_load_dwordx4 v[48:51], v207, s[16:17]
	v_readlane_b32 s16, v65, 12
	s_waitcnt vmcnt(15)
; #define P4_FOR16(M) M(0) M(1) M(2) M(3) M(4) M(5) M(6) M(7) M(8) M(9) M(10) M(11) M(12) M(13) M(14) M(15)
; #define P4_V(i) { const unsigned wu_ = (unsigned)__builtin_amdgcn_readlane((int)__float_as_uint(wreg), i); const unsigned long long wp_ = ((unsigned long long)wu_ << 32) | wu_; \
;               P4_ACC(b##i, wp_); const int nk_ = __builtin_amdgcn_readlane(ksel, nb + i); P4_LOAD(b##i, Vg, nk_); }
; #define P4_V(i) { const unsigned wu_ = (unsigned)__builtin_amdgcn_readlane((int)__float_as_uint(wreg), i); const unsigned long long wp_ = ((unsigned long long)wu_ << 32) | wu_; \
;               P4_ACC(b##i, wp_); const int nk_ = __builtin_amdgcn_readlane(kn, i); P4_LOAD(b##i, Vg, nk_); }
; #define P4_V(i) { const unsigned wu_ = (unsigned)__builtin_amdgcn_readlane((int)__float_as_uint(wreg), i); const unsigned long long wp_ = ((unsigned long long)wu_ << 32) | wu_; \
;               P4_ACC(b##i, wp_); }
; __device__ __forceinline__ void peer_gather_f4p(const float* X, const int* __restrict__ IDX, const float* __restrict__ G, ...
;     ...
;         for (int bt = 0; bt < 7; ++bt) {
;             const int ksel = (bt + 1 < 4) ? k0 : k1;
;             const int nb = (16 * (bt + 1)) & 63;
;             const float wreg = wbuf[kt * 128 + bt * 16 + (lane & 15)];
;     ...
;             P4_FOR16(P4_V)
	v_cvt_scalef32_pk_f32_fp4 v[66:67], v52, 1.0
	v_cvt_scalef32_pk_f32_fp4 v[68:69], v52, 1.0 op_sel:[1,0,0]
	v_cvt_scalef32_pk_f32_fp4 v[70:71], v52, 1.0 op_sel:[0,1,0]
	s_mov_b32 s17, s16
	v_cvt_scalef32_pk_f32_fp4 v[72:73], v52, 1.0 op_sel:[1,1,0]
	v_pk_fma_f32 v[132:133], s[16:17], v[66:67], v[132:133]
	v_pk_fma_f32 v[162:163], s[16:17], v[68:69], v[162:163]
	v_pk_fma_f32 v[160:161], s[16:17], v[70:71], v[160:161]
	v_pk_fma_f32 v[158:159], s[16:17], v[72:73], v[158:159]
	v_cvt_scalef32_pk_f32_fp4 v[66:67], v53, 1.0
	v_cvt_scalef32_pk_f32_fp4 v[68:69], v53, 1.0 op_sel:[1,0,0]
	v_cvt_scalef32_pk_f32_fp4 v[70:71], v53, 1.0 op_sel:[0,1,0]
	v_cvt_scalef32_pk_f32_fp4 v[52:53], v53, 1.0 op_sel:[1,1,0]
	v_pk_fma_f32 v[156:157], s[16:17], v[66:67], v[156:157]
	v_pk_fma_f32 v[154:155], s[16:17], v[68:69], v[154:155]
	v_pk_fma_f32 v[152:153], s[16:17], v[70:71], v[152:153]
	v_pk_fma_f32 v[150:151], s[16:17], v[52:53], v[150:151]
	v_cvt_scalef32_pk_f32_fp4 v[52:53], v54, 1.0
	v_cvt_scalef32_pk_f32_fp4 v[66:67], v54, 1.0 op_sel:[1,0,0]
	v_cvt_scalef32_pk_f32_fp4 v[68:69], v54, 1.0 op_sel:[0,1,0]
	v_cvt_scalef32_pk_f32_fp4 v[70:71], v54, 1.0 op_sel:[1,1,0]
	v_pk_fma_f32 v[148:149], s[16:17], v[52:53], v[148:149]
	v_pk_fma_f32 v[146:147], s[16:17], v[66:67], v[146:147]
	v_pk_fma_f32 v[144:145], s[16:17], v[68:69], v[144:145]
	v_pk_fma_f32 v[142:143], s[16:17], v[70:71], v[142:143]
	v_cvt_scalef32_pk_f32_fp4 v[52:53], v55, 1.0
	v_cvt_scalef32_pk_f32_fp4 v[66:67], v55, 1.0 op_sel:[1,0,0]
	v_cvt_scalef32_pk_f32_fp4 v[68:69], v55, 1.0 op_sel:[0,1,0]
	v_cvt_scalef32_pk_f32_fp4 v[54:55], v55, 1.0 op_sel:[1,1,0]
	v_pk_fma_f32 v[140:141], s[16:17], v[52:53], v[140:141]
	v_pk_fma_f32 v[138:139], s[16:17], v[66:67], v[138:139]
	v_pk_fma_f32 v[136:137], s[16:17], v[68:69], v[136:137]
	v_pk_fma_f32 v[134:135], s[16:17], v[54:55], v[134:135]
	s_add_i32 s16, s27, -3
	v_readlane_b32 s16, v64, s16
	s_lshr_b32 s40, s16, 7
	s_lshl_b64 s[16:17], s[40:41], 10
	s_add_u32 s16, s16, s100
	s_addc_u32 s17, s17, s101
	global_load_dwordx4 v[52:55], v207, s[16:17]
	v_readlane_b32 s16, v65, 13
	s_waitcnt vmcnt(15)
	v_cvt_scalef32_pk_f32_fp4 v[66:67], v56, 1.0
	v_cvt_scalef32_pk_f32_fp4 v[68:69], v56, 1.0 op_sel:[1,0,0]
	v_cvt_scalef32_pk_f32_fp4 v[70:71], v56, 1.0 op_sel:[0,1,0]
	s_mov_b32 s17, s16
	v_cvt_scalef32_pk_f32_fp4 v[72:73], v56, 1.0 op_sel:[1,1,0]
	v_pk_fma_f32 v[132:133], s[16:17], v[66:67], v[132:133]
	v_pk_fma_f32 v[162:163], s[16:17], v[68:69], v[162:163]
	v_pk_fma_f32 v[160:161], s[16:17], v[70:71], v[160:161]
	v_pk_fma_f32 v[158:159], s[16:17], v[72:73], v[158:159]
	v_cvt_scalef32_pk_f32_fp4 v[66:67], v57, 1.0
	v_cvt_scalef32_pk_f32_fp4 v[68:69], v57, 1.0 op_sel:[1,0,0]
	v_cvt_scalef32_pk_f32_fp4 v[70:71], v57, 1.0 op_sel:[0,1,0]
	v_cvt_scalef32_pk_f32_fp4 v[56:57], v57, 1.0 op_sel:[1,1,0]
	v_pk_fma_f32 v[156:157], s[16:17], v[66:67], v[156:157]
	v_pk_fma_f32 v[154:155], s[16:17], v[68:69], v[154:155]
	v_pk_fma_f32 v[152:153], s[16:17], v[70:71], v[152:153]
	v_pk_fma_f32 v[150:151], s[16:17], v[56:57], v[150:151]
	v_cvt_scalef32_pk_f32_fp4 v[56:57], v58, 1.0
	v_cvt_scalef32_pk_f32_fp4 v[66:67], v58, 1.0 op_sel:[1,0,0]
	v_cvt_scalef32_pk_f32_fp4 v[68:69], v58, 1.0 op_sel:[0,1,0]
	v_cvt_scalef32_pk_f32_fp4 v[70:71], v58, 1.0 op_sel:[1,1,0]
	v_pk_fma_f32 v[148:149], s[16:17], v[56:57], v[148:149]
	v_pk_fma_f32 v[146:147], s[16:17], v[66:67], v[146:147]
	v_pk_fma_f32 v[144:145], s[16:17], v[68:69], v[144:145]
	v_pk_fma_f32 v[142:143], s[16:17], v[70:71], v[142:143]
	v_cvt_scalef32_pk_f32_fp4 v[56:57], v59, 1.0
	v_cvt_scalef32_pk_f32_fp4 v[66:67], v59, 1.0 op_sel:[1,0,0]
	v_cvt_scalef32_pk_f32_fp4 v[68:69], v59, 1.0 op_sel:[0,1,0]
	v_cvt_scalef32_pk_f32_fp4 v[58:59], v59, 1.0 op_sel:[1,1,0]
	v_pk_fma_f32 v[140:141], s[16:17], v[56:57], v[140:141]
	v_pk_fma_f32 v[138:139], s[16:17], v[66:67], v[138:139]
	v_pk_fma_f32 v[136:137], s[16:17], v[68:69], v[136:137]
	v_pk_fma_f32 v[134:135], s[16:17], v[58:59], v[134:135]
	s_add_i32 s16, s27, -2
	v_readlane_b32 s16, v64, s16
	s_lshr_b32 s40, s16, 7
	s_lshl_b64 s[16:17], s[40:41], 10
	s_add_u32 s16, s16, s100
	s_addc_u32 s17, s17, s101
	global_load_dwordx4 v[56:59], v207, s[16:17]
	v_readlane_b32 s16, v65, 14
	s_waitcnt vmcnt(15)
	v_cvt_scalef32_pk_f32_fp4 v[66:67], v60, 1.0
	v_cvt_scalef32_pk_f32_fp4 v[68:69], v60, 1.0 op_sel:[1,0,0]
	v_cvt_scalef32_pk_f32_fp4 v[70:71], v60, 1.0 op_sel:[0,1,0]
	s_mov_b32 s17, s16
	v_cvt_scalef32_pk_f32_fp4 v[72:73], v60, 1.0 op_sel:[1,1,0]
	v_pk_fma_f32 v[132:133], s[16:17], v[66:67], v[132:133]
	v_pk_fma_f32 v[162:163], s[16:17], v[68:69], v[162:163]
	v_pk_fma_f32 v[160:161], s[16:17], v[70:71], v[160:161]
	v_pk_fma_f32 v[158:159], s[16:17], v[72:73], v[158:159]
	v_cvt_scalef32_pk_f32_fp4 v[66:67], v61, 1.0
	v_cvt_scalef32_pk_f32_fp4 v[68:69], v61, 1.0 op_sel:[1,0,0]
	v_cvt_scalef32_pk_f32_fp4 v[70:71], v61, 1.0 op_sel:[0,1,0]
	v_cvt_scalef32_pk_f32_fp4 v[60:61], v61, 1.0 op_sel:[1,1,0]
	v_pk_fma_f32 v[156:157], s[16:17], v[66:67], v[156:157]
	v_pk_fma_f32 v[154:155], s[16:17], v[68:69], v[154:155]
	v_pk_fma_f32 v[152:153], s[16:17], v[70:71], v[152:153]
	v_pk_fma_f32 v[150:151], s[16:17], v[60:61], v[150:151]
	v_cvt_scalef32_pk_f32_fp4 v[60:61], v62, 1.0
	v_cvt_scalef32_pk_f32_fp4 v[66:67], v62, 1.0 op_sel:[1,0,0]
	v_cvt_scalef32_pk_f32_fp4 v[68:69], v62, 1.0 op_sel:[0,1,0]
	v_cvt_scalef32_pk_f32_fp4 v[70:71], v62, 1.0 op_sel:[1,1,0]
	v_pk_fma_f32 v[148:149], s[16:17], v[60:61], v[148:149]
	v_pk_fma_f32 v[146:147], s[16:17], v[66:67], v[146:147]
	v_pk_fma_f32 v[144:145], s[16:17], v[68:69], v[144:145]
	v_pk_fma_f32 v[142:143], s[16:17], v[70:71], v[142:143]
	v_cvt_scalef32_pk_f32_fp4 v[60:61], v63, 1.0
	v_cvt_scalef32_pk_f32_fp4 v[66:67], v63, 1.0 op_sel:[1,0,0]
	v_cvt_scalef32_pk_f32_fp4 v[68:69], v63, 1.0 op_sel:[0,1,0]
	v_cvt_scalef32_pk_f32_fp4 v[62:63], v63, 1.0 op_sel:[1,1,0]
	v_pk_fma_f32 v[140:141], s[16:17], v[60:61], v[140:141]
	v_pk_fma_f32 v[138:139], s[16:17], v[66:67], v[138:139]
	v_pk_fma_f32 v[136:137], s[16:17], v[68:69], v[136:137]
	v_pk_fma_f32 v[134:135], s[16:17], v[62:63], v[134:135]
	s_add_i32 s16, s27, -1
	v_readlane_b32 s16, v64, s16
	s_lshr_b32 s40, s16, 7
	s_lshl_b64 s[16:17], s[40:41], 10
	s_add_u32 s16, s16, s100
	s_addc_u32 s17, s17, s101
	global_load_dwordx4 v[60:63], v207, s[16:17]
	v_readlane_b32 s16, v65, 15
	s_waitcnt vmcnt(15)
; #define P4_FOR16(M) M(0) M(1) M(2) M(3) M(4) M(5) M(6) M(7) M(8) M(9) M(10) M(11) M(12) M(13) M(14) M(15)
; #define P4_V(i) { const unsigned wu_ = (unsigned)__builtin_amdgcn_readlane((int)__float_as_uint(wreg), i); const unsigned long long wp_ = ((unsigned long long)wu_ << 32) | wu_; \
;               P4_ACC(b##i, wp_); const int nk_ = __builtin_amdgcn_readlane(ksel, nb + i); P4_LOAD(b##i, Vg, nk_); }
; #define P4_V(i) { const unsigned wu_ = (unsigned)__builtin_amdgcn_readlane((int)__float_as_uint(wreg), i); const unsigned long long wp_ = ((unsigned long long)wu_ << 32) | wu_; \
;               P4_ACC(b##i, wp_); const int nk_ = __builtin_amdgcn_readlane(kn, i); P4_LOAD(b##i, Vg, nk_); }
; #define P4_V(i) { const unsigned wu_ = (unsigned)__builtin_amdgcn_readlane((int)__float_as_uint(wreg), i); const unsigned long long wp_ = ((unsigned long long)wu_ << 32) | wu_; \
;               P4_ACC(b##i, wp_); }
; __device__ __forceinline__ void peer_gather_f4p(const float* X, const int* __restrict__ IDX, const float* __restrict__ G, ...
;     ...
;         for (int bt = 0; bt < 7; ++bt) {
;             const int ksel = (bt + 1 < 4) ? k0 : k1;
;             const int nb = (16 * (bt + 1)) & 63;
;             const float wreg = wbuf[kt * 128 + bt * 16 + (lane & 15)];
;     ...
;             P4_FOR16(P4_V)
;     ...
;         }
;         {
;             const float wreg = wbuf[kt * 128 + 7 * 16 + (lane & 15)];
;             if (kt < 3) {
;     ...
;                 P4_FOR16(P4_V)
	v_cvt_scalef32_pk_f32_fp4 v[66:67], v80, 1.0
	v_cvt_scalef32_pk_f32_fp4 v[68:69], v80, 1.0 op_sel:[1,0,0]
	v_cvt_scalef32_pk_f32_fp4 v[70:71], v80, 1.0 op_sel:[0,1,0]
	v_cvt_scalef32_pk_f32_fp4 v[72:73], v80, 1.0 op_sel:[1,1,0]
	s_mov_b32 s17, s16
	v_pk_fma_f32 v[132:133], s[16:17], v[66:67], v[132:133]
	v_pk_fma_f32 v[162:163], s[16:17], v[68:69], v[162:163]
	v_pk_fma_f32 v[160:161], s[16:17], v[70:71], v[160:161]
	v_pk_fma_f32 v[158:159], s[16:17], v[72:73], v[158:159]
	v_cvt_scalef32_pk_f32_fp4 v[66:67], v81, 1.0
	v_cvt_scalef32_pk_f32_fp4 v[68:69], v81, 1.0 op_sel:[1,0,0]
	v_cvt_scalef32_pk_f32_fp4 v[70:71], v81, 1.0 op_sel:[0,1,0]
	v_cvt_scalef32_pk_f32_fp4 v[72:73], v81, 1.0 op_sel:[1,1,0]
	v_pk_fma_f32 v[156:157], s[16:17], v[66:67], v[156:157]
	v_pk_fma_f32 v[154:155], s[16:17], v[68:69], v[154:155]
	v_pk_fma_f32 v[152:153], s[16:17], v[70:71], v[152:153]
	v_pk_fma_f32 v[150:151], s[16:17], v[72:73], v[150:151]
	v_cvt_scalef32_pk_f32_fp4 v[66:67], v82, 1.0
	v_cvt_scalef32_pk_f32_fp4 v[68:69], v82, 1.0 op_sel:[1,0,0]
	v_cvt_scalef32_pk_f32_fp4 v[70:71], v82, 1.0 op_sel:[0,1,0]
	v_cvt_scalef32_pk_f32_fp4 v[72:73], v82, 1.0 op_sel:[1,1,0]
	v_pk_fma_f32 v[148:149], s[16:17], v[66:67], v[148:149]
	v_pk_fma_f32 v[146:147], s[16:17], v[68:69], v[146:147]
	v_pk_fma_f32 v[144:145], s[16:17], v[70:71], v[144:145]
	v_pk_fma_f32 v[142:143], s[16:17], v[72:73], v[142:143]
	v_cvt_scalef32_pk_f32_fp4 v[66:67], v83, 1.0
	v_cvt_scalef32_pk_f32_fp4 v[68:69], v83, 1.0 op_sel:[1,0,0]
	v_cvt_scalef32_pk_f32_fp4 v[70:71], v83, 1.0 op_sel:[0,1,0]
	v_cvt_scalef32_pk_f32_fp4 v[72:73], v83, 1.0 op_sel:[1,1,0]
	v_pk_fma_f32 v[140:141], s[16:17], v[66:67], v[140:141]
	v_pk_fma_f32 v[138:139], s[16:17], v[68:69], v[138:139]
	v_pk_fma_f32 v[136:137], s[16:17], v[70:71], v[136:137]
	v_pk_fma_f32 v[134:135], s[16:17], v[72:73], v[134:135]
	v_readlane_b32 s16, v64, s27
	s_lshr_b32 s40, s16, 7
	s_lshl_b64 s[40:41], s[40:41], 10
	s_add_u32 s40, s40, s100
	s_addc_u32 s41, s41, s101
	global_load_dwordx4 v[80:83], v207, s[40:41]
	s_add_i32 s27, s27, 16
	s_cmpk_eq_i32 s27, 0x8f
	s_cbranch_scc0 .LBB0_1247
	v_lshl_add_u32 v64, v170, 2, s26
	ds_read_b32 v209, v64 offset:4544
	s_cmp_lg_u32 s19, 3
	s_mov_b64 s[40:41], -1
	s_cbranch_scc0 .LBB0_1250
	v_readlane_b32 s16, v208, 0
	s_waitcnt lgkmcnt(0)
	v_readlane_b32 s40, v209, 0
	s_waitcnt vmcnt(15)
	v_cvt_scalef32_pk_f32_fp4 v[64:65], v4, 1.0
	v_mov_b64_e32 v[166:167], v[132:133]
	v_mov_b64_e32 v[168:169], v[162:163]
	v_mov_b64_e32 v[170:171], v[160:161]
	v_mov_b64_e32 v[172:173], v[158:159]
	s_lshr_b32 s16, s16, 7
	s_mov_b32 s17, s86
	s_mov_b32 s41, s40
	v_cvt_scalef32_pk_f32_fp4 v[66:67], v4, 1.0 op_sel:[1,0,0]
	v_cvt_scalef32_pk_f32_fp4 v[68:69], v4, 1.0 op_sel:[0,1,0]
	v_cvt_scalef32_pk_f32_fp4 v[70:71], v4, 1.0 op_sel:[1,1,0]
	v_pk_fma_f32 v[166:167], s[40:41], v[64:65], v[166:167]
	v_mov_b64_e32 v[174:175], v[156:157]
	v_pk_fma_f32 v[168:169], s[40:41], v[66:67], v[168:169]
	v_pk_fma_f32 v[170:171], s[40:41], v[68:69], v[170:171]
	v_pk_fma_f32 v[172:173], s[40:41], v[70:71], v[172:173]
	v_cvt_scalef32_pk_f32_fp4 v[64:65], v5, 1.0
	v_mov_b64_e32 v[176:177], v[154:155]
	v_mov_b64_e32 v[178:179], v[152:153]
	v_mov_b64_e32 v[180:181], v[150:151]
	s_lshl_b64 s[16:17], s[16:17], 10
	v_cvt_scalef32_pk_f32_fp4 v[66:67], v5, 1.0 op_sel:[1,0,0]
	v_cvt_scalef32_pk_f32_fp4 v[68:69], v5, 1.0 op_sel:[0,1,0]
	v_cvt_scalef32_pk_f32_fp4 v[70:71], v5, 1.0 op_sel:[1,1,0]
	v_pk_fma_f32 v[174:175], s[40:41], v[64:65], v[174:175]
	v_mov_b64_e32 v[182:183], v[148:149]
	v_pk_fma_f32 v[176:177], s[40:41], v[66:67], v[176:177]
	v_pk_fma_f32 v[178:179], s[40:41], v[68:69], v[178:179]
	v_pk_fma_f32 v[180:181], s[40:41], v[70:71], v[180:181]
	v_cvt_scalef32_pk_f32_fp4 v[64:65], v6, 1.0
	v_mov_b64_e32 v[184:185], v[146:147]
	v_mov_b64_e32 v[186:187], v[144:145]
	v_mov_b64_e32 v[188:189], v[142:143]
	s_add_u32 s16, s52, s16
	v_cvt_scalef32_pk_f32_fp4 v[66:67], v6, 1.0 op_sel:[1,0,0]
	v_cvt_scalef32_pk_f32_fp4 v[68:69], v6, 1.0 op_sel:[0,1,0]
	v_cvt_scalef32_pk_f32_fp4 v[70:71], v6, 1.0 op_sel:[1,1,0]
	v_pk_fma_f32 v[182:183], s[40:41], v[64:65], v[182:183]
	v_mov_b64_e32 v[190:191], v[140:141]
	v_pk_fma_f32 v[184:185], s[40:41], v[66:67], v[184:185]
	v_pk_fma_f32 v[186:187], s[40:41], v[68:69], v[186:187]
	v_pk_fma_f32 v[188:189], s[40:41], v[70:71], v[188:189]
	v_cvt_scalef32_pk_f32_fp4 v[64:65], v7, 1.0
	s_addc_u32 s17, s53, s17
	v_cvt_scalef32_pk_f32_fp4 v[66:67], v7, 1.0 op_sel:[1,0,0]
	v_cvt_scalef32_pk_f32_fp4 v[68:69], v7, 1.0 op_sel:[0,1,0]
	v_cvt_scalef32_pk_f32_fp4 v[70:71], v7, 1.0 op_sel:[1,1,0]
	v_pk_fma_f32 v[190:191], s[40:41], v[64:65], v[190:191]
	v_mov_b64_e32 v[192:193], v[138:139]
	v_mov_b64_e32 v[194:195], v[136:137]
	v_mov_b64_e32 v[196:197], v[134:135]
	v_lshl_add_u64 v[64:65], s[16:17], 0, v[164:165]
	v_readlane_b32 s16, v208, 1
	v_pk_fma_f32 v[192:193], s[40:41], v[66:67], v[192:193]
	v_pk_fma_f32 v[194:195], s[40:41], v[68:69], v[194:195]
	v_pk_fma_f32 v[196:197], s[40:41], v[70:71], v[196:197]
	global_load_dwordx4 v[64:67], v[64:65], off
	v_readlane_b32 s40, v209, 1
	s_waitcnt vmcnt(15)
; #define P4_FOR16(M) M(0) M(1) M(2) M(3) M(4) M(5) M(6) M(7) M(8) M(9) M(10) M(11) M(12) M(13) M(14) M(15)
; #define P4_V(i) { const unsigned wu_ = (unsigned)__builtin_amdgcn_readlane((int)__float_as_uint(wreg), i); const unsigned long long wp_ = ((unsigned long long)wu_ << 32) | wu_; \
;               P4_ACC(b##i, wp_); const int nk_ = __builtin_amdgcn_readlane(ksel, nb + i); P4_LOAD(b##i, Vg, nk_); }
; #define P4_V(i) { const unsigned wu_ = (unsigned)__builtin_amdgcn_readlane((int)__float_as_uint(wreg), i); const unsigned long long wp_ = ((unsigned long long)wu_ << 32) | wu_; \
;               P4_ACC(b##i, wp_); const int nk_ = __builtin_amdgcn_readlane(kn, i); P4_LOAD(b##i, Vg, nk_); }
; #define P4_V(i) { const unsigned wu_ = (unsigned)__builtin_amdgcn_readlane((int)__float_as_uint(wreg), i); const unsigned long long wp_ = ((unsigned long long)wu_ << 32) | wu_; \
;               P4_ACC(b##i, wp_); }
; __device__ __forceinline__ void peer_gather_f4p(const float* X, const int* __restrict__ IDX, const float* __restrict__ G, ...
;     ...
;         {
;             const float wreg = wbuf[kt * 128 + 7 * 16 + (lane & 15)];
;             if (kt < 3) {
;     ...
;                 P4_FOR16(P4_V)
	v_cvt_scalef32_pk_f32_fp4 v[68:69], v8, 1.0
	s_lshr_b32 s16, s16, 7
	s_mov_b32 s17, s86
	s_mov_b32 s41, s40
	v_cvt_scalef32_pk_f32_fp4 v[70:71], v8, 1.0 op_sel:[1,0,0]
	v_cvt_scalef32_pk_f32_fp4 v[72:73], v8, 1.0 op_sel:[0,1,0]
	v_cvt_scalef32_pk_f32_fp4 v[74:75], v8, 1.0 op_sel:[1,1,0]
	v_pk_fma_f32 v[166:167], s[40:41], v[68:69], v[166:167]
	s_lshl_b64 s[16:17], s[16:17], 10
	v_pk_fma_f32 v[168:169], s[40:41], v[70:71], v[168:169]
	v_pk_fma_f32 v[170:171], s[40:41], v[72:73], v[170:171]
	v_pk_fma_f32 v[172:173], s[40:41], v[74:75], v[172:173]
	v_cvt_scalef32_pk_f32_fp4 v[68:69], v9, 1.0
	v_cvt_scalef32_pk_f32_fp4 v[70:71], v9, 1.0 op_sel:[1,0,0]
	v_cvt_scalef32_pk_f32_fp4 v[72:73], v9, 1.0 op_sel:[0,1,0]
	v_cvt_scalef32_pk_f32_fp4 v[74:75], v9, 1.0 op_sel:[1,1,0]
	s_add_u32 s16, s52, s16
	v_pk_fma_f32 v[174:175], s[40:41], v[68:69], v[174:175]
	v_pk_fma_f32 v[176:177], s[40:41], v[70:71], v[176:177]
	v_pk_fma_f32 v[178:179], s[40:41], v[72:73], v[178:179]
	v_pk_fma_f32 v[180:181], s[40:41], v[74:75], v[180:181]
	v_cvt_scalef32_pk_f32_fp4 v[68:69], v10, 1.0
	v_cvt_scalef32_pk_f32_fp4 v[70:71], v10, 1.0 op_sel:[1,0,0]
	v_cvt_scalef32_pk_f32_fp4 v[72:73], v10, 1.0 op_sel:[0,1,0]
	v_cvt_scalef32_pk_f32_fp4 v[74:75], v10, 1.0 op_sel:[1,1,0]
	s_addc_u32 s17, s53, s17
	v_pk_fma_f32 v[182:183], s[40:41], v[68:69], v[182:183]
	v_pk_fma_f32 v[184:185], s[40:41], v[70:71], v[184:185]
	v_pk_fma_f32 v[186:187], s[40:41], v[72:73], v[186:187]
	v_pk_fma_f32 v[188:189], s[40:41], v[74:75], v[188:189]
	v_cvt_scalef32_pk_f32_fp4 v[68:69], v11, 1.0
	v_cvt_scalef32_pk_f32_fp4 v[70:71], v11, 1.0 op_sel:[1,0,0]
	v_cvt_scalef32_pk_f32_fp4 v[72:73], v11, 1.0 op_sel:[0,1,0]
	v_cvt_scalef32_pk_f32_fp4 v[74:75], v11, 1.0 op_sel:[1,1,0]
	v_pk_fma_f32 v[190:191], s[40:41], v[68:69], v[190:191]
	v_lshl_add_u64 v[68:69], s[16:17], 0, v[164:165]
	v_readlane_b32 s16, v208, 2
	v_pk_fma_f32 v[192:193], s[40:41], v[70:71], v[192:193]
	v_pk_fma_f32 v[194:195], s[40:41], v[72:73], v[194:195]
	v_pk_fma_f32 v[196:197], s[40:41], v[74:75], v[196:197]
	global_load_dwordx4 v[68:71], v[68:69], off
	v_readlane_b32 s40, v209, 2
	s_waitcnt vmcnt(15)
	v_cvt_scalef32_pk_f32_fp4 v[72:73], v12, 1.0
	s_lshr_b32 s16, s16, 7
	s_mov_b32 s17, s86
	s_mov_b32 s41, s40
	v_cvt_scalef32_pk_f32_fp4 v[74:75], v12, 1.0 op_sel:[1,0,0]
	v_cvt_scalef32_pk_f32_fp4 v[76:77], v12, 1.0 op_sel:[0,1,0]
	v_cvt_scalef32_pk_f32_fp4 v[78:79], v12, 1.0 op_sel:[1,1,0]
	v_pk_fma_f32 v[166:167], s[40:41], v[72:73], v[166:167]
	s_lshl_b64 s[16:17], s[16:17], 10
	v_pk_fma_f32 v[168:169], s[40:41], v[74:75], v[168:169]
	v_pk_fma_f32 v[170:171], s[40:41], v[76:77], v[170:171]
	v_pk_fma_f32 v[172:173], s[40:41], v[78:79], v[172:173]
	v_cvt_scalef32_pk_f32_fp4 v[72:73], v13, 1.0
	v_cvt_scalef32_pk_f32_fp4 v[74:75], v13, 1.0 op_sel:[1,0,0]
	v_cvt_scalef32_pk_f32_fp4 v[76:77], v13, 1.0 op_sel:[0,1,0]
	v_cvt_scalef32_pk_f32_fp4 v[78:79], v13, 1.0 op_sel:[1,1,0]
	s_add_u32 s16, s52, s16
	v_pk_fma_f32 v[174:175], s[40:41], v[72:73], v[174:175]
	v_pk_fma_f32 v[176:177], s[40:41], v[74:75], v[176:177]
	v_pk_fma_f32 v[178:179], s[40:41], v[76:77], v[178:179]
	v_pk_fma_f32 v[180:181], s[40:41], v[78:79], v[180:181]
	v_cvt_scalef32_pk_f32_fp4 v[72:73], v14, 1.0
	v_cvt_scalef32_pk_f32_fp4 v[74:75], v14, 1.0 op_sel:[1,0,0]
	v_cvt_scalef32_pk_f32_fp4 v[76:77], v14, 1.0 op_sel:[0,1,0]
	v_cvt_scalef32_pk_f32_fp4 v[78:79], v14, 1.0 op_sel:[1,1,0]
	s_addc_u32 s17, s53, s17
	v_pk_fma_f32 v[182:183], s[40:41], v[72:73], v[182:183]
	v_pk_fma_f32 v[184:185], s[40:41], v[74:75], v[184:185]
	v_pk_fma_f32 v[186:187], s[40:41], v[76:77], v[186:187]
	v_pk_fma_f32 v[188:189], s[40:41], v[78:79], v[188:189]
	v_cvt_scalef32_pk_f32_fp4 v[72:73], v15, 1.0
	v_cvt_scalef32_pk_f32_fp4 v[74:75], v15, 1.0 op_sel:[1,0,0]
	v_cvt_scalef32_pk_f32_fp4 v[76:77], v15, 1.0 op_sel:[0,1,0]
	v_cvt_scalef32_pk_f32_fp4 v[78:79], v15, 1.0 op_sel:[1,1,0]
	v_pk_fma_f32 v[190:191], s[40:41], v[72:73], v[190:191]
	v_lshl_add_u64 v[72:73], s[16:17], 0, v[164:165]
	v_readlane_b32 s16, v208, 3
	v_pk_fma_f32 v[192:193], s[40:41], v[74:75], v[192:193]
	v_pk_fma_f32 v[194:195], s[40:41], v[76:77], v[194:195]
	v_pk_fma_f32 v[196:197], s[40:41], v[78:79], v[196:197]
	global_load_dwordx4 v[72:75], v[72:73], off
	v_readlane_b32 s40, v209, 3
	s_waitcnt vmcnt(15)
	v_cvt_scalef32_pk_f32_fp4 v[76:77], v16, 1.0
	s_lshr_b32 s16, s16, 7
	s_mov_b32 s17, s86
	s_mov_b32 s41, s40
	v_cvt_scalef32_pk_f32_fp4 v[78:79], v16, 1.0 op_sel:[1,0,0]
	v_cvt_scalef32_pk_f32_fp4 v[84:85], v16, 1.0 op_sel:[0,1,0]
	v_cvt_scalef32_pk_f32_fp4 v[86:87], v16, 1.0 op_sel:[1,1,0]
	v_pk_fma_f32 v[166:167], s[40:41], v[76:77], v[166:167]
	s_lshl_b64 s[16:17], s[16:17], 10
	v_pk_fma_f32 v[168:169], s[40:41], v[78:79], v[168:169]
	v_pk_fma_f32 v[170:171], s[40:41], v[84:85], v[170:171]
	v_pk_fma_f32 v[172:173], s[40:41], v[86:87], v[172:173]
	v_cvt_scalef32_pk_f32_fp4 v[76:77], v17, 1.0
	v_cvt_scalef32_pk_f32_fp4 v[78:79], v17, 1.0 op_sel:[1,0,0]
	v_cvt_scalef32_pk_f32_fp4 v[84:85], v17, 1.0 op_sel:[0,1,0]
	v_cvt_scalef32_pk_f32_fp4 v[86:87], v17, 1.0 op_sel:[1,1,0]
	s_add_u32 s16, s52, s16
	v_pk_fma_f32 v[174:175], s[40:41], v[76:77], v[174:175]
	v_pk_fma_f32 v[176:177], s[40:41], v[78:79], v[176:177]
	v_pk_fma_f32 v[178:179], s[40:41], v[84:85], v[178:179]
	v_pk_fma_f32 v[180:181], s[40:41], v[86:87], v[180:181]
	v_cvt_scalef32_pk_f32_fp4 v[76:77], v18, 1.0
	v_cvt_scalef32_pk_f32_fp4 v[78:79], v18, 1.0 op_sel:[1,0,0]
	v_cvt_scalef32_pk_f32_fp4 v[84:85], v18, 1.0 op_sel:[0,1,0]
	v_cvt_scalef32_pk_f32_fp4 v[86:87], v18, 1.0 op_sel:[1,1,0]
	s_addc_u32 s17, s53, s17
	v_pk_fma_f32 v[182:183], s[40:41], v[76:77], v[182:183]
	v_pk_fma_f32 v[184:185], s[40:41], v[78:79], v[184:185]
	v_pk_fma_f32 v[186:187], s[40:41], v[84:85], v[186:187]
	v_pk_fma_f32 v[188:189], s[40:41], v[86:87], v[188:189]
	v_cvt_scalef32_pk_f32_fp4 v[76:77], v19, 1.0
	v_cvt_scalef32_pk_f32_fp4 v[78:79], v19, 1.0 op_sel:[1,0,0]
	v_cvt_scalef32_pk_f32_fp4 v[84:85], v19, 1.0 op_sel:[0,1,0]
	v_cvt_scalef32_pk_f32_fp4 v[86:87], v19, 1.0 op_sel:[1,1,0]
	v_pk_fma_f32 v[190:191], s[40:41], v[76:77], v[190:191]
	v_lshl_add_u64 v[76:77], s[16:17], 0, v[164:165]
	v_readlane_b32 s16, v208, 4
	v_pk_fma_f32 v[192:193], s[40:41], v[78:79], v[192:193]
	v_pk_fma_f32 v[194:195], s[40:41], v[84:85], v[194:195]
	v_pk_fma_f32 v[196:197], s[40:41], v[86:87], v[196:197]
	global_load_dwordx4 v[76:79], v[76:77], off
	v_readlane_b32 s40, v209, 4
	s_waitcnt vmcnt(15)
; #define P4_FOR16(M) M(0) M(1) M(2) M(3) M(4) M(5) M(6) M(7) M(8) M(9) M(10) M(11) M(12) M(13) M(14) M(15)
; #define P4_V(i) { const unsigned wu_ = (unsigned)__builtin_amdgcn_readlane((int)__float_as_uint(wreg), i); const unsigned long long wp_ = ((unsigned long long)wu_ << 32) | wu_; \
;               P4_ACC(b##i, wp_); const int nk_ = __builtin_amdgcn_readlane(ksel, nb + i); P4_LOAD(b##i, Vg, nk_); }
; #define P4_V(i) { const unsigned wu_ = (unsigned)__builtin_amdgcn_readlane((int)__float_as_uint(wreg), i); const unsigned long long wp_ = ((unsigned long long)wu_ << 32) | wu_; \
;               P4_ACC(b##i, wp_); const int nk_ = __builtin_amdgcn_readlane(kn, i); P4_LOAD(b##i, Vg, nk_); }
; #define P4_V(i) { const unsigned wu_ = (unsigned)__builtin_amdgcn_readlane((int)__float_as_uint(wreg), i); const unsigned long long wp_ = ((unsigned long long)wu_ << 32) | wu_; \
;               P4_ACC(b##i, wp_); }
; __device__ __forceinline__ void peer_gather_f4p(const float* X, const int* __restrict__ IDX, const float* __restrict__ G, ...
;     ...
;         {
;             const float wreg = wbuf[kt * 128 + 7 * 16 + (lane & 15)];
;             if (kt < 3) {
;     ...
;                 P4_FOR16(P4_V)
	v_cvt_scalef32_pk_f32_fp4 v[84:85], v20, 1.0
	s_lshr_b32 s16, s16, 7
	s_mov_b32 s17, s86
	s_mov_b32 s41, s40
	v_cvt_scalef32_pk_f32_fp4 v[86:87], v20, 1.0 op_sel:[1,0,0]
	v_cvt_scalef32_pk_f32_fp4 v[88:89], v20, 1.0 op_sel:[0,1,0]
	v_cvt_scalef32_pk_f32_fp4 v[90:91], v20, 1.0 op_sel:[1,1,0]
	v_pk_fma_f32 v[166:167], s[40:41], v[84:85], v[166:167]
	s_lshl_b64 s[16:17], s[16:17], 10
	v_pk_fma_f32 v[168:169], s[40:41], v[86:87], v[168:169]
	v_pk_fma_f32 v[170:171], s[40:41], v[88:89], v[170:171]
	v_pk_fma_f32 v[172:173], s[40:41], v[90:91], v[172:173]
	v_cvt_scalef32_pk_f32_fp4 v[84:85], v21, 1.0
	v_cvt_scalef32_pk_f32_fp4 v[86:87], v21, 1.0 op_sel:[1,0,0]
	v_cvt_scalef32_pk_f32_fp4 v[88:89], v21, 1.0 op_sel:[0,1,0]
	v_cvt_scalef32_pk_f32_fp4 v[90:91], v21, 1.0 op_sel:[1,1,0]
	s_add_u32 s16, s52, s16
	v_pk_fma_f32 v[174:175], s[40:41], v[84:85], v[174:175]
	v_pk_fma_f32 v[176:177], s[40:41], v[86:87], v[176:177]
	v_pk_fma_f32 v[178:179], s[40:41], v[88:89], v[178:179]
	v_pk_fma_f32 v[180:181], s[40:41], v[90:91], v[180:181]
	v_cvt_scalef32_pk_f32_fp4 v[84:85], v22, 1.0
	v_cvt_scalef32_pk_f32_fp4 v[86:87], v22, 1.0 op_sel:[1,0,0]
	v_cvt_scalef32_pk_f32_fp4 v[88:89], v22, 1.0 op_sel:[0,1,0]
	v_cvt_scalef32_pk_f32_fp4 v[90:91], v22, 1.0 op_sel:[1,1,0]
	s_addc_u32 s17, s53, s17
	v_pk_fma_f32 v[182:183], s[40:41], v[84:85], v[182:183]
	v_pk_fma_f32 v[184:185], s[40:41], v[86:87], v[184:185]
	v_pk_fma_f32 v[186:187], s[40:41], v[88:89], v[186:187]
	v_pk_fma_f32 v[188:189], s[40:41], v[90:91], v[188:189]
	v_cvt_scalef32_pk_f32_fp4 v[84:85], v23, 1.0
	v_cvt_scalef32_pk_f32_fp4 v[86:87], v23, 1.0 op_sel:[1,0,0]
	v_cvt_scalef32_pk_f32_fp4 v[88:89], v23, 1.0 op_sel:[0,1,0]
	v_cvt_scalef32_pk_f32_fp4 v[90:91], v23, 1.0 op_sel:[1,1,0]
	v_pk_fma_f32 v[190:191], s[40:41], v[84:85], v[190:191]
	v_lshl_add_u64 v[84:85], s[16:17], 0, v[164:165]
	v_readlane_b32 s16, v208, 5
	v_pk_fma_f32 v[192:193], s[40:41], v[86:87], v[192:193]
	v_pk_fma_f32 v[194:195], s[40:41], v[88:89], v[194:195]
	v_pk_fma_f32 v[196:197], s[40:41], v[90:91], v[196:197]
	global_load_dwordx4 v[84:87], v[84:85], off
	v_readlane_b32 s40, v209, 5
	s_waitcnt vmcnt(15)
	v_cvt_scalef32_pk_f32_fp4 v[88:89], v24, 1.0
	s_lshr_b32 s16, s16, 7
	s_mov_b32 s17, s86
	s_mov_b32 s41, s40
	v_cvt_scalef32_pk_f32_fp4 v[90:91], v24, 1.0 op_sel:[1,0,0]
	v_cvt_scalef32_pk_f32_fp4 v[92:93], v24, 1.0 op_sel:[0,1,0]
	v_cvt_scalef32_pk_f32_fp4 v[94:95], v24, 1.0 op_sel:[1,1,0]
	v_pk_fma_f32 v[166:167], s[40:41], v[88:89], v[166:167]
	s_lshl_b64 s[16:17], s[16:17], 10
	v_pk_fma_f32 v[168:169], s[40:41], v[90:91], v[168:169]
	v_pk_fma_f32 v[170:171], s[40:41], v[92:93], v[170:171]
	v_pk_fma_f32 v[172:173], s[40:41], v[94:95], v[172:173]
	v_cvt_scalef32_pk_f32_fp4 v[88:89], v25, 1.0
	v_cvt_scalef32_pk_f32_fp4 v[90:91], v25, 1.0 op_sel:[1,0,0]
	v_cvt_scalef32_pk_f32_fp4 v[92:93], v25, 1.0 op_sel:[0,1,0]
	v_cvt_scalef32_pk_f32_fp4 v[94:95], v25, 1.0 op_sel:[1,1,0]
	s_add_u32 s16, s52, s16
	v_pk_fma_f32 v[174:175], s[40:41], v[88:89], v[174:175]
	v_pk_fma_f32 v[176:177], s[40:41], v[90:91], v[176:177]
	v_pk_fma_f32 v[178:179], s[40:41], v[92:93], v[178:179]
	v_pk_fma_f32 v[180:181], s[40:41], v[94:95], v[180:181]
	v_cvt_scalef32_pk_f32_fp4 v[88:89], v26, 1.0
	v_cvt_scalef32_pk_f32_fp4 v[90:91], v26, 1.0 op_sel:[1,0,0]
	v_cvt_scalef32_pk_f32_fp4 v[92:93], v26, 1.0 op_sel:[0,1,0]
	v_cvt_scalef32_pk_f32_fp4 v[94:95], v26, 1.0 op_sel:[1,1,0]
	s_addc_u32 s17, s53, s17
	v_pk_fma_f32 v[182:183], s[40:41], v[88:89], v[182:183]
	v_pk_fma_f32 v[184:185], s[40:41], v[90:91], v[184:185]
	v_pk_fma_f32 v[186:187], s[40:41], v[92:93], v[186:187]
	v_pk_fma_f32 v[188:189], s[40:41], v[94:95], v[188:189]
	v_cvt_scalef32_pk_f32_fp4 v[88:89], v27, 1.0
	v_cvt_scalef32_pk_f32_fp4 v[90:91], v27, 1.0 op_sel:[1,0,0]
	v_cvt_scalef32_pk_f32_fp4 v[92:93], v27, 1.0 op_sel:[0,1,0]
	v_cvt_scalef32_pk_f32_fp4 v[94:95], v27, 1.0 op_sel:[1,1,0]
	v_pk_fma_f32 v[190:191], s[40:41], v[88:89], v[190:191]
	v_lshl_add_u64 v[88:89], s[16:17], 0, v[164:165]
	v_readlane_b32 s16, v208, 6
	v_pk_fma_f32 v[192:193], s[40:41], v[90:91], v[192:193]
	v_pk_fma_f32 v[194:195], s[40:41], v[92:93], v[194:195]
	v_pk_fma_f32 v[196:197], s[40:41], v[94:95], v[196:197]
	global_load_dwordx4 v[88:91], v[88:89], off
	v_readlane_b32 s40, v209, 6
	s_waitcnt vmcnt(15)
	v_cvt_scalef32_pk_f32_fp4 v[92:93], v28, 1.0
	s_lshr_b32 s16, s16, 7
	s_mov_b32 s17, s86
	s_mov_b32 s41, s40
	v_cvt_scalef32_pk_f32_fp4 v[94:95], v28, 1.0 op_sel:[1,0,0]
	v_cvt_scalef32_pk_f32_fp4 v[96:97], v28, 1.0 op_sel:[0,1,0]
	v_cvt_scalef32_pk_f32_fp4 v[98:99], v28, 1.0 op_sel:[1,1,0]
	v_pk_fma_f32 v[166:167], s[40:41], v[92:93], v[166:167]
	s_lshl_b64 s[16:17], s[16:17], 10
	v_pk_fma_f32 v[168:169], s[40:41], v[94:95], v[168:169]
	v_pk_fma_f32 v[170:171], s[40:41], v[96:97], v[170:171]
	v_pk_fma_f32 v[172:173], s[40:41], v[98:99], v[172:173]
	v_cvt_scalef32_pk_f32_fp4 v[92:93], v29, 1.0
	v_cvt_scalef32_pk_f32_fp4 v[94:95], v29, 1.0 op_sel:[1,0,0]
	v_cvt_scalef32_pk_f32_fp4 v[96:97], v29, 1.0 op_sel:[0,1,0]
	v_cvt_scalef32_pk_f32_fp4 v[98:99], v29, 1.0 op_sel:[1,1,0]
	s_add_u32 s16, s52, s16
	v_pk_fma_f32 v[174:175], s[40:41], v[92:93], v[174:175]
	v_pk_fma_f32 v[176:177], s[40:41], v[94:95], v[176:177]
	v_pk_fma_f32 v[178:179], s[40:41], v[96:97], v[178:179]
	v_pk_fma_f32 v[180:181], s[40:41], v[98:99], v[180:181]
	v_cvt_scalef32_pk_f32_fp4 v[92:93], v30, 1.0
	v_cvt_scalef32_pk_f32_fp4 v[94:95], v30, 1.0 op_sel:[1,0,0]
	v_cvt_scalef32_pk_f32_fp4 v[96:97], v30, 1.0 op_sel:[0,1,0]
	v_cvt_scalef32_pk_f32_fp4 v[98:99], v30, 1.0 op_sel:[1,1,0]
	s_addc_u32 s17, s53, s17
	v_pk_fma_f32 v[182:183], s[40:41], v[92:93], v[182:183]
	v_pk_fma_f32 v[184:185], s[40:41], v[94:95], v[184:185]
	v_pk_fma_f32 v[186:187], s[40:41], v[96:97], v[186:187]
	v_pk_fma_f32 v[188:189], s[40:41], v[98:99], v[188:189]
	v_cvt_scalef32_pk_f32_fp4 v[92:93], v31, 1.0
	v_cvt_scalef32_pk_f32_fp4 v[94:95], v31, 1.0 op_sel:[1,0,0]
	v_cvt_scalef32_pk_f32_fp4 v[96:97], v31, 1.0 op_sel:[0,1,0]
	v_cvt_scalef32_pk_f32_fp4 v[98:99], v31, 1.0 op_sel:[1,1,0]
	v_pk_fma_f32 v[190:191], s[40:41], v[92:93], v[190:191]
	v_lshl_add_u64 v[92:93], s[16:17], 0, v[164:165]
	v_readlane_b32 s16, v208, 7
	v_pk_fma_f32 v[192:193], s[40:41], v[94:95], v[192:193]
	v_pk_fma_f32 v[194:195], s[40:41], v[96:97], v[194:195]
	v_pk_fma_f32 v[196:197], s[40:41], v[98:99], v[196:197]
	global_load_dwordx4 v[92:95], v[92:93], off
	v_readlane_b32 s40, v209, 7
	s_waitcnt vmcnt(15)
; #define P4_FOR16(M) M(0) M(1) M(2) M(3) M(4) M(5) M(6) M(7) M(8) M(9) M(10) M(11) M(12) M(13) M(14) M(15)
; #define P4_V(i) { const unsigned wu_ = (unsigned)__builtin_amdgcn_readlane((int)__float_as_uint(wreg), i); const unsigned long long wp_ = ((unsigned long long)wu_ << 32) | wu_; \
;               P4_ACC(b##i, wp_); const int nk_ = __builtin_amdgcn_readlane(ksel, nb + i); P4_LOAD(b##i, Vg, nk_); }
; #define P4_V(i) { const unsigned wu_ = (unsigned)__builtin_amdgcn_readlane((int)__float_as_uint(wreg), i); const unsigned long long wp_ = ((unsigned long long)wu_ << 32) | wu_; \
;               P4_ACC(b##i, wp_); const int nk_ = __builtin_amdgcn_readlane(kn, i); P4_LOAD(b##i, Vg, nk_); }
; #define P4_V(i) { const unsigned wu_ = (unsigned)__builtin_amdgcn_readlane((int)__float_as_uint(wreg), i); const unsigned long long wp_ = ((unsigned long long)wu_ << 32) | wu_; \
;               P4_ACC(b##i, wp_); }
; __device__ __forceinline__ void peer_gather_f4p(const float* X, const int* __restrict__ IDX, const float* __restrict__ G, ...
;     ...
;         {
;             const float wreg = wbuf[kt * 128 + 7 * 16 + (lane & 15)];
;             if (kt < 3) {
;     ...
;                 P4_FOR16(P4_V)
	v_cvt_scalef32_pk_f32_fp4 v[96:97], v32, 1.0
	s_lshr_b32 s16, s16, 7
	s_mov_b32 s17, s86
	s_mov_b32 s41, s40
	v_cvt_scalef32_pk_f32_fp4 v[98:99], v32, 1.0 op_sel:[1,0,0]
	v_cvt_scalef32_pk_f32_fp4 v[100:101], v32, 1.0 op_sel:[0,1,0]
	v_cvt_scalef32_pk_f32_fp4 v[102:103], v32, 1.0 op_sel:[1,1,0]
	v_pk_fma_f32 v[166:167], s[40:41], v[96:97], v[166:167]
	s_lshl_b64 s[16:17], s[16:17], 10
	v_pk_fma_f32 v[168:169], s[40:41], v[98:99], v[168:169]
	v_pk_fma_f32 v[170:171], s[40:41], v[100:101], v[170:171]
	v_pk_fma_f32 v[172:173], s[40:41], v[102:103], v[172:173]
	v_cvt_scalef32_pk_f32_fp4 v[96:97], v33, 1.0
	v_cvt_scalef32_pk_f32_fp4 v[98:99], v33, 1.0 op_sel:[1,0,0]
	v_cvt_scalef32_pk_f32_fp4 v[100:101], v33, 1.0 op_sel:[0,1,0]
	v_cvt_scalef32_pk_f32_fp4 v[102:103], v33, 1.0 op_sel:[1,1,0]
	s_add_u32 s16, s52, s16
	v_pk_fma_f32 v[174:175], s[40:41], v[96:97], v[174:175]
	v_pk_fma_f32 v[176:177], s[40:41], v[98:99], v[176:177]
	v_pk_fma_f32 v[178:179], s[40:41], v[100:101], v[178:179]
	v_pk_fma_f32 v[180:181], s[40:41], v[102:103], v[180:181]
	v_cvt_scalef32_pk_f32_fp4 v[96:97], v34, 1.0
	v_cvt_scalef32_pk_f32_fp4 v[98:99], v34, 1.0 op_sel:[1,0,0]
	v_cvt_scalef32_pk_f32_fp4 v[100:101], v34, 1.0 op_sel:[0,1,0]
	v_cvt_scalef32_pk_f32_fp4 v[102:103], v34, 1.0 op_sel:[1,1,0]
	s_addc_u32 s17, s53, s17
	v_pk_fma_f32 v[182:183], s[40:41], v[96:97], v[182:183]
	v_pk_fma_f32 v[184:185], s[40:41], v[98:99], v[184:185]
	v_pk_fma_f32 v[186:187], s[40:41], v[100:101], v[186:187]
	v_pk_fma_f32 v[188:189], s[40:41], v[102:103], v[188:189]
	v_cvt_scalef32_pk_f32_fp4 v[96:97], v35, 1.0
	v_cvt_scalef32_pk_f32_fp4 v[98:99], v35, 1.0 op_sel:[1,0,0]
	v_cvt_scalef32_pk_f32_fp4 v[100:101], v35, 1.0 op_sel:[0,1,0]
	v_cvt_scalef32_pk_f32_fp4 v[102:103], v35, 1.0 op_sel:[1,1,0]
	v_pk_fma_f32 v[190:191], s[40:41], v[96:97], v[190:191]
	v_lshl_add_u64 v[96:97], s[16:17], 0, v[164:165]
	v_readlane_b32 s16, v208, 8
	v_pk_fma_f32 v[192:193], s[40:41], v[98:99], v[192:193]
	v_pk_fma_f32 v[194:195], s[40:41], v[100:101], v[194:195]
	v_pk_fma_f32 v[196:197], s[40:41], v[102:103], v[196:197]
	global_load_dwordx4 v[96:99], v[96:97], off
	v_readlane_b32 s40, v209, 8
	s_waitcnt vmcnt(15)
	v_cvt_scalef32_pk_f32_fp4 v[100:101], v36, 1.0
	s_lshr_b32 s16, s16, 7
	s_mov_b32 s17, s86
	s_mov_b32 s41, s40
	v_cvt_scalef32_pk_f32_fp4 v[102:103], v36, 1.0 op_sel:[1,0,0]
	v_cvt_scalef32_pk_f32_fp4 v[104:105], v36, 1.0 op_sel:[0,1,0]
	v_cvt_scalef32_pk_f32_fp4 v[106:107], v36, 1.0 op_sel:[1,1,0]
	v_pk_fma_f32 v[166:167], s[40:41], v[100:101], v[166:167]
	s_lshl_b64 s[16:17], s[16:17], 10
	v_pk_fma_f32 v[168:169], s[40:41], v[102:103], v[168:169]
	v_pk_fma_f32 v[170:171], s[40:41], v[104:105], v[170:171]
	v_pk_fma_f32 v[172:173], s[40:41], v[106:107], v[172:173]
	v_cvt_scalef32_pk_f32_fp4 v[100:101], v37, 1.0
	v_cvt_scalef32_pk_f32_fp4 v[102:103], v37, 1.0 op_sel:[1,0,0]
	v_cvt_scalef32_pk_f32_fp4 v[104:105], v37, 1.0 op_sel:[0,1,0]
	v_cvt_scalef32_pk_f32_fp4 v[106:107], v37, 1.0 op_sel:[1,1,0]
	s_add_u32 s16, s52, s16
	v_pk_fma_f32 v[174:175], s[40:41], v[100:101], v[174:175]
	v_pk_fma_f32 v[176:177], s[40:41], v[102:103], v[176:177]
	v_pk_fma_f32 v[178:179], s[40:41], v[104:105], v[178:179]
	v_pk_fma_f32 v[180:181], s[40:41], v[106:107], v[180:181]
	v_cvt_scalef32_pk_f32_fp4 v[100:101], v38, 1.0
	v_cvt_scalef32_pk_f32_fp4 v[102:103], v38, 1.0 op_sel:[1,0,0]
	v_cvt_scalef32_pk_f32_fp4 v[104:105], v38, 1.0 op_sel:[0,1,0]
	v_cvt_scalef32_pk_f32_fp4 v[106:107], v38, 1.0 op_sel:[1,1,0]
	s_addc_u32 s17, s53, s17
	v_pk_fma_f32 v[182:183], s[40:41], v[100:101], v[182:183]
	v_pk_fma_f32 v[184:185], s[40:41], v[102:103], v[184:185]
	v_pk_fma_f32 v[186:187], s[40:41], v[104:105], v[186:187]
	v_pk_fma_f32 v[188:189], s[40:41], v[106:107], v[188:189]
	v_cvt_scalef32_pk_f32_fp4 v[100:101], v39, 1.0
	v_cvt_scalef32_pk_f32_fp4 v[102:103], v39, 1.0 op_sel:[1,0,0]
	v_cvt_scalef32_pk_f32_fp4 v[104:105], v39, 1.0 op_sel:[0,1,0]
	v_cvt_scalef32_pk_f32_fp4 v[106:107], v39, 1.0 op_sel:[1,1,0]
	v_pk_fma_f32 v[190:191], s[40:41], v[100:101], v[190:191]
	v_lshl_add_u64 v[100:101], s[16:17], 0, v[164:165]
	v_readlane_b32 s16, v208, 9
	v_pk_fma_f32 v[192:193], s[40:41], v[102:103], v[192:193]
	v_pk_fma_f32 v[194:195], s[40:41], v[104:105], v[194:195]
	v_pk_fma_f32 v[196:197], s[40:41], v[106:107], v[196:197]
	global_load_dwordx4 v[100:103], v[100:101], off
	v_readlane_b32 s40, v209, 9
	s_waitcnt vmcnt(15)
	v_cvt_scalef32_pk_f32_fp4 v[104:105], v40, 1.0
	s_lshr_b32 s16, s16, 7
	s_mov_b32 s17, s86
	s_mov_b32 s41, s40
	v_cvt_scalef32_pk_f32_fp4 v[106:107], v40, 1.0 op_sel:[1,0,0]
	v_cvt_scalef32_pk_f32_fp4 v[108:109], v40, 1.0 op_sel:[0,1,0]
	v_cvt_scalef32_pk_f32_fp4 v[110:111], v40, 1.0 op_sel:[1,1,0]
	v_pk_fma_f32 v[166:167], s[40:41], v[104:105], v[166:167]
	s_lshl_b64 s[16:17], s[16:17], 10
	v_pk_fma_f32 v[168:169], s[40:41], v[106:107], v[168:169]
	v_pk_fma_f32 v[170:171], s[40:41], v[108:109], v[170:171]
	v_pk_fma_f32 v[172:173], s[40:41], v[110:111], v[172:173]
	v_cvt_scalef32_pk_f32_fp4 v[104:105], v41, 1.0
	v_cvt_scalef32_pk_f32_fp4 v[106:107], v41, 1.0 op_sel:[1,0,0]
	v_cvt_scalef32_pk_f32_fp4 v[108:109], v41, 1.0 op_sel:[0,1,0]
	v_cvt_scalef32_pk_f32_fp4 v[110:111], v41, 1.0 op_sel:[1,1,0]
	s_add_u32 s16, s52, s16
	v_pk_fma_f32 v[174:175], s[40:41], v[104:105], v[174:175]
	v_pk_fma_f32 v[176:177], s[40:41], v[106:107], v[176:177]
	v_pk_fma_f32 v[178:179], s[40:41], v[108:109], v[178:179]
	v_pk_fma_f32 v[180:181], s[40:41], v[110:111], v[180:181]
	v_cvt_scalef32_pk_f32_fp4 v[104:105], v42, 1.0
	v_cvt_scalef32_pk_f32_fp4 v[106:107], v42, 1.0 op_sel:[1,0,0]
	v_cvt_scalef32_pk_f32_fp4 v[108:109], v42, 1.0 op_sel:[0,1,0]
	v_cvt_scalef32_pk_f32_fp4 v[110:111], v42, 1.0 op_sel:[1,1,0]
	s_addc_u32 s17, s53, s17
	v_pk_fma_f32 v[182:183], s[40:41], v[104:105], v[182:183]
	v_pk_fma_f32 v[184:185], s[40:41], v[106:107], v[184:185]
	v_pk_fma_f32 v[186:187], s[40:41], v[108:109], v[186:187]
	v_pk_fma_f32 v[188:189], s[40:41], v[110:111], v[188:189]
	v_cvt_scalef32_pk_f32_fp4 v[104:105], v43, 1.0
	v_cvt_scalef32_pk_f32_fp4 v[106:107], v43, 1.0 op_sel:[1,0,0]
	v_cvt_scalef32_pk_f32_fp4 v[108:109], v43, 1.0 op_sel:[0,1,0]
	v_cvt_scalef32_pk_f32_fp4 v[110:111], v43, 1.0 op_sel:[1,1,0]
	v_pk_fma_f32 v[190:191], s[40:41], v[104:105], v[190:191]
	v_lshl_add_u64 v[104:105], s[16:17], 0, v[164:165]
	v_readlane_b32 s16, v208, 10
	v_pk_fma_f32 v[192:193], s[40:41], v[106:107], v[192:193]
	v_pk_fma_f32 v[194:195], s[40:41], v[108:109], v[194:195]
	v_pk_fma_f32 v[196:197], s[40:41], v[110:111], v[196:197]
	global_load_dwordx4 v[104:107], v[104:105], off
	v_readlane_b32 s40, v209, 10
	s_waitcnt vmcnt(15)
; #define P4_FOR16(M) M(0) M(1) M(2) M(3) M(4) M(5) M(6) M(7) M(8) M(9) M(10) M(11) M(12) M(13) M(14) M(15)
; #define P4_V(i) { const unsigned wu_ = (unsigned)__builtin_amdgcn_readlane((int)__float_as_uint(wreg), i); const unsigned long long wp_ = ((unsigned long long)wu_ << 32) | wu_; \
;               P4_ACC(b##i, wp_); const int nk_ = __builtin_amdgcn_readlane(ksel, nb + i); P4_LOAD(b##i, Vg, nk_); }
; #define P4_V(i) { const unsigned wu_ = (unsigned)__builtin_amdgcn_readlane((int)__float_as_uint(wreg), i); const unsigned long long wp_ = ((unsigned long long)wu_ << 32) | wu_; \
;               P4_ACC(b##i, wp_); const int nk_ = __builtin_amdgcn_readlane(kn, i); P4_LOAD(b##i, Vg, nk_); }
; #define P4_V(i) { const unsigned wu_ = (unsigned)__builtin_amdgcn_readlane((int)__float_as_uint(wreg), i); const unsigned long long wp_ = ((unsigned long long)wu_ << 32) | wu_; \
;               P4_ACC(b##i, wp_); }
; __device__ __forceinline__ void peer_gather_f4p(const float* X, const int* __restrict__ IDX, const float* __restrict__ G, ...
;     ...
;         {
;             const float wreg = wbuf[kt * 128 + 7 * 16 + (lane & 15)];
;             if (kt < 3) {
;     ...
;                 P4_FOR16(P4_V)
	v_cvt_scalef32_pk_f32_fp4 v[108:109], v44, 1.0
	s_lshr_b32 s16, s16, 7
	s_mov_b32 s17, s86
	s_mov_b32 s41, s40
	v_cvt_scalef32_pk_f32_fp4 v[110:111], v44, 1.0 op_sel:[1,0,0]
	v_cvt_scalef32_pk_f32_fp4 v[112:113], v44, 1.0 op_sel:[0,1,0]
	v_cvt_scalef32_pk_f32_fp4 v[114:115], v44, 1.0 op_sel:[1,1,0]
	v_pk_fma_f32 v[166:167], s[40:41], v[108:109], v[166:167]
	s_lshl_b64 s[16:17], s[16:17], 10
	v_pk_fma_f32 v[168:169], s[40:41], v[110:111], v[168:169]
	v_pk_fma_f32 v[170:171], s[40:41], v[112:113], v[170:171]
	v_pk_fma_f32 v[172:173], s[40:41], v[114:115], v[172:173]
	v_cvt_scalef32_pk_f32_fp4 v[108:109], v45, 1.0
	v_cvt_scalef32_pk_f32_fp4 v[110:111], v45, 1.0 op_sel:[1,0,0]
	v_cvt_scalef32_pk_f32_fp4 v[112:113], v45, 1.0 op_sel:[0,1,0]
	v_cvt_scalef32_pk_f32_fp4 v[114:115], v45, 1.0 op_sel:[1,1,0]
	s_add_u32 s16, s52, s16
	v_pk_fma_f32 v[174:175], s[40:41], v[108:109], v[174:175]
	v_pk_fma_f32 v[176:177], s[40:41], v[110:111], v[176:177]
	v_pk_fma_f32 v[178:179], s[40:41], v[112:113], v[178:179]
	v_pk_fma_f32 v[180:181], s[40:41], v[114:115], v[180:181]
	v_cvt_scalef32_pk_f32_fp4 v[108:109], v46, 1.0
	v_cvt_scalef32_pk_f32_fp4 v[110:111], v46, 1.0 op_sel:[1,0,0]
	v_cvt_scalef32_pk_f32_fp4 v[112:113], v46, 1.0 op_sel:[0,1,0]
	v_cvt_scalef32_pk_f32_fp4 v[114:115], v46, 1.0 op_sel:[1,1,0]
	s_addc_u32 s17, s53, s17
	v_pk_fma_f32 v[182:183], s[40:41], v[108:109], v[182:183]
	v_pk_fma_f32 v[184:185], s[40:41], v[110:111], v[184:185]
	v_pk_fma_f32 v[186:187], s[40:41], v[112:113], v[186:187]
	v_pk_fma_f32 v[188:189], s[40:41], v[114:115], v[188:189]
	v_cvt_scalef32_pk_f32_fp4 v[108:109], v47, 1.0
	v_cvt_scalef32_pk_f32_fp4 v[110:111], v47, 1.0 op_sel:[1,0,0]
	v_cvt_scalef32_pk_f32_fp4 v[112:113], v47, 1.0 op_sel:[0,1,0]
	v_cvt_scalef32_pk_f32_fp4 v[114:115], v47, 1.0 op_sel:[1,1,0]
	v_pk_fma_f32 v[190:191], s[40:41], v[108:109], v[190:191]
	v_lshl_add_u64 v[108:109], s[16:17], 0, v[164:165]
	v_readlane_b32 s16, v208, 11
	v_pk_fma_f32 v[192:193], s[40:41], v[110:111], v[192:193]
	v_pk_fma_f32 v[194:195], s[40:41], v[112:113], v[194:195]
	v_pk_fma_f32 v[196:197], s[40:41], v[114:115], v[196:197]
	global_load_dwordx4 v[108:111], v[108:109], off
	v_readlane_b32 s40, v209, 11
	s_waitcnt vmcnt(15)
	v_cvt_scalef32_pk_f32_fp4 v[112:113], v48, 1.0
	s_lshr_b32 s16, s16, 7
	s_mov_b32 s17, s86
	s_mov_b32 s41, s40
	v_cvt_scalef32_pk_f32_fp4 v[114:115], v48, 1.0 op_sel:[1,0,0]
	v_cvt_scalef32_pk_f32_fp4 v[116:117], v48, 1.0 op_sel:[0,1,0]
	v_cvt_scalef32_pk_f32_fp4 v[118:119], v48, 1.0 op_sel:[1,1,0]
	v_pk_fma_f32 v[166:167], s[40:41], v[112:113], v[166:167]
	s_lshl_b64 s[16:17], s[16:17], 10
	v_pk_fma_f32 v[168:169], s[40:41], v[114:115], v[168:169]
	v_pk_fma_f32 v[170:171], s[40:41], v[116:117], v[170:171]
	v_pk_fma_f32 v[172:173], s[40:41], v[118:119], v[172:173]
	v_cvt_scalef32_pk_f32_fp4 v[112:113], v49, 1.0
	v_cvt_scalef32_pk_f32_fp4 v[114:115], v49, 1.0 op_sel:[1,0,0]
	v_cvt_scalef32_pk_f32_fp4 v[116:117], v49, 1.0 op_sel:[0,1,0]
	v_cvt_scalef32_pk_f32_fp4 v[118:119], v49, 1.0 op_sel:[1,1,0]
	s_add_u32 s16, s52, s16
	v_pk_fma_f32 v[174:175], s[40:41], v[112:113], v[174:175]
	v_pk_fma_f32 v[176:177], s[40:41], v[114:115], v[176:177]
	v_pk_fma_f32 v[178:179], s[40:41], v[116:117], v[178:179]
	v_pk_fma_f32 v[180:181], s[40:41], v[118:119], v[180:181]
	v_cvt_scalef32_pk_f32_fp4 v[112:113], v50, 1.0
	v_cvt_scalef32_pk_f32_fp4 v[114:115], v50, 1.0 op_sel:[1,0,0]
	v_cvt_scalef32_pk_f32_fp4 v[116:117], v50, 1.0 op_sel:[0,1,0]
	v_cvt_scalef32_pk_f32_fp4 v[118:119], v50, 1.0 op_sel:[1,1,0]
	s_addc_u32 s17, s53, s17
	v_pk_fma_f32 v[182:183], s[40:41], v[112:113], v[182:183]
	v_pk_fma_f32 v[184:185], s[40:41], v[114:115], v[184:185]
	v_pk_fma_f32 v[186:187], s[40:41], v[116:117], v[186:187]
	v_pk_fma_f32 v[188:189], s[40:41], v[118:119], v[188:189]
	v_cvt_scalef32_pk_f32_fp4 v[112:113], v51, 1.0
	v_cvt_scalef32_pk_f32_fp4 v[114:115], v51, 1.0 op_sel:[1,0,0]
	v_cvt_scalef32_pk_f32_fp4 v[116:117], v51, 1.0 op_sel:[0,1,0]
	v_cvt_scalef32_pk_f32_fp4 v[118:119], v51, 1.0 op_sel:[1,1,0]
	v_pk_fma_f32 v[190:191], s[40:41], v[112:113], v[190:191]
	v_lshl_add_u64 v[112:113], s[16:17], 0, v[164:165]
	v_readlane_b32 s16, v208, 12
	v_pk_fma_f32 v[192:193], s[40:41], v[114:115], v[192:193]
	v_pk_fma_f32 v[194:195], s[40:41], v[116:117], v[194:195]
	v_pk_fma_f32 v[196:197], s[40:41], v[118:119], v[196:197]
	global_load_dwordx4 v[112:115], v[112:113], off
	v_readlane_b32 s40, v209, 12
	s_waitcnt vmcnt(15)
	v_cvt_scalef32_pk_f32_fp4 v[116:117], v52, 1.0
	s_lshr_b32 s16, s16, 7
	s_mov_b32 s17, s86
	s_mov_b32 s41, s40
	v_cvt_scalef32_pk_f32_fp4 v[118:119], v52, 1.0 op_sel:[1,0,0]
	v_cvt_scalef32_pk_f32_fp4 v[120:121], v52, 1.0 op_sel:[0,1,0]
	v_cvt_scalef32_pk_f32_fp4 v[122:123], v52, 1.0 op_sel:[1,1,0]
	v_pk_fma_f32 v[166:167], s[40:41], v[116:117], v[166:167]
	s_lshl_b64 s[16:17], s[16:17], 10
	v_pk_fma_f32 v[168:169], s[40:41], v[118:119], v[168:169]
	v_pk_fma_f32 v[170:171], s[40:41], v[120:121], v[170:171]
	v_pk_fma_f32 v[172:173], s[40:41], v[122:123], v[172:173]
	v_cvt_scalef32_pk_f32_fp4 v[116:117], v53, 1.0
	v_cvt_scalef32_pk_f32_fp4 v[118:119], v53, 1.0 op_sel:[1,0,0]
	v_cvt_scalef32_pk_f32_fp4 v[120:121], v53, 1.0 op_sel:[0,1,0]
	v_cvt_scalef32_pk_f32_fp4 v[122:123], v53, 1.0 op_sel:[1,1,0]
	s_add_u32 s16, s52, s16
	v_pk_fma_f32 v[174:175], s[40:41], v[116:117], v[174:175]
	v_pk_fma_f32 v[176:177], s[40:41], v[118:119], v[176:177]
	v_pk_fma_f32 v[178:179], s[40:41], v[120:121], v[178:179]
	v_pk_fma_f32 v[180:181], s[40:41], v[122:123], v[180:181]
	v_cvt_scalef32_pk_f32_fp4 v[116:117], v54, 1.0
	v_cvt_scalef32_pk_f32_fp4 v[118:119], v54, 1.0 op_sel:[1,0,0]
	v_cvt_scalef32_pk_f32_fp4 v[120:121], v54, 1.0 op_sel:[0,1,0]
	v_cvt_scalef32_pk_f32_fp4 v[122:123], v54, 1.0 op_sel:[1,1,0]
	s_addc_u32 s17, s53, s17
	v_pk_fma_f32 v[182:183], s[40:41], v[116:117], v[182:183]
	v_pk_fma_f32 v[184:185], s[40:41], v[118:119], v[184:185]
	v_pk_fma_f32 v[186:187], s[40:41], v[120:121], v[186:187]
	v_pk_fma_f32 v[188:189], s[40:41], v[122:123], v[188:189]
	v_cvt_scalef32_pk_f32_fp4 v[116:117], v55, 1.0
	v_cvt_scalef32_pk_f32_fp4 v[118:119], v55, 1.0 op_sel:[1,0,0]
	v_cvt_scalef32_pk_f32_fp4 v[120:121], v55, 1.0 op_sel:[0,1,0]
	v_cvt_scalef32_pk_f32_fp4 v[122:123], v55, 1.0 op_sel:[1,1,0]
	v_pk_fma_f32 v[190:191], s[40:41], v[116:117], v[190:191]
	v_lshl_add_u64 v[116:117], s[16:17], 0, v[164:165]
	v_readlane_b32 s16, v208, 13
	v_pk_fma_f32 v[192:193], s[40:41], v[118:119], v[192:193]
	v_pk_fma_f32 v[194:195], s[40:41], v[120:121], v[194:195]
	v_pk_fma_f32 v[196:197], s[40:41], v[122:123], v[196:197]
	global_load_dwordx4 v[116:119], v[116:117], off
	v_readlane_b32 s40, v209, 13
	s_waitcnt vmcnt(15)
; #define P4_FOR16(M) M(0) M(1) M(2) M(3) M(4) M(5) M(6) M(7) M(8) M(9) M(10) M(11) M(12) M(13) M(14) M(15)
; #define P4_V(i) { const unsigned wu_ = (unsigned)__builtin_amdgcn_readlane((int)__float_as_uint(wreg), i); const unsigned long long wp_ = ((unsigned long long)wu_ << 32) | wu_; \
;               P4_ACC(b##i, wp_); const int nk_ = __builtin_amdgcn_readlane(ksel, nb + i); P4_LOAD(b##i, Vg, nk_); }
; #define P4_V(i) { const unsigned wu_ = (unsigned)__builtin_amdgcn_readlane((int)__float_as_uint(wreg), i); const unsigned long long wp_ = ((unsigned long long)wu_ << 32) | wu_; \
;               P4_ACC(b##i, wp_); const int nk_ = __builtin_amdgcn_readlane(kn, i); P4_LOAD(b##i, Vg, nk_); }
; #define P4_V(i) { const unsigned wu_ = (unsigned)__builtin_amdgcn_readlane((int)__float_as_uint(wreg), i); const unsigned long long wp_ = ((unsigned long long)wu_ << 32) | wu_; \
;               P4_ACC(b##i, wp_); }
; __device__ __forceinline__ void peer_gather_f4p(const float* X, const int* __restrict__ IDX, const float* __restrict__ G, ...
;     ...
;         {
;             const float wreg = wbuf[kt * 128 + 7 * 16 + (lane & 15)];
;             if (kt < 3) {
;     ...
;                 P4_FOR16(P4_V)
	v_cvt_scalef32_pk_f32_fp4 v[120:121], v56, 1.0
	s_lshr_b32 s16, s16, 7
	s_mov_b32 s17, s86
	s_mov_b32 s41, s40
	v_cvt_scalef32_pk_f32_fp4 v[122:123], v56, 1.0 op_sel:[1,0,0]
	v_cvt_scalef32_pk_f32_fp4 v[124:125], v56, 1.0 op_sel:[0,1,0]
	v_cvt_scalef32_pk_f32_fp4 v[126:127], v56, 1.0 op_sel:[1,1,0]
	v_pk_fma_f32 v[166:167], s[40:41], v[120:121], v[166:167]
	s_lshl_b64 s[16:17], s[16:17], 10
	v_pk_fma_f32 v[168:169], s[40:41], v[122:123], v[168:169]
	v_pk_fma_f32 v[170:171], s[40:41], v[124:125], v[170:171]
	v_pk_fma_f32 v[172:173], s[40:41], v[126:127], v[172:173]
	v_cvt_scalef32_pk_f32_fp4 v[120:121], v57, 1.0
	v_cvt_scalef32_pk_f32_fp4 v[122:123], v57, 1.0 op_sel:[1,0,0]
	v_cvt_scalef32_pk_f32_fp4 v[124:125], v57, 1.0 op_sel:[0,1,0]
	v_cvt_scalef32_pk_f32_fp4 v[126:127], v57, 1.0 op_sel:[1,1,0]
	s_add_u32 s16, s52, s16
	v_pk_fma_f32 v[174:175], s[40:41], v[120:121], v[174:175]
	v_pk_fma_f32 v[176:177], s[40:41], v[122:123], v[176:177]
	v_pk_fma_f32 v[178:179], s[40:41], v[124:125], v[178:179]
	v_pk_fma_f32 v[180:181], s[40:41], v[126:127], v[180:181]
	v_cvt_scalef32_pk_f32_fp4 v[120:121], v58, 1.0
	v_cvt_scalef32_pk_f32_fp4 v[122:123], v58, 1.0 op_sel:[1,0,0]
	v_cvt_scalef32_pk_f32_fp4 v[124:125], v58, 1.0 op_sel:[0,1,0]
	v_cvt_scalef32_pk_f32_fp4 v[126:127], v58, 1.0 op_sel:[1,1,0]
	s_addc_u32 s17, s53, s17
	v_pk_fma_f32 v[182:183], s[40:41], v[120:121], v[182:183]
	v_pk_fma_f32 v[184:185], s[40:41], v[122:123], v[184:185]
	v_pk_fma_f32 v[186:187], s[40:41], v[124:125], v[186:187]
	v_pk_fma_f32 v[188:189], s[40:41], v[126:127], v[188:189]
	v_cvt_scalef32_pk_f32_fp4 v[120:121], v59, 1.0
	v_cvt_scalef32_pk_f32_fp4 v[122:123], v59, 1.0 op_sel:[1,0,0]
	v_cvt_scalef32_pk_f32_fp4 v[124:125], v59, 1.0 op_sel:[0,1,0]
	v_cvt_scalef32_pk_f32_fp4 v[126:127], v59, 1.0 op_sel:[1,1,0]
	v_pk_fma_f32 v[190:191], s[40:41], v[120:121], v[190:191]
	v_lshl_add_u64 v[120:121], s[16:17], 0, v[164:165]
	v_readlane_b32 s16, v208, 14
	v_pk_fma_f32 v[192:193], s[40:41], v[122:123], v[192:193]
	v_pk_fma_f32 v[194:195], s[40:41], v[124:125], v[194:195]
	v_pk_fma_f32 v[196:197], s[40:41], v[126:127], v[196:197]
	global_load_dwordx4 v[120:123], v[120:121], off
	v_readlane_b32 s40, v209, 14
	s_waitcnt vmcnt(15)
	v_cvt_scalef32_pk_f32_fp4 v[124:125], v60, 1.0
	s_lshr_b32 s16, s16, 7
	s_mov_b32 s17, s86
	s_mov_b32 s41, s40
	v_cvt_scalef32_pk_f32_fp4 v[126:127], v60, 1.0 op_sel:[1,0,0]
	v_cvt_scalef32_pk_f32_fp4 v[128:129], v60, 1.0 op_sel:[0,1,0]
	v_cvt_scalef32_pk_f32_fp4 v[130:131], v60, 1.0 op_sel:[1,1,0]
	v_pk_fma_f32 v[166:167], s[40:41], v[124:125], v[166:167]
	s_lshl_b64 s[16:17], s[16:17], 10
	v_pk_fma_f32 v[168:169], s[40:41], v[126:127], v[168:169]
	v_pk_fma_f32 v[170:171], s[40:41], v[128:129], v[170:171]
	v_pk_fma_f32 v[172:173], s[40:41], v[130:131], v[172:173]
	v_cvt_scalef32_pk_f32_fp4 v[124:125], v61, 1.0
	v_cvt_scalef32_pk_f32_fp4 v[126:127], v61, 1.0 op_sel:[1,0,0]
	v_cvt_scalef32_pk_f32_fp4 v[128:129], v61, 1.0 op_sel:[0,1,0]
	v_cvt_scalef32_pk_f32_fp4 v[130:131], v61, 1.0 op_sel:[1,1,0]
	s_add_u32 s16, s52, s16
	v_pk_fma_f32 v[174:175], s[40:41], v[124:125], v[174:175]
	v_pk_fma_f32 v[176:177], s[40:41], v[126:127], v[176:177]
	v_pk_fma_f32 v[178:179], s[40:41], v[128:129], v[178:179]
	v_pk_fma_f32 v[180:181], s[40:41], v[130:131], v[180:181]
	v_cvt_scalef32_pk_f32_fp4 v[124:125], v62, 1.0
	v_cvt_scalef32_pk_f32_fp4 v[126:127], v62, 1.0 op_sel:[1,0,0]
	v_cvt_scalef32_pk_f32_fp4 v[128:129], v62, 1.0 op_sel:[0,1,0]
	v_cvt_scalef32_pk_f32_fp4 v[130:131], v62, 1.0 op_sel:[1,1,0]
	s_addc_u32 s17, s53, s17
	v_pk_fma_f32 v[182:183], s[40:41], v[124:125], v[182:183]
	v_pk_fma_f32 v[184:185], s[40:41], v[126:127], v[184:185]
	v_pk_fma_f32 v[186:187], s[40:41], v[128:129], v[186:187]
	v_pk_fma_f32 v[188:189], s[40:41], v[130:131], v[188:189]
	v_cvt_scalef32_pk_f32_fp4 v[124:125], v63, 1.0
	v_cvt_scalef32_pk_f32_fp4 v[126:127], v63, 1.0 op_sel:[1,0,0]
	v_cvt_scalef32_pk_f32_fp4 v[128:129], v63, 1.0 op_sel:[0,1,0]
	v_cvt_scalef32_pk_f32_fp4 v[130:131], v63, 1.0 op_sel:[1,1,0]
	v_pk_fma_f32 v[190:191], s[40:41], v[124:125], v[190:191]
	v_lshl_add_u64 v[124:125], s[16:17], 0, v[164:165]
	v_readlane_b32 s16, v208, 15
	v_pk_fma_f32 v[192:193], s[40:41], v[126:127], v[192:193]
	v_pk_fma_f32 v[194:195], s[40:41], v[128:129], v[194:195]
	v_pk_fma_f32 v[196:197], s[40:41], v[130:131], v[196:197]
	global_load_dwordx4 v[124:127], v[124:125], off
	v_readlane_b32 s40, v209, 15
	s_waitcnt vmcnt(15)
	v_cvt_scalef32_pk_f32_fp4 v[128:129], v80, 1.0
	s_lshr_b32 s16, s16, 7
	s_mov_b32 s17, s86
	s_mov_b32 s41, s40
	v_cvt_scalef32_pk_f32_fp4 v[130:131], v80, 1.0 op_sel:[1,0,0]
	v_cvt_scalef32_pk_f32_fp4 v[210:211], v80, 1.0 op_sel:[0,1,0]
	v_cvt_scalef32_pk_f32_fp4 v[212:213], v80, 1.0 op_sel:[1,1,0]
	v_pk_fma_f32 v[166:167], s[40:41], v[128:129], v[166:167]
	s_lshl_b64 s[16:17], s[16:17], 10
	v_pk_fma_f32 v[168:169], s[40:41], v[130:131], v[168:169]
	v_pk_fma_f32 v[170:171], s[40:41], v[210:211], v[170:171]
	v_pk_fma_f32 v[172:173], s[40:41], v[212:213], v[172:173]
	v_cvt_scalef32_pk_f32_fp4 v[128:129], v81, 1.0
	v_cvt_scalef32_pk_f32_fp4 v[130:131], v81, 1.0 op_sel:[1,0,0]
	v_cvt_scalef32_pk_f32_fp4 v[210:211], v81, 1.0 op_sel:[0,1,0]
	v_cvt_scalef32_pk_f32_fp4 v[212:213], v81, 1.0 op_sel:[1,1,0]
	s_add_u32 s16, s52, s16
	v_pk_fma_f32 v[174:175], s[40:41], v[128:129], v[174:175]
	v_pk_fma_f32 v[176:177], s[40:41], v[130:131], v[176:177]
	v_pk_fma_f32 v[178:179], s[40:41], v[210:211], v[178:179]
	v_pk_fma_f32 v[180:181], s[40:41], v[212:213], v[180:181]
	v_cvt_scalef32_pk_f32_fp4 v[128:129], v82, 1.0
	v_cvt_scalef32_pk_f32_fp4 v[130:131], v82, 1.0 op_sel:[1,0,0]
	v_cvt_scalef32_pk_f32_fp4 v[210:211], v82, 1.0 op_sel:[0,1,0]
	v_cvt_scalef32_pk_f32_fp4 v[212:213], v82, 1.0 op_sel:[1,1,0]
	s_addc_u32 s17, s53, s17
	v_pk_fma_f32 v[182:183], s[40:41], v[128:129], v[182:183]
	v_pk_fma_f32 v[184:185], s[40:41], v[130:131], v[184:185]
	v_pk_fma_f32 v[186:187], s[40:41], v[210:211], v[186:187]
	v_pk_fma_f32 v[188:189], s[40:41], v[212:213], v[188:189]
	v_cvt_scalef32_pk_f32_fp4 v[128:129], v83, 1.0
	v_cvt_scalef32_pk_f32_fp4 v[130:131], v83, 1.0 op_sel:[1,0,0]
	v_cvt_scalef32_pk_f32_fp4 v[210:211], v83, 1.0 op_sel:[0,1,0]
	v_cvt_scalef32_pk_f32_fp4 v[212:213], v83, 1.0 op_sel:[1,1,0]
	v_pk_fma_f32 v[190:191], s[40:41], v[128:129], v[190:191]
	v_lshl_add_u64 v[128:129], s[16:17], 0, v[164:165]
	v_pk_fma_f32 v[192:193], s[40:41], v[130:131], v[192:193]
	v_pk_fma_f32 v[194:195], s[40:41], v[210:211], v[194:195]
	v_pk_fma_f32 v[196:197], s[40:41], v[212:213], v[196:197]
	global_load_dwordx4 v[128:131], v[128:129], off
	s_mov_b64 s[40:41], 0
; #define P4_FOR16(M) M(0) M(1) M(2) M(3) M(4) M(5) M(6) M(7) M(8) M(9) M(10) M(11) M(12) M(13) M(14) M(15)
; #define P4_V(i) { const unsigned wu_ = (unsigned)__builtin_amdgcn_readlane((int)__float_as_uint(wreg), i); const unsigned long long wp_ = ((unsigned long long)wu_ << 32) | wu_; \
;               P4_ACC(b##i, wp_); const int nk_ = __builtin_amdgcn_readlane(ksel, nb + i); P4_LOAD(b##i, Vg, nk_); }
; #define P4_V(i) { const unsigned wu_ = (unsigned)__builtin_amdgcn_readlane((int)__float_as_uint(wreg), i); const unsigned long long wp_ = ((unsigned long long)wu_ << 32) | wu_; \
;               P4_ACC(b##i, wp_); const int nk_ = __builtin_amdgcn_readlane(kn, i); P4_LOAD(b##i, Vg, nk_); }
; #define P4_V(i) { const unsigned wu_ = (unsigned)__builtin_amdgcn_readlane((int)__float_as_uint(wreg), i); const unsigned long long wp_ = ((unsigned long long)wu_ << 32) | wu_; \
;               P4_ACC(b##i, wp_); }
; __device__ __forceinline__ void peer_gather_f4p(const float* X, const int* __restrict__ IDX, const float* __restrict__ G, ...
;     ...
;                 P4_FOR16(P4_V)
.LBB0_1250:
	s_andn2_b64 vcc, exec, s[40:41]
	s_cbranch_vccnz .LBB0_1252
	s_waitcnt lgkmcnt(0)
	v_readlane_b32 s40, v209, 0
	s_waitcnt vmcnt(15)
	v_cvt_scalef32_pk_f32_fp4 v[64:65], v4, 1.0
	v_cvt_scalef32_pk_f32_fp4 v[66:67], v4, 1.0 op_sel:[1,0,0]
	s_waitcnt vmcnt(14)
	v_cvt_scalef32_pk_f32_fp4 v[68:69], v4, 1.0 op_sel:[0,1,0]
	v_cvt_scalef32_pk_f32_fp4 v[70:71], v4, 1.0 op_sel:[1,1,0]
	s_mov_b32 s41, s40
	v_pk_fma_f32 v[132:133], s[40:41], v[64:65], v[132:133]
	v_pk_fma_f32 v[162:163], s[40:41], v[66:67], v[162:163]
	v_pk_fma_f32 v[160:161], s[40:41], v[68:69], v[160:161]
	v_pk_fma_f32 v[158:159], s[40:41], v[70:71], v[158:159]
	v_cvt_scalef32_pk_f32_fp4 v[64:65], v5, 1.0
	v_cvt_scalef32_pk_f32_fp4 v[66:67], v5, 1.0 op_sel:[1,0,0]
	v_cvt_scalef32_pk_f32_fp4 v[68:69], v5, 1.0 op_sel:[0,1,0]
	v_cvt_scalef32_pk_f32_fp4 v[70:71], v5, 1.0 op_sel:[1,1,0]
	s_waitcnt vmcnt(0)
	v_mov_b64_e32 v[130:131], v[82:83]
	v_pk_fma_f32 v[156:157], s[40:41], v[64:65], v[156:157]
	v_pk_fma_f32 v[154:155], s[40:41], v[66:67], v[154:155]
	v_pk_fma_f32 v[152:153], s[40:41], v[68:69], v[152:153]
	v_pk_fma_f32 v[150:151], s[40:41], v[70:71], v[150:151]
	v_cvt_scalef32_pk_f32_fp4 v[64:65], v6, 1.0
	v_cvt_scalef32_pk_f32_fp4 v[66:67], v6, 1.0 op_sel:[1,0,0]
	v_cvt_scalef32_pk_f32_fp4 v[68:69], v6, 1.0 op_sel:[0,1,0]
	v_cvt_scalef32_pk_f32_fp4 v[70:71], v6, 1.0 op_sel:[1,1,0]
	v_mov_b64_e32 v[126:127], v[62:63]
	v_pk_fma_f32 v[148:149], s[40:41], v[64:65], v[148:149]
	v_pk_fma_f32 v[146:147], s[40:41], v[66:67], v[146:147]
	v_pk_fma_f32 v[144:145], s[40:41], v[68:69], v[144:145]
	v_pk_fma_f32 v[142:143], s[40:41], v[70:71], v[142:143]
	v_cvt_scalef32_pk_f32_fp4 v[64:65], v7, 1.0
	v_cvt_scalef32_pk_f32_fp4 v[66:67], v7, 1.0 op_sel:[1,0,0]
	v_cvt_scalef32_pk_f32_fp4 v[68:69], v7, 1.0 op_sel:[0,1,0]
	v_cvt_scalef32_pk_f32_fp4 v[70:71], v7, 1.0 op_sel:[1,1,0]
	v_mov_b64_e32 v[122:123], v[58:59]
	v_pk_fma_f32 v[140:141], s[40:41], v[64:65], v[140:141]
	v_pk_fma_f32 v[138:139], s[40:41], v[66:67], v[138:139]
	v_pk_fma_f32 v[136:137], s[40:41], v[68:69], v[136:137]
	v_pk_fma_f32 v[134:135], s[40:41], v[70:71], v[134:135]
	v_readlane_b32 s40, v209, 1
	v_cvt_scalef32_pk_f32_fp4 v[64:65], v8, 1.0
	v_cvt_scalef32_pk_f32_fp4 v[66:67], v8, 1.0 op_sel:[1,0,0]
	v_cvt_scalef32_pk_f32_fp4 v[68:69], v8, 1.0 op_sel:[0,1,0]
	v_cvt_scalef32_pk_f32_fp4 v[70:71], v8, 1.0 op_sel:[1,1,0]
	s_mov_b32 s41, s40
	v_pk_fma_f32 v[132:133], s[40:41], v[64:65], v[132:133]
	v_pk_fma_f32 v[162:163], s[40:41], v[66:67], v[162:163]
	v_pk_fma_f32 v[160:161], s[40:41], v[68:69], v[160:161]
	v_pk_fma_f32 v[158:159], s[40:41], v[70:71], v[158:159]
	v_cvt_scalef32_pk_f32_fp4 v[64:65], v9, 1.0
	v_cvt_scalef32_pk_f32_fp4 v[66:67], v9, 1.0 op_sel:[1,0,0]
	v_cvt_scalef32_pk_f32_fp4 v[68:69], v9, 1.0 op_sel:[0,1,0]
	v_cvt_scalef32_pk_f32_fp4 v[70:71], v9, 1.0 op_sel:[1,1,0]
	v_mov_b64_e32 v[118:119], v[54:55]
	v_pk_fma_f32 v[156:157], s[40:41], v[64:65], v[156:157]
	v_pk_fma_f32 v[154:155], s[40:41], v[66:67], v[154:155]
	v_pk_fma_f32 v[152:153], s[40:41], v[68:69], v[152:153]
	v_pk_fma_f32 v[150:151], s[40:41], v[70:71], v[150:151]
	v_cvt_scalef32_pk_f32_fp4 v[64:65], v10, 1.0
	v_cvt_scalef32_pk_f32_fp4 v[66:67], v10, 1.0 op_sel:[1,0,0]
	v_cvt_scalef32_pk_f32_fp4 v[68:69], v10, 1.0 op_sel:[0,1,0]
	v_cvt_scalef32_pk_f32_fp4 v[70:71], v10, 1.0 op_sel:[1,1,0]
	v_mov_b64_e32 v[114:115], v[50:51]
	v_pk_fma_f32 v[148:149], s[40:41], v[64:65], v[148:149]
	v_pk_fma_f32 v[146:147], s[40:41], v[66:67], v[146:147]
	v_pk_fma_f32 v[144:145], s[40:41], v[68:69], v[144:145]
	v_pk_fma_f32 v[142:143], s[40:41], v[70:71], v[142:143]
	v_cvt_scalef32_pk_f32_fp4 v[64:65], v11, 1.0
	v_cvt_scalef32_pk_f32_fp4 v[66:67], v11, 1.0 op_sel:[1,0,0]
	v_cvt_scalef32_pk_f32_fp4 v[68:69], v11, 1.0 op_sel:[0,1,0]
	v_cvt_scalef32_pk_f32_fp4 v[70:71], v11, 1.0 op_sel:[1,1,0]
	v_mov_b64_e32 v[110:111], v[46:47]
	v_pk_fma_f32 v[140:141], s[40:41], v[64:65], v[140:141]
	v_pk_fma_f32 v[138:139], s[40:41], v[66:67], v[138:139]
	v_pk_fma_f32 v[136:137], s[40:41], v[68:69], v[136:137]
	v_pk_fma_f32 v[134:135], s[40:41], v[70:71], v[134:135]
	v_readlane_b32 s40, v209, 2
	v_cvt_scalef32_pk_f32_fp4 v[64:65], v12, 1.0
	v_cvt_scalef32_pk_f32_fp4 v[66:67], v12, 1.0 op_sel:[1,0,0]
	v_cvt_scalef32_pk_f32_fp4 v[68:69], v12, 1.0 op_sel:[0,1,0]
	v_cvt_scalef32_pk_f32_fp4 v[70:71], v12, 1.0 op_sel:[1,1,0]
	s_mov_b32 s41, s40
	v_pk_fma_f32 v[132:133], s[40:41], v[64:65], v[132:133]
	v_pk_fma_f32 v[162:163], s[40:41], v[66:67], v[162:163]
	v_pk_fma_f32 v[160:161], s[40:41], v[68:69], v[160:161]
	v_pk_fma_f32 v[158:159], s[40:41], v[70:71], v[158:159]
	v_cvt_scalef32_pk_f32_fp4 v[64:65], v13, 1.0
	v_cvt_scalef32_pk_f32_fp4 v[66:67], v13, 1.0 op_sel:[1,0,0]
	v_cvt_scalef32_pk_f32_fp4 v[68:69], v13, 1.0 op_sel:[0,1,0]
	v_cvt_scalef32_pk_f32_fp4 v[70:71], v13, 1.0 op_sel:[1,1,0]
	v_mov_b64_e32 v[106:107], v[42:43]
	v_pk_fma_f32 v[156:157], s[40:41], v[64:65], v[156:157]
	v_pk_fma_f32 v[154:155], s[40:41], v[66:67], v[154:155]
	v_pk_fma_f32 v[152:153], s[40:41], v[68:69], v[152:153]
	v_pk_fma_f32 v[150:151], s[40:41], v[70:71], v[150:151]
	v_cvt_scalef32_pk_f32_fp4 v[64:65], v14, 1.0
	v_cvt_scalef32_pk_f32_fp4 v[66:67], v14, 1.0 op_sel:[1,0,0]
	v_cvt_scalef32_pk_f32_fp4 v[68:69], v14, 1.0 op_sel:[0,1,0]
	v_cvt_scalef32_pk_f32_fp4 v[70:71], v14, 1.0 op_sel:[1,1,0]
	v_mov_b64_e32 v[102:103], v[38:39]
	v_pk_fma_f32 v[148:149], s[40:41], v[64:65], v[148:149]
	v_pk_fma_f32 v[146:147], s[40:41], v[66:67], v[146:147]
	v_pk_fma_f32 v[144:145], s[40:41], v[68:69], v[144:145]
	v_pk_fma_f32 v[142:143], s[40:41], v[70:71], v[142:143]
	v_cvt_scalef32_pk_f32_fp4 v[64:65], v15, 1.0
; #define P4_FOR16(M) M(0) M(1) M(2) M(3) M(4) M(5) M(6) M(7) M(8) M(9) M(10) M(11) M(12) M(13) M(14) M(15)
; #define P4_V(i) { const unsigned wu_ = (unsigned)__builtin_amdgcn_readlane((int)__float_as_uint(wreg), i); const unsigned long long wp_ = ((unsigned long long)wu_ << 32) | wu_; \
;               P4_ACC(b##i, wp_); const int nk_ = __builtin_amdgcn_readlane(ksel, nb + i); P4_LOAD(b##i, Vg, nk_); }
; #define P4_V(i) { const unsigned wu_ = (unsigned)__builtin_amdgcn_readlane((int)__float_as_uint(wreg), i); const unsigned long long wp_ = ((unsigned long long)wu_ << 32) | wu_; \
;               P4_ACC(b##i, wp_); const int nk_ = __builtin_amdgcn_readlane(kn, i); P4_LOAD(b##i, Vg, nk_); }
; #define P4_V(i) { const unsigned wu_ = (unsigned)__builtin_amdgcn_readlane((int)__float_as_uint(wreg), i); const unsigned long long wp_ = ((unsigned long long)wu_ << 32) | wu_; \
;               P4_ACC(b##i, wp_); }
; __device__ __forceinline__ void peer_gather_f4p(const float* X, const int* __restrict__ IDX, const float* __restrict__ G, ...
;     ...
;                 P4_FOR16(P4_V)
	v_cvt_scalef32_pk_f32_fp4 v[66:67], v15, 1.0 op_sel:[1,0,0]
	v_cvt_scalef32_pk_f32_fp4 v[68:69], v15, 1.0 op_sel:[0,1,0]
	v_cvt_scalef32_pk_f32_fp4 v[70:71], v15, 1.0 op_sel:[1,1,0]
	v_mov_b64_e32 v[98:99], v[34:35]
	v_pk_fma_f32 v[140:141], s[40:41], v[64:65], v[140:141]
	v_pk_fma_f32 v[138:139], s[40:41], v[66:67], v[138:139]
	v_pk_fma_f32 v[136:137], s[40:41], v[68:69], v[136:137]
	v_pk_fma_f32 v[134:135], s[40:41], v[70:71], v[134:135]
	v_readlane_b32 s40, v209, 3
	v_cvt_scalef32_pk_f32_fp4 v[64:65], v16, 1.0
	v_cvt_scalef32_pk_f32_fp4 v[66:67], v16, 1.0 op_sel:[1,0,0]
	v_cvt_scalef32_pk_f32_fp4 v[68:69], v16, 1.0 op_sel:[0,1,0]
	v_cvt_scalef32_pk_f32_fp4 v[70:71], v16, 1.0 op_sel:[1,1,0]
	s_mov_b32 s41, s40
	v_pk_fma_f32 v[132:133], s[40:41], v[64:65], v[132:133]
	v_pk_fma_f32 v[162:163], s[40:41], v[66:67], v[162:163]
	v_pk_fma_f32 v[160:161], s[40:41], v[68:69], v[160:161]
	v_pk_fma_f32 v[158:159], s[40:41], v[70:71], v[158:159]
	v_cvt_scalef32_pk_f32_fp4 v[64:65], v17, 1.0
	v_cvt_scalef32_pk_f32_fp4 v[66:67], v17, 1.0 op_sel:[1,0,0]
	v_cvt_scalef32_pk_f32_fp4 v[68:69], v17, 1.0 op_sel:[0,1,0]
	v_cvt_scalef32_pk_f32_fp4 v[70:71], v17, 1.0 op_sel:[1,1,0]
	v_mov_b64_e32 v[94:95], v[30:31]
	v_pk_fma_f32 v[156:157], s[40:41], v[64:65], v[156:157]
	v_pk_fma_f32 v[154:155], s[40:41], v[66:67], v[154:155]
	v_pk_fma_f32 v[152:153], s[40:41], v[68:69], v[152:153]
	v_pk_fma_f32 v[150:151], s[40:41], v[70:71], v[150:151]
	v_cvt_scalef32_pk_f32_fp4 v[64:65], v18, 1.0
	v_cvt_scalef32_pk_f32_fp4 v[66:67], v18, 1.0 op_sel:[1,0,0]
	v_cvt_scalef32_pk_f32_fp4 v[68:69], v18, 1.0 op_sel:[0,1,0]
	v_cvt_scalef32_pk_f32_fp4 v[70:71], v18, 1.0 op_sel:[1,1,0]
	v_mov_b64_e32 v[90:91], v[26:27]
	v_pk_fma_f32 v[148:149], s[40:41], v[64:65], v[148:149]
	v_pk_fma_f32 v[146:147], s[40:41], v[66:67], v[146:147]
	v_pk_fma_f32 v[144:145], s[40:41], v[68:69], v[144:145]
	v_pk_fma_f32 v[142:143], s[40:41], v[70:71], v[142:143]
	v_cvt_scalef32_pk_f32_fp4 v[64:65], v19, 1.0
	v_cvt_scalef32_pk_f32_fp4 v[66:67], v19, 1.0 op_sel:[1,0,0]
	v_cvt_scalef32_pk_f32_fp4 v[68:69], v19, 1.0 op_sel:[0,1,0]
	v_cvt_scalef32_pk_f32_fp4 v[70:71], v19, 1.0 op_sel:[1,1,0]
	v_mov_b64_e32 v[86:87], v[22:23]
	v_pk_fma_f32 v[140:141], s[40:41], v[64:65], v[140:141]
	v_pk_fma_f32 v[138:139], s[40:41], v[66:67], v[138:139]
	v_pk_fma_f32 v[136:137], s[40:41], v[68:69], v[136:137]
	v_pk_fma_f32 v[134:135], s[40:41], v[70:71], v[134:135]
	v_readlane_b32 s40, v209, 4
	v_cvt_scalef32_pk_f32_fp4 v[64:65], v20, 1.0
	v_cvt_scalef32_pk_f32_fp4 v[66:67], v20, 1.0 op_sel:[1,0,0]
	v_cvt_scalef32_pk_f32_fp4 v[68:69], v20, 1.0 op_sel:[0,1,0]
	v_cvt_scalef32_pk_f32_fp4 v[70:71], v20, 1.0 op_sel:[1,1,0]
	s_mov_b32 s41, s40
	v_pk_fma_f32 v[132:133], s[40:41], v[64:65], v[132:133]
	v_pk_fma_f32 v[162:163], s[40:41], v[66:67], v[162:163]
	v_pk_fma_f32 v[160:161], s[40:41], v[68:69], v[160:161]
	v_pk_fma_f32 v[158:159], s[40:41], v[70:71], v[158:159]
	v_cvt_scalef32_pk_f32_fp4 v[64:65], v21, 1.0
	v_cvt_scalef32_pk_f32_fp4 v[66:67], v21, 1.0 op_sel:[1,0,0]
	v_cvt_scalef32_pk_f32_fp4 v[68:69], v21, 1.0 op_sel:[0,1,0]
	v_cvt_scalef32_pk_f32_fp4 v[70:71], v21, 1.0 op_sel:[1,1,0]
	v_mov_b64_e32 v[78:79], v[18:19]
	v_pk_fma_f32 v[156:157], s[40:41], v[64:65], v[156:157]
	v_pk_fma_f32 v[154:155], s[40:41], v[66:67], v[154:155]
	v_pk_fma_f32 v[152:153], s[40:41], v[68:69], v[152:153]
	v_pk_fma_f32 v[150:151], s[40:41], v[70:71], v[150:151]
	v_cvt_scalef32_pk_f32_fp4 v[64:65], v22, 1.0
	v_cvt_scalef32_pk_f32_fp4 v[66:67], v22, 1.0 op_sel:[1,0,0]
	v_cvt_scalef32_pk_f32_fp4 v[68:69], v22, 1.0 op_sel:[0,1,0]
	v_cvt_scalef32_pk_f32_fp4 v[70:71], v22, 1.0 op_sel:[1,1,0]
	v_mov_b64_e32 v[74:75], v[14:15]
	v_pk_fma_f32 v[148:149], s[40:41], v[64:65], v[148:149]
	v_pk_fma_f32 v[146:147], s[40:41], v[66:67], v[146:147]
	v_pk_fma_f32 v[144:145], s[40:41], v[68:69], v[144:145]
	v_pk_fma_f32 v[142:143], s[40:41], v[70:71], v[142:143]
	v_cvt_scalef32_pk_f32_fp4 v[64:65], v23, 1.0
	v_cvt_scalef32_pk_f32_fp4 v[66:67], v23, 1.0 op_sel:[1,0,0]
	v_cvt_scalef32_pk_f32_fp4 v[68:69], v23, 1.0 op_sel:[0,1,0]
	v_cvt_scalef32_pk_f32_fp4 v[70:71], v23, 1.0 op_sel:[1,1,0]
	v_mov_b64_e32 v[128:129], v[80:81]
	v_pk_fma_f32 v[140:141], s[40:41], v[64:65], v[140:141]
	v_pk_fma_f32 v[138:139], s[40:41], v[66:67], v[138:139]
	v_pk_fma_f32 v[136:137], s[40:41], v[68:69], v[136:137]
	v_pk_fma_f32 v[134:135], s[40:41], v[70:71], v[134:135]
	v_readlane_b32 s40, v209, 5
	v_cvt_scalef32_pk_f32_fp4 v[64:65], v24, 1.0
	v_cvt_scalef32_pk_f32_fp4 v[66:67], v24, 1.0 op_sel:[1,0,0]
	v_cvt_scalef32_pk_f32_fp4 v[68:69], v24, 1.0 op_sel:[0,1,0]
	v_cvt_scalef32_pk_f32_fp4 v[70:71], v24, 1.0 op_sel:[1,1,0]
	s_mov_b32 s41, s40
	v_pk_fma_f32 v[132:133], s[40:41], v[64:65], v[132:133]
	v_pk_fma_f32 v[162:163], s[40:41], v[66:67], v[162:163]
	v_pk_fma_f32 v[160:161], s[40:41], v[68:69], v[160:161]
	v_pk_fma_f32 v[158:159], s[40:41], v[70:71], v[158:159]
	v_cvt_scalef32_pk_f32_fp4 v[64:65], v25, 1.0
	v_cvt_scalef32_pk_f32_fp4 v[66:67], v25, 1.0 op_sel:[1,0,0]
	v_cvt_scalef32_pk_f32_fp4 v[68:69], v25, 1.0 op_sel:[0,1,0]
	v_cvt_scalef32_pk_f32_fp4 v[70:71], v25, 1.0 op_sel:[1,1,0]
	v_mov_b64_e32 v[124:125], v[60:61]
	v_pk_fma_f32 v[156:157], s[40:41], v[64:65], v[156:157]
	v_pk_fma_f32 v[154:155], s[40:41], v[66:67], v[154:155]
	v_pk_fma_f32 v[152:153], s[40:41], v[68:69], v[152:153]
	v_pk_fma_f32 v[150:151], s[40:41], v[70:71], v[150:151]
	v_cvt_scalef32_pk_f32_fp4 v[64:65], v26, 1.0
	v_cvt_scalef32_pk_f32_fp4 v[66:67], v26, 1.0 op_sel:[1,0,0]
	v_cvt_scalef32_pk_f32_fp4 v[68:69], v26, 1.0 op_sel:[0,1,0]
	v_cvt_scalef32_pk_f32_fp4 v[70:71], v26, 1.0 op_sel:[1,1,0]
; #define P4_FOR16(M) M(0) M(1) M(2) M(3) M(4) M(5) M(6) M(7) M(8) M(9) M(10) M(11) M(12) M(13) M(14) M(15)
; #define P4_V(i) { const unsigned wu_ = (unsigned)__builtin_amdgcn_readlane((int)__float_as_uint(wreg), i); const unsigned long long wp_ = ((unsigned long long)wu_ << 32) | wu_; \
;               P4_ACC(b##i, wp_); const int nk_ = __builtin_amdgcn_readlane(ksel, nb + i); P4_LOAD(b##i, Vg, nk_); }
; #define P4_V(i) { const unsigned wu_ = (unsigned)__builtin_amdgcn_readlane((int)__float_as_uint(wreg), i); const unsigned long long wp_ = ((unsigned long long)wu_ << 32) | wu_; \
;               P4_ACC(b##i, wp_); const int nk_ = __builtin_amdgcn_readlane(kn, i); P4_LOAD(b##i, Vg, nk_); }
; #define P4_V(i) { const unsigned wu_ = (unsigned)__builtin_amdgcn_readlane((int)__float_as_uint(wreg), i); const unsigned long long wp_ = ((unsigned long long)wu_ << 32) | wu_; \
;               P4_ACC(b##i, wp_); }
; __device__ __forceinline__ void peer_gather_f4p(const float* X, const int* __restrict__ IDX, const float* __restrict__ G, ...
;     ...
;                 P4_FOR16(P4_V)
	v_mov_b64_e32 v[120:121], v[56:57]
	v_pk_fma_f32 v[148:149], s[40:41], v[64:65], v[148:149]
	v_pk_fma_f32 v[146:147], s[40:41], v[66:67], v[146:147]
	v_pk_fma_f32 v[144:145], s[40:41], v[68:69], v[144:145]
	v_pk_fma_f32 v[142:143], s[40:41], v[70:71], v[142:143]
	v_cvt_scalef32_pk_f32_fp4 v[64:65], v27, 1.0
	v_cvt_scalef32_pk_f32_fp4 v[66:67], v27, 1.0 op_sel:[1,0,0]
	v_cvt_scalef32_pk_f32_fp4 v[68:69], v27, 1.0 op_sel:[0,1,0]
	v_cvt_scalef32_pk_f32_fp4 v[70:71], v27, 1.0 op_sel:[1,1,0]
	v_mov_b64_e32 v[116:117], v[52:53]
	v_pk_fma_f32 v[140:141], s[40:41], v[64:65], v[140:141]
	v_pk_fma_f32 v[138:139], s[40:41], v[66:67], v[138:139]
	v_pk_fma_f32 v[136:137], s[40:41], v[68:69], v[136:137]
	v_pk_fma_f32 v[134:135], s[40:41], v[70:71], v[134:135]
	v_readlane_b32 s40, v209, 6
	v_cvt_scalef32_pk_f32_fp4 v[64:65], v28, 1.0
	v_cvt_scalef32_pk_f32_fp4 v[66:67], v28, 1.0 op_sel:[1,0,0]
	v_cvt_scalef32_pk_f32_fp4 v[68:69], v28, 1.0 op_sel:[0,1,0]
	v_cvt_scalef32_pk_f32_fp4 v[70:71], v28, 1.0 op_sel:[1,1,0]
	s_mov_b32 s41, s40
	v_pk_fma_f32 v[132:133], s[40:41], v[64:65], v[132:133]
	v_pk_fma_f32 v[162:163], s[40:41], v[66:67], v[162:163]
	v_pk_fma_f32 v[160:161], s[40:41], v[68:69], v[160:161]
	v_pk_fma_f32 v[158:159], s[40:41], v[70:71], v[158:159]
	v_cvt_scalef32_pk_f32_fp4 v[64:65], v29, 1.0
	v_cvt_scalef32_pk_f32_fp4 v[66:67], v29, 1.0 op_sel:[1,0,0]
	v_cvt_scalef32_pk_f32_fp4 v[68:69], v29, 1.0 op_sel:[0,1,0]
	v_cvt_scalef32_pk_f32_fp4 v[70:71], v29, 1.0 op_sel:[1,1,0]
	v_mov_b64_e32 v[112:113], v[48:49]
	v_pk_fma_f32 v[156:157], s[40:41], v[64:65], v[156:157]
	v_pk_fma_f32 v[154:155], s[40:41], v[66:67], v[154:155]
	v_pk_fma_f32 v[152:153], s[40:41], v[68:69], v[152:153]
	v_pk_fma_f32 v[150:151], s[40:41], v[70:71], v[150:151]
	v_cvt_scalef32_pk_f32_fp4 v[64:65], v30, 1.0
	v_cvt_scalef32_pk_f32_fp4 v[66:67], v30, 1.0 op_sel:[1,0,0]
	v_cvt_scalef32_pk_f32_fp4 v[68:69], v30, 1.0 op_sel:[0,1,0]
	v_cvt_scalef32_pk_f32_fp4 v[70:71], v30, 1.0 op_sel:[1,1,0]
	v_mov_b64_e32 v[108:109], v[44:45]
	v_pk_fma_f32 v[148:149], s[40:41], v[64:65], v[148:149]
	v_pk_fma_f32 v[146:147], s[40:41], v[66:67], v[146:147]
	v_pk_fma_f32 v[144:145], s[40:41], v[68:69], v[144:145]
	v_pk_fma_f32 v[142:143], s[40:41], v[70:71], v[142:143]
	v_cvt_scalef32_pk_f32_fp4 v[64:65], v31, 1.0
	v_cvt_scalef32_pk_f32_fp4 v[66:67], v31, 1.0 op_sel:[1,0,0]
	v_cvt_scalef32_pk_f32_fp4 v[68:69], v31, 1.0 op_sel:[0,1,0]
	v_cvt_scalef32_pk_f32_fp4 v[70:71], v31, 1.0 op_sel:[1,1,0]
	v_mov_b64_e32 v[104:105], v[40:41]
	v_pk_fma_f32 v[140:141], s[40:41], v[64:65], v[140:141]
	v_pk_fma_f32 v[138:139], s[40:41], v[66:67], v[138:139]
	v_pk_fma_f32 v[136:137], s[40:41], v[68:69], v[136:137]
	v_pk_fma_f32 v[134:135], s[40:41], v[70:71], v[134:135]
	v_readlane_b32 s40, v209, 7
	v_cvt_scalef32_pk_f32_fp4 v[64:65], v32, 1.0
	v_cvt_scalef32_pk_f32_fp4 v[66:67], v32, 1.0 op_sel:[1,0,0]
	v_cvt_scalef32_pk_f32_fp4 v[68:69], v32, 1.0 op_sel:[0,1,0]
	v_cvt_scalef32_pk_f32_fp4 v[70:71], v32, 1.0 op_sel:[1,1,0]
	s_mov_b32 s41, s40
	v_pk_fma_f32 v[132:133], s[40:41], v[64:65], v[132:133]
	v_pk_fma_f32 v[162:163], s[40:41], v[66:67], v[162:163]
	v_pk_fma_f32 v[160:161], s[40:41], v[68:69], v[160:161]
	v_pk_fma_f32 v[158:159], s[40:41], v[70:71], v[158:159]
	v_cvt_scalef32_pk_f32_fp4 v[64:65], v33, 1.0
	v_cvt_scalef32_pk_f32_fp4 v[66:67], v33, 1.0 op_sel:[1,0,0]
	v_cvt_scalef32_pk_f32_fp4 v[68:69], v33, 1.0 op_sel:[0,1,0]
	v_cvt_scalef32_pk_f32_fp4 v[70:71], v33, 1.0 op_sel:[1,1,0]
	v_mov_b64_e32 v[100:101], v[36:37]
	v_pk_fma_f32 v[156:157], s[40:41], v[64:65], v[156:157]
	v_pk_fma_f32 v[154:155], s[40:41], v[66:67], v[154:155]
	v_pk_fma_f32 v[152:153], s[40:41], v[68:69], v[152:153]
	v_pk_fma_f32 v[150:151], s[40:41], v[70:71], v[150:151]
	v_cvt_scalef32_pk_f32_fp4 v[64:65], v34, 1.0
	v_cvt_scalef32_pk_f32_fp4 v[66:67], v34, 1.0 op_sel:[1,0,0]
	v_cvt_scalef32_pk_f32_fp4 v[68:69], v34, 1.0 op_sel:[0,1,0]
	v_cvt_scalef32_pk_f32_fp4 v[70:71], v34, 1.0 op_sel:[1,1,0]
	v_mov_b64_e32 v[96:97], v[32:33]
	v_pk_fma_f32 v[148:149], s[40:41], v[64:65], v[148:149]
	v_pk_fma_f32 v[146:147], s[40:41], v[66:67], v[146:147]
	v_pk_fma_f32 v[144:145], s[40:41], v[68:69], v[144:145]
	v_pk_fma_f32 v[142:143], s[40:41], v[70:71], v[142:143]
	v_cvt_scalef32_pk_f32_fp4 v[64:65], v35, 1.0
	v_cvt_scalef32_pk_f32_fp4 v[66:67], v35, 1.0 op_sel:[1,0,0]
	v_cvt_scalef32_pk_f32_fp4 v[68:69], v35, 1.0 op_sel:[0,1,0]
	v_cvt_scalef32_pk_f32_fp4 v[70:71], v35, 1.0 op_sel:[1,1,0]
	v_mov_b64_e32 v[92:93], v[28:29]
	v_pk_fma_f32 v[140:141], s[40:41], v[64:65], v[140:141]
	v_pk_fma_f32 v[138:139], s[40:41], v[66:67], v[138:139]
	v_pk_fma_f32 v[136:137], s[40:41], v[68:69], v[136:137]
	v_pk_fma_f32 v[134:135], s[40:41], v[70:71], v[134:135]
	v_readlane_b32 s40, v209, 8
	v_cvt_scalef32_pk_f32_fp4 v[64:65], v36, 1.0
	v_cvt_scalef32_pk_f32_fp4 v[66:67], v36, 1.0 op_sel:[1,0,0]
	v_cvt_scalef32_pk_f32_fp4 v[68:69], v36, 1.0 op_sel:[0,1,0]
	v_cvt_scalef32_pk_f32_fp4 v[70:71], v36, 1.0 op_sel:[1,1,0]
	s_mov_b32 s41, s40
	v_pk_fma_f32 v[132:133], s[40:41], v[64:65], v[132:133]
	v_pk_fma_f32 v[162:163], s[40:41], v[66:67], v[162:163]
	v_pk_fma_f32 v[160:161], s[40:41], v[68:69], v[160:161]
	v_pk_fma_f32 v[158:159], s[40:41], v[70:71], v[158:159]
	v_cvt_scalef32_pk_f32_fp4 v[64:65], v37, 1.0
	v_cvt_scalef32_pk_f32_fp4 v[66:67], v37, 1.0 op_sel:[1,0,0]
	v_cvt_scalef32_pk_f32_fp4 v[68:69], v37, 1.0 op_sel:[0,1,0]
	v_cvt_scalef32_pk_f32_fp4 v[70:71], v37, 1.0 op_sel:[1,1,0]
	v_mov_b64_e32 v[88:89], v[24:25]
	v_pk_fma_f32 v[156:157], s[40:41], v[64:65], v[156:157]
	v_pk_fma_f32 v[154:155], s[40:41], v[66:67], v[154:155]
	v_pk_fma_f32 v[152:153], s[40:41], v[68:69], v[152:153]
; #define P4_FOR16(M) M(0) M(1) M(2) M(3) M(4) M(5) M(6) M(7) M(8) M(9) M(10) M(11) M(12) M(13) M(14) M(15)
; #define P4_V(i) { const unsigned wu_ = (unsigned)__builtin_amdgcn_readlane((int)__float_as_uint(wreg), i); const unsigned long long wp_ = ((unsigned long long)wu_ << 32) | wu_; \
;               P4_ACC(b##i, wp_); const int nk_ = __builtin_amdgcn_readlane(ksel, nb + i); P4_LOAD(b##i, Vg, nk_); }
; #define P4_V(i) { const unsigned wu_ = (unsigned)__builtin_amdgcn_readlane((int)__float_as_uint(wreg), i); const unsigned long long wp_ = ((unsigned long long)wu_ << 32) | wu_; \
;               P4_ACC(b##i, wp_); const int nk_ = __builtin_amdgcn_readlane(kn, i); P4_LOAD(b##i, Vg, nk_); }
; #define P4_V(i) { const unsigned wu_ = (unsigned)__builtin_amdgcn_readlane((int)__float_as_uint(wreg), i); const unsigned long long wp_ = ((unsigned long long)wu_ << 32) | wu_; \
;               P4_ACC(b##i, wp_); }
; __device__ __forceinline__ void peer_gather_f4p(const float* X, const int* __restrict__ IDX, const float* __restrict__ G, ...
;     ...
;                 P4_FOR16(P4_V)
	v_pk_fma_f32 v[150:151], s[40:41], v[70:71], v[150:151]
	v_cvt_scalef32_pk_f32_fp4 v[64:65], v38, 1.0
	v_cvt_scalef32_pk_f32_fp4 v[66:67], v38, 1.0 op_sel:[1,0,0]
	v_cvt_scalef32_pk_f32_fp4 v[68:69], v38, 1.0 op_sel:[0,1,0]
	v_cvt_scalef32_pk_f32_fp4 v[70:71], v38, 1.0 op_sel:[1,1,0]
	v_mov_b64_e32 v[84:85], v[20:21]
	v_pk_fma_f32 v[148:149], s[40:41], v[64:65], v[148:149]
	v_pk_fma_f32 v[146:147], s[40:41], v[66:67], v[146:147]
	v_pk_fma_f32 v[144:145], s[40:41], v[68:69], v[144:145]
	v_pk_fma_f32 v[142:143], s[40:41], v[70:71], v[142:143]
	v_cvt_scalef32_pk_f32_fp4 v[64:65], v39, 1.0
	v_cvt_scalef32_pk_f32_fp4 v[66:67], v39, 1.0 op_sel:[1,0,0]
	v_cvt_scalef32_pk_f32_fp4 v[68:69], v39, 1.0 op_sel:[0,1,0]
	v_cvt_scalef32_pk_f32_fp4 v[70:71], v39, 1.0 op_sel:[1,1,0]
	v_mov_b64_e32 v[76:77], v[16:17]
	v_pk_fma_f32 v[140:141], s[40:41], v[64:65], v[140:141]
	v_pk_fma_f32 v[138:139], s[40:41], v[66:67], v[138:139]
	v_pk_fma_f32 v[136:137], s[40:41], v[68:69], v[136:137]
	v_pk_fma_f32 v[134:135], s[40:41], v[70:71], v[134:135]
	v_readlane_b32 s40, v209, 9
	v_cvt_scalef32_pk_f32_fp4 v[64:65], v40, 1.0
	v_cvt_scalef32_pk_f32_fp4 v[66:67], v40, 1.0 op_sel:[1,0,0]
	v_cvt_scalef32_pk_f32_fp4 v[68:69], v40, 1.0 op_sel:[0,1,0]
	v_cvt_scalef32_pk_f32_fp4 v[70:71], v40, 1.0 op_sel:[1,1,0]
	s_mov_b32 s41, s40
	v_pk_fma_f32 v[132:133], s[40:41], v[64:65], v[132:133]
	v_pk_fma_f32 v[162:163], s[40:41], v[66:67], v[162:163]
	v_pk_fma_f32 v[160:161], s[40:41], v[68:69], v[160:161]
	v_pk_fma_f32 v[158:159], s[40:41], v[70:71], v[158:159]
	v_cvt_scalef32_pk_f32_fp4 v[64:65], v41, 1.0
	v_cvt_scalef32_pk_f32_fp4 v[66:67], v41, 1.0 op_sel:[1,0,0]
	v_cvt_scalef32_pk_f32_fp4 v[68:69], v41, 1.0 op_sel:[0,1,0]
	v_cvt_scalef32_pk_f32_fp4 v[70:71], v41, 1.0 op_sel:[1,1,0]
	v_mov_b64_e32 v[72:73], v[12:13]
	v_pk_fma_f32 v[156:157], s[40:41], v[64:65], v[156:157]
	v_pk_fma_f32 v[154:155], s[40:41], v[66:67], v[154:155]
	v_pk_fma_f32 v[152:153], s[40:41], v[68:69], v[152:153]
	v_pk_fma_f32 v[150:151], s[40:41], v[70:71], v[150:151]
	v_cvt_scalef32_pk_f32_fp4 v[64:65], v42, 1.0
	v_cvt_scalef32_pk_f32_fp4 v[66:67], v42, 1.0 op_sel:[1,0,0]
	v_cvt_scalef32_pk_f32_fp4 v[68:69], v42, 1.0 op_sel:[0,1,0]
	v_cvt_scalef32_pk_f32_fp4 v[70:71], v42, 1.0 op_sel:[1,1,0]
	v_pk_fma_f32 v[148:149], s[40:41], v[64:65], v[148:149]
	v_pk_fma_f32 v[146:147], s[40:41], v[66:67], v[146:147]
	v_pk_fma_f32 v[144:145], s[40:41], v[68:69], v[144:145]
	v_pk_fma_f32 v[142:143], s[40:41], v[70:71], v[142:143]
	v_cvt_scalef32_pk_f32_fp4 v[64:65], v43, 1.0
	v_cvt_scalef32_pk_f32_fp4 v[66:67], v43, 1.0 op_sel:[1,0,0]
	v_cvt_scalef32_pk_f32_fp4 v[68:69], v43, 1.0 op_sel:[0,1,0]
	v_cvt_scalef32_pk_f32_fp4 v[70:71], v43, 1.0 op_sel:[1,1,0]
	v_pk_fma_f32 v[140:141], s[40:41], v[64:65], v[140:141]
	v_pk_fma_f32 v[138:139], s[40:41], v[66:67], v[138:139]
	v_pk_fma_f32 v[136:137], s[40:41], v[68:69], v[136:137]
	v_pk_fma_f32 v[134:135], s[40:41], v[70:71], v[134:135]
	v_readlane_b32 s40, v209, 10
	v_cvt_scalef32_pk_f32_fp4 v[64:65], v44, 1.0
	v_cvt_scalef32_pk_f32_fp4 v[66:67], v44, 1.0 op_sel:[1,0,0]
	v_cvt_scalef32_pk_f32_fp4 v[68:69], v44, 1.0 op_sel:[0,1,0]
	v_cvt_scalef32_pk_f32_fp4 v[70:71], v44, 1.0 op_sel:[1,1,0]
	s_mov_b32 s41, s40
	v_pk_fma_f32 v[132:133], s[40:41], v[64:65], v[132:133]
	v_pk_fma_f32 v[162:163], s[40:41], v[66:67], v[162:163]
	v_pk_fma_f32 v[160:161], s[40:41], v[68:69], v[160:161]
	v_pk_fma_f32 v[158:159], s[40:41], v[70:71], v[158:159]
	v_cvt_scalef32_pk_f32_fp4 v[64:65], v45, 1.0
	v_cvt_scalef32_pk_f32_fp4 v[66:67], v45, 1.0 op_sel:[1,0,0]
	v_cvt_scalef32_pk_f32_fp4 v[68:69], v45, 1.0 op_sel:[0,1,0]
	v_cvt_scalef32_pk_f32_fp4 v[70:71], v45, 1.0 op_sel:[1,1,0]
	v_pk_fma_f32 v[156:157], s[40:41], v[64:65], v[156:157]
	v_pk_fma_f32 v[154:155], s[40:41], v[66:67], v[154:155]
	v_pk_fma_f32 v[152:153], s[40:41], v[68:69], v[152:153]
	v_pk_fma_f32 v[150:151], s[40:41], v[70:71], v[150:151]
	v_cvt_scalef32_pk_f32_fp4 v[64:65], v46, 1.0
	v_cvt_scalef32_pk_f32_fp4 v[66:67], v46, 1.0 op_sel:[1,0,0]
	v_cvt_scalef32_pk_f32_fp4 v[68:69], v46, 1.0 op_sel:[0,1,0]
	v_cvt_scalef32_pk_f32_fp4 v[70:71], v46, 1.0 op_sel:[1,1,0]
	v_pk_fma_f32 v[148:149], s[40:41], v[64:65], v[148:149]
	v_pk_fma_f32 v[146:147], s[40:41], v[66:67], v[146:147]
	v_pk_fma_f32 v[144:145], s[40:41], v[68:69], v[144:145]
	v_pk_fma_f32 v[142:143], s[40:41], v[70:71], v[142:143]
	v_cvt_scalef32_pk_f32_fp4 v[64:65], v47, 1.0
	v_cvt_scalef32_pk_f32_fp4 v[66:67], v47, 1.0 op_sel:[1,0,0]
	v_cvt_scalef32_pk_f32_fp4 v[68:69], v47, 1.0 op_sel:[0,1,0]
	v_cvt_scalef32_pk_f32_fp4 v[70:71], v47, 1.0 op_sel:[1,1,0]
	v_pk_fma_f32 v[140:141], s[40:41], v[64:65], v[140:141]
	v_pk_fma_f32 v[138:139], s[40:41], v[66:67], v[138:139]
	v_pk_fma_f32 v[136:137], s[40:41], v[68:69], v[136:137]
	v_pk_fma_f32 v[134:135], s[40:41], v[70:71], v[134:135]
	v_readlane_b32 s40, v209, 11
	v_cvt_scalef32_pk_f32_fp4 v[64:65], v48, 1.0
	v_cvt_scalef32_pk_f32_fp4 v[66:67], v48, 1.0 op_sel:[1,0,0]
	v_cvt_scalef32_pk_f32_fp4 v[68:69], v48, 1.0 op_sel:[0,1,0]
	v_cvt_scalef32_pk_f32_fp4 v[70:71], v48, 1.0 op_sel:[1,1,0]
	s_mov_b32 s41, s40
	v_pk_fma_f32 v[132:133], s[40:41], v[64:65], v[132:133]
	v_pk_fma_f32 v[162:163], s[40:41], v[66:67], v[162:163]
	v_pk_fma_f32 v[160:161], s[40:41], v[68:69], v[160:161]
	v_pk_fma_f32 v[158:159], s[40:41], v[70:71], v[158:159]
	v_cvt_scalef32_pk_f32_fp4 v[64:65], v49, 1.0
	v_cvt_scalef32_pk_f32_fp4 v[66:67], v49, 1.0 op_sel:[1,0,0]
	v_cvt_scalef32_pk_f32_fp4 v[68:69], v49, 1.0 op_sel:[0,1,0]
	v_cvt_scalef32_pk_f32_fp4 v[70:71], v49, 1.0 op_sel:[1,1,0]
	v_pk_fma_f32 v[156:157], s[40:41], v[64:65], v[156:157]
; #define P4_FOR16(M) M(0) M(1) M(2) M(3) M(4) M(5) M(6) M(7) M(8) M(9) M(10) M(11) M(12) M(13) M(14) M(15)
; #define P4_V(i) { const unsigned wu_ = (unsigned)__builtin_amdgcn_readlane((int)__float_as_uint(wreg), i); const unsigned long long wp_ = ((unsigned long long)wu_ << 32) | wu_; \
;               P4_ACC(b##i, wp_); const int nk_ = __builtin_amdgcn_readlane(ksel, nb + i); P4_LOAD(b##i, Vg, nk_); }
; #define P4_V(i) { const unsigned wu_ = (unsigned)__builtin_amdgcn_readlane((int)__float_as_uint(wreg), i); const unsigned long long wp_ = ((unsigned long long)wu_ << 32) | wu_; \
;               P4_ACC(b##i, wp_); const int nk_ = __builtin_amdgcn_readlane(kn, i); P4_LOAD(b##i, Vg, nk_); }
; #define P4_V(i) { const unsigned wu_ = (unsigned)__builtin_amdgcn_readlane((int)__float_as_uint(wreg), i); const unsigned long long wp_ = ((unsigned long long)wu_ << 32) | wu_; \
;               P4_ACC(b##i, wp_); }
; __device__ __forceinline__ void peer_gather_f4p(const float* X, const int* __restrict__ IDX, const float* __restrict__ G, ...
;     ...
;                 P4_FOR16(P4_V)
	v_pk_fma_f32 v[154:155], s[40:41], v[66:67], v[154:155]
	v_pk_fma_f32 v[152:153], s[40:41], v[68:69], v[152:153]
	v_pk_fma_f32 v[150:151], s[40:41], v[70:71], v[150:151]
	v_cvt_scalef32_pk_f32_fp4 v[64:65], v50, 1.0
	v_cvt_scalef32_pk_f32_fp4 v[66:67], v50, 1.0 op_sel:[1,0,0]
	v_cvt_scalef32_pk_f32_fp4 v[68:69], v50, 1.0 op_sel:[0,1,0]
	v_cvt_scalef32_pk_f32_fp4 v[70:71], v50, 1.0 op_sel:[1,1,0]
	v_pk_fma_f32 v[148:149], s[40:41], v[64:65], v[148:149]
	v_pk_fma_f32 v[146:147], s[40:41], v[66:67], v[146:147]
	v_pk_fma_f32 v[144:145], s[40:41], v[68:69], v[144:145]
	v_pk_fma_f32 v[142:143], s[40:41], v[70:71], v[142:143]
	v_cvt_scalef32_pk_f32_fp4 v[64:65], v51, 1.0
	v_cvt_scalef32_pk_f32_fp4 v[66:67], v51, 1.0 op_sel:[1,0,0]
	v_cvt_scalef32_pk_f32_fp4 v[68:69], v51, 1.0 op_sel:[0,1,0]
	v_cvt_scalef32_pk_f32_fp4 v[70:71], v51, 1.0 op_sel:[1,1,0]
	v_pk_fma_f32 v[140:141], s[40:41], v[64:65], v[140:141]
	v_pk_fma_f32 v[138:139], s[40:41], v[66:67], v[138:139]
	v_pk_fma_f32 v[136:137], s[40:41], v[68:69], v[136:137]
	v_pk_fma_f32 v[134:135], s[40:41], v[70:71], v[134:135]
	v_readlane_b32 s40, v209, 12
	v_cvt_scalef32_pk_f32_fp4 v[64:65], v52, 1.0
	v_cvt_scalef32_pk_f32_fp4 v[66:67], v52, 1.0 op_sel:[1,0,0]
	v_cvt_scalef32_pk_f32_fp4 v[68:69], v52, 1.0 op_sel:[0,1,0]
	v_cvt_scalef32_pk_f32_fp4 v[70:71], v52, 1.0 op_sel:[1,1,0]
	s_mov_b32 s41, s40
	v_pk_fma_f32 v[132:133], s[40:41], v[64:65], v[132:133]
	v_pk_fma_f32 v[162:163], s[40:41], v[66:67], v[162:163]
	v_pk_fma_f32 v[160:161], s[40:41], v[68:69], v[160:161]
	v_pk_fma_f32 v[158:159], s[40:41], v[70:71], v[158:159]
	v_cvt_scalef32_pk_f32_fp4 v[64:65], v53, 1.0
	v_cvt_scalef32_pk_f32_fp4 v[66:67], v53, 1.0 op_sel:[1,0,0]
	v_cvt_scalef32_pk_f32_fp4 v[68:69], v53, 1.0 op_sel:[0,1,0]
	v_cvt_scalef32_pk_f32_fp4 v[70:71], v53, 1.0 op_sel:[1,1,0]
	v_pk_fma_f32 v[156:157], s[40:41], v[64:65], v[156:157]
	v_pk_fma_f32 v[154:155], s[40:41], v[66:67], v[154:155]
	v_pk_fma_f32 v[152:153], s[40:41], v[68:69], v[152:153]
	v_pk_fma_f32 v[150:151], s[40:41], v[70:71], v[150:151]
	v_cvt_scalef32_pk_f32_fp4 v[64:65], v54, 1.0
	v_cvt_scalef32_pk_f32_fp4 v[66:67], v54, 1.0 op_sel:[1,0,0]
	v_cvt_scalef32_pk_f32_fp4 v[68:69], v54, 1.0 op_sel:[0,1,0]
	v_cvt_scalef32_pk_f32_fp4 v[70:71], v54, 1.0 op_sel:[1,1,0]
	v_pk_fma_f32 v[148:149], s[40:41], v[64:65], v[148:149]
	v_pk_fma_f32 v[146:147], s[40:41], v[66:67], v[146:147]
	v_pk_fma_f32 v[144:145], s[40:41], v[68:69], v[144:145]
	v_pk_fma_f32 v[142:143], s[40:41], v[70:71], v[142:143]
	v_cvt_scalef32_pk_f32_fp4 v[64:65], v55, 1.0
	v_cvt_scalef32_pk_f32_fp4 v[66:67], v55, 1.0 op_sel:[1,0,0]
	v_cvt_scalef32_pk_f32_fp4 v[68:69], v55, 1.0 op_sel:[0,1,0]
	v_cvt_scalef32_pk_f32_fp4 v[70:71], v55, 1.0 op_sel:[1,1,0]
	v_pk_fma_f32 v[140:141], s[40:41], v[64:65], v[140:141]
	v_pk_fma_f32 v[138:139], s[40:41], v[66:67], v[138:139]
	v_pk_fma_f32 v[136:137], s[40:41], v[68:69], v[136:137]
	v_pk_fma_f32 v[134:135], s[40:41], v[70:71], v[134:135]
	v_readlane_b32 s40, v209, 13
	v_cvt_scalef32_pk_f32_fp4 v[64:65], v56, 1.0
	v_cvt_scalef32_pk_f32_fp4 v[66:67], v56, 1.0 op_sel:[1,0,0]
	v_cvt_scalef32_pk_f32_fp4 v[68:69], v56, 1.0 op_sel:[0,1,0]
	v_cvt_scalef32_pk_f32_fp4 v[70:71], v56, 1.0 op_sel:[1,1,0]
	s_mov_b32 s41, s40
	v_pk_fma_f32 v[132:133], s[40:41], v[64:65], v[132:133]
	v_pk_fma_f32 v[162:163], s[40:41], v[66:67], v[162:163]
	v_pk_fma_f32 v[160:161], s[40:41], v[68:69], v[160:161]
	v_pk_fma_f32 v[158:159], s[40:41], v[70:71], v[158:159]
	v_cvt_scalef32_pk_f32_fp4 v[64:65], v57, 1.0
	v_cvt_scalef32_pk_f32_fp4 v[66:67], v57, 1.0 op_sel:[1,0,0]
	v_cvt_scalef32_pk_f32_fp4 v[68:69], v57, 1.0 op_sel:[0,1,0]
	v_cvt_scalef32_pk_f32_fp4 v[70:71], v57, 1.0 op_sel:[1,1,0]
	v_pk_fma_f32 v[156:157], s[40:41], v[64:65], v[156:157]
	v_pk_fma_f32 v[154:155], s[40:41], v[66:67], v[154:155]
	v_pk_fma_f32 v[152:153], s[40:41], v[68:69], v[152:153]
	v_pk_fma_f32 v[150:151], s[40:41], v[70:71], v[150:151]
	v_cvt_scalef32_pk_f32_fp4 v[64:65], v58, 1.0
	v_cvt_scalef32_pk_f32_fp4 v[66:67], v58, 1.0 op_sel:[1,0,0]
	v_cvt_scalef32_pk_f32_fp4 v[68:69], v58, 1.0 op_sel:[0,1,0]
	v_cvt_scalef32_pk_f32_fp4 v[70:71], v58, 1.0 op_sel:[1,1,0]
	v_pk_fma_f32 v[148:149], s[40:41], v[64:65], v[148:149]
	v_pk_fma_f32 v[146:147], s[40:41], v[66:67], v[146:147]
	v_pk_fma_f32 v[144:145], s[40:41], v[68:69], v[144:145]
	v_pk_fma_f32 v[142:143], s[40:41], v[70:71], v[142:143]
	v_cvt_scalef32_pk_f32_fp4 v[64:65], v59, 1.0
	v_cvt_scalef32_pk_f32_fp4 v[66:67], v59, 1.0 op_sel:[1,0,0]
	v_cvt_scalef32_pk_f32_fp4 v[68:69], v59, 1.0 op_sel:[0,1,0]
	v_cvt_scalef32_pk_f32_fp4 v[70:71], v59, 1.0 op_sel:[1,1,0]
	v_pk_fma_f32 v[140:141], s[40:41], v[64:65], v[140:141]
	v_pk_fma_f32 v[138:139], s[40:41], v[66:67], v[138:139]
	v_pk_fma_f32 v[136:137], s[40:41], v[68:69], v[136:137]
; #define GAS __attribute__((address_space(1)))
; #define P4_FOR16(M) M(0) M(1) M(2) M(3) M(4) M(5) M(6) M(7) M(8) M(9) M(10) M(11) M(12) M(13) M(14) M(15)
; #define P4_V(i) { const unsigned wu_ = (unsigned)__builtin_amdgcn_readlane((int)__float_as_uint(wreg), i); const unsigned long long wp_ = ((unsigned long long)wu_ << 32) | wu_; \
;               P4_ACC(b##i, wp_); const int nk_ = __builtin_amdgcn_readlane(ksel, nb + i); P4_LOAD(b##i, Vg, nk_); }
; #define P4_V(i) { const unsigned wu_ = (unsigned)__builtin_amdgcn_readlane((int)__float_as_uint(wreg), i); const unsigned long long wp_ = ((unsigned long long)wu_ << 32) | wu_; \
;               P4_ACC(b##i, wp_); const int nk_ = __builtin_amdgcn_readlane(kn, i); P4_LOAD(b##i, Vg, nk_); }
; #define P4_V(i) { const unsigned wu_ = (unsigned)__builtin_amdgcn_readlane((int)__float_as_uint(wreg), i); const unsigned long long wp_ = ((unsigned long long)wu_ << 32) | wu_; \
;               P4_ACC(b##i, wp_); }
; __device__ __forceinline__ void peer_gather_f4p(const float* X, const int* __restrict__ IDX, const float* __restrict__ G, ...
;     ...
;                 P4_FOR16(P4_V)
;     ...
;         asm volatile("" : "+v"(lane));
;         f32x2 xr[16];
; #pragma unroll
;         for (int j = 0; j < 8; ++j) {
;             if (RES_BF16) {
;                 const u32x2 t2 = *(const GAS u32x2*)((const GAS bf16_t*)xbout + (size_t)row * D + 256 * j + lane * 4);
;                 xr[2 * j] = f32x2{__uint_as_float(t2[0] << 16), __uint_as_float(t2[0] & 0xffff0000u)}; xr[2 * j + 1] = f32x2{__uint_as_float(t2[1] << 16), __uint_as_float(t2[1] & 0xffff0000u)};
;             } else {
;                 const f32x4 t4 = *(const GAS f32x4*)((const GAS float*)X + (size_t)row * D + 256 * j + lane * 4);
;                 xr[2 * j] = f32x2{t4[0], t4[1]}; xr[2 * j + 1] = f32x2{t4[2], t4[3]};
;             }
;         }
;         float s1 = 0.f;
; #pragma unroll
;         for (int k = 0; k < 16; ++k) { acc[k][0] = fmaf(ALPHA, xr[k][0], acc[k][0]); acc[k][1] = fmaf(ALPHA, xr[k][1], acc[k][1]); s1 += acc[k][0] + acc[k][1]; }
	v_pk_fma_f32 v[134:135], s[40:41], v[70:71], v[134:135]
	v_readlane_b32 s40, v209, 14
	v_cvt_scalef32_pk_f32_fp4 v[64:65], v60, 1.0
	v_cvt_scalef32_pk_f32_fp4 v[66:67], v60, 1.0 op_sel:[1,0,0]
	v_cvt_scalef32_pk_f32_fp4 v[68:69], v60, 1.0 op_sel:[0,1,0]
	v_cvt_scalef32_pk_f32_fp4 v[70:71], v60, 1.0 op_sel:[1,1,0]
	s_mov_b32 s41, s40
	v_pk_fma_f32 v[132:133], s[40:41], v[64:65], v[132:133]
	v_pk_fma_f32 v[162:163], s[40:41], v[66:67], v[162:163]
	v_pk_fma_f32 v[160:161], s[40:41], v[68:69], v[160:161]
	v_pk_fma_f32 v[158:159], s[40:41], v[70:71], v[158:159]
	v_cvt_scalef32_pk_f32_fp4 v[64:65], v61, 1.0
	v_cvt_scalef32_pk_f32_fp4 v[66:67], v61, 1.0 op_sel:[1,0,0]
	v_cvt_scalef32_pk_f32_fp4 v[68:69], v61, 1.0 op_sel:[0,1,0]
	v_cvt_scalef32_pk_f32_fp4 v[70:71], v61, 1.0 op_sel:[1,1,0]
	v_pk_fma_f32 v[156:157], s[40:41], v[64:65], v[156:157]
	v_pk_fma_f32 v[154:155], s[40:41], v[66:67], v[154:155]
	v_pk_fma_f32 v[152:153], s[40:41], v[68:69], v[152:153]
	v_pk_fma_f32 v[150:151], s[40:41], v[70:71], v[150:151]
	v_cvt_scalef32_pk_f32_fp4 v[64:65], v62, 1.0
	v_cvt_scalef32_pk_f32_fp4 v[66:67], v62, 1.0 op_sel:[1,0,0]
	v_cvt_scalef32_pk_f32_fp4 v[68:69], v62, 1.0 op_sel:[0,1,0]
	v_cvt_scalef32_pk_f32_fp4 v[70:71], v62, 1.0 op_sel:[1,1,0]
	v_pk_fma_f32 v[148:149], s[40:41], v[64:65], v[148:149]
	v_pk_fma_f32 v[146:147], s[40:41], v[66:67], v[146:147]
	v_pk_fma_f32 v[144:145], s[40:41], v[68:69], v[144:145]
	v_pk_fma_f32 v[142:143], s[40:41], v[70:71], v[142:143]
	v_cvt_scalef32_pk_f32_fp4 v[64:65], v63, 1.0
	v_cvt_scalef32_pk_f32_fp4 v[66:67], v63, 1.0 op_sel:[1,0,0]
	v_cvt_scalef32_pk_f32_fp4 v[68:69], v63, 1.0 op_sel:[0,1,0]
	v_cvt_scalef32_pk_f32_fp4 v[70:71], v63, 1.0 op_sel:[1,1,0]
	v_pk_fma_f32 v[140:141], s[40:41], v[64:65], v[140:141]
	v_pk_fma_f32 v[138:139], s[40:41], v[66:67], v[138:139]
	v_pk_fma_f32 v[136:137], s[40:41], v[68:69], v[136:137]
	v_pk_fma_f32 v[134:135], s[40:41], v[70:71], v[134:135]
	v_readlane_b32 s40, v209, 15
	v_cvt_scalef32_pk_f32_fp4 v[64:65], v80, 1.0
	v_cvt_scalef32_pk_f32_fp4 v[66:67], v80, 1.0 op_sel:[1,0,0]
	v_cvt_scalef32_pk_f32_fp4 v[68:69], v80, 1.0 op_sel:[0,1,0]
	v_cvt_scalef32_pk_f32_fp4 v[70:71], v80, 1.0 op_sel:[1,1,0]
	s_mov_b32 s41, s40
	v_pk_fma_f32 v[132:133], s[40:41], v[64:65], v[132:133]
	v_pk_fma_f32 v[162:163], s[40:41], v[66:67], v[162:163]
	v_pk_fma_f32 v[160:161], s[40:41], v[68:69], v[160:161]
	v_pk_fma_f32 v[158:159], s[40:41], v[70:71], v[158:159]
	v_cvt_scalef32_pk_f32_fp4 v[64:65], v81, 1.0
	v_cvt_scalef32_pk_f32_fp4 v[66:67], v81, 1.0 op_sel:[1,0,0]
	v_cvt_scalef32_pk_f32_fp4 v[68:69], v81, 1.0 op_sel:[0,1,0]
	v_cvt_scalef32_pk_f32_fp4 v[70:71], v81, 1.0 op_sel:[1,1,0]
	s_nop 0
	v_mov_b32_e32 v166, v132
	v_pk_fma_f32 v[156:157], s[40:41], v[64:65], v[156:157]
	v_pk_fma_f32 v[154:155], s[40:41], v[66:67], v[154:155]
	v_pk_fma_f32 v[152:153], s[40:41], v[68:69], v[152:153]
	v_pk_fma_f32 v[150:151], s[40:41], v[70:71], v[150:151]
	v_cvt_scalef32_pk_f32_fp4 v[64:65], v82, 1.0
	v_cvt_scalef32_pk_f32_fp4 v[66:67], v82, 1.0 op_sel:[1,0,0]
	v_cvt_scalef32_pk_f32_fp4 v[68:69], v82, 1.0 op_sel:[0,1,0]
	v_cvt_scalef32_pk_f32_fp4 v[70:71], v82, 1.0 op_sel:[1,1,0]
	v_mov_b32_e32 v167, v133
	v_pk_fma_f32 v[148:149], s[40:41], v[64:65], v[148:149]
	v_pk_fma_f32 v[146:147], s[40:41], v[66:67], v[146:147]
	v_pk_fma_f32 v[144:145], s[40:41], v[68:69], v[144:145]
	v_pk_fma_f32 v[142:143], s[40:41], v[70:71], v[142:143]
	v_cvt_scalef32_pk_f32_fp4 v[64:65], v83, 1.0
	v_cvt_scalef32_pk_f32_fp4 v[66:67], v83, 1.0 op_sel:[1,0,0]
	v_cvt_scalef32_pk_f32_fp4 v[68:69], v83, 1.0 op_sel:[0,1,0]
	v_cvt_scalef32_pk_f32_fp4 v[70:71], v83, 1.0 op_sel:[1,1,0]
	v_mov_b32_e32 v168, v162
	v_pk_fma_f32 v[140:141], s[40:41], v[64:65], v[140:141]
	v_pk_fma_f32 v[138:139], s[40:41], v[66:67], v[138:139]
	v_pk_fma_f32 v[136:137], s[40:41], v[68:69], v[136:137]
	v_pk_fma_f32 v[134:135], s[40:41], v[70:71], v[134:135]
	v_mov_b64_e32 v[70:71], v[10:11]
	v_mov_b64_e32 v[66:67], v[6:7]
	v_mov_b64_e32 v[68:69], v[8:9]
	v_mov_b64_e32 v[64:65], v[4:5]
	v_mov_b32_e32 v169, v163
	v_mov_b32_e32 v170, v160
	v_mov_b32_e32 v171, v161
	v_mov_b32_e32 v172, v158
	v_mov_b32_e32 v173, v159
	v_mov_b32_e32 v174, v156
	v_mov_b32_e32 v175, v157
	v_mov_b32_e32 v176, v154
	v_mov_b32_e32 v177, v155
	v_mov_b32_e32 v178, v152
	v_mov_b32_e32 v179, v153
	v_mov_b32_e32 v180, v150
	v_mov_b32_e32 v181, v151
	v_mov_b32_e32 v182, v148
	v_mov_b32_e32 v183, v149
	v_mov_b32_e32 v184, v146
	v_mov_b32_e32 v185, v147
	v_mov_b32_e32 v186, v144
	v_mov_b32_e32 v187, v145
	v_mov_b32_e32 v188, v142
	v_mov_b32_e32 v189, v143
	v_mov_b32_e32 v190, v140
	v_mov_b32_e32 v191, v141
	v_mov_b32_e32 v192, v138
	v_mov_b32_e32 v193, v139
	v_mov_b32_e32 v194, v136
	v_mov_b32_e32 v195, v137
	v_mov_b32_e32 v196, v134
	v_mov_b32_e32 v197, v135
